# P9: PEER table fp4 conversion interleaved into the routing loop of every wave (loads issued in the register-only stretches, converted at the next point); copy loops skipped
# speedup vs baseline: 1.0044x; 1.0044x over previous
.LBB0_783:
	s_cmp_lt_i32 s74, 10
	s_cselect_b64 s[0:1], -1, 0
	s_cmp_gt_i32 s75, 9
	s_cselect_b64 s[2:3], -1, 0
	s_and_b64 s[0:1], s[0:1], s[2:3]
	s_andn2_b64 vcc, exec, s[0:1]
	s_cbranch_vccnz .LBB0_864
	s_ashr_i32 s19, s18, 31
	s_ashr_i32 s91, s90, 31
	s_lshl_b64 s[0:1], s[18:19], 9
	s_lshl_b64 s[4:5], s[90:91], 9
	s_add_u32 s2, s72, 0xab00000
	s_addc_u32 s3, s73, 0
	s_add_u32 s6, s72, 0x2200000
	s_addc_u32 s7, s73, 0
	s_add_u32 s8, s72, 0x1eb00000
	s_addc_u32 s9, s73, 0
	s_add_u32 s10, s72, 0x1f300000
	v_readlane_b32 s91, v243, 0
	s_addc_u32 s11, s73, 0
	s_lshl_b32 s12, s90, 3
	s_add_i32 s19, s12, s91
	s_and_b32 s99, s19, 0x7ff
	s_load_dwordx2 s[92:93], s[68:69], 0x58
	s_load_dwordx2 s[94:95], s[68:69], 0x60
	s_lshl_b32 s52, s99, 13
	s_lshl_b32 s53, s99, 10
	s_add_u32 s46, s72, 0x2b00000
	s_addc_u32 s47, s73, 0
	s_add_u32 s46, s46, s53
	s_addc_u32 s47, s47, 0
	s_add_u32 s48, s46, 0x1800000
	s_addc_u32 s49, s47, 0
	s_waitcnt lgkmcnt(0)
	s_add_u32 s92, s92, s52
	s_addc_u32 s93, s93, 0
	s_add_u32 s94, s94, s52
	s_addc_u32 s95, s95, 0
	s_mov_b32 s98, 0
	v_mov_b32_e32 v244, 0x1000000
	v_mov_b32_e32 v245, 0
	v_mov_b32_e32 v246, 0x200000
	v_mov_b32_e32 v247, 0
	v_mov_b32_e32 v250, 0x1000
	v_mov_b32_e32 v251, 0
	s_lshl_b32 s12, s91, 13
	v_and_b32_e32 v76, 0x3f0, v1
	v_mov_b32_e32 v77, 0
	s_lshl_b32 s21, s18, 3
	s_add_i32 s26, s12, 0
	v_lshl_add_u64 v[2:3], s[72:73], 0, v[76:77]
	s_mov_b64 s[14:15], 0x2b00000
	s_cmpk_lt_i32 s19, 0x1000
	v_or_b32_e32 v70, s4, v0
	v_mov_b32_e32 v71, s5
	s_mov_b64 s[4:5], 0x100000
	v_lshl_add_u64 v[74:75], v[2:3], 0, s[14:15]
	s_mov_b64 s[14:15], 0x4300000
	s_cselect_b64 s[12:13], -1, 0
	s_cmpk_gt_u32 s76, 0xff
	v_cmp_gt_u64_e64 s[4:5], s[4:5], v[70:71]
	v_lshl_add_u64 v[72:73], v[2:3], 0, s[14:15]
	v_and_b32_e32 v1, 63, v0
	s_mov_b64 s[14:15], -1
	s_cbranch_scc1 .LBB0_787
	s_and_b64 vcc, exec, s[14:15]
	s_cbranch_vccnz .LBB0_799

.LBB0_787:
	s_load_dwordx2 s[16:17], s[68:69], 0x58
	s_waitcnt lgkmcnt(0)
	s_cmpk_eq_i32 s18, 0x100
	s_cbranch_scc1 .LBB0_790
	s_and_saveexec_b64 s[14:15], s[4:5]
	s_cbranch_execz .LBB0_790
	v_lshlrev_b32_e32 v2, 2, v76
	v_mov_b32_e32 v3, 0
	v_lshl_add_u64 v[2:3], s[16:17], 0, v[2:3]
	s_mov_b64 s[16:17], 0
	s_mov_b32 s20, 0x42580000
	s_mov_b64 s[22:23], 0x1000
	s_movk_i32 s27, 0x1000
	s_mov_b64 s[24:25], 0xfffff
	v_mov_b64_e32 v[4:5], v[70:71]

.LBB0_790:
	s_or_b64 exec, exec, s[14:15]
	s_load_dwordx2 s[16:17], s[68:69], 0x60
	s_waitcnt lgkmcnt(0)
	s_cmpk_eq_i32 s18, 0x100
	s_cbranch_scc1 .LBB0_793
	s_and_saveexec_b64 s[14:15], s[4:5]
	s_cbranch_execz .LBB0_793
	v_lshlrev_b32_e32 v2, 2, v76
	v_mov_b32_e32 v3, 0
	v_lshl_add_u64 v[2:3], s[16:17], 0, v[2:3]
	s_mov_b64 s[16:17], 0
	s_mov_b32 s20, 0x40b66666
	s_mov_b64 s[22:23], 0x1000
	s_movk_i32 s27, 0x1000
	s_mov_b64 s[24:25], 0xfffff
	v_mov_b64_e32 v[4:5], v[70:71]

.LBB0_796:
	s_bitcmp1_b32 s98, 0
	s_cselect_b32 s52, s94, s92
	s_cselect_b32 s53, s95, s93
	s_cselect_b32 s54, s48, s46
	s_cselect_b32 s55, s49, s47
	s_mov_b32 s96, 0x42580000
	s_cselect_b32 s96, 0x40b66666, s96
	s_add_i32 s98, s98, 1
	v_mbcnt_lo_u32_b32 v248, -1, 0
	v_mbcnt_hi_u32_b32 v248, -1, v248
	v_lshlrev_b32_e32 v236, 6, v248
	v_mov_b32_e32 v237, 0
	v_lshl_add_u64 v[236:237], s[52:53], 0, v[236:237]
	v_lshl_add_u64 v[238:239], v[236:237], 0, v[250:251]
	v_lshlrev_b32_e32 v240, 4, v248
	v_mov_b32_e32 v241, 0
	v_lshl_add_u64 v[240:241], s[54:55], 0, v[240:241]
	s_lshr_b32 s14, s34, 3
	s_and_b32 s14, s14, 0x7fffff8
	v_mov_b32_e32 v87, v1
	s_or_b32 s14, s14, s20
	s_lshl_b32 s36, s14, 5
	v_and_b32_e32 v4, 31, v87
	v_or_b32_e32 v2, s36, v4
	v_ashrrev_i32_e32 v3, 31, v2
	v_ashrrev_i32_e32 v118, 5, v87
	v_lshlrev_b64 v[2:3], 12, v[2:3]
	v_lshl_add_u64 v[6:7], s[2:3], 0, v[2:3]
	v_lshlrev_b32_e32 v2, 3, v118
	v_ashrrev_i32_e32 v3, 31, v2
	s_bfe_u32 s35, s34, 0x30003
	v_lshlrev_b64 v[8:9], 1, v[2:3]
	v_lshlrev_b32_e32 v4, 8, v4
	v_lshl_add_u64 v[2:3], s[6:7], 0, v[8:9]
	v_lshl_or_b32 v78, s35, 16, v4
	v_lshl_add_u64 v[80:81], v[2:3], 0, v[78:79]
	global_load_dwordx4 v[2:5], v[80:81], off
	s_lshl_b32 s14, s35, 9
	v_lshl_add_u64 v[6:7], v[6:7], 0, s[14:15]
	v_lshl_add_u64 v[82:83], v[6:7], 0, v[8:9]
	global_load_dwordx4 v[34:37], v[82:83], off
	global_load_dwordx4 v[88:91], v[80:81], off offset:32
	global_load_dwordx4 v[92:95], v[80:81], off offset:64
	global_load_dwordx4 v[96:99], v[80:81], off offset:96
	global_load_dwordx4 v[100:103], v[80:81], off offset:128
	global_load_dwordx4 v[104:107], v[80:81], off offset:160
	global_load_dwordx4 v[108:111], v[80:81], off offset:192
	global_load_dwordx4 v[66:69], v[80:81], off offset:224
	global_load_dwordx4 v[62:65], v[82:83], off offset:32
	global_load_dwordx4 v[58:61], v[82:83], off offset:64
	global_load_dwordx4 v[54:57], v[82:83], off offset:96
	global_load_dwordx4 v[50:53], v[82:83], off offset:128
	global_load_dwordx4 v[46:49], v[82:83], off offset:160
	global_load_dwordx4 v[42:45], v[82:83], off offset:192
	global_load_dwordx4 v[38:41], v[82:83], off offset:224
	v_add_co_u32_e32 v116, vcc, s24, v80
	v_lshlrev_b32_e32 v146, 2, v118
	s_nop 0
	v_addc_co_u32_e32 v117, vcc, 0, v81, vcc
	global_load_dwordx4 v[6:9], v[116:117], off
	global_load_dwordx4 v[112:115], v[116:117], off offset:32
	v_add_co_u32_e32 v136, vcc, s25, v80
	v_sub_u32_e32 v78, 0x66, v146
	s_nop 0
	v_addc_co_u32_e32 v137, vcc, 0, v81, vcc
	v_sub_u32_e32 v144, 6, v146
	v_sub_u32_e32 v145, 5, v146
	s_waitcnt vmcnt(0)
	v_mfma_f32_32x32x16_bf16 v[18:33], v[2:5], v[34:37], 0
	v_mfma_f32_32x32x16_bf16 v[18:33], v[88:91], v[62:65], v[18:33]
	global_load_dwordx4 v[88:91], v[116:117], off offset:64
	v_mfma_f32_32x32x16_bf16 v[2:17], v[6:9], v[34:37], 0
	v_mfma_f32_32x32x16_bf16 v[2:17], v[112:115], v[62:65], v[2:17]
	global_load_dwordx4 v[112:115], v[116:117], off offset:160
	v_mfma_f32_32x32x16_bf16 v[18:33], v[92:95], v[58:61], v[18:33]
	global_load_dwordx4 v[92:95], v[116:117], off offset:96
	s_waitcnt vmcnt(0)
	v_mfma_f32_32x32x16_bf16 v[2:17], v[88:91], v[58:61], v[2:17]
	global_load_dwordx4 v[88:91], v[116:117], off offset:128
	v_mfma_f32_32x32x16_bf16 v[18:33], v[96:99], v[54:57], v[18:33]
	v_sub_u32_e32 v98, 0x7e, v146
	v_or_b32_e32 v99, 3, v146
	v_sub_u32_e32 v97, 0x77, v146
	v_sub_u32_e32 v96, 0x76, v146
	v_sub_u32_e32 v99, 0x7f, v99
	v_mfma_f32_32x32x16_bf16 v[18:33], v[100:103], v[50:53], v[18:33]
	v_sub_u32_e32 v100, 0x7f, v146
	v_mfma_f32_32x32x16_bf16 v[18:33], v[104:107], v[46:49], v[18:33]
	v_mfma_f32_32x32x16_bf16 v[18:33], v[108:111], v[42:45], v[18:33]
	global_load_dwordx4 v[104:107], v[116:117], off offset:192
	global_load_dwordx4 v[108:111], v[116:117], off offset:224
	v_mfma_f32_32x32x16_bf16 v[2:17], v[92:95], v[54:57], v[2:17]
	v_sub_u32_e32 v95, 0x75, v146
	v_sub_u32_e32 v94, 0x74, v146
	v_sub_u32_e32 v93, 0x6f, v146
	v_sub_u32_e32 v92, 0x6e, v146
	v_mfma_f32_32x32x16_bf16 v[18:33], v[66:69], v[38:41], v[18:33]
	s_waitcnt vmcnt(0)
	v_mfma_f32_32x32x16_bf16 v[2:17], v[88:91], v[50:53], v[2:17]
	s_nop 9
	v_not_b32_e32 v66, v18
	v_or_b32_e32 v67, 0x80000000, v18
	v_cmp_gt_i32_e32 vcc, 0, v18
	v_or_b32_e32 v91, 2, v146
	v_not_b32_e32 v68, v19
	v_or_b32_e32 v69, 0x80000000, v19
	v_cndmask_b32_e32 v18, v67, v66, vcc
	v_mfma_f32_32x32x16_bf16 v[2:17], v[112:115], v[46:49], v[2:17]
	global_load_dwordx4 v[112:115], v[136:137], off
	v_cmp_gt_i32_e32 vcc, 0, v19
	v_sub_u32_e32 v101, 0x7f, v91
	v_not_b32_e32 v91, v20
	v_or_b32_e32 v102, 0x80000000, v20
	v_cndmask_b32_e32 v19, v69, v68, vcc
	v_cmp_gt_i32_e32 vcc, 0, v20
	v_not_b32_e32 v103, v21
	v_or_b32_e32 v116, 0x80000000, v21
	v_cndmask_b32_e32 v20, v102, v91, vcc
	v_cmp_gt_i32_e32 vcc, 0, v21
	v_not_b32_e32 v117, v22
	v_or_b32_e32 v118, 0x80000000, v22
	v_cndmask_b32_e32 v21, v116, v103, vcc
	v_cmp_gt_i32_e32 vcc, 0, v22
	v_not_b32_e32 v119, v23
	v_or_b32_e32 v120, 0x80000000, v23
	v_cndmask_b32_e32 v22, v118, v117, vcc
	v_cmp_gt_i32_e32 vcc, 0, v23
	v_not_b32_e32 v121, v24
	v_or_b32_e32 v122, 0x80000000, v24
	v_cndmask_b32_e32 v23, v120, v119, vcc
	global_load_dwordx4 v[116:119], v[136:137], off offset:32
	v_cmp_gt_i32_e32 vcc, 0, v24
	v_not_b32_e32 v123, v25
	v_or_b32_e32 v124, 0x80000000, v25
	v_cndmask_b32_e32 v24, v122, v121, vcc
	v_cmp_gt_i32_e32 vcc, 0, v25
	v_not_b32_e32 v125, v26
	v_or_b32_e32 v126, 0x80000000, v26
	v_cndmask_b32_e32 v25, v124, v123, vcc
	global_load_dwordx4 v[120:123], v[136:137], off offset:64
	v_cmp_gt_i32_e32 vcc, 0, v26
	v_not_b32_e32 v127, v27
	v_or_b32_e32 v128, 0x80000000, v27
	v_cndmask_b32_e32 v26, v126, v125, vcc
	v_cmp_gt_i32_e32 vcc, 0, v27
	v_mfma_f32_32x32x16_bf16 v[2:17], v[104:107], v[42:45], v[2:17]
	v_not_b32_e32 v129, v28
	v_cndmask_b32_e32 v27, v128, v127, vcc
	global_load_dwordx4 v[124:127], v[136:137], off offset:96
	v_or_b32_e32 v130, 0x80000000, v28
	v_cmp_gt_i32_e32 vcc, 0, v28
	v_not_b32_e32 v131, v29
	v_or_b32_e32 v132, 0x80000000, v29
	v_cndmask_b32_e32 v28, v130, v129, vcc
	v_cmp_gt_i32_e32 vcc, 0, v29
	v_mfma_f32_32x32x16_bf16 v[2:17], v[108:111], v[38:41], v[2:17]
	v_not_b32_e32 v133, v30
	v_cndmask_b32_e32 v29, v132, v131, vcc
	global_load_dwordx4 v[128:131], v[136:137], off offset:128
	v_or_b32_e32 v134, 0x80000000, v30
	v_cmp_gt_i32_e32 vcc, 0, v30
	v_not_b32_e32 v135, v31
	v_or_b32_e32 v138, 0x80000000, v31
	v_cndmask_b32_e32 v30, v134, v133, vcc
	v_cmp_gt_i32_e32 vcc, 0, v31
	v_and_or_b32 v159, v18, s23, v100
	v_and_or_b32 v168, v19, s23, v98
	v_cndmask_b32_e32 v31, v138, v135, vcc
	v_not_b32_e32 v18, v32
	v_or_b32_e32 v19, 0x80000000, v32
	v_cmp_gt_i32_e32 vcc, 0, v32
	v_sub_u32_e32 v102, 0x65, v146
	v_sub_u32_e32 v103, 0x64, v146
	v_cndmask_b32_e32 v18, v19, v18, vcc
	v_and_or_b32 v181, v18, s23, v102
	v_not_b32_e32 v18, v33
	v_or_b32_e32 v19, 0x80000000, v33
	v_cmp_gt_i32_e32 vcc, 0, v33
	global_load_dwordx4 v[132:135], v[136:137], off offset:160
	v_sub_u32_e32 v104, 0x5f, v146
	v_cndmask_b32_e32 v18, v19, v18, vcc
	v_and_or_b32 v182, v18, s23, v103
	v_not_b32_e32 v18, v2
	v_or_b32_e32 v19, 0x80000000, v2
	v_cmp_gt_i32_e32 vcc, 0, v2
	v_sub_u32_e32 v105, 0x5e, v146
	v_sub_u32_e32 v107, 0x5d, v146
	v_cndmask_b32_e32 v2, v19, v18, vcc
	v_and_or_b32 v147, v2, s23, v104
	v_not_b32_e32 v2, v3
	v_or_b32_e32 v18, 0x80000000, v3
	v_cmp_gt_i32_e32 vcc, 0, v3
	v_or_b32_e32 v3, 0x80000000, v4
	v_sub_u32_e32 v106, 0x5c, v146
	v_cndmask_b32_e32 v2, v18, v2, vcc
	v_and_or_b32 v148, v2, s23, v105
	v_not_b32_e32 v2, v4
	v_cmp_gt_i32_e32 vcc, 0, v4
	v_or_b32_e32 v19, 0x80000000, v6
	v_sub_u32_e32 v108, 0x57, v146
	v_cndmask_b32_e32 v2, v3, v2, vcc
	v_and_or_b32 v149, v2, s23, v107
	v_not_b32_e32 v2, v5
	v_or_b32_e32 v3, 0x80000000, v5
	v_cmp_gt_i32_e32 vcc, 0, v5
	v_sub_u32_e32 v90, 0x6d, v146
	v_sub_u32_e32 v89, 0x6c, v146
	v_cndmask_b32_e32 v18, v3, v2, vcc
	global_load_dwordx4 v[2:5], v[136:137], off offset:192
	v_and_or_b32 v150, v18, s23, v106
	global_load_dwordx4 v[136:139], v[136:137], off offset:224
	v_not_b32_e32 v18, v6
	v_cmp_gt_i32_e32 vcc, 0, v6
	v_sub_u32_e32 v88, 0x67, v146
	v_and_or_b32 v169, v20, s23, v101
	v_cndmask_b32_e32 v6, v19, v18, vcc
	v_and_or_b32 v151, v6, s23, v108
	v_not_b32_e32 v6, v7
	v_or_b32_e32 v18, 0x80000000, v7
	v_cmp_gt_i32_e32 vcc, 0, v7
	v_and_or_b32 v170, v21, s23, v99
	v_and_or_b32 v171, v22, s23, v97
	v_and_or_b32 v172, v23, s23, v96
	v_and_or_b32 v173, v24, s23, v95
	v_and_or_b32 v174, v25, s23, v94
	v_and_or_b32 v175, v26, s23, v93
	v_and_or_b32 v176, v27, s23, v92
	v_and_or_b32 v177, v28, s23, v90
	v_and_or_b32 v178, v29, s23, v89
	v_and_or_b32 v179, v30, s23, v88
	v_and_or_b32 v180, v31, s23, v78
	v_cndmask_b32_e32 v6, v18, v6, vcc
	v_sub_u32_e32 v109, 0x56, v146
	s_waitcnt vmcnt(0)
	v_mfma_f32_32x32x16_bf16 v[18:33], v[112:115], v[34:37], 0
	v_and_or_b32 v152, v6, s23, v109
	v_not_b32_e32 v6, v8
	v_or_b32_e32 v7, 0x80000000, v8
	v_cmp_gt_i32_e32 vcc, 0, v8
	v_sub_u32_e32 v110, 0x55, v146
	v_sub_u32_e32 v111, 0x54, v146
	v_cndmask_b32_e32 v6, v7, v6, vcc
	v_and_or_b32 v153, v6, s23, v110
	v_not_b32_e32 v6, v9
	v_or_b32_e32 v7, 0x80000000, v9
	v_cmp_gt_i32_e32 vcc, 0, v9
	v_sub_u32_e32 v68, 0x4f, v146
	v_sub_u32_e32 v91, 0x4e, v146
	v_cndmask_b32_e32 v6, v7, v6, vcc
	v_and_or_b32 v154, v6, s23, v111
	v_not_b32_e32 v6, v10
	v_or_b32_e32 v7, 0x80000000, v10
	v_cmp_gt_i32_e32 vcc, 0, v10
	v_mfma_f32_32x32x16_bf16 v[18:33], v[116:119], v[62:65], v[18:33]
	v_sub_u32_e32 v69, 0x4d, v146
	v_cndmask_b32_e32 v6, v7, v6, vcc
	v_and_or_b32 v155, v6, s23, v68
	v_not_b32_e32 v6, v11
	v_or_b32_e32 v7, 0x80000000, v11
	v_cmp_gt_i32_e32 vcc, 0, v11
	v_sub_u32_e32 v67, 0x4c, v146
	v_mfma_f32_32x32x16_bf16 v[18:33], v[120:123], v[58:61], v[18:33]
	v_cndmask_b32_e32 v6, v7, v6, vcc
	v_and_or_b32 v156, v6, s23, v91
	v_not_b32_e32 v6, v12
	v_or_b32_e32 v7, 0x80000000, v12
	v_cmp_gt_i32_e32 vcc, 0, v12
	v_sub_u32_e32 v66, 0x47, v146
	v_sub_u32_e32 v112, 0x46, v146
	v_cndmask_b32_e32 v6, v7, v6, vcc
	v_and_or_b32 v157, v6, s23, v69
	v_not_b32_e32 v6, v13
	v_or_b32_e32 v7, 0x80000000, v13
	v_cmp_gt_i32_e32 vcc, 0, v13
	v_mfma_f32_32x32x16_bf16 v[18:33], v[124:127], v[54:57], v[18:33]
	v_or_b32_e32 v13, 0x80000000, v15
	v_cndmask_b32_e32 v6, v7, v6, vcc
	v_and_or_b32 v158, v6, s23, v67
	v_not_b32_e32 v6, v14
	v_or_b32_e32 v7, 0x80000000, v14
	v_cmp_gt_i32_e32 vcc, 0, v14
	v_sub_u32_e32 v113, 0x45, v146
	v_mfma_f32_32x32x16_bf16 v[18:33], v[128:131], v[50:53], v[18:33]
	v_cndmask_b32_e32 v12, v7, v6, vcc
	v_add_co_u32_e32 v10, vcc, s27, v80
	v_and_or_b32 v183, v12, s23, v66
	s_nop 0
	v_addc_co_u32_e32 v11, vcc, 0, v81, vcc
	global_load_dwordx4 v[6:9], v[10:11], off
	global_load_dwordx4 v[124:127], v[10:11], off offset:32
	global_load_dwordx4 v[128:131], v[10:11], off offset:64
	v_mfma_f32_32x32x16_bf16 v[18:33], v[132:135], v[46:49], v[18:33]
	global_load_dwordx4 v[132:135], v[10:11], off offset:96
	global_load_dwordx4 v[140:143], v[10:11], off offset:128
	global_load_dwordx4 v[160:163], v[10:11], off offset:192
	global_load_dwordx4 v[164:167], v[10:11], off offset:224
	v_not_b32_e32 v12, v15
	v_cmp_gt_i32_e32 vcc, 0, v15
	v_sub_u32_e32 v114, 0x44, v146
	v_mfma_f32_32x32x16_bf16 v[18:33], v[2:5], v[42:45], v[18:33]
	v_cndmask_b32_e32 v12, v13, v12, vcc
	v_and_or_b32 v184, v12, s23, v112
	v_not_b32_e32 v12, v16
	v_or_b32_e32 v13, 0x80000000, v16
	v_cmp_gt_i32_e32 vcc, 0, v16
	v_or_b32_e32 v2, 0x80000000, v17
	v_sub_u32_e32 v115, 63, v146
	v_mfma_f32_32x32x16_bf16 v[18:33], v[136:139], v[38:41], v[18:33]
	global_load_dwordx4 v[136:139], v[10:11], off offset:160
	v_cndmask_b32_e32 v12, v13, v12, vcc
	v_and_or_b32 v185, v12, s23, v113
	v_not_b32_e32 v12, v17
	v_cmp_gt_i32_e32 vcc, 0, v17
	v_sub_u32_e32 v116, 62, v146
	v_sub_u32_e32 v117, 61, v146
	v_cndmask_b32_e32 v2, v2, v12, vcc
	v_and_or_b32 v186, v2, s23, v114
	s_nop 2
	v_not_b32_e32 v2, v18
	v_or_b32_e32 v3, 0x80000000, v18
	v_cmp_gt_i32_e32 vcc, 0, v18
	v_sub_u32_e32 v118, 60, v146
	v_sub_u32_e32 v119, 55, v146
	v_cndmask_b32_e32 v2, v3, v2, vcc
	v_and_or_b32 v18, v2, s23, v115
	v_not_b32_e32 v2, v19
	v_or_b32_e32 v3, 0x80000000, v19
	v_cmp_gt_i32_e32 vcc, 0, v19
	v_sub_u32_e32 v120, 54, v146
	v_sub_u32_e32 v121, 53, v146
	v_cndmask_b32_e32 v2, v3, v2, vcc
	v_and_or_b32 v19, v2, s23, v116
	v_not_b32_e32 v2, v20
	v_or_b32_e32 v3, 0x80000000, v20
	v_cmp_gt_i32_e32 vcc, 0, v20
	v_sub_u32_e32 v122, 52, v146
	v_sub_u32_e32 v123, 47, v146
	v_cndmask_b32_e32 v2, v3, v2, vcc
	v_and_or_b32 v20, v2, s23, v117
	v_not_b32_e32 v2, v21
	v_or_b32_e32 v3, 0x80000000, v21
	v_cmp_gt_i32_e32 vcc, 0, v21
	s_nop 1
	v_cndmask_b32_e32 v2, v3, v2, vcc
	v_and_or_b32 v21, v2, s23, v118
	v_not_b32_e32 v2, v22
	v_or_b32_e32 v3, 0x80000000, v22
	v_cmp_gt_i32_e32 vcc, 0, v22
	s_nop 1
	v_cndmask_b32_e32 v2, v3, v2, vcc
	v_and_or_b32 v22, v2, s23, v119
	v_not_b32_e32 v2, v23
	v_or_b32_e32 v3, 0x80000000, v23
	v_cmp_gt_i32_e32 vcc, 0, v23
	s_nop 1
	v_cndmask_b32_e32 v2, v3, v2, vcc
	v_and_or_b32 v23, v2, s23, v120
	v_not_b32_e32 v2, v24
	v_or_b32_e32 v3, 0x80000000, v24
	v_cmp_gt_i32_e32 vcc, 0, v24
	s_nop 1
	v_cndmask_b32_e32 v2, v3, v2, vcc
	v_and_or_b32 v24, v2, s23, v121
	v_not_b32_e32 v2, v25
	v_or_b32_e32 v3, 0x80000000, v25
	v_cmp_gt_i32_e32 vcc, 0, v25
	s_nop 1
	v_cndmask_b32_e32 v25, v3, v2, vcc
	s_waitcnt vmcnt(0)
	v_mfma_f32_32x32x16_bf16 v[2:17], v[6:9], v[34:37], 0
	v_not_b32_e32 v34, v26
	v_or_b32_e32 v35, 0x80000000, v26
	v_cmp_gt_i32_e32 vcc, 0, v26
	v_and_or_b32 v25, v25, s23, v122
	v_max_u32_e32 v36, v169, v170
	v_cndmask_b32_e32 v26, v35, v34, vcc
	v_not_b32_e32 v34, v27
	v_mfma_f32_32x32x16_bf16 v[2:17], v[124:127], v[62:65], v[2:17]
	v_or_b32_e32 v35, 0x80000000, v27
	v_cmp_gt_i32_e32 vcc, 0, v27
	v_sub_u32_e32 v124, 46, v146
	v_sub_u32_e32 v125, 45, v146
	v_cndmask_b32_e32 v27, v35, v34, vcc
	v_not_b32_e32 v34, v28
	v_or_b32_e32 v35, 0x80000000, v28
	v_mfma_f32_32x32x16_bf16 v[2:17], v[128:131], v[58:61], v[2:17]
	v_cmp_gt_i32_e32 vcc, 0, v28
	v_sub_u32_e32 v126, 44, v146
	v_sub_u32_e32 v127, 39, v146
	v_cndmask_b32_e32 v28, v35, v34, vcc
	v_not_b32_e32 v34, v29
	v_or_b32_e32 v35, 0x80000000, v29
	v_cmp_gt_i32_e32 vcc, 0, v29
	v_mfma_f32_32x32x16_bf16 v[2:17], v[132:135], v[54:57], v[2:17]
	v_sub_u32_e32 v128, 38, v146
	v_cndmask_b32_e32 v29, v35, v34, vcc
	v_not_b32_e32 v34, v30
	v_or_b32_e32 v35, 0x80000000, v30
	v_cmp_gt_i32_e32 vcc, 0, v30
	v_sub_u32_e32 v129, 37, v146
	v_sub_u32_e32 v130, 36, v146
	v_mfma_f32_32x32x16_bf16 v[2:17], v[140:143], v[50:53], v[2:17]
	v_cndmask_b32_e32 v30, v35, v34, vcc
	v_not_b32_e32 v34, v31
	v_or_b32_e32 v35, 0x80000000, v31
	v_cmp_gt_i32_e32 vcc, 0, v31
	v_sub_u32_e32 v131, 31, v146
	v_sub_u32_e32 v132, 30, v146
	v_cndmask_b32_e32 v31, v35, v34, vcc
	v_mfma_f32_32x32x16_bf16 v[2:17], v[136:139], v[46:49], v[2:17]
	v_not_b32_e32 v34, v32
	v_or_b32_e32 v35, 0x80000000, v32
	v_cmp_gt_i32_e32 vcc, 0, v32
	v_sub_u32_e32 v133, 29, v146
	v_sub_u32_e32 v134, 28, v146
	v_cndmask_b32_e32 v32, v35, v34, vcc
	v_not_b32_e32 v34, v33
	v_mfma_f32_32x32x16_bf16 v[2:17], v[160:163], v[42:45], v[2:17]
	v_or_b32_e32 v35, 0x80000000, v33
	v_cmp_gt_i32_e32 vcc, 0, v33
	v_sub_u32_e32 v135, 23, v146
	v_sub_u32_e32 v136, 22, v146
	v_cndmask_b32_e32 v33, v35, v34, vcc
	v_sub_u32_e32 v137, 21, v146
	v_sub_u32_e32 v138, 20, v146
	v_mfma_f32_32x32x16_bf16 v[2:17], v[164:167], v[38:41], v[2:17]
	v_sub_u32_e32 v139, 15, v146
	v_sub_u32_e32 v140, 14, v146
	v_sub_u32_e32 v141, 13, v146
	v_sub_u32_e32 v142, 12, v146
	v_sub_u32_e32 v143, 7, v146
	v_sub_u32_e32 v146, 4, v146
	v_and_or_b32 v26, v26, s23, v123
	s_nop 4
	v_not_b32_e32 v34, v2
	v_or_b32_e32 v35, 0x80000000, v2
	v_cmp_gt_i32_e32 vcc, 0, v2
	v_and_or_b32 v27, v27, s23, v124
	global_load_dwordx4 v[200:203], v[236:237], off
	global_load_dwordx4 v[204:207], v[236:237], off offset:16
	global_load_dwordx4 v[208:211], v[236:237], off offset:32
	global_load_dwordx4 v[212:215], v[236:237], off offset:48
	global_load_dwordx4 v[216:219], v[238:239], off
	global_load_dwordx4 v[220:223], v[238:239], off offset:16
	global_load_dwordx4 v[224:227], v[238:239], off offset:32
	global_load_dwordx4 v[228:231], v[238:239], off offset:48
	v_lshl_add_u64 v[236:237], v[236:237], 0, v[244:245]
	v_lshl_add_u64 v[238:239], v[238:239], 0, v[244:245]
	v_and_or_b32 v28, v28, s23, v125
	v_cndmask_b32_e32 v2, v35, v34, vcc
	v_not_b32_e32 v34, v3
	v_or_b32_e32 v35, 0x80000000, v3
	v_cmp_gt_i32_e32 vcc, 0, v3
	v_and_or_b32 v29, v29, s23, v126
	v_and_or_b32 v30, v30, s23, v127
	v_cndmask_b32_e32 v3, v35, v34, vcc
	v_not_b32_e32 v34, v4
	v_or_b32_e32 v35, 0x80000000, v4
	v_cmp_gt_i32_e32 vcc, 0, v4
	v_and_or_b32 v31, v31, s23, v128
	v_and_or_b32 v32, v32, s23, v129
	v_cndmask_b32_e32 v4, v35, v34, vcc
	v_not_b32_e32 v34, v5
	v_or_b32_e32 v35, 0x80000000, v5
	v_cmp_gt_i32_e32 vcc, 0, v5
	v_and_or_b32 v33, v33, s23, v130
	v_and_or_b32 v2, v2, s23, v131
	v_cndmask_b32_e32 v5, v35, v34, vcc
	v_not_b32_e32 v34, v6
	v_or_b32_e32 v35, 0x80000000, v6
	v_cmp_gt_i32_e32 vcc, 0, v6
	v_and_or_b32 v3, v3, s23, v132
	v_and_or_b32 v4, v4, s23, v133
	v_cndmask_b32_e32 v6, v35, v34, vcc
	v_not_b32_e32 v34, v7
	v_or_b32_e32 v35, 0x80000000, v7
	v_cmp_gt_i32_e32 vcc, 0, v7
	v_and_or_b32 v5, v5, s23, v134
	v_and_or_b32 v6, v6, s23, v135
	v_cndmask_b32_e32 v7, v35, v34, vcc
	v_not_b32_e32 v34, v8
	v_or_b32_e32 v35, 0x80000000, v8
	v_cmp_gt_i32_e32 vcc, 0, v8
	v_and_or_b32 v7, v7, s23, v136
	v_min_u32_e32 v37, v169, v170
	v_cndmask_b32_e32 v8, v35, v34, vcc
	v_not_b32_e32 v34, v9
	v_or_b32_e32 v35, 0x80000000, v9
	v_cmp_gt_i32_e32 vcc, 0, v9
	v_and_or_b32 v8, v8, s23, v137
	v_max_u32_e32 v38, v171, v172
	v_cndmask_b32_e32 v9, v35, v34, vcc
	v_not_b32_e32 v34, v10
	v_or_b32_e32 v35, 0x80000000, v10
	v_cmp_gt_i32_e32 vcc, 0, v10
	v_and_or_b32 v9, v9, s23, v138
	v_min_u32_e32 v39, v171, v172
	v_cndmask_b32_e32 v10, v35, v34, vcc
	v_not_b32_e32 v34, v11
	v_or_b32_e32 v35, 0x80000000, v11
	v_cmp_gt_i32_e32 vcc, 0, v11
	v_and_or_b32 v10, v10, s23, v139
	v_max_u32_e32 v40, v173, v174
	v_cndmask_b32_e32 v11, v35, v34, vcc
	v_not_b32_e32 v34, v12
	v_or_b32_e32 v35, 0x80000000, v12
	v_cmp_gt_i32_e32 vcc, 0, v12
	v_and_or_b32 v11, v11, s23, v140
	v_min_u32_e32 v41, v173, v174
	v_cndmask_b32_e32 v12, v35, v34, vcc
	v_not_b32_e32 v34, v13
	v_or_b32_e32 v35, 0x80000000, v13
	v_cmp_gt_i32_e32 vcc, 0, v13
	v_and_or_b32 v12, v12, s23, v141
	v_max_u32_e32 v42, v175, v176
	v_cndmask_b32_e32 v13, v35, v34, vcc
	v_not_b32_e32 v34, v14
	v_or_b32_e32 v35, 0x80000000, v14
	v_cmp_gt_i32_e32 vcc, 0, v14
	v_and_or_b32 v13, v13, s23, v142
	v_min_u32_e32 v43, v175, v176
	v_cndmask_b32_e32 v14, v35, v34, vcc
	v_not_b32_e32 v34, v15
	v_or_b32_e32 v35, 0x80000000, v15
	v_cmp_gt_i32_e32 vcc, 0, v15
	v_and_or_b32 v14, v14, s23, v143
	v_max_u32_e32 v44, v177, v178
	v_cndmask_b32_e32 v15, v35, v34, vcc
	v_not_b32_e32 v34, v16
	v_or_b32_e32 v35, 0x80000000, v16
	v_cmp_gt_i32_e32 vcc, 0, v16
	v_and_or_b32 v15, v15, s23, v144
	v_min_u32_e32 v45, v177, v178
	v_cndmask_b32_e32 v16, v35, v34, vcc
	v_not_b32_e32 v34, v17
	v_or_b32_e32 v35, 0x80000000, v17
	v_cmp_gt_i32_e32 vcc, 0, v17
	v_and_or_b32 v16, v16, s23, v145
	v_max_u32_e32 v46, v179, v180
	v_cndmask_b32_e32 v17, v35, v34, vcc
	v_and_or_b32 v17, v17, s23, v146
	v_max_u32_e32 v34, v159, v168
	v_min_u32_e32 v35, v159, v168
	v_min_u32_e32 v47, v179, v180
	v_max_u32_e32 v48, v181, v182
	v_min_u32_e32 v49, v181, v182
	v_max_u32_e32 v58, v147, v148
	v_min_u32_e32 v59, v147, v148
	v_max_u32_e32 v60, v149, v150
	v_min_u32_e32 v61, v149, v150
	v_max_u32_e32 v62, v151, v152
	v_min_u32_e32 v63, v151, v152
	v_max_u32_e32 v64, v153, v154
	v_min_u32_e32 v65, v153, v154
	v_max_u32_e32 v147, v155, v156
	v_min_u32_e32 v148, v155, v156
	v_max_u32_e32 v149, v157, v158
	v_min_u32_e32 v150, v157, v158
	v_max_u32_e32 v151, v183, v184
	v_min_u32_e32 v152, v183, v184
	v_max_u32_e32 v153, v185, v186
	v_min_u32_e32 v154, v185, v186
	v_max_u32_e32 v163, v18, v19
	v_min_u32_e32 v18, v18, v19
	v_max_u32_e32 v19, v20, v21
	v_min_u32_e32 v20, v20, v21
	v_max_u32_e32 v21, v22, v23
	v_min_u32_e32 v22, v22, v23
	v_max_u32_e32 v23, v24, v25
	v_min_u32_e32 v24, v24, v25
	v_max_u32_e32 v25, v26, v27
	v_min_u32_e32 v26, v26, v27
	v_max_u32_e32 v27, v28, v29
	v_min_u32_e32 v28, v28, v29
	v_max_u32_e32 v29, v30, v31
	v_min_u32_e32 v30, v30, v31
	v_max_u32_e32 v31, v32, v33
	v_min_u32_e32 v32, v32, v33
	v_max_u32_e32 v171, v2, v3
	v_min_u32_e32 v2, v2, v3
	v_max_u32_e32 v3, v4, v5
	v_min_u32_e32 v4, v4, v5
	v_max_u32_e32 v5, v6, v7
	v_min_u32_e32 v6, v6, v7
	v_max_u32_e32 v7, v8, v9
	v_min_u32_e32 v8, v8, v9
	v_max_u32_e32 v9, v10, v11
	v_min_u32_e32 v10, v10, v11
	v_max_u32_e32 v11, v12, v13
	v_min_u32_e32 v12, v12, v13
	v_max_u32_e32 v13, v14, v15
	v_min_u32_e32 v14, v14, v15
	v_max_u32_e32 v15, v16, v17
	v_min_u32_e32 v16, v16, v17
	v_max_u32_e32 v50, v34, v37
	v_min_u32_e32 v34, v34, v37
	v_max_u32_e32 v37, v35, v36
	v_min_u32_e32 v35, v35, v36
	v_max_u32_e32 v36, v38, v41
	v_min_u32_e32 v38, v38, v41
	v_max_u32_e32 v41, v39, v40
	v_min_u32_e32 v39, v39, v40
	v_max_u32_e32 v40, v42, v45
	v_min_u32_e32 v42, v42, v45
	v_max_u32_e32 v45, v43, v44
	v_min_u32_e32 v43, v43, v44
	v_max_u32_e32 v44, v46, v49
	v_min_u32_e32 v46, v46, v49
	v_max_u32_e32 v49, v47, v48
	v_min_u32_e32 v47, v47, v48
	v_max_u32_e32 v155, v58, v61
	v_min_u32_e32 v58, v58, v61
	v_max_u32_e32 v61, v59, v60
	v_min_u32_e32 v59, v59, v60
	v_max_u32_e32 v60, v62, v65
	v_min_u32_e32 v62, v62, v65
	v_max_u32_e32 v65, v63, v64
	v_min_u32_e32 v63, v63, v64
	v_max_u32_e32 v64, v147, v150
	v_min_u32_e32 v147, v147, v150
	v_max_u32_e32 v150, v148, v149
	v_min_u32_e32 v148, v148, v149
	v_max_u32_e32 v149, v151, v154
	v_min_u32_e32 v151, v151, v154
	v_max_u32_e32 v154, v152, v153
	v_min_u32_e32 v152, v152, v153
	v_max_u32_e32 v33, v163, v20
	v_min_u32_e32 v20, v163, v20
	v_max_u32_e32 v163, v18, v19
	v_min_u32_e32 v18, v18, v19
	v_max_u32_e32 v19, v21, v24
	v_min_u32_e32 v21, v21, v24
	v_max_u32_e32 v24, v22, v23
	v_min_u32_e32 v22, v22, v23
	v_max_u32_e32 v23, v25, v28
	v_min_u32_e32 v25, v25, v28
	v_max_u32_e32 v28, v26, v27
	v_min_u32_e32 v26, v26, v27
	v_max_u32_e32 v27, v29, v32
	v_min_u32_e32 v29, v29, v32
	v_max_u32_e32 v32, v30, v31
	v_min_u32_e32 v30, v30, v31
	v_max_u32_e32 v17, v171, v4
	v_min_u32_e32 v4, v171, v4
	v_max_u32_e32 v171, v2, v3
	v_min_u32_e32 v2, v2, v3
	v_max_u32_e32 v3, v5, v8
	v_min_u32_e32 v5, v5, v8
	v_max_u32_e32 v8, v6, v7
	v_min_u32_e32 v6, v6, v7
	v_max_u32_e32 v7, v9, v12
	v_min_u32_e32 v9, v9, v12
	v_max_u32_e32 v12, v10, v11
	v_min_u32_e32 v10, v10, v11
	v_max_u32_e32 v11, v13, v16
	v_min_u32_e32 v13, v13, v16
	v_max_u32_e32 v16, v14, v15
	v_min_u32_e32 v14, v14, v15
	v_max_u32_e32 v48, v50, v37
	v_min_u32_e32 v37, v50, v37
	v_max_u32_e32 v50, v34, v35
	v_min_u32_e32 v34, v34, v35
	v_max_u32_e32 v35, v38, v39
	v_min_u32_e32 v38, v38, v39
	v_max_u32_e32 v39, v36, v41
	v_min_u32_e32 v36, v36, v41
	v_max_u32_e32 v41, v40, v45
	v_min_u32_e32 v40, v40, v45
	v_max_u32_e32 v45, v42, v43
	v_min_u32_e32 v42, v42, v43
	v_max_u32_e32 v43, v46, v47
	v_min_u32_e32 v46, v46, v47
	v_max_u32_e32 v47, v44, v49
	v_min_u32_e32 v44, v44, v49
	v_max_u32_e32 v153, v155, v61
	v_min_u32_e32 v61, v155, v61
	v_max_u32_e32 v155, v58, v59
	v_min_u32_e32 v58, v58, v59
	v_max_u32_e32 v59, v62, v63
	v_min_u32_e32 v62, v62, v63
	v_max_u32_e32 v63, v60, v65
	v_min_u32_e32 v60, v60, v65
	v_max_u32_e32 v65, v64, v150
	v_min_u32_e32 v64, v64, v150
	v_max_u32_e32 v150, v147, v148
	v_min_u32_e32 v147, v147, v148
	v_max_u32_e32 v148, v151, v152
	v_min_u32_e32 v151, v151, v152
	v_max_u32_e32 v152, v149, v154
	v_min_u32_e32 v149, v149, v154
	v_max_u32_e32 v31, v33, v163
	v_min_u32_e32 v33, v33, v163
	v_max_u32_e32 v163, v20, v18
	v_min_u32_e32 v18, v20, v18
	v_max_u32_e32 v20, v21, v22
	v_min_u32_e32 v21, v21, v22
	v_max_u32_e32 v22, v19, v24
	v_min_u32_e32 v19, v19, v24
	v_max_u32_e32 v24, v23, v28
	v_min_u32_e32 v23, v23, v28
	v_max_u32_e32 v28, v25, v26
	v_min_u32_e32 v25, v25, v26
	v_max_u32_e32 v26, v29, v30
	v_min_u32_e32 v29, v29, v30
	v_max_u32_e32 v30, v27, v32
	v_min_u32_e32 v27, v27, v32
	v_max_u32_e32 v15, v17, v171
	v_min_u32_e32 v17, v17, v171
	v_max_u32_e32 v171, v4, v2
	v_min_u32_e32 v2, v4, v2
	v_max_u32_e32 v4, v5, v6
	v_min_u32_e32 v5, v5, v6
	v_max_u32_e32 v6, v3, v8
	v_min_u32_e32 v3, v3, v8
	v_max_u32_e32 v8, v7, v12
	v_min_u32_e32 v7, v7, v12
	v_max_u32_e32 v12, v9, v10
	v_min_u32_e32 v9, v9, v10
	v_max_u32_e32 v10, v13, v14
	v_min_u32_e32 v13, v13, v14
	v_max_u32_e32 v14, v11, v16
	v_min_u32_e32 v11, v11, v16
	v_max_u32_e32 v49, v48, v38
	v_min_u32_e32 v38, v48, v38
	v_max_u32_e32 v48, v37, v35
	v_min_u32_e32 v35, v37, v35
	v_max_u32_e32 v37, v50, v36
	v_min_u32_e32 v36, v50, v36
	v_max_u32_e32 v50, v34, v39
	v_min_u32_e32 v34, v34, v39
	v_max_u32_e32 v39, v41, v46
	v_min_u32_e32 v41, v41, v46
	v_max_u32_e32 v46, v40, v43
	v_min_u32_e32 v40, v40, v43
	v_max_u32_e32 v43, v45, v44
	v_min_u32_e32 v44, v45, v44
	v_max_u32_e32 v45, v42, v47
	v_min_u32_e32 v42, v42, v47
	v_max_u32_e32 v154, v153, v62
	v_min_u32_e32 v62, v153, v62
	v_max_u32_e32 v153, v61, v59
	s_waitcnt vmcnt(0)
	v_pk_mul_f32 v[200:201], v[200:201], s[96:97] op_sel_hi:[1,0]
	v_pk_mul_f32 v[202:203], v[202:203], s[96:97] op_sel_hi:[1,0]
	v_pk_mul_f32 v[204:205], v[204:205], s[96:97] op_sel_hi:[1,0]
	v_pk_mul_f32 v[206:207], v[206:207], s[96:97] op_sel_hi:[1,0]
	v_pk_mul_f32 v[208:209], v[208:209], s[96:97] op_sel_hi:[1,0]
	v_pk_mul_f32 v[210:211], v[210:211], s[96:97] op_sel_hi:[1,0]
	v_pk_mul_f32 v[212:213], v[212:213], s[96:97] op_sel_hi:[1,0]
	v_pk_mul_f32 v[214:215], v[214:215], s[96:97] op_sel_hi:[1,0]
	v_pk_mul_f32 v[216:217], v[216:217], s[96:97] op_sel_hi:[1,0]
	v_pk_mul_f32 v[218:219], v[218:219], s[96:97] op_sel_hi:[1,0]
	v_pk_mul_f32 v[220:221], v[220:221], s[96:97] op_sel_hi:[1,0]
	v_pk_mul_f32 v[222:223], v[222:223], s[96:97] op_sel_hi:[1,0]
	v_pk_mul_f32 v[224:225], v[224:225], s[96:97] op_sel_hi:[1,0]
	v_pk_mul_f32 v[226:227], v[226:227], s[96:97] op_sel_hi:[1,0]
	v_pk_mul_f32 v[228:229], v[228:229], s[96:97] op_sel_hi:[1,0]
	v_pk_mul_f32 v[230:231], v[230:231], s[96:97] op_sel_hi:[1,0]
	v_cvt_scalef32_pk_fp4_f32 v232, v200, v201, 1.0
	v_cvt_scalef32_pk_fp4_f32 v233, v208, v209, 1.0
	v_cvt_scalef32_pk_fp4_f32 v234, v216, v217, 1.0
	v_cvt_scalef32_pk_fp4_f32 v235, v224, v225, 1.0
	v_cvt_scalef32_pk_fp4_f32 v232, v202, v203, 1.0 op_sel:[0,0,1,0]
	v_cvt_scalef32_pk_fp4_f32 v233, v210, v211, 1.0 op_sel:[0,0,1,0]
	v_cvt_scalef32_pk_fp4_f32 v234, v218, v219, 1.0 op_sel:[0,0,1,0]
	v_cvt_scalef32_pk_fp4_f32 v235, v226, v227, 1.0 op_sel:[0,0,1,0]
	v_cvt_scalef32_pk_fp4_f32 v232, v204, v205, 1.0 op_sel:[0,0,0,1]
	v_cvt_scalef32_pk_fp4_f32 v233, v212, v213, 1.0 op_sel:[0,0,0,1]
	v_cvt_scalef32_pk_fp4_f32 v234, v220, v221, 1.0 op_sel:[0,0,0,1]
	v_cvt_scalef32_pk_fp4_f32 v235, v228, v229, 1.0 op_sel:[0,0,0,1]
	v_cvt_scalef32_pk_fp4_f32 v232, v206, v207, 1.0 op_sel:[0,0,1,1]
	v_cvt_scalef32_pk_fp4_f32 v233, v214, v215, 1.0 op_sel:[0,0,1,1]
	v_cvt_scalef32_pk_fp4_f32 v234, v222, v223, 1.0 op_sel:[0,0,1,1]
	v_cvt_scalef32_pk_fp4_f32 v235, v230, v231, 1.0 op_sel:[0,0,1,1]
	s_nop 0
	global_store_dwordx4 v[240:241], v[232:235], off
	v_lshl_add_u64 v[240:241], v[240:241], 0, v[246:247]
	global_load_dwordx4 v[200:203], v[236:237], off
	global_load_dwordx4 v[204:207], v[236:237], off offset:16
	global_load_dwordx4 v[208:211], v[236:237], off offset:32
	global_load_dwordx4 v[212:215], v[236:237], off offset:48
	global_load_dwordx4 v[216:219], v[238:239], off
	global_load_dwordx4 v[220:223], v[238:239], off offset:16
	global_load_dwordx4 v[224:227], v[238:239], off offset:32
	global_load_dwordx4 v[228:231], v[238:239], off offset:48
	v_lshl_add_u64 v[236:237], v[236:237], 0, v[244:245]
	v_lshl_add_u64 v[238:239], v[238:239], 0, v[244:245]
	v_min_u32_e32 v59, v61, v59
	v_max_u32_e32 v61, v155, v60
	v_min_u32_e32 v60, v155, v60
	v_max_u32_e32 v155, v58, v63
	v_min_u32_e32 v58, v58, v63
	v_max_u32_e32 v63, v65, v151
	v_min_u32_e32 v65, v65, v151
	v_max_u32_e32 v151, v64, v148
	v_min_u32_e32 v64, v64, v148
	v_max_u32_e32 v148, v150, v149
	v_min_u32_e32 v149, v150, v149
	v_max_u32_e32 v150, v147, v152
	v_min_u32_e32 v147, v147, v152
	v_max_u32_e32 v32, v31, v21
	v_min_u32_e32 v21, v31, v21
	v_max_u32_e32 v31, v33, v20
	v_min_u32_e32 v20, v33, v20
	v_max_u32_e32 v33, v163, v19
	v_min_u32_e32 v19, v163, v19
	v_max_u32_e32 v163, v18, v22
	v_min_u32_e32 v18, v18, v22
	v_max_u32_e32 v22, v24, v29
	v_min_u32_e32 v24, v24, v29
	v_max_u32_e32 v29, v23, v26
	v_min_u32_e32 v23, v23, v26
	v_max_u32_e32 v26, v28, v27
	v_min_u32_e32 v27, v28, v27
	v_max_u32_e32 v28, v25, v30
	v_min_u32_e32 v25, v25, v30
	v_max_u32_e32 v16, v15, v5
	v_min_u32_e32 v5, v15, v5
	v_max_u32_e32 v15, v17, v4
	v_min_u32_e32 v4, v17, v4
	v_max_u32_e32 v17, v171, v3
	v_min_u32_e32 v3, v171, v3
	v_max_u32_e32 v171, v2, v6
	v_min_u32_e32 v2, v2, v6
	v_max_u32_e32 v6, v8, v13
	v_min_u32_e32 v8, v8, v13
	v_max_u32_e32 v13, v7, v10
	v_min_u32_e32 v7, v7, v10
	v_max_u32_e32 v10, v12, v11
	v_min_u32_e32 v11, v12, v11
	v_max_u32_e32 v12, v9, v14
	v_min_u32_e32 v9, v9, v14
	v_max_u32_e32 v47, v49, v37
	v_min_u32_e32 v37, v49, v37
	v_max_u32_e32 v49, v48, v50
	v_min_u32_e32 v48, v48, v50
	v_max_u32_e32 v50, v38, v36
	v_min_u32_e32 v36, v38, v36
	v_max_u32_e32 v38, v35, v34
	v_min_u32_e32 v34, v35, v34
	v_max_u32_e32 v35, v41, v44
	v_min_u32_e32 v41, v41, v44
	v_max_u32_e32 v44, v40, v42
	v_min_u32_e32 v40, v40, v42
	v_max_u32_e32 v42, v39, v43
	v_min_u32_e32 v39, v39, v43
	v_max_u32_e32 v43, v46, v45
	v_min_u32_e32 v45, v46, v45
	v_max_u32_e32 v152, v154, v61
	v_min_u32_e32 v61, v154, v61
	v_max_u32_e32 v154, v153, v155
	v_min_u32_e32 v153, v153, v155
	v_max_u32_e32 v155, v62, v60
	v_min_u32_e32 v60, v62, v60
	v_max_u32_e32 v62, v59, v58
	v_min_u32_e32 v58, v59, v58
	v_max_u32_e32 v59, v65, v149
	v_min_u32_e32 v65, v65, v149
	v_max_u32_e32 v149, v64, v147
	v_min_u32_e32 v64, v64, v147
	v_max_u32_e32 v147, v63, v148
	v_min_u32_e32 v63, v63, v148
	v_max_u32_e32 v148, v151, v150
	v_min_u32_e32 v150, v151, v150
	v_max_u32_e32 v30, v32, v33
	v_min_u32_e32 v32, v32, v33
	v_max_u32_e32 v33, v31, v163
	v_min_u32_e32 v31, v31, v163
	v_max_u32_e32 v163, v21, v19
	v_min_u32_e32 v19, v21, v19
	v_max_u32_e32 v21, v20, v18
	v_min_u32_e32 v18, v20, v18
	v_max_u32_e32 v20, v24, v27
	v_min_u32_e32 v24, v24, v27
	v_max_u32_e32 v27, v23, v25
	v_min_u32_e32 v23, v23, v25
	v_max_u32_e32 v25, v22, v26
	v_min_u32_e32 v22, v22, v26
	v_max_u32_e32 v26, v29, v28
	v_min_u32_e32 v28, v29, v28
	v_max_u32_e32 v14, v16, v17
	v_min_u32_e32 v16, v16, v17
	v_max_u32_e32 v17, v15, v171
	v_min_u32_e32 v15, v15, v171
	v_max_u32_e32 v171, v5, v3
	v_min_u32_e32 v3, v5, v3
	v_max_u32_e32 v5, v4, v2
	v_min_u32_e32 v2, v4, v2
	v_max_u32_e32 v4, v8, v11
	v_min_u32_e32 v8, v8, v11
	v_max_u32_e32 v11, v7, v9
	v_min_u32_e32 v7, v7, v9
	v_max_u32_e32 v9, v6, v10
	v_min_u32_e32 v6, v6, v10
	v_max_u32_e32 v10, v13, v12
	v_min_u32_e32 v12, v13, v12
	v_max_u32_e32 v46, v47, v49
	v_min_u32_e32 v47, v47, v49
	v_max_u32_e32 v49, v37, v48
	v_min_u32_e32 v37, v37, v48
	v_max_u32_e32 v48, v50, v38
	v_min_u32_e32 v38, v50, v38
	v_max_u32_e32 v50, v36, v34
	v_min_u32_e32 v34, v36, v34
	v_max_u32_e32 v36, v41, v40
	v_min_u32_e32 v40, v41, v40
	v_max_u32_e32 v41, v35, v44
	v_min_u32_e32 v35, v35, v44
	v_max_u32_e32 v44, v39, v45
	v_min_u32_e32 v39, v39, v45
	v_max_u32_e32 v45, v42, v43
	v_min_u32_e32 v42, v42, v43
	v_max_u32_e32 v151, v152, v154
	v_min_u32_e32 v152, v152, v154
	v_max_u32_e32 v154, v61, v153
	v_min_u32_e32 v61, v61, v153
	v_max_u32_e32 v153, v155, v62
	v_min_u32_e32 v62, v155, v62
	v_max_u32_e32 v155, v60, v58
	v_min_u32_e32 v58, v60, v58
	v_max_u32_e32 v60, v65, v64
	v_min_u32_e32 v64, v65, v64
	v_max_u32_e32 v65, v59, v149
	v_min_u32_e32 v59, v59, v149
	v_max_u32_e32 v149, v63, v150
	v_min_u32_e32 v63, v63, v150
	v_max_u32_e32 v150, v147, v148
	v_min_u32_e32 v147, v147, v148
	v_max_u32_e32 v29, v30, v33
	v_min_u32_e32 v30, v30, v33
	v_max_u32_e32 v33, v32, v31
	v_min_u32_e32 v31, v32, v31
	v_max_u32_e32 v32, v163, v21
	v_min_u32_e32 v21, v163, v21
	v_max_u32_e32 v163, v19, v18
	v_min_u32_e32 v18, v19, v18
	v_max_u32_e32 v19, v24, v23
	v_min_u32_e32 v23, v24, v23
	v_max_u32_e32 v24, v20, v27
	v_min_u32_e32 v20, v20, v27
	v_max_u32_e32 v27, v22, v28
	v_min_u32_e32 v22, v22, v28
	v_max_u32_e32 v28, v25, v26
	v_min_u32_e32 v25, v25, v26
	v_max_u32_e32 v13, v14, v17
	v_min_u32_e32 v14, v14, v17
	v_max_u32_e32 v17, v16, v15
	v_min_u32_e32 v15, v16, v15
	v_max_u32_e32 v16, v171, v5
	v_min_u32_e32 v5, v171, v5
	v_max_u32_e32 v171, v3, v2
	v_min_u32_e32 v2, v3, v2
	v_max_u32_e32 v3, v8, v7
	v_min_u32_e32 v7, v8, v7
	v_max_u32_e32 v8, v4, v11
	v_min_u32_e32 v4, v4, v11
	v_max_u32_e32 v11, v6, v12
	v_min_u32_e32 v6, v6, v12
	v_max_u32_e32 v12, v9, v10
	v_min_u32_e32 v9, v9, v10
	v_max_u32_e32 v43, v46, v40
	v_min_u32_e32 v40, v46, v40
	v_max_u32_e32 v46, v47, v36
	v_min_u32_e32 v36, v47, v36
	v_max_u32_e32 v47, v49, v35
	v_min_u32_e32 v35, v49, v35
	v_max_u32_e32 v49, v37, v41
	v_min_u32_e32 v37, v37, v41
	v_max_u32_e32 v41, v48, v39
	v_min_u32_e32 v39, v48, v39
	v_max_u32_e32 v48, v38, v44
	v_min_u32_e32 v38, v38, v44
	v_max_u32_e32 v44, v50, v42
	v_min_u32_e32 v42, v50, v42
	v_max_u32_e32 v50, v34, v45
	v_min_u32_e32 v34, v34, v45
	v_max_u32_e32 v148, v151, v64
	v_min_u32_e32 v64, v151, v64
	v_max_u32_e32 v151, v152, v60
	v_min_u32_e32 v60, v152, v60
	v_max_u32_e32 v152, v154, v59
	v_min_u32_e32 v59, v154, v59
	v_max_u32_e32 v154, v61, v65
	v_min_u32_e32 v61, v61, v65
	v_max_u32_e32 v65, v153, v63
	v_min_u32_e32 v63, v153, v63
	v_max_u32_e32 v153, v62, v149
	v_min_u32_e32 v62, v62, v149
	v_max_u32_e32 v149, v155, v147
	v_min_u32_e32 v147, v155, v147
	v_max_u32_e32 v155, v58, v150
	v_min_u32_e32 v58, v58, v150
	v_max_u32_e32 v26, v29, v23
	v_min_u32_e32 v23, v29, v23
	v_max_u32_e32 v29, v30, v19
	v_min_u32_e32 v19, v30, v19
	v_max_u32_e32 v30, v33, v20
	v_min_u32_e32 v20, v33, v20
	v_max_u32_e32 v33, v31, v24
	v_min_u32_e32 v24, v31, v24
	v_max_u32_e32 v31, v32, v22
	v_min_u32_e32 v22, v32, v22
	v_max_u32_e32 v32, v21, v27
	v_min_u32_e32 v21, v21, v27
	v_max_u32_e32 v27, v163, v25
	v_min_u32_e32 v25, v163, v25
	v_max_u32_e32 v163, v18, v28
	v_min_u32_e32 v18, v18, v28
	v_max_u32_e32 v10, v13, v7
	v_min_u32_e32 v7, v13, v7
	v_max_u32_e32 v13, v14, v3
	v_min_u32_e32 v3, v14, v3
	v_max_u32_e32 v14, v17, v4
	v_min_u32_e32 v4, v17, v4
	v_max_u32_e32 v17, v15, v8
	v_min_u32_e32 v8, v15, v8
	v_max_u32_e32 v15, v16, v6
	v_min_u32_e32 v6, v16, v6
	v_max_u32_e32 v16, v5, v11
	v_min_u32_e32 v5, v5, v11
	v_max_u32_e32 v11, v171, v9
	v_min_u32_e32 v9, v171, v9
	v_max_u32_e32 v171, v2, v12
	v_min_u32_e32 v2, v2, v12
	v_max_u32_e32 v45, v43, v41
	v_min_u32_e32 v41, v43, v41
	v_max_u32_e32 v43, v46, v48
	v_min_u32_e32 v46, v46, v48
	v_max_u32_e32 v48, v47, v44
	v_min_u32_e32 v44, v47, v44
	v_max_u32_e32 v47, v49, v50
	v_min_u32_e32 v49, v49, v50
	v_max_u32_e32 v50, v40, v39
	v_min_u32_e32 v39, v40, v39
	v_max_u32_e32 v40, v36, v38
	v_min_u32_e32 v36, v36, v38
	v_max_u32_e32 v38, v35, v42
	v_min_u32_e32 v35, v35, v42
	v_max_u32_e32 v42, v37, v34
	v_min_u32_e32 v34, v37, v34
	v_max_u32_e32 v150, v148, v65
	v_min_u32_e32 v65, v148, v65
	v_max_u32_e32 v148, v151, v153
	v_min_u32_e32 v151, v151, v153
	v_max_u32_e32 v153, v152, v149
	v_min_u32_e32 v149, v152, v149
	v_max_u32_e32 v152, v154, v155
	v_min_u32_e32 v154, v154, v155
	v_max_u32_e32 v155, v64, v63
	v_min_u32_e32 v63, v64, v63
	v_max_u32_e32 v64, v60, v62
	v_min_u32_e32 v60, v60, v62
	v_max_u32_e32 v62, v59, v147
	v_min_u32_e32 v59, v59, v147
	v_max_u32_e32 v147, v61, v58
	v_min_u32_e32 v58, v61, v58
	v_max_u32_e32 v28, v26, v31
	v_min_u32_e32 v26, v26, v31
	v_max_u32_e32 v31, v29, v32
	v_min_u32_e32 v29, v29, v32
	v_max_u32_e32 v32, v30, v27
	v_min_u32_e32 v27, v30, v27
	v_max_u32_e32 v30, v33, v163
	v_min_u32_e32 v33, v33, v163
	v_max_u32_e32 v163, v23, v22
	v_min_u32_e32 v22, v23, v22
	v_max_u32_e32 v23, v19, v21
	v_min_u32_e32 v19, v19, v21
	v_max_u32_e32 v21, v20, v25
	v_min_u32_e32 v20, v20, v25
	v_max_u32_e32 v25, v24, v18
	v_min_u32_e32 v18, v24, v18
	v_max_u32_e32 v12, v10, v15
	v_min_u32_e32 v10, v10, v15
	v_max_u32_e32 v15, v13, v16
	v_min_u32_e32 v13, v13, v16
	v_max_u32_e32 v16, v14, v11
	v_min_u32_e32 v11, v14, v11
	v_max_u32_e32 v14, v17, v171
	v_min_u32_e32 v17, v17, v171
	v_max_u32_e32 v171, v7, v6
	v_min_u32_e32 v6, v7, v6
	v_max_u32_e32 v7, v3, v5
	v_min_u32_e32 v3, v3, v5
	v_max_u32_e32 v5, v4, v9
	v_min_u32_e32 v4, v4, v9
	v_max_u32_e32 v9, v8, v2
	v_min_u32_e32 v2, v8, v2
	v_max_u32_e32 v37, v45, v48
	v_min_u32_e32 v45, v45, v48
	v_max_u32_e32 v48, v43, v47
	v_min_u32_e32 v43, v43, v47
	s_waitcnt vmcnt(0)
	v_pk_mul_f32 v[200:201], v[200:201], s[96:97] op_sel_hi:[1,0]
	v_pk_mul_f32 v[202:203], v[202:203], s[96:97] op_sel_hi:[1,0]
	v_pk_mul_f32 v[204:205], v[204:205], s[96:97] op_sel_hi:[1,0]
	v_pk_mul_f32 v[206:207], v[206:207], s[96:97] op_sel_hi:[1,0]
	v_pk_mul_f32 v[208:209], v[208:209], s[96:97] op_sel_hi:[1,0]
	v_pk_mul_f32 v[210:211], v[210:211], s[96:97] op_sel_hi:[1,0]
	v_pk_mul_f32 v[212:213], v[212:213], s[96:97] op_sel_hi:[1,0]
	v_pk_mul_f32 v[214:215], v[214:215], s[96:97] op_sel_hi:[1,0]
	v_pk_mul_f32 v[216:217], v[216:217], s[96:97] op_sel_hi:[1,0]
	v_pk_mul_f32 v[218:219], v[218:219], s[96:97] op_sel_hi:[1,0]
	v_pk_mul_f32 v[220:221], v[220:221], s[96:97] op_sel_hi:[1,0]
	v_pk_mul_f32 v[222:223], v[222:223], s[96:97] op_sel_hi:[1,0]
	v_pk_mul_f32 v[224:225], v[224:225], s[96:97] op_sel_hi:[1,0]
	v_pk_mul_f32 v[226:227], v[226:227], s[96:97] op_sel_hi:[1,0]
	v_pk_mul_f32 v[228:229], v[228:229], s[96:97] op_sel_hi:[1,0]
	v_pk_mul_f32 v[230:231], v[230:231], s[96:97] op_sel_hi:[1,0]
	v_cvt_scalef32_pk_fp4_f32 v232, v200, v201, 1.0
	v_cvt_scalef32_pk_fp4_f32 v233, v208, v209, 1.0
	v_cvt_scalef32_pk_fp4_f32 v234, v216, v217, 1.0
	v_cvt_scalef32_pk_fp4_f32 v235, v224, v225, 1.0
	v_cvt_scalef32_pk_fp4_f32 v232, v202, v203, 1.0 op_sel:[0,0,1,0]
	v_cvt_scalef32_pk_fp4_f32 v233, v210, v211, 1.0 op_sel:[0,0,1,0]
	v_cvt_scalef32_pk_fp4_f32 v234, v218, v219, 1.0 op_sel:[0,0,1,0]
	v_cvt_scalef32_pk_fp4_f32 v235, v226, v227, 1.0 op_sel:[0,0,1,0]
	v_cvt_scalef32_pk_fp4_f32 v232, v204, v205, 1.0 op_sel:[0,0,0,1]
	v_cvt_scalef32_pk_fp4_f32 v233, v212, v213, 1.0 op_sel:[0,0,0,1]
	v_cvt_scalef32_pk_fp4_f32 v234, v220, v221, 1.0 op_sel:[0,0,0,1]
	v_cvt_scalef32_pk_fp4_f32 v235, v228, v229, 1.0 op_sel:[0,0,0,1]
	v_cvt_scalef32_pk_fp4_f32 v232, v206, v207, 1.0 op_sel:[0,0,1,1]
	v_cvt_scalef32_pk_fp4_f32 v233, v214, v215, 1.0 op_sel:[0,0,1,1]
	v_cvt_scalef32_pk_fp4_f32 v234, v222, v223, 1.0 op_sel:[0,0,1,1]
	v_cvt_scalef32_pk_fp4_f32 v235, v230, v231, 1.0 op_sel:[0,0,1,1]
	s_nop 0
	global_store_dwordx4 v[240:241], v[232:235], off
	v_lshl_add_u64 v[240:241], v[240:241], 0, v[246:247]
	global_load_dwordx4 v[200:203], v[236:237], off
	global_load_dwordx4 v[204:207], v[236:237], off offset:16
	global_load_dwordx4 v[208:211], v[236:237], off offset:32
	global_load_dwordx4 v[212:215], v[236:237], off offset:48
	global_load_dwordx4 v[216:219], v[238:239], off
	global_load_dwordx4 v[220:223], v[238:239], off offset:16
	global_load_dwordx4 v[224:227], v[238:239], off offset:32
	global_load_dwordx4 v[228:231], v[238:239], off offset:48
	v_lshl_add_u64 v[236:237], v[236:237], 0, v[244:245]
	v_lshl_add_u64 v[238:239], v[238:239], 0, v[244:245]
	v_max_u32_e32 v47, v41, v44
	v_min_u32_e32 v41, v41, v44
	v_max_u32_e32 v44, v46, v49
	v_min_u32_e32 v46, v46, v49
	v_max_u32_e32 v49, v50, v38
	v_min_u32_e32 v38, v50, v38
	v_max_u32_e32 v50, v40, v42
	v_min_u32_e32 v40, v40, v42
	v_max_u32_e32 v42, v39, v35
	v_min_u32_e32 v35, v39, v35
	v_max_u32_e32 v39, v36, v34
	v_min_u32_e32 v34, v36, v34
	v_max_u32_e32 v61, v150, v153
	v_min_u32_e32 v150, v150, v153
	v_max_u32_e32 v153, v148, v152
	v_min_u32_e32 v148, v148, v152
	v_max_u32_e32 v152, v65, v149
	v_min_u32_e32 v65, v65, v149
	v_max_u32_e32 v149, v151, v154
	v_min_u32_e32 v151, v151, v154
	v_max_u32_e32 v154, v155, v62
	v_min_u32_e32 v62, v155, v62
	v_max_u32_e32 v155, v64, v147
	v_min_u32_e32 v64, v64, v147
	v_max_u32_e32 v147, v63, v59
	v_min_u32_e32 v59, v63, v59
	v_max_u32_e32 v63, v60, v58
	v_min_u32_e32 v58, v60, v58
	v_max_u32_e32 v24, v28, v32
	v_min_u32_e32 v28, v28, v32
	v_max_u32_e32 v32, v31, v30
	v_min_u32_e32 v30, v31, v30
	v_max_u32_e32 v31, v26, v27
	v_min_u32_e32 v26, v26, v27
	v_max_u32_e32 v27, v29, v33
	v_min_u32_e32 v29, v29, v33
	v_max_u32_e32 v33, v163, v21
	v_min_u32_e32 v21, v163, v21
	v_max_u32_e32 v163, v23, v25
	v_min_u32_e32 v23, v23, v25
	v_max_u32_e32 v25, v22, v20
	v_min_u32_e32 v20, v22, v20
	v_max_u32_e32 v22, v19, v18
	v_min_u32_e32 v18, v19, v18
	v_max_u32_e32 v8, v12, v16
	v_min_u32_e32 v12, v12, v16
	v_max_u32_e32 v16, v15, v14
	v_min_u32_e32 v14, v15, v14
	v_max_u32_e32 v15, v10, v11
	v_min_u32_e32 v10, v10, v11
	v_max_u32_e32 v11, v13, v17
	v_min_u32_e32 v13, v13, v17
	v_max_u32_e32 v17, v171, v5
	v_min_u32_e32 v5, v171, v5
	v_max_u32_e32 v171, v7, v9
	v_min_u32_e32 v7, v7, v9
	v_max_u32_e32 v9, v6, v4
	v_min_u32_e32 v4, v6, v4
	v_max_u32_e32 v6, v3, v2
	v_min_u32_e32 v2, v3, v2
	v_min_u32_e32 v36, v37, v48
	v_min_u32_e32 v51, v45, v43
	v_min_u32_e32 v52, v47, v44
	v_min_u32_e32 v53, v41, v46
	v_min_u32_e32 v54, v49, v50
	v_min_u32_e32 v55, v38, v40
	v_min_u32_e32 v56, v42, v39
	v_min_u32_e32 v57, v35, v34
	v_min_u32_e32 v60, v61, v153
	v_min_u32_e32 v156, v150, v148
	v_min_u32_e32 v157, v152, v149
	v_min_u32_e32 v158, v65, v151
	v_min_u32_e32 v159, v154, v155
	v_min_u32_e32 v160, v62, v64
	v_min_u32_e32 v161, v147, v63
	v_min_u32_e32 v162, v59, v58
	v_min_u32_e32 v19, v24, v32
	v_min_u32_e32 v164, v28, v30
	v_min_u32_e32 v165, v31, v27
	v_min_u32_e32 v166, v26, v29
	v_min_u32_e32 v167, v33, v163
	v_min_u32_e32 v168, v21, v23
	v_min_u32_e32 v169, v25, v22
	v_min_u32_e32 v170, v20, v18
	v_min_u32_e32 v3, v8, v16
	v_min_u32_e32 v172, v12, v14
	v_min_u32_e32 v173, v15, v11
	v_min_u32_e32 v174, v10, v13
	v_min_u32_e32 v175, v17, v171
	v_min_u32_e32 v176, v5, v7
	v_min_u32_e32 v177, v9, v6
	v_min_u32_e32 v178, v4, v2
	v_max3_u32 v37, v37, v48, v162
	v_max3_u32 v24, v24, v32, v178
	v_max3_u32 v32, v36, v59, v58
	v_max3_u32 v2, v19, v4, v2
	v_max3_u32 v4, v45, v43, v161
	v_max3_u32 v19, v28, v30, v177
	v_max3_u32 v28, v51, v147, v63
	v_max3_u32 v6, v164, v9, v6
	v_max3_u32 v9, v47, v44, v160
	v_max3_u32 v27, v31, v27, v176
	v_max3_u32 v30, v52, v62, v64
	v_max3_u32 v5, v165, v5, v7
	v_max3_u32 v7, v41, v46, v159
	v_max3_u32 v26, v26, v29, v175
	v_max3_u32 v29, v53, v154, v155
	v_max3_u32 v17, v166, v17, v171
	v_max3_u32 v31, v49, v50, v158
	v_max3_u32 v33, v33, v163, v174
	v_max3_u32 v36, v54, v65, v151
	v_max3_u32 v10, v167, v10, v13
	v_max3_u32 v13, v38, v40, v157
	v_max3_u32 v21, v21, v23, v173
	v_max3_u32 v23, v55, v152, v149
	v_max3_u32 v11, v168, v15, v11
	v_max3_u32 v15, v42, v39, v156
	v_max3_u32 v22, v25, v22, v172
	v_max3_u32 v25, v56, v150, v148
	v_max3_u32 v12, v169, v12, v14
	v_max3_u32 v14, v35, v34, v60
	v_max3_u32 v3, v20, v18, v3
	v_max3_u32 v18, v57, v61, v153
	v_max3_u32 v8, v170, v8, v16
	v_max_u32_e32 v16, v37, v31
	v_min_u32_e32 v20, v37, v31
	v_max_u32_e32 v31, v32, v36
	v_min_u32_e32 v32, v32, v36
	v_max_u32_e32 v34, v4, v13
	v_min_u32_e32 v4, v4, v13
	v_max_u32_e32 v13, v28, v23
	v_min_u32_e32 v23, v28, v23
	v_max_u32_e32 v28, v9, v15
	v_min_u32_e32 v9, v9, v15
	v_max_u32_e32 v15, v30, v25
	v_min_u32_e32 v25, v30, v25
	v_max_u32_e32 v30, v7, v14
	v_min_u32_e32 v7, v7, v14
	v_max_u32_e32 v14, v29, v18
	v_min_u32_e32 v18, v29, v18
	v_max_u32_e32 v42, v24, v33
	v_min_u32_e32 v24, v24, v33
	v_max_u32_e32 v33, v2, v10
	v_min_u32_e32 v2, v2, v10
	v_max_u32_e32 v10, v19, v21
	v_min_u32_e32 v19, v19, v21
	v_max_u32_e32 v21, v6, v11
	v_min_u32_e32 v6, v6, v11
	v_max_u32_e32 v11, v27, v22
	v_min_u32_e32 v22, v27, v22
	v_max_u32_e32 v27, v5, v12
	v_min_u32_e32 v5, v5, v12
	v_max_u32_e32 v12, v26, v3
	v_min_u32_e32 v3, v26, v3
	v_max_u32_e32 v26, v17, v8
	v_min_u32_e32 v8, v17, v8
	v_max_u32_e32 v29, v16, v28
	v_min_u32_e32 v16, v16, v28
	v_max_u32_e32 v28, v31, v15
	v_min_u32_e32 v15, v31, v15
	v_max_u32_e32 v31, v34, v30
	v_min_u32_e32 v30, v34, v30
	v_max_u32_e32 v34, v13, v14
	v_min_u32_e32 v13, v13, v14
	v_max_u32_e32 v14, v20, v9
	v_min_u32_e32 v9, v20, v9
	v_max_u32_e32 v20, v32, v25
	v_min_u32_e32 v25, v32, v25
	v_max_u32_e32 v32, v4, v7
	v_min_u32_e32 v4, v4, v7
	v_max_u32_e32 v7, v23, v18
	v_min_u32_e32 v18, v23, v18
	v_max_u32_e32 v17, v42, v11
	v_min_u32_e32 v11, v42, v11
	v_max_u32_e32 v42, v33, v27
	v_min_u32_e32 v27, v33, v27
	v_max_u32_e32 v33, v10, v12
	v_min_u32_e32 v10, v10, v12
	v_max_u32_e32 v12, v21, v26
	v_min_u32_e32 v21, v21, v26
	v_max_u32_e32 v26, v24, v22
	v_min_u32_e32 v22, v24, v22
	v_max_u32_e32 v24, v2, v5
	v_min_u32_e32 v2, v2, v5
	v_max_u32_e32 v5, v19, v3
	v_min_u32_e32 v3, v19, v3
	v_max_u32_e32 v19, v6, v8
	v_min_u32_e32 v6, v6, v8
	v_max_u32_e32 v23, v29, v31
	v_min_u32_e32 v29, v29, v31
	v_max_u32_e32 v31, v28, v34
	v_min_u32_e32 v28, v28, v34
	v_max_u32_e32 v34, v16, v30
	v_min_u32_e32 v16, v16, v30
	v_max_u32_e32 v30, v15, v13
	v_min_u32_e32 v13, v15, v13
	v_max_u32_e32 v15, v14, v32
	v_min_u32_e32 v14, v14, v32
	v_max_u32_e32 v32, v20, v7
	v_min_u32_e32 v7, v20, v7
	v_max_u32_e32 v20, v9, v4
	v_min_u32_e32 v4, v9, v4
	v_max_u32_e32 v9, v25, v18
	v_min_u32_e32 v18, v25, v18
	v_max_u32_e32 v8, v17, v33
	v_min_u32_e32 v17, v17, v33
	v_max_u32_e32 v33, v42, v12
	v_min_u32_e32 v12, v42, v12
	v_max_u32_e32 v42, v11, v10
	v_min_u32_e32 v10, v11, v10
	v_max_u32_e32 v11, v27, v21
	v_min_u32_e32 v21, v27, v21
	v_max_u32_e32 v27, v26, v5
	v_min_u32_e32 v5, v26, v5
	v_max_u32_e32 v26, v24, v19
	v_min_u32_e32 v19, v24, v19
	v_max_u32_e32 v24, v22, v3
	v_min_u32_e32 v3, v22, v3
	v_max_u32_e32 v22, v2, v6
	v_min_u32_e32 v2, v2, v6
	v_min_u32_e32 v25, v23, v31
	v_min_u32_e32 v35, v29, v28
	v_min_u32_e32 v36, v34, v30
	v_min_u32_e32 v37, v16, v13
	v_min_u32_e32 v38, v15, v32
	v_min_u32_e32 v39, v14, v7
	v_min_u32_e32 v40, v20, v9
	v_min_u32_e32 v41, v4, v18
	v_min_u32_e32 v6, v8, v33
	v_min_u32_e32 v43, v17, v12
	v_min_u32_e32 v44, v42, v11
	v_min_u32_e32 v45, v10, v21
	v_min_u32_e32 v46, v27, v26
	v_min_u32_e32 v47, v5, v19
	v_min_u32_e32 v48, v24, v22
	v_min_u32_e32 v49, v3, v2
	v_max3_u32 v23, v23, v31, v49
	v_max3_u32 v2, v25, v3, v2
	v_max3_u32 v3, v29, v28, v48
	v_max3_u32 v22, v35, v24, v22
	v_max3_u32 v24, v34, v30, v47
	v_max3_u32 v5, v36, v5, v19
	v_max3_u32 v13, v16, v13, v46
	v_max3_u32 v16, v37, v27, v26
	v_max3_u32 v15, v15, v32, v45
	s_waitcnt vmcnt(0)
	v_pk_mul_f32 v[200:201], v[200:201], s[96:97] op_sel_hi:[1,0]
	v_pk_mul_f32 v[202:203], v[202:203], s[96:97] op_sel_hi:[1,0]
	v_pk_mul_f32 v[204:205], v[204:205], s[96:97] op_sel_hi:[1,0]
	v_pk_mul_f32 v[206:207], v[206:207], s[96:97] op_sel_hi:[1,0]
	v_pk_mul_f32 v[208:209], v[208:209], s[96:97] op_sel_hi:[1,0]
	v_pk_mul_f32 v[210:211], v[210:211], s[96:97] op_sel_hi:[1,0]
	v_pk_mul_f32 v[212:213], v[212:213], s[96:97] op_sel_hi:[1,0]
	v_pk_mul_f32 v[214:215], v[214:215], s[96:97] op_sel_hi:[1,0]
	v_pk_mul_f32 v[216:217], v[216:217], s[96:97] op_sel_hi:[1,0]
	v_pk_mul_f32 v[218:219], v[218:219], s[96:97] op_sel_hi:[1,0]
	v_pk_mul_f32 v[220:221], v[220:221], s[96:97] op_sel_hi:[1,0]
	v_pk_mul_f32 v[222:223], v[222:223], s[96:97] op_sel_hi:[1,0]
	v_pk_mul_f32 v[224:225], v[224:225], s[96:97] op_sel_hi:[1,0]
	v_pk_mul_f32 v[226:227], v[226:227], s[96:97] op_sel_hi:[1,0]
	v_pk_mul_f32 v[228:229], v[228:229], s[96:97] op_sel_hi:[1,0]
	v_pk_mul_f32 v[230:231], v[230:231], s[96:97] op_sel_hi:[1,0]
	v_cvt_scalef32_pk_fp4_f32 v232, v200, v201, 1.0
	v_cvt_scalef32_pk_fp4_f32 v233, v208, v209, 1.0
	v_cvt_scalef32_pk_fp4_f32 v234, v216, v217, 1.0
	v_cvt_scalef32_pk_fp4_f32 v235, v224, v225, 1.0
	v_cvt_scalef32_pk_fp4_f32 v232, v202, v203, 1.0 op_sel:[0,0,1,0]
	v_cvt_scalef32_pk_fp4_f32 v233, v210, v211, 1.0 op_sel:[0,0,1,0]
	v_cvt_scalef32_pk_fp4_f32 v234, v218, v219, 1.0 op_sel:[0,0,1,0]
	v_cvt_scalef32_pk_fp4_f32 v235, v226, v227, 1.0 op_sel:[0,0,1,0]
	v_cvt_scalef32_pk_fp4_f32 v232, v204, v205, 1.0 op_sel:[0,0,0,1]
	v_cvt_scalef32_pk_fp4_f32 v233, v212, v213, 1.0 op_sel:[0,0,0,1]
	v_cvt_scalef32_pk_fp4_f32 v234, v220, v221, 1.0 op_sel:[0,0,0,1]
	v_cvt_scalef32_pk_fp4_f32 v235, v228, v229, 1.0 op_sel:[0,0,0,1]
	v_cvt_scalef32_pk_fp4_f32 v232, v206, v207, 1.0 op_sel:[0,0,1,1]
	v_cvt_scalef32_pk_fp4_f32 v233, v214, v215, 1.0 op_sel:[0,0,1,1]
	v_cvt_scalef32_pk_fp4_f32 v234, v222, v223, 1.0 op_sel:[0,0,1,1]
	v_cvt_scalef32_pk_fp4_f32 v235, v230, v231, 1.0 op_sel:[0,0,1,1]
	s_nop 0
	global_store_dwordx4 v[240:241], v[232:235], off
	v_lshl_add_u64 v[240:241], v[240:241], 0, v[246:247]
	v_max3_u32 v10, v38, v10, v21
	v_max3_u32 v7, v14, v7, v44
	v_max3_u32 v11, v39, v42, v11
	v_max3_u32 v9, v20, v9, v43
	v_max3_u32 v12, v40, v17, v12
	v_max3_u32 v4, v4, v18, v6
	v_max3_u32 v6, v41, v8, v33
	v_max_u32_e32 v8, v23, v15
	v_min_u32_e32 v14, v23, v15
	v_max_u32_e32 v15, v2, v10
	v_min_u32_e32 v2, v2, v10
	v_max_u32_e32 v10, v3, v7
	v_min_u32_e32 v3, v3, v7
	v_max_u32_e32 v7, v22, v11
	v_max_u32_e32 v17, v24, v9
	v_max_u32_e32 v18, v5, v12
	v_min_u32_e32 v5, v5, v12
	v_max_u32_e32 v12, v13, v4
	v_min_u32_e32 v4, v13, v4
	v_max_u32_e32 v13, v16, v6
	v_min_u32_e32 v11, v22, v11
	v_min_u32_e32 v9, v24, v9
	v_min_u32_e32 v6, v16, v6
	v_max_u32_e32 v16, v8, v17
	v_min_u32_e32 v8, v8, v17
	v_max_u32_e32 v17, v15, v18
	v_min_u32_e32 v15, v15, v18
	v_max_u32_e32 v18, v10, v12
	v_min_u32_e32 v10, v10, v12
	v_max_u32_e32 v12, v7, v13
	v_min_u32_e32 v7, v7, v13
	v_max_u32_e32 v13, v14, v9
	v_min_u32_e32 v9, v14, v9
	v_max_u32_e32 v14, v2, v5
	v_min_u32_e32 v2, v2, v5
	v_max_u32_e32 v5, v3, v4
	v_min_u32_e32 v3, v3, v4
	v_max_u32_e32 v4, v11, v6
	v_min_u32_e32 v6, v11, v6
	v_max_u32_e32 v11, v16, v18
	v_min_u32_e32 v16, v16, v18
	v_max_u32_e32 v18, v17, v12
	v_min_u32_e32 v12, v17, v12
	v_max_u32_e32 v17, v8, v10
	v_min_u32_e32 v8, v8, v10
	v_add_co_u32_e32 v10, vcc, s28, v80
	v_max_u32_e32 v25, v11, v18
	v_min_u32_e32 v18, v11, v18
	v_addc_co_u32_e32 v11, vcc, 0, v81, vcc
	v_max_u32_e32 v19, v15, v7
	v_min_u32_e32 v7, v15, v7
	v_max_u32_e32 v15, v13, v5
	v_min_u32_e32 v13, v13, v5
	v_max_u32_e32 v20, v14, v4
	v_min_u32_e32 v14, v14, v4
	v_max_u32_e32 v21, v9, v3
	v_min_u32_e32 v22, v9, v3
	v_max_u32_e32 v23, v2, v6
	v_min_u32_e32 v24, v2, v6
	global_load_dwordx4 v[2:5], v[10:11], off
	global_load_dwordx4 v[34:37], v[82:83], off offset:256
	global_load_dwordx4 v[38:41], v[82:83], off offset:288
	v_max_u32_e32 v26, v16, v12
	v_min_u32_e32 v12, v16, v12
	v_max_u32_e32 v16, v17, v19
	v_min_u32_e32 v17, v17, v19
	v_max_u32_e32 v19, v8, v7
	v_min_u32_e32 v27, v8, v7
	global_load_dwordx4 v[6:9], v[10:11], off offset:32
	global_load_dwordx4 v[28:31], v[10:11], off offset:64
	global_load_dwordx4 v[148:151], v[10:11], off offset:96
	v_cmp_lt_i32_e32 vcc, v84, v85
	global_load_dwordx4 v[42:45], v[82:83], off offset:320
	v_max_u32_e32 v33, v22, v24
	v_min_u32_e32 v22, v22, v24
	v_cndmask_b32_e32 v24, v77, v84, vcc
	v_max_u32_e32 v32, v15, v20
	v_min_u32_e32 v15, v15, v20
	v_max_u32_e32 v20, v13, v14
	v_min_u32_e32 v13, v13, v14
	v_min_u32_e32 v14, v21, v23
	v_lshlrev_b32_e32 v153, 2, v24
	ds_bpermute_b32 v46, v153, v33
	ds_bpermute_b32 v47, v153, v14
	ds_bpermute_b32 v50, v153, v13
	ds_bpermute_b32 v51, v153, v20
	ds_bpermute_b32 v52, v153, v15
	s_waitcnt lgkmcnt(0)
	v_max_u32_e32 v147, v18, v46
	v_max_u32_e32 v152, v26, v47
	global_load_dwordx4 v[46:49], v[82:83], off offset:352
	ds_bpermute_b32 v53, v153, v32
	global_load_dwordx4 v[154:157], v[10:11], off offset:128
	global_load_dwordx4 v[158:161], v[10:11], off offset:160
	v_max_u32_e32 v170, v16, v50
	v_max_u32_e32 v171, v17, v51
	v_max_u32_e32 v172, v19, v52
	s_waitcnt lgkmcnt(0)
	v_max_u32_e32 v173, v27, v53
	global_load_dwordx4 v[50:53], v[82:83], off offset:384
	global_load_dwordx4 v[54:57], v[82:83], off offset:416
	global_load_dwordx4 v[162:165], v[10:11], off offset:192
	global_load_dwordx4 v[166:169], v[10:11], off offset:224
	global_load_dwordx4 v[58:61], v[82:83], off offset:448
	global_load_dwordx4 v[62:65], v[82:83], off offset:480
	v_max_u32_e32 v21, v21, v23
	ds_bpermute_b32 v23, v153, v21
	ds_bpermute_b32 v16, v153, v16
	ds_bpermute_b32 v19, v153, v19
	ds_bpermute_b32 v24, v153, v22
	ds_bpermute_b32 v27, v153, v27
	s_waitcnt lgkmcnt(4)
	v_max_u32_e32 v23, v12, v23
	ds_bpermute_b32 v17, v153, v17
	s_waitcnt lgkmcnt(4)
	v_max_u32_e32 v13, v13, v16
	ds_bpermute_b32 v12, v153, v12
	ds_bpermute_b32 v16, v153, v26
	ds_bpermute_b32 v18, v153, v18
	s_waitcnt lgkmcnt(6)
	v_max_u32_e32 v15, v15, v19
	ds_bpermute_b32 v19, v153, v25
	s_waitcnt lgkmcnt(6)
	v_max_u32_e32 v24, v25, v24
	s_waitcnt lgkmcnt(5)
	v_max_u32_e32 v27, v32, v27
	s_waitcnt lgkmcnt(4)
	v_max_u32_e32 v17, v20, v17
	s_waitcnt lgkmcnt(3)
	v_max_u32_e32 v12, v21, v12
	s_waitcnt lgkmcnt(2)
	v_max_u32_e32 v14, v14, v16
	s_waitcnt lgkmcnt(1)
	v_max_u32_e32 v16, v33, v18
	s_waitcnt lgkmcnt(0)
	v_max_u32_e32 v10, v22, v19
	v_max_u32_e32 v11, v24, v27
	v_max_u32_e32 v18, v147, v15
	v_min_u32_e32 v33, v147, v15
	v_max_u32_e32 v15, v152, v17
	v_min_u32_e32 v82, v152, v17
	v_max_u32_e32 v83, v23, v13
	v_min_u32_e32 v147, v23, v13
	v_max_u32_e32 v13, v170, v12
	v_min_u32_e32 v152, v170, v12
	v_max_u32_e32 v12, v171, v14
	v_min_u32_e32 v170, v171, v14
	v_max_u32_e32 v14, v172, v16
	v_min_u32_e32 v32, v24, v27
	v_min_u32_e32 v171, v172, v16
	v_max_u32_e32 v172, v173, v10
	v_min_u32_e32 v10, v173, v10
	v_max_u32_e32 v173, v11, v13
	v_min_u32_e32 v11, v11, v13
	v_max_u32_e32 v174, v18, v12
	v_min_u32_e32 v175, v18, v12
	v_max_u32_e32 v176, v15, v14
	v_min_u32_e32 v177, v15, v14
	s_waitcnt vmcnt(14)
	v_mfma_f32_32x32x16_bf16 v[12:27], v[2:5], v[34:37], 0
	v_max_u32_e32 v2, v83, v172
	v_max_u32_e32 v178, v174, v2
	v_min_u32_e32 v174, v174, v2
	v_min_u32_e32 v83, v83, v172
	v_max_u32_e32 v172, v32, v152
	v_min_u32_e32 v32, v32, v152
	s_waitcnt vmcnt(12)
	v_mfma_f32_32x32x16_bf16 v[12:27], v[6:9], v[38:41], v[12:27]
	v_add_co_u32_e32 v6, vcc, s29, v80
	v_max_u32_e32 v152, v33, v170
	s_nop 0
	v_addc_co_u32_e32 v7, vcc, 0, v81, vcc
	global_load_dwordx4 v[2:5], v[6:7], off
	v_min_u32_e32 v33, v33, v170
	s_waitcnt vmcnt(10)
	v_mfma_f32_32x32x16_bf16 v[12:27], v[28:31], v[42:45], v[12:27]
	global_load_dwordx4 v[28:31], v[6:7], off offset:32
	v_max_u32_e32 v170, v82, v171
	v_min_u32_e32 v8, v82, v171
	v_max_u32_e32 v9, v147, v10
	v_min_u32_e32 v10, v147, v10
	v_max_u32_e32 v147, v173, v176
	v_min_u32_e32 v176, v173, v176
	s_waitcnt vmcnt(10)
	v_mfma_f32_32x32x16_bf16 v[12:27], v[148:151], v[46:49], v[12:27]
	v_max_u32_e32 v148, v172, v170
	v_min_u32_e32 v149, v172, v170
	global_load_dwordx4 v[170:173], v[6:7], off offset:64
	v_max_u32_e32 v179, v11, v177
	v_min_u32_e32 v11, v11, v177
	v_max_u32_e32 v177, v175, v83
	v_min_u32_e32 v83, v175, v83
	s_waitcnt vmcnt(8)
	v_mfma_f32_32x32x16_bf16 v[12:27], v[154:157], v[50:53], v[12:27]
	v_max_u32_e32 v156, v176, v174
	v_min_u32_e32 v157, v176, v174
	v_max_u32_e32 v150, v152, v9
	v_min_u32_e32 v9, v152, v9
	v_max_u32_e32 v82, v147, v178
	v_min_u32_e32 v152, v147, v178
	global_load_dwordx4 v[182:185], v[6:7], off offset:224
	s_waitcnt vmcnt(8)
	v_mfma_f32_32x32x16_bf16 v[12:27], v[158:161], v[54:57], v[12:27]
	v_max_u32_e32 v158, v179, v177
	v_min_u32_e32 v159, v179, v177
	global_load_dwordx4 v[174:177], v[6:7], off offset:96
	global_load_dwordx4 v[178:181], v[6:7], off offset:192
	v_max_u32_e32 v151, v32, v8
	v_min_u32_e32 v8, v32, v8
	v_max_u32_e32 v32, v33, v10
	s_waitcnt vmcnt(7)
	v_mfma_f32_32x32x16_bf16 v[12:27], v[162:165], v[58:61], v[12:27]
	global_load_dwordx4 v[162:165], v[6:7], off offset:128
	v_min_u32_e32 v10, v33, v10
	v_max_u32_e32 v160, v11, v83
	v_min_u32_e32 v161, v11, v83
	v_max_u32_e32 v83, v148, v150
	v_min_u32_e32 v147, v148, v150
	v_max_u32_e32 v148, v149, v9
	s_waitcnt vmcnt(7)
	v_mfma_f32_32x32x16_bf16 v[12:27], v[166:169], v[62:65], v[12:27]
	global_load_dwordx4 v[166:169], v[6:7], off offset:160
	v_min_u32_e32 v149, v149, v9
	v_max_u32_e32 v154, v8, v10
	v_min_u32_e32 v155, v8, v10
	v_max_u32_e32 v150, v151, v32
	v_min_u32_e32 v151, v151, v32
	s_nop 5
	v_not_b32_e32 v8, v12
	v_or_b32_e32 v9, 0x80000000, v12
	v_cmp_gt_i32_e32 vcc, 0, v12
	v_not_b32_e32 v6, v15
	v_or_b32_e32 v7, 0x80000000, v15
	v_cndmask_b32_e32 v8, v9, v8, vcc
	v_and_or_b32 v100, v8, s23, v100
	v_not_b32_e32 v8, v13
	v_or_b32_e32 v9, 0x80000000, v13
	v_cmp_gt_i32_e32 vcc, 0, v13
	v_or_b32_e32 v32, 0x80000000, v19
	s_nop 0
	v_cndmask_b32_e32 v8, v9, v8, vcc
	v_and_or_b32 v98, v8, s23, v98
	v_not_b32_e32 v8, v14
	v_or_b32_e32 v9, 0x80000000, v14
	v_cmp_gt_i32_e32 vcc, 0, v14
	s_nop 1
	v_cndmask_b32_e32 v8, v9, v8, vcc
	v_cmp_gt_i32_e32 vcc, 0, v15
	v_and_or_b32 v101, v8, s23, v101
	s_nop 0
	v_cndmask_b32_e32 v6, v7, v6, vcc
	v_and_or_b32 v99, v6, s23, v99
	v_not_b32_e32 v6, v16
	v_or_b32_e32 v7, 0x80000000, v16
	v_cmp_gt_i32_e32 vcc, 0, v16
	s_nop 1
	v_cndmask_b32_e32 v6, v7, v6, vcc
	v_and_or_b32 v97, v6, s23, v97
	v_not_b32_e32 v6, v17
	v_or_b32_e32 v7, 0x80000000, v17
	v_cmp_gt_i32_e32 vcc, 0, v17
	s_nop 1
	v_cndmask_b32_e32 v6, v7, v6, vcc
	v_and_or_b32 v96, v6, s23, v96
	v_not_b32_e32 v6, v18
	v_or_b32_e32 v7, 0x80000000, v18
	v_cmp_gt_i32_e32 vcc, 0, v18
	v_not_b32_e32 v18, v19
	s_nop 0
	v_cndmask_b32_e32 v6, v7, v6, vcc
	v_and_or_b32 v95, v6, s23, v95
	s_waitcnt vmcnt(7)
	v_mfma_f32_32x32x16_bf16 v[2:17], v[2:5], v[34:37], 0
	v_cmp_gt_i32_e32 vcc, 0, v19
	v_or_b32_e32 v19, 0x80000000, v20
	s_nop 0
	v_cndmask_b32_e32 v18, v32, v18, vcc
	v_and_or_b32 v94, v18, s23, v94
	v_not_b32_e32 v18, v20
	v_cmp_gt_i32_e32 vcc, 0, v20
	s_waitcnt vmcnt(6)
	v_mfma_f32_32x32x16_bf16 v[2:17], v[28:31], v[38:41], v[2:17]
	v_not_b32_e32 v30, v22
	v_cndmask_b32_e32 v18, v19, v18, vcc
	v_and_or_b32 v93, v18, s23, v93
	v_not_b32_e32 v18, v21
	v_or_b32_e32 v19, 0x80000000, v21
	v_cmp_gt_i32_e32 vcc, 0, v21
	v_or_b32_e32 v31, 0x80000000, v22
	s_waitcnt vmcnt(5)
	v_mfma_f32_32x32x16_bf16 v[2:17], v[170:173], v[42:45], v[2:17]
	v_cndmask_b32_e32 v18, v19, v18, vcc
	v_add_co_u32_e32 v28, vcc, s30, v80
	v_and_or_b32 v92, v18, s23, v92
	s_nop 0
	v_addc_co_u32_e32 v29, vcc, 0, v81, vcc
	global_load_dwordx4 v[18:21], v[28:29], off
	global_load_dwordx4 v[170:173], v[28:29], off offset:32
	s_waitcnt vmcnt(5)
	v_mfma_f32_32x32x16_bf16 v[2:17], v[174:177], v[46:49], v[2:17]
	global_load_dwordx4 v[174:177], v[28:29], off offset:128
	v_cmp_gt_i32_e32 vcc, 0, v22
	s_nop 1
	v_cndmask_b32_e32 v22, v31, v30, vcc
	v_and_or_b32 v90, v22, s23, v90
	v_not_b32_e32 v22, v23
	s_waitcnt vmcnt(4)
	v_mfma_f32_32x32x16_bf16 v[2:17], v[162:165], v[50:53], v[2:17]
	global_load_dwordx4 v[162:165], v[28:29], off offset:64
	v_or_b32_e32 v30, 0x80000000, v23
	v_cmp_gt_i32_e32 vcc, 0, v23
	v_or_b32_e32 v23, 0x80000000, v24
	s_nop 0
	v_cndmask_b32_e32 v22, v30, v22, vcc
	v_and_or_b32 v186, v22, s23, v89
	s_waitcnt vmcnt(4)
	v_mfma_f32_32x32x16_bf16 v[2:17], v[166:169], v[54:57], v[2:17]
	global_load_dwordx4 v[166:169], v[28:29], off offset:96
	v_not_b32_e32 v22, v24
	v_cmp_gt_i32_e32 vcc, 0, v24
	s_nop 1
	v_cndmask_b32_e32 v22, v23, v22, vcc
	v_and_or_b32 v187, v22, s23, v88
	v_mfma_f32_32x32x16_bf16 v[2:17], v[178:181], v[58:61], v[2:17]
	global_load_dwordx4 v[178:181], v[28:29], off offset:160
	v_not_b32_e32 v22, v25
	v_or_b32_e32 v23, 0x80000000, v25
	v_cmp_gt_i32_e32 vcc, 0, v25
	s_nop 1
	v_cndmask_b32_e32 v22, v23, v22, vcc
	v_mfma_f32_32x32x16_bf16 v[2:17], v[182:185], v[62:65], v[2:17]
	v_and_or_b32 v188, v22, s23, v78
	v_not_b32_e32 v22, v26
	v_or_b32_e32 v23, 0x80000000, v26
	v_cmp_gt_i32_e32 vcc, 0, v26
	global_load_dwordx4 v[182:185], v[28:29], off offset:192
	s_nop 0
	v_cndmask_b32_e32 v22, v23, v22, vcc
	v_and_or_b32 v189, v22, s23, v102
	v_not_b32_e32 v22, v27
	v_or_b32_e32 v23, 0x80000000, v27
	v_cmp_gt_i32_e32 vcc, 0, v27
	s_nop 1
	v_cndmask_b32_e32 v22, v23, v22, vcc
	v_and_or_b32 v190, v22, s23, v103
	v_not_b32_e32 v22, v2
	v_or_b32_e32 v23, 0x80000000, v2
	v_cmp_gt_i32_e32 vcc, 0, v2
	s_nop 1
	v_cndmask_b32_e32 v2, v23, v22, vcc
	v_and_or_b32 v78, v2, s23, v104
	v_not_b32_e32 v2, v3
	v_or_b32_e32 v22, 0x80000000, v3
	v_cmp_gt_i32_e32 vcc, 0, v3
	v_or_b32_e32 v3, 0x80000000, v4
	s_nop 0
	v_cndmask_b32_e32 v2, v22, v2, vcc
	v_and_or_b32 v88, v2, s23, v105
	global_load_dwordx4 v[102:105], v[28:29], off offset:224
	v_not_b32_e32 v2, v4
	v_cmp_gt_i32_e32 vcc, 0, v4
	s_waitcnt vmcnt(7)
	v_mfma_f32_32x32x16_bf16 v[18:33], v[18:21], v[34:37], 0
	v_cndmask_b32_e32 v2, v3, v2, vcc
	v_and_or_b32 v89, v2, s23, v107
	v_not_b32_e32 v2, v5
	v_or_b32_e32 v3, 0x80000000, v5
	v_cmp_gt_i32_e32 vcc, 0, v5
	s_nop 1
	v_cndmask_b32_e32 v2, v3, v2, vcc
	v_and_or_b32 v191, v2, s23, v106
	v_not_b32_e32 v2, v6
	v_or_b32_e32 v3, 0x80000000, v6
	v_cmp_gt_i32_e32 vcc, 0, v6
	s_waitcnt vmcnt(6)
	v_mfma_f32_32x32x16_bf16 v[18:33], v[170:173], v[38:41], v[18:33]
	v_cndmask_b32_e32 v2, v3, v2, vcc
	v_and_or_b32 v192, v2, s23, v108
	v_not_b32_e32 v2, v7
	v_or_b32_e32 v3, 0x80000000, v7
	v_cmp_gt_i32_e32 vcc, 0, v7
	s_waitcnt vmcnt(4)
	v_mfma_f32_32x32x16_bf16 v[18:33], v[162:165], v[42:45], v[18:33]
	v_cndmask_b32_e32 v2, v3, v2, vcc
	v_and_or_b32 v193, v2, s23, v109
	v_not_b32_e32 v2, v8
	v_or_b32_e32 v3, 0x80000000, v8
	v_cmp_gt_i32_e32 vcc, 0, v8
	s_nop 1
	v_cndmask_b32_e32 v2, v3, v2, vcc
	v_and_or_b32 v194, v2, s23, v110
	v_not_b32_e32 v2, v9
	v_or_b32_e32 v3, 0x80000000, v9
	v_cmp_gt_i32_e32 vcc, 0, v9
	v_or_b32_e32 v9, 0x80000000, v11
	s_waitcnt vmcnt(3)
	v_mfma_f32_32x32x16_bf16 v[18:33], v[166:169], v[46:49], v[18:33]
	v_cndmask_b32_e32 v2, v3, v2, vcc
	v_and_or_b32 v195, v2, s23, v111
	v_not_b32_e32 v2, v10
	v_or_b32_e32 v3, 0x80000000, v10
	v_cmp_gt_i32_e32 vcc, 0, v10
	s_nop 1
	v_cndmask_b32_e32 v8, v3, v2, vcc
	v_add_co_u32_e32 v6, vcc, s31, v80
	v_and_or_b32 v80, v8, s23, v68
	s_nop 0
	v_addc_co_u32_e32 v7, vcc, 0, v81, vcc
	global_load_dwordx4 v[2:5], v[6:7], off
	global_load_dwordx4 v[106:109], v[6:7], off offset:32
	global_load_dwordx4 v[162:165], v[6:7], off offset:64
	global_load_dwordx4 v[166:169], v[6:7], off offset:96
	v_not_b32_e32 v8, v11
	v_cmp_gt_i32_e32 vcc, 0, v11
	v_mfma_f32_32x32x16_bf16 v[18:33], v[174:177], v[50:53], v[18:33]
	global_load_dwordx4 v[170:173], v[6:7], off offset:192
	v_cndmask_b32_e32 v8, v9, v8, vcc
	v_and_or_b32 v81, v8, s23, v91
	v_not_b32_e32 v8, v12
	v_or_b32_e32 v9, 0x80000000, v12
	v_cmp_gt_i32_e32 vcc, 0, v12
	s_waitcnt vmcnt(7)
	v_mfma_f32_32x32x16_bf16 v[18:33], v[178:181], v[54:57], v[18:33]
	v_cndmask_b32_e32 v8, v9, v8, vcc
	v_and_or_b32 v91, v8, s23, v69
	v_not_b32_e32 v8, v13
	v_or_b32_e32 v9, 0x80000000, v13
	v_cmp_gt_i32_e32 vcc, 0, v13
	s_nop 1
	v_cndmask_b32_e32 v8, v9, v8, vcc
	v_and_or_b32 v196, v8, s23, v67
	v_not_b32_e32 v8, v14
	v_or_b32_e32 v9, 0x80000000, v14
	v_cmp_gt_i32_e32 vcc, 0, v14
	s_waitcnt vmcnt(6)
	v_mfma_f32_32x32x16_bf16 v[18:33], v[182:185], v[58:61], v[18:33]
	v_cndmask_b32_e32 v8, v9, v8, vcc
	v_and_or_b32 v174, v8, s23, v66
	global_load_dwordx4 v[66:69], v[6:7], off offset:128
	v_not_b32_e32 v8, v15
	v_or_b32_e32 v9, 0x80000000, v15
	v_cmp_gt_i32_e32 vcc, 0, v15
	s_waitcnt vmcnt(6)
	v_mfma_f32_32x32x16_bf16 v[18:33], v[102:105], v[62:65], v[18:33]
	global_load_dwordx4 v[102:105], v[6:7], off offset:224
	v_cndmask_b32_e32 v8, v9, v8, vcc
	v_and_or_b32 v175, v8, s23, v112
	v_not_b32_e32 v8, v16
	v_or_b32_e32 v9, 0x80000000, v16
	v_cmp_gt_i32_e32 vcc, 0, v16
	s_nop 1
	v_cndmask_b32_e32 v8, v9, v8, vcc
	v_and_or_b32 v176, v8, s23, v113
	global_load_dwordx4 v[110:113], v[6:7], off offset:160
	v_not_b32_e32 v8, v17
	v_or_b32_e32 v9, 0x80000000, v17
	v_cmp_gt_i32_e32 vcc, 0, v17
	v_not_b32_e32 v6, v19
	v_or_b32_e32 v7, 0x80000000, v19
	v_cndmask_b32_e32 v8, v9, v8, vcc
	v_and_or_b32 v114, v8, s23, v114
	v_not_b32_e32 v8, v18
	v_or_b32_e32 v9, 0x80000000, v18
	v_cmp_gt_i32_e32 vcc, 0, v18
	s_nop 1
	v_cndmask_b32_e32 v8, v9, v8, vcc
	v_cmp_gt_i32_e32 vcc, 0, v19
	v_and_or_b32 v18, v8, s23, v115
	v_not_b32_e32 v115, v23
	v_cndmask_b32_e32 v6, v7, v6, vcc
	v_and_or_b32 v19, v6, s23, v116
	v_not_b32_e32 v6, v20
	v_or_b32_e32 v7, 0x80000000, v20
	v_cmp_gt_i32_e32 vcc, 0, v20
	v_or_b32_e32 v116, 0x80000000, v23
	s_nop 0
	v_cndmask_b32_e32 v6, v7, v6, vcc
	v_and_or_b32 v20, v6, s23, v117
	v_not_b32_e32 v6, v21
	v_or_b32_e32 v7, 0x80000000, v21
	v_cmp_gt_i32_e32 vcc, 0, v21
	s_nop 1
	v_cndmask_b32_e32 v6, v7, v6, vcc
	v_and_or_b32 v21, v6, s23, v118
	v_not_b32_e32 v6, v22
	v_or_b32_e32 v7, 0x80000000, v22
	v_cmp_gt_i32_e32 vcc, 0, v22
	s_nop 1
	v_cndmask_b32_e32 v6, v7, v6, vcc
	v_and_or_b32 v22, v6, s23, v119
	s_waitcnt vmcnt(7)
	v_mfma_f32_32x32x16_bf16 v[2:17], v[2:5], v[34:37], 0
	v_cmp_gt_i32_e32 vcc, 0, v23
	v_not_b32_e32 v34, v24
	v_or_b32_e32 v35, 0x80000000, v24
	v_cndmask_b32_e32 v23, v116, v115, vcc
	v_cmp_gt_i32_e32 vcc, 0, v24
	v_and_or_b32 v23, v23, s23, v120
	v_max_u32_e32 v36, v101, v99
	s_waitcnt vmcnt(6)
	v_mfma_f32_32x32x16_bf16 v[2:17], v[106:109], v[38:41], v[2:17]
	v_cndmask_b32_e32 v24, v35, v34, vcc
	v_not_b32_e32 v34, v25
	v_or_b32_e32 v35, 0x80000000, v25
	v_cmp_gt_i32_e32 vcc, 0, v25
	v_and_or_b32 v24, v24, s23, v121
	v_min_u32_e32 v37, v101, v99
	v_cndmask_b32_e32 v25, v35, v34, vcc
	s_waitcnt vmcnt(5)
	v_mfma_f32_32x32x16_bf16 v[2:17], v[162:165], v[42:45], v[2:17]
	v_not_b32_e32 v34, v26
	v_or_b32_e32 v35, 0x80000000, v26
	v_cmp_gt_i32_e32 vcc, 0, v26
	v_and_or_b32 v25, v25, s23, v122
	v_max_u32_e32 v38, v97, v96
	v_cndmask_b32_e32 v26, v35, v34, vcc
	v_not_b32_e32 v34, v27
	s_waitcnt vmcnt(4)
	v_mfma_f32_32x32x16_bf16 v[2:17], v[166:169], v[46:49], v[2:17]
	v_or_b32_e32 v35, 0x80000000, v27
	v_cmp_gt_i32_e32 vcc, 0, v27
	v_and_or_b32 v26, v26, s23, v123
	v_min_u32_e32 v39, v97, v96
	v_cndmask_b32_e32 v27, v35, v34, vcc
	v_not_b32_e32 v34, v28
	v_or_b32_e32 v35, 0x80000000, v28
	s_waitcnt vmcnt(2)
	v_mfma_f32_32x32x16_bf16 v[2:17], v[66:69], v[50:53], v[2:17]
	v_cmp_gt_i32_e32 vcc, 0, v28
	v_and_or_b32 v27, v27, s23, v124
	v_max_u32_e32 v40, v95, v94
	v_cndmask_b32_e32 v28, v35, v34, vcc
	v_not_b32_e32 v34, v29
	v_or_b32_e32 v35, 0x80000000, v29
	v_cmp_gt_i32_e32 vcc, 0, v29
	s_waitcnt vmcnt(0)
	v_mfma_f32_32x32x16_bf16 v[2:17], v[110:113], v[54:57], v[2:17]
	v_cndmask_b32_e32 v29, v35, v34, vcc
	v_not_b32_e32 v34, v30
	v_or_b32_e32 v35, 0x80000000, v30
	v_cmp_gt_i32_e32 vcc, 0, v30
	v_and_or_b32 v28, v28, s23, v125
	v_and_or_b32 v29, v29, s23, v126
	v_cndmask_b32_e32 v30, v35, v34, vcc
	v_mfma_f32_32x32x16_bf16 v[2:17], v[170:173], v[58:61], v[2:17]
	v_not_b32_e32 v34, v31
	v_or_b32_e32 v35, 0x80000000, v31
	v_cmp_gt_i32_e32 vcc, 0, v31
	v_and_or_b32 v30, v30, s23, v127
	v_min_u32_e32 v41, v95, v94
	v_cndmask_b32_e32 v31, v35, v34, vcc
	v_not_b32_e32 v34, v32
	v_mfma_f32_32x32x16_bf16 v[2:17], v[102:105], v[62:65], v[2:17]
	v_or_b32_e32 v35, 0x80000000, v32
	v_cmp_gt_i32_e32 vcc, 0, v32
	v_and_or_b32 v31, v31, s23, v128
	v_max_u32_e32 v42, v93, v92
	v_cndmask_b32_e32 v32, v35, v34, vcc
	v_not_b32_e32 v34, v33
	v_or_b32_e32 v35, 0x80000000, v33
	v_cmp_gt_i32_e32 vcc, 0, v33
	v_and_or_b32 v32, v32, s23, v129
	v_min_u32_e32 v43, v93, v92
	v_cndmask_b32_e32 v33, v35, v34, vcc
	s_nop 0
	v_not_b32_e32 v34, v2
	v_or_b32_e32 v35, 0x80000000, v2
	v_cmp_gt_i32_e32 vcc, 0, v2
	global_load_dwordx4 v[200:203], v[236:237], off
	global_load_dwordx4 v[204:207], v[236:237], off offset:16
	global_load_dwordx4 v[208:211], v[236:237], off offset:32
	global_load_dwordx4 v[212:215], v[236:237], off offset:48
	global_load_dwordx4 v[216:219], v[238:239], off
	global_load_dwordx4 v[220:223], v[238:239], off offset:16
	global_load_dwordx4 v[224:227], v[238:239], off offset:32
	global_load_dwordx4 v[228:231], v[238:239], off offset:48
	v_lshl_add_u64 v[236:237], v[236:237], 0, v[244:245]
	v_lshl_add_u64 v[238:239], v[238:239], 0, v[244:245]
	v_and_or_b32 v33, v33, s23, v130
	v_max_u32_e32 v44, v90, v186
	v_cndmask_b32_e32 v2, v35, v34, vcc
	v_not_b32_e32 v34, v3
	v_or_b32_e32 v35, 0x80000000, v3
	v_cmp_gt_i32_e32 vcc, 0, v3
	v_and_or_b32 v2, v2, s23, v131
	v_min_u32_e32 v45, v90, v186
	v_cndmask_b32_e32 v3, v35, v34, vcc
	v_not_b32_e32 v34, v4
	v_or_b32_e32 v35, 0x80000000, v4
	v_cmp_gt_i32_e32 vcc, 0, v4
	v_and_or_b32 v3, v3, s23, v132
	v_max_u32_e32 v46, v187, v188
	v_cndmask_b32_e32 v4, v35, v34, vcc
	v_not_b32_e32 v34, v5
	v_or_b32_e32 v35, 0x80000000, v5
	v_cmp_gt_i32_e32 vcc, 0, v5
	v_and_or_b32 v4, v4, s23, v133
	v_min_u32_e32 v47, v187, v188
	v_cndmask_b32_e32 v5, v35, v34, vcc
	v_not_b32_e32 v34, v6
	v_or_b32_e32 v35, 0x80000000, v6
	v_cmp_gt_i32_e32 vcc, 0, v6
	v_and_or_b32 v5, v5, s23, v134
	v_max_u32_e32 v48, v189, v190
	v_cndmask_b32_e32 v6, v35, v34, vcc
	v_not_b32_e32 v34, v7
	v_or_b32_e32 v35, 0x80000000, v7
	v_cmp_gt_i32_e32 vcc, 0, v7
	v_and_or_b32 v6, v6, s23, v135
	v_min_u32_e32 v49, v189, v190
	v_cndmask_b32_e32 v7, v35, v34, vcc
	v_not_b32_e32 v34, v8
	v_or_b32_e32 v35, 0x80000000, v8
	v_cmp_gt_i32_e32 vcc, 0, v8
	v_and_or_b32 v7, v7, s23, v136
	v_max_u32_e32 v58, v78, v88
	v_cndmask_b32_e32 v8, v35, v34, vcc
	v_not_b32_e32 v34, v9
	v_or_b32_e32 v35, 0x80000000, v9
	v_cmp_gt_i32_e32 vcc, 0, v9
	v_and_or_b32 v8, v8, s23, v137
	v_min_u32_e32 v59, v78, v88
	v_cndmask_b32_e32 v9, v35, v34, vcc
	v_not_b32_e32 v34, v10
	v_or_b32_e32 v35, 0x80000000, v10
	v_cmp_gt_i32_e32 vcc, 0, v10
	v_and_or_b32 v9, v9, s23, v138
	v_max_u32_e32 v60, v89, v191
	v_cndmask_b32_e32 v10, v35, v34, vcc
	v_not_b32_e32 v34, v11
	v_or_b32_e32 v35, 0x80000000, v11
	v_cmp_gt_i32_e32 vcc, 0, v11
	v_and_or_b32 v10, v10, s23, v139
	v_min_u32_e32 v61, v89, v191
	v_cndmask_b32_e32 v11, v35, v34, vcc
	v_not_b32_e32 v34, v12
	v_or_b32_e32 v35, 0x80000000, v12
	v_cmp_gt_i32_e32 vcc, 0, v12
	v_and_or_b32 v11, v11, s23, v140
	v_max_u32_e32 v62, v192, v193
	v_cndmask_b32_e32 v12, v35, v34, vcc
	v_not_b32_e32 v34, v13
	v_or_b32_e32 v35, 0x80000000, v13
	v_cmp_gt_i32_e32 vcc, 0, v13
	v_and_or_b32 v12, v12, s23, v141
	v_min_u32_e32 v63, v192, v193
	v_cndmask_b32_e32 v13, v35, v34, vcc
	v_not_b32_e32 v34, v14
	v_or_b32_e32 v35, 0x80000000, v14
	v_cmp_gt_i32_e32 vcc, 0, v14
	v_and_or_b32 v13, v13, s23, v142
	v_max_u32_e32 v64, v194, v195
	v_cndmask_b32_e32 v14, v35, v34, vcc
	v_not_b32_e32 v34, v15
	v_or_b32_e32 v35, 0x80000000, v15
	v_cmp_gt_i32_e32 vcc, 0, v15
	v_and_or_b32 v14, v14, s23, v143
	v_min_u32_e32 v65, v194, v195
	v_cndmask_b32_e32 v15, v35, v34, vcc
	v_not_b32_e32 v34, v16
	v_or_b32_e32 v35, 0x80000000, v16
	v_cmp_gt_i32_e32 vcc, 0, v16
	v_and_or_b32 v15, v15, s23, v144
	v_max_u32_e32 v66, v80, v81
	v_cndmask_b32_e32 v16, v35, v34, vcc
	v_not_b32_e32 v34, v17
	v_or_b32_e32 v35, 0x80000000, v17
	v_cmp_gt_i32_e32 vcc, 0, v17
	v_and_or_b32 v16, v16, s23, v145
	v_min_u32_e32 v67, v80, v81
	v_cndmask_b32_e32 v17, v35, v34, vcc
	v_and_or_b32 v17, v17, s23, v146
	v_max_u32_e32 v34, v100, v98
	v_min_u32_e32 v35, v100, v98
	v_max_u32_e32 v68, v91, v196
	v_min_u32_e32 v69, v91, v196
	v_max_u32_e32 v78, v174, v175
	v_min_u32_e32 v80, v174, v175
	v_max_u32_e32 v81, v176, v114
	v_min_u32_e32 v88, v176, v114
	v_max_u32_e32 v97, v18, v19
	v_min_u32_e32 v18, v18, v19
	v_max_u32_e32 v19, v20, v21
	v_min_u32_e32 v20, v20, v21
	v_max_u32_e32 v21, v22, v23
	v_min_u32_e32 v22, v22, v23
	v_max_u32_e32 v23, v24, v25
	v_min_u32_e32 v24, v24, v25
	v_max_u32_e32 v25, v26, v27
	v_min_u32_e32 v26, v26, v27
	v_max_u32_e32 v27, v28, v29
	v_min_u32_e32 v28, v28, v29
	v_max_u32_e32 v29, v30, v31
	v_min_u32_e32 v30, v30, v31
	v_max_u32_e32 v31, v32, v33
	v_min_u32_e32 v32, v32, v33
	v_max_u32_e32 v105, v2, v3
	v_min_u32_e32 v2, v2, v3
	v_max_u32_e32 v3, v4, v5
	v_min_u32_e32 v4, v4, v5
	v_max_u32_e32 v5, v6, v7
	v_min_u32_e32 v6, v6, v7
	v_max_u32_e32 v7, v8, v9
	v_min_u32_e32 v8, v8, v9
	v_max_u32_e32 v9, v10, v11
	v_min_u32_e32 v10, v10, v11
	v_max_u32_e32 v11, v12, v13
	v_min_u32_e32 v12, v12, v13
	v_max_u32_e32 v13, v14, v15
	v_min_u32_e32 v14, v14, v15
	v_max_u32_e32 v15, v16, v17
	v_min_u32_e32 v16, v16, v17
	v_max_u32_e32 v50, v34, v37
	v_min_u32_e32 v34, v34, v37
	v_max_u32_e32 v37, v35, v36
	v_min_u32_e32 v35, v35, v36
	v_max_u32_e32 v36, v38, v41
	v_min_u32_e32 v38, v38, v41
	v_max_u32_e32 v41, v39, v40
	v_min_u32_e32 v39, v39, v40
	v_max_u32_e32 v40, v42, v45
	v_min_u32_e32 v42, v42, v45
	v_max_u32_e32 v45, v43, v44
	v_min_u32_e32 v43, v43, v44
	v_max_u32_e32 v44, v46, v49
	v_min_u32_e32 v46, v46, v49
	v_max_u32_e32 v49, v47, v48
	v_min_u32_e32 v47, v47, v48
	v_max_u32_e32 v89, v58, v61
	v_min_u32_e32 v58, v58, v61
	v_max_u32_e32 v61, v59, v60
	v_min_u32_e32 v59, v59, v60
	v_max_u32_e32 v60, v62, v65
	v_min_u32_e32 v62, v62, v65
	v_max_u32_e32 v65, v63, v64
	v_min_u32_e32 v63, v63, v64
	v_max_u32_e32 v64, v66, v69
	v_min_u32_e32 v66, v66, v69
	v_max_u32_e32 v69, v67, v68
	v_min_u32_e32 v67, v67, v68
	v_max_u32_e32 v68, v78, v88
	v_min_u32_e32 v78, v78, v88
	v_max_u32_e32 v88, v80, v81
	v_min_u32_e32 v80, v80, v81
	v_max_u32_e32 v33, v97, v20
	v_min_u32_e32 v20, v97, v20
	v_max_u32_e32 v97, v18, v19
	v_min_u32_e32 v18, v18, v19
	v_max_u32_e32 v19, v21, v24
	v_min_u32_e32 v21, v21, v24
	v_max_u32_e32 v24, v22, v23
	v_min_u32_e32 v22, v22, v23
	v_max_u32_e32 v23, v25, v28
	v_min_u32_e32 v25, v25, v28
	v_max_u32_e32 v28, v26, v27
	v_min_u32_e32 v26, v26, v27
	v_max_u32_e32 v27, v29, v32
	v_min_u32_e32 v29, v29, v32
	v_max_u32_e32 v32, v30, v31
	v_min_u32_e32 v30, v30, v31
	v_max_u32_e32 v17, v105, v4
	v_min_u32_e32 v4, v105, v4
	v_max_u32_e32 v105, v2, v3
	v_min_u32_e32 v2, v2, v3
	v_max_u32_e32 v3, v5, v8
	v_min_u32_e32 v5, v5, v8
	v_max_u32_e32 v8, v6, v7
	v_min_u32_e32 v6, v6, v7
	v_max_u32_e32 v7, v9, v12
	v_min_u32_e32 v9, v9, v12
	v_max_u32_e32 v12, v10, v11
	v_min_u32_e32 v10, v10, v11
	v_max_u32_e32 v11, v13, v16
	v_min_u32_e32 v13, v13, v16
	v_max_u32_e32 v16, v14, v15
	v_min_u32_e32 v14, v14, v15
	v_max_u32_e32 v48, v50, v37
	v_min_u32_e32 v37, v50, v37
	v_max_u32_e32 v50, v34, v35
	v_min_u32_e32 v34, v34, v35
	v_max_u32_e32 v35, v38, v39
	v_min_u32_e32 v38, v38, v39
	v_max_u32_e32 v39, v36, v41
	v_min_u32_e32 v36, v36, v41
	v_max_u32_e32 v41, v40, v45
	v_min_u32_e32 v40, v40, v45
	v_max_u32_e32 v45, v42, v43
	v_min_u32_e32 v42, v42, v43
	v_max_u32_e32 v43, v46, v47
	v_min_u32_e32 v46, v46, v47
	v_max_u32_e32 v47, v44, v49
	v_min_u32_e32 v44, v44, v49
	v_max_u32_e32 v81, v89, v61
	v_min_u32_e32 v61, v89, v61
	v_max_u32_e32 v89, v58, v59
	v_min_u32_e32 v58, v58, v59
	v_max_u32_e32 v59, v62, v63
	v_min_u32_e32 v62, v62, v63
	v_max_u32_e32 v63, v60, v65
	v_min_u32_e32 v60, v60, v65
	v_max_u32_e32 v65, v64, v69
	v_min_u32_e32 v64, v64, v69
	v_max_u32_e32 v69, v66, v67
	v_min_u32_e32 v66, v66, v67
	v_max_u32_e32 v67, v78, v80
	v_min_u32_e32 v78, v78, v80
	v_max_u32_e32 v80, v68, v88
	v_min_u32_e32 v68, v68, v88
	v_max_u32_e32 v31, v33, v97
	v_min_u32_e32 v33, v33, v97
	v_max_u32_e32 v97, v20, v18
	v_min_u32_e32 v18, v20, v18
	v_max_u32_e32 v20, v21, v22
	v_min_u32_e32 v21, v21, v22
	v_max_u32_e32 v22, v19, v24
	v_min_u32_e32 v19, v19, v24
	v_max_u32_e32 v24, v23, v28
	v_min_u32_e32 v23, v23, v28
	v_max_u32_e32 v28, v25, v26
	v_min_u32_e32 v25, v25, v26
	v_max_u32_e32 v26, v29, v30
	v_min_u32_e32 v29, v29, v30
	v_max_u32_e32 v30, v27, v32
	v_min_u32_e32 v27, v27, v32
	v_max_u32_e32 v15, v17, v105
	v_min_u32_e32 v17, v17, v105
	v_max_u32_e32 v105, v4, v2
	v_min_u32_e32 v2, v4, v2
	v_max_u32_e32 v4, v5, v6
	v_min_u32_e32 v5, v5, v6
	v_max_u32_e32 v6, v3, v8
	v_min_u32_e32 v3, v3, v8
	v_max_u32_e32 v8, v7, v12
	v_min_u32_e32 v7, v7, v12
	v_max_u32_e32 v12, v9, v10
	v_min_u32_e32 v9, v9, v10
	v_max_u32_e32 v10, v13, v14
	v_min_u32_e32 v13, v13, v14
	v_max_u32_e32 v14, v11, v16
	v_min_u32_e32 v11, v11, v16
	v_max_u32_e32 v49, v48, v38
	v_min_u32_e32 v38, v48, v38
	v_max_u32_e32 v48, v37, v35
	v_min_u32_e32 v35, v37, v35
	v_max_u32_e32 v37, v50, v36
	v_min_u32_e32 v36, v50, v36
	v_max_u32_e32 v50, v34, v39
	v_min_u32_e32 v34, v34, v39
	v_max_u32_e32 v39, v41, v46
	v_min_u32_e32 v41, v41, v46
	v_max_u32_e32 v46, v40, v43
	v_min_u32_e32 v40, v40, v43
	v_max_u32_e32 v43, v45, v44
	v_min_u32_e32 v44, v45, v44
	v_max_u32_e32 v45, v42, v47
	v_min_u32_e32 v42, v42, v47
	v_max_u32_e32 v88, v81, v62
	v_min_u32_e32 v62, v81, v62
	v_max_u32_e32 v81, v61, v59
	v_min_u32_e32 v59, v61, v59
	v_max_u32_e32 v61, v89, v60
	v_min_u32_e32 v60, v89, v60
	v_max_u32_e32 v89, v58, v63
	v_min_u32_e32 v58, v58, v63
	v_max_u32_e32 v63, v65, v78
	v_min_u32_e32 v65, v65, v78
	v_max_u32_e32 v78, v64, v67
	v_min_u32_e32 v64, v64, v67
	v_max_u32_e32 v67, v69, v68
	v_min_u32_e32 v68, v69, v68
	v_max_u32_e32 v69, v66, v80
	v_min_u32_e32 v66, v66, v80
	v_max_u32_e32 v32, v31, v21
	v_min_u32_e32 v21, v31, v21
	v_max_u32_e32 v31, v33, v20
	v_min_u32_e32 v20, v33, v20
	v_max_u32_e32 v33, v97, v19
	v_min_u32_e32 v19, v97, v19
	v_max_u32_e32 v97, v18, v22
	v_min_u32_e32 v18, v18, v22
	v_max_u32_e32 v22, v24, v29
	v_min_u32_e32 v24, v24, v29
	v_max_u32_e32 v29, v23, v26
	v_min_u32_e32 v23, v23, v26
	v_max_u32_e32 v26, v28, v27
	v_min_u32_e32 v27, v28, v27
	v_max_u32_e32 v28, v25, v30
	v_min_u32_e32 v25, v25, v30
	v_max_u32_e32 v16, v15, v5
	v_min_u32_e32 v5, v15, v5
	v_max_u32_e32 v15, v17, v4
	v_min_u32_e32 v4, v17, v4
	v_max_u32_e32 v17, v105, v3
	v_min_u32_e32 v3, v105, v3
	v_max_u32_e32 v105, v2, v6
	v_min_u32_e32 v2, v2, v6
	v_max_u32_e32 v6, v8, v13
	v_min_u32_e32 v8, v8, v13
	v_max_u32_e32 v13, v7, v10
	v_min_u32_e32 v7, v7, v10
	v_max_u32_e32 v10, v12, v11
	v_min_u32_e32 v11, v12, v11
	v_max_u32_e32 v12, v9, v14
	v_min_u32_e32 v9, v9, v14
	v_max_u32_e32 v47, v49, v37
	v_min_u32_e32 v37, v49, v37
	v_max_u32_e32 v49, v48, v50
	v_min_u32_e32 v48, v48, v50
	v_max_u32_e32 v50, v38, v36
	v_min_u32_e32 v36, v38, v36
	v_max_u32_e32 v38, v35, v34
	v_min_u32_e32 v34, v35, v34
	v_max_u32_e32 v35, v41, v44
	v_min_u32_e32 v41, v41, v44
	v_max_u32_e32 v44, v40, v42
	v_min_u32_e32 v40, v40, v42
	v_max_u32_e32 v42, v39, v43
	v_min_u32_e32 v39, v39, v43
	v_max_u32_e32 v43, v46, v45
	v_min_u32_e32 v45, v46, v45
	v_max_u32_e32 v80, v88, v61
	v_min_u32_e32 v61, v88, v61
	v_max_u32_e32 v88, v81, v89
	s_waitcnt vmcnt(0)
	v_pk_mul_f32 v[200:201], v[200:201], s[96:97] op_sel_hi:[1,0]
	v_pk_mul_f32 v[202:203], v[202:203], s[96:97] op_sel_hi:[1,0]
	v_pk_mul_f32 v[204:205], v[204:205], s[96:97] op_sel_hi:[1,0]
	v_pk_mul_f32 v[206:207], v[206:207], s[96:97] op_sel_hi:[1,0]
	v_pk_mul_f32 v[208:209], v[208:209], s[96:97] op_sel_hi:[1,0]
	v_pk_mul_f32 v[210:211], v[210:211], s[96:97] op_sel_hi:[1,0]
	v_pk_mul_f32 v[212:213], v[212:213], s[96:97] op_sel_hi:[1,0]
	v_pk_mul_f32 v[214:215], v[214:215], s[96:97] op_sel_hi:[1,0]
	v_pk_mul_f32 v[216:217], v[216:217], s[96:97] op_sel_hi:[1,0]
	v_pk_mul_f32 v[218:219], v[218:219], s[96:97] op_sel_hi:[1,0]
	v_pk_mul_f32 v[220:221], v[220:221], s[96:97] op_sel_hi:[1,0]
	v_pk_mul_f32 v[222:223], v[222:223], s[96:97] op_sel_hi:[1,0]
	v_pk_mul_f32 v[224:225], v[224:225], s[96:97] op_sel_hi:[1,0]
	v_pk_mul_f32 v[226:227], v[226:227], s[96:97] op_sel_hi:[1,0]
	v_pk_mul_f32 v[228:229], v[228:229], s[96:97] op_sel_hi:[1,0]
	v_pk_mul_f32 v[230:231], v[230:231], s[96:97] op_sel_hi:[1,0]
	v_cvt_scalef32_pk_fp4_f32 v232, v200, v201, 1.0
	v_cvt_scalef32_pk_fp4_f32 v233, v208, v209, 1.0
	v_cvt_scalef32_pk_fp4_f32 v234, v216, v217, 1.0
	v_cvt_scalef32_pk_fp4_f32 v235, v224, v225, 1.0
	v_cvt_scalef32_pk_fp4_f32 v232, v202, v203, 1.0 op_sel:[0,0,1,0]
	v_cvt_scalef32_pk_fp4_f32 v233, v210, v211, 1.0 op_sel:[0,0,1,0]
	v_cvt_scalef32_pk_fp4_f32 v234, v218, v219, 1.0 op_sel:[0,0,1,0]
	v_cvt_scalef32_pk_fp4_f32 v235, v226, v227, 1.0 op_sel:[0,0,1,0]
	v_cvt_scalef32_pk_fp4_f32 v232, v204, v205, 1.0 op_sel:[0,0,0,1]
	v_cvt_scalef32_pk_fp4_f32 v233, v212, v213, 1.0 op_sel:[0,0,0,1]
	v_cvt_scalef32_pk_fp4_f32 v234, v220, v221, 1.0 op_sel:[0,0,0,1]
	v_cvt_scalef32_pk_fp4_f32 v235, v228, v229, 1.0 op_sel:[0,0,0,1]
	v_cvt_scalef32_pk_fp4_f32 v232, v206, v207, 1.0 op_sel:[0,0,1,1]
	v_cvt_scalef32_pk_fp4_f32 v233, v214, v215, 1.0 op_sel:[0,0,1,1]
	v_cvt_scalef32_pk_fp4_f32 v234, v222, v223, 1.0 op_sel:[0,0,1,1]
	v_cvt_scalef32_pk_fp4_f32 v235, v230, v231, 1.0 op_sel:[0,0,1,1]
	s_nop 0
	global_store_dwordx4 v[240:241], v[232:235], off
	v_lshl_add_u64 v[240:241], v[240:241], 0, v[246:247]
	global_load_dwordx4 v[200:203], v[236:237], off
	global_load_dwordx4 v[204:207], v[236:237], off offset:16
	global_load_dwordx4 v[208:211], v[236:237], off offset:32
	global_load_dwordx4 v[212:215], v[236:237], off offset:48
	global_load_dwordx4 v[216:219], v[238:239], off
	global_load_dwordx4 v[220:223], v[238:239], off offset:16
	global_load_dwordx4 v[224:227], v[238:239], off offset:32
	global_load_dwordx4 v[228:231], v[238:239], off offset:48
	v_lshl_add_u64 v[236:237], v[236:237], 0, v[244:245]
	v_lshl_add_u64 v[238:239], v[238:239], 0, v[244:245]
	v_min_u32_e32 v81, v81, v89
	v_max_u32_e32 v89, v62, v60
	v_min_u32_e32 v60, v62, v60
	v_max_u32_e32 v62, v59, v58
	v_min_u32_e32 v58, v59, v58
	v_max_u32_e32 v59, v65, v68
	v_min_u32_e32 v65, v65, v68
	v_max_u32_e32 v68, v64, v66
	v_min_u32_e32 v64, v64, v66
	v_max_u32_e32 v66, v63, v67
	v_min_u32_e32 v63, v63, v67
	v_max_u32_e32 v67, v78, v69
	v_min_u32_e32 v69, v78, v69
	v_max_u32_e32 v30, v32, v33
	v_min_u32_e32 v32, v32, v33
	v_max_u32_e32 v33, v31, v97
	v_min_u32_e32 v31, v31, v97
	v_max_u32_e32 v97, v21, v19
	v_min_u32_e32 v19, v21, v19
	v_max_u32_e32 v21, v20, v18
	v_min_u32_e32 v18, v20, v18
	v_max_u32_e32 v20, v24, v27
	v_min_u32_e32 v24, v24, v27
	v_max_u32_e32 v27, v23, v25
	v_min_u32_e32 v23, v23, v25
	v_max_u32_e32 v25, v22, v26
	v_min_u32_e32 v22, v22, v26
	v_max_u32_e32 v26, v29, v28
	v_min_u32_e32 v28, v29, v28
	v_max_u32_e32 v14, v16, v17
	v_min_u32_e32 v16, v16, v17
	v_max_u32_e32 v17, v15, v105
	v_min_u32_e32 v15, v15, v105
	v_max_u32_e32 v105, v5, v3
	v_min_u32_e32 v3, v5, v3
	v_max_u32_e32 v5, v4, v2
	v_min_u32_e32 v2, v4, v2
	v_max_u32_e32 v4, v8, v11
	v_min_u32_e32 v8, v8, v11
	v_max_u32_e32 v11, v7, v9
	v_min_u32_e32 v7, v7, v9
	v_max_u32_e32 v9, v6, v10
	v_min_u32_e32 v6, v6, v10
	v_max_u32_e32 v10, v13, v12
	v_min_u32_e32 v12, v13, v12
	v_max_u32_e32 v46, v47, v49
	v_min_u32_e32 v47, v47, v49
	v_max_u32_e32 v49, v37, v48
	v_min_u32_e32 v37, v37, v48
	v_max_u32_e32 v48, v50, v38
	v_min_u32_e32 v38, v50, v38
	v_max_u32_e32 v50, v36, v34
	v_min_u32_e32 v34, v36, v34
	v_max_u32_e32 v36, v41, v40
	v_min_u32_e32 v40, v41, v40
	v_max_u32_e32 v41, v35, v44
	v_min_u32_e32 v35, v35, v44
	v_max_u32_e32 v44, v39, v45
	v_min_u32_e32 v39, v39, v45
	v_max_u32_e32 v45, v42, v43
	v_min_u32_e32 v42, v42, v43
	v_max_u32_e32 v78, v80, v88
	v_min_u32_e32 v80, v80, v88
	v_max_u32_e32 v88, v61, v81
	v_min_u32_e32 v61, v61, v81
	v_max_u32_e32 v81, v89, v62
	v_min_u32_e32 v62, v89, v62
	v_max_u32_e32 v89, v60, v58
	v_min_u32_e32 v58, v60, v58
	v_max_u32_e32 v60, v65, v64
	v_min_u32_e32 v64, v65, v64
	v_max_u32_e32 v65, v59, v68
	v_min_u32_e32 v59, v59, v68
	v_max_u32_e32 v68, v63, v69
	v_min_u32_e32 v63, v63, v69
	v_max_u32_e32 v69, v66, v67
	v_min_u32_e32 v66, v66, v67
	v_max_u32_e32 v29, v30, v33
	v_min_u32_e32 v30, v30, v33
	v_max_u32_e32 v33, v32, v31
	v_min_u32_e32 v31, v32, v31
	v_max_u32_e32 v32, v97, v21
	v_min_u32_e32 v21, v97, v21
	v_max_u32_e32 v97, v19, v18
	v_min_u32_e32 v18, v19, v18
	v_max_u32_e32 v19, v24, v23
	v_min_u32_e32 v23, v24, v23
	v_max_u32_e32 v24, v20, v27
	v_min_u32_e32 v20, v20, v27
	v_max_u32_e32 v27, v22, v28
	v_min_u32_e32 v22, v22, v28
	v_max_u32_e32 v28, v25, v26
	v_min_u32_e32 v25, v25, v26
	v_max_u32_e32 v13, v14, v17
	v_min_u32_e32 v14, v14, v17
	v_max_u32_e32 v17, v16, v15
	v_min_u32_e32 v15, v16, v15
	v_max_u32_e32 v16, v105, v5
	v_min_u32_e32 v5, v105, v5
	v_max_u32_e32 v105, v3, v2
	v_min_u32_e32 v2, v3, v2
	v_max_u32_e32 v3, v8, v7
	v_min_u32_e32 v7, v8, v7
	v_max_u32_e32 v8, v4, v11
	v_min_u32_e32 v4, v4, v11
	v_max_u32_e32 v11, v6, v12
	v_min_u32_e32 v6, v6, v12
	v_max_u32_e32 v12, v9, v10
	v_min_u32_e32 v9, v9, v10
	v_max_u32_e32 v43, v46, v40
	v_min_u32_e32 v40, v46, v40
	v_max_u32_e32 v46, v47, v36
	v_min_u32_e32 v36, v47, v36
	v_max_u32_e32 v47, v49, v35
	v_min_u32_e32 v35, v49, v35
	v_max_u32_e32 v49, v37, v41
	v_min_u32_e32 v37, v37, v41
	v_max_u32_e32 v41, v48, v39
	v_min_u32_e32 v39, v48, v39
	v_max_u32_e32 v48, v38, v44
	v_min_u32_e32 v38, v38, v44
	v_max_u32_e32 v44, v50, v42
	v_min_u32_e32 v42, v50, v42
	v_max_u32_e32 v50, v34, v45
	v_min_u32_e32 v34, v34, v45
	v_max_u32_e32 v67, v78, v64
	v_min_u32_e32 v64, v78, v64
	v_max_u32_e32 v78, v80, v60
	v_min_u32_e32 v60, v80, v60
	v_max_u32_e32 v80, v88, v59
	v_min_u32_e32 v59, v88, v59
	v_max_u32_e32 v88, v61, v65
	v_min_u32_e32 v61, v61, v65
	v_max_u32_e32 v65, v81, v63
	v_min_u32_e32 v63, v81, v63
	v_max_u32_e32 v81, v62, v68
	v_min_u32_e32 v62, v62, v68
	v_max_u32_e32 v68, v89, v66
	v_min_u32_e32 v66, v89, v66
	v_max_u32_e32 v89, v58, v69
	v_min_u32_e32 v58, v58, v69
	v_max_u32_e32 v26, v29, v23
	v_min_u32_e32 v23, v29, v23
	v_max_u32_e32 v29, v30, v19
	v_min_u32_e32 v19, v30, v19
	v_max_u32_e32 v30, v33, v20
	v_min_u32_e32 v20, v33, v20
	v_max_u32_e32 v33, v31, v24
	v_min_u32_e32 v24, v31, v24
	v_max_u32_e32 v31, v32, v22
	v_min_u32_e32 v22, v32, v22
	v_max_u32_e32 v32, v21, v27
	v_min_u32_e32 v21, v21, v27
	v_max_u32_e32 v27, v97, v25
	v_min_u32_e32 v25, v97, v25
	v_max_u32_e32 v97, v18, v28
	v_min_u32_e32 v18, v18, v28
	v_max_u32_e32 v10, v13, v7
	v_min_u32_e32 v7, v13, v7
	v_max_u32_e32 v13, v14, v3
	v_min_u32_e32 v3, v14, v3
	v_max_u32_e32 v14, v17, v4
	v_min_u32_e32 v4, v17, v4
	v_max_u32_e32 v17, v15, v8
	v_min_u32_e32 v8, v15, v8
	v_max_u32_e32 v15, v16, v6
	v_min_u32_e32 v6, v16, v6
	v_max_u32_e32 v16, v5, v11
	v_min_u32_e32 v5, v5, v11
	v_max_u32_e32 v11, v105, v9
	v_min_u32_e32 v9, v105, v9
	v_max_u32_e32 v105, v2, v12
	v_min_u32_e32 v2, v2, v12
	v_max_u32_e32 v45, v43, v41
	v_min_u32_e32 v41, v43, v41
	v_max_u32_e32 v43, v46, v48
	v_min_u32_e32 v46, v46, v48
	v_max_u32_e32 v48, v47, v44
	v_min_u32_e32 v44, v47, v44
	v_max_u32_e32 v47, v49, v50
	v_min_u32_e32 v49, v49, v50
	v_max_u32_e32 v50, v40, v39
	v_min_u32_e32 v39, v40, v39
	v_max_u32_e32 v40, v36, v38
	v_min_u32_e32 v36, v36, v38
	v_max_u32_e32 v38, v35, v42
	v_min_u32_e32 v35, v35, v42
	v_max_u32_e32 v42, v37, v34
	v_min_u32_e32 v34, v37, v34
	v_max_u32_e32 v69, v67, v65
	v_min_u32_e32 v65, v67, v65
	v_max_u32_e32 v67, v78, v81
	v_min_u32_e32 v78, v78, v81
	v_max_u32_e32 v81, v80, v68
	v_min_u32_e32 v68, v80, v68
	v_max_u32_e32 v80, v88, v89
	v_min_u32_e32 v88, v88, v89
	v_max_u32_e32 v89, v64, v63
	v_min_u32_e32 v63, v64, v63
	v_max_u32_e32 v64, v60, v62
	v_min_u32_e32 v60, v60, v62
	v_max_u32_e32 v62, v59, v66
	v_min_u32_e32 v59, v59, v66
	v_max_u32_e32 v66, v61, v58
	v_min_u32_e32 v58, v61, v58
	v_max_u32_e32 v28, v26, v31
	v_min_u32_e32 v26, v26, v31
	v_max_u32_e32 v31, v29, v32
	v_min_u32_e32 v29, v29, v32
	v_max_u32_e32 v32, v30, v27
	v_min_u32_e32 v27, v30, v27
	v_max_u32_e32 v30, v33, v97
	v_min_u32_e32 v33, v33, v97
	v_max_u32_e32 v97, v23, v22
	v_min_u32_e32 v22, v23, v22
	v_max_u32_e32 v23, v19, v21
	v_min_u32_e32 v19, v19, v21
	v_max_u32_e32 v21, v20, v25
	v_min_u32_e32 v20, v20, v25
	v_max_u32_e32 v25, v24, v18
	v_min_u32_e32 v18, v24, v18
	v_max_u32_e32 v12, v10, v15
	v_min_u32_e32 v10, v10, v15
	v_max_u32_e32 v15, v13, v16
	v_min_u32_e32 v13, v13, v16
	v_max_u32_e32 v16, v14, v11
	v_min_u32_e32 v11, v14, v11
	v_max_u32_e32 v14, v17, v105
	v_min_u32_e32 v17, v17, v105
	v_max_u32_e32 v105, v7, v6
	v_min_u32_e32 v6, v7, v6
	v_max_u32_e32 v7, v3, v5
	v_min_u32_e32 v3, v3, v5
	v_max_u32_e32 v5, v4, v9
	v_min_u32_e32 v4, v4, v9
	v_max_u32_e32 v9, v8, v2
	v_min_u32_e32 v2, v8, v2
	v_max_u32_e32 v37, v45, v48
	v_min_u32_e32 v45, v45, v48
	v_max_u32_e32 v48, v43, v47
	v_min_u32_e32 v43, v43, v47
	v_max_u32_e32 v47, v41, v44
	v_min_u32_e32 v41, v41, v44
	v_max_u32_e32 v44, v46, v49
	v_min_u32_e32 v46, v46, v49
	v_max_u32_e32 v49, v50, v38
	v_min_u32_e32 v38, v50, v38
	v_max_u32_e32 v50, v40, v42
	v_min_u32_e32 v40, v40, v42
	v_max_u32_e32 v42, v39, v35
	v_min_u32_e32 v35, v39, v35
	v_max_u32_e32 v39, v36, v34
	v_min_u32_e32 v34, v36, v34
	v_max_u32_e32 v61, v69, v81
	v_min_u32_e32 v69, v69, v81
	v_max_u32_e32 v81, v67, v80
	v_min_u32_e32 v67, v67, v80
	v_max_u32_e32 v80, v65, v68
	v_min_u32_e32 v65, v65, v68
	v_max_u32_e32 v68, v78, v88
	v_min_u32_e32 v78, v78, v88
	v_max_u32_e32 v88, v89, v62
	v_min_u32_e32 v62, v89, v62
	v_max_u32_e32 v89, v64, v66
	v_min_u32_e32 v64, v64, v66
	v_max_u32_e32 v66, v63, v59
	v_min_u32_e32 v59, v63, v59
	v_max_u32_e32 v63, v60, v58
	v_min_u32_e32 v58, v60, v58
	v_max_u32_e32 v24, v28, v32
	v_min_u32_e32 v28, v28, v32
	v_max_u32_e32 v32, v31, v30
	v_min_u32_e32 v30, v31, v30
	v_max_u32_e32 v31, v26, v27
	v_min_u32_e32 v26, v26, v27
	v_max_u32_e32 v27, v29, v33
	v_min_u32_e32 v29, v29, v33
	v_max_u32_e32 v33, v97, v21
	v_min_u32_e32 v21, v97, v21
	v_max_u32_e32 v97, v23, v25
	v_min_u32_e32 v23, v23, v25
	v_max_u32_e32 v25, v22, v20
	v_min_u32_e32 v20, v22, v20
	v_max_u32_e32 v22, v19, v18
	v_min_u32_e32 v18, v19, v18
	v_max_u32_e32 v8, v12, v16
	v_min_u32_e32 v12, v12, v16
	v_max_u32_e32 v16, v15, v14
	v_min_u32_e32 v14, v15, v14
	v_max_u32_e32 v15, v10, v11
	v_min_u32_e32 v10, v10, v11
	v_max_u32_e32 v11, v13, v17
	v_min_u32_e32 v13, v13, v17
	v_max_u32_e32 v17, v105, v5
	v_min_u32_e32 v5, v105, v5
	v_max_u32_e32 v105, v7, v9
	v_min_u32_e32 v7, v7, v9
	v_max_u32_e32 v9, v6, v4
	v_min_u32_e32 v4, v6, v4
	v_max_u32_e32 v6, v3, v2
	v_min_u32_e32 v2, v3, v2
	v_min_u32_e32 v36, v37, v48
	v_min_u32_e32 v51, v45, v43
	v_min_u32_e32 v52, v47, v44
	v_min_u32_e32 v53, v41, v46
	v_min_u32_e32 v54, v49, v50
	v_min_u32_e32 v55, v38, v40
	v_min_u32_e32 v56, v42, v39
	v_min_u32_e32 v57, v35, v34
	v_min_u32_e32 v60, v61, v81
	v_min_u32_e32 v90, v69, v67
	v_min_u32_e32 v91, v80, v68
	v_min_u32_e32 v92, v65, v78
	v_min_u32_e32 v93, v88, v89
	v_min_u32_e32 v94, v62, v64
	v_min_u32_e32 v95, v66, v63
	v_min_u32_e32 v96, v59, v58
	v_min_u32_e32 v19, v24, v32
	v_min_u32_e32 v98, v28, v30
	v_min_u32_e32 v99, v31, v27
	v_min_u32_e32 v100, v26, v29
	v_min_u32_e32 v101, v33, v97
	v_min_u32_e32 v102, v21, v23
	v_min_u32_e32 v103, v25, v22
	v_min_u32_e32 v104, v20, v18
	v_min_u32_e32 v3, v8, v16
	v_min_u32_e32 v106, v12, v14
	v_min_u32_e32 v107, v15, v11
	v_min_u32_e32 v108, v10, v13
	v_min_u32_e32 v109, v17, v105
	v_min_u32_e32 v110, v5, v7
	v_min_u32_e32 v111, v9, v6
	v_min_u32_e32 v112, v4, v2
	v_max3_u32 v37, v37, v48, v96
	v_max3_u32 v24, v24, v32, v112
	v_max3_u32 v32, v36, v59, v58
	v_max3_u32 v2, v19, v4, v2
	v_max3_u32 v4, v45, v43, v95
	v_max3_u32 v19, v28, v30, v111
	v_max3_u32 v28, v51, v66, v63
	v_max3_u32 v6, v98, v9, v6
	v_max3_u32 v9, v47, v44, v94
	v_max3_u32 v27, v31, v27, v110
	v_max3_u32 v30, v52, v62, v64
	v_max3_u32 v5, v99, v5, v7
	v_max3_u32 v7, v41, v46, v93
	v_max3_u32 v26, v26, v29, v109
	v_max3_u32 v29, v53, v88, v89
	v_max3_u32 v17, v100, v17, v105
	v_max3_u32 v31, v49, v50, v92
	v_max3_u32 v33, v33, v97, v108
	v_max3_u32 v36, v54, v65, v78
	v_max3_u32 v10, v101, v10, v13
	v_max3_u32 v13, v38, v40, v91
	v_max3_u32 v21, v21, v23, v107
	v_max3_u32 v23, v55, v80, v68
	v_max3_u32 v11, v102, v15, v11
	v_max3_u32 v15, v42, v39, v90
	v_max3_u32 v22, v25, v22, v106
	v_max3_u32 v25, v56, v69, v67
	s_waitcnt vmcnt(0)
	v_pk_mul_f32 v[200:201], v[200:201], s[96:97] op_sel_hi:[1,0]
	v_pk_mul_f32 v[202:203], v[202:203], s[96:97] op_sel_hi:[1,0]
	v_pk_mul_f32 v[204:205], v[204:205], s[96:97] op_sel_hi:[1,0]
	v_pk_mul_f32 v[206:207], v[206:207], s[96:97] op_sel_hi:[1,0]
	v_pk_mul_f32 v[208:209], v[208:209], s[96:97] op_sel_hi:[1,0]
	v_pk_mul_f32 v[210:211], v[210:211], s[96:97] op_sel_hi:[1,0]
	v_pk_mul_f32 v[212:213], v[212:213], s[96:97] op_sel_hi:[1,0]
	v_pk_mul_f32 v[214:215], v[214:215], s[96:97] op_sel_hi:[1,0]
	v_pk_mul_f32 v[216:217], v[216:217], s[96:97] op_sel_hi:[1,0]
	v_pk_mul_f32 v[218:219], v[218:219], s[96:97] op_sel_hi:[1,0]
	v_pk_mul_f32 v[220:221], v[220:221], s[96:97] op_sel_hi:[1,0]
	v_pk_mul_f32 v[222:223], v[222:223], s[96:97] op_sel_hi:[1,0]
	v_pk_mul_f32 v[224:225], v[224:225], s[96:97] op_sel_hi:[1,0]
	v_pk_mul_f32 v[226:227], v[226:227], s[96:97] op_sel_hi:[1,0]
	v_pk_mul_f32 v[228:229], v[228:229], s[96:97] op_sel_hi:[1,0]
	v_pk_mul_f32 v[230:231], v[230:231], s[96:97] op_sel_hi:[1,0]
	v_cvt_scalef32_pk_fp4_f32 v232, v200, v201, 1.0
	v_cvt_scalef32_pk_fp4_f32 v233, v208, v209, 1.0
	v_cvt_scalef32_pk_fp4_f32 v234, v216, v217, 1.0
	v_cvt_scalef32_pk_fp4_f32 v235, v224, v225, 1.0
	v_cvt_scalef32_pk_fp4_f32 v232, v202, v203, 1.0 op_sel:[0,0,1,0]
	v_cvt_scalef32_pk_fp4_f32 v233, v210, v211, 1.0 op_sel:[0,0,1,0]
	v_cvt_scalef32_pk_fp4_f32 v234, v218, v219, 1.0 op_sel:[0,0,1,0]
	v_cvt_scalef32_pk_fp4_f32 v235, v226, v227, 1.0 op_sel:[0,0,1,0]
	v_cvt_scalef32_pk_fp4_f32 v232, v204, v205, 1.0 op_sel:[0,0,0,1]
	v_cvt_scalef32_pk_fp4_f32 v233, v212, v213, 1.0 op_sel:[0,0,0,1]
	v_cvt_scalef32_pk_fp4_f32 v234, v220, v221, 1.0 op_sel:[0,0,0,1]
	v_cvt_scalef32_pk_fp4_f32 v235, v228, v229, 1.0 op_sel:[0,0,0,1]
	v_cvt_scalef32_pk_fp4_f32 v232, v206, v207, 1.0 op_sel:[0,0,1,1]
	v_cvt_scalef32_pk_fp4_f32 v233, v214, v215, 1.0 op_sel:[0,0,1,1]
	v_cvt_scalef32_pk_fp4_f32 v234, v222, v223, 1.0 op_sel:[0,0,1,1]
	v_cvt_scalef32_pk_fp4_f32 v235, v230, v231, 1.0 op_sel:[0,0,1,1]
	s_nop 0
	global_store_dwordx4 v[240:241], v[232:235], off
	v_lshl_add_u64 v[240:241], v[240:241], 0, v[246:247]
	global_load_dwordx4 v[200:203], v[236:237], off
	global_load_dwordx4 v[204:207], v[236:237], off offset:16
	global_load_dwordx4 v[208:211], v[236:237], off offset:32
	global_load_dwordx4 v[212:215], v[236:237], off offset:48
	global_load_dwordx4 v[216:219], v[238:239], off
	global_load_dwordx4 v[220:223], v[238:239], off offset:16
	global_load_dwordx4 v[224:227], v[238:239], off offset:32
	global_load_dwordx4 v[228:231], v[238:239], off offset:48
	v_lshl_add_u64 v[236:237], v[236:237], 0, v[244:245]
	v_lshl_add_u64 v[238:239], v[238:239], 0, v[244:245]
	v_max3_u32 v12, v103, v12, v14
	v_max3_u32 v14, v35, v34, v60
	v_max3_u32 v3, v20, v18, v3
	v_max3_u32 v18, v57, v61, v81
	v_max3_u32 v8, v104, v8, v16
	v_max_u32_e32 v16, v37, v31
	v_min_u32_e32 v20, v37, v31
	v_max_u32_e32 v31, v32, v36
	v_min_u32_e32 v32, v32, v36
	v_max_u32_e32 v34, v4, v13
	v_min_u32_e32 v4, v4, v13
	v_max_u32_e32 v13, v28, v23
	v_min_u32_e32 v23, v28, v23
	v_max_u32_e32 v28, v9, v15
	v_min_u32_e32 v9, v9, v15
	v_max_u32_e32 v15, v30, v25
	v_min_u32_e32 v25, v30, v25
	v_max_u32_e32 v30, v7, v14
	v_min_u32_e32 v7, v7, v14
	v_max_u32_e32 v14, v29, v18
	v_min_u32_e32 v18, v29, v18
	v_max_u32_e32 v42, v24, v33
	v_min_u32_e32 v24, v24, v33
	v_max_u32_e32 v33, v2, v10
	v_min_u32_e32 v2, v2, v10
	v_max_u32_e32 v10, v19, v21
	v_min_u32_e32 v19, v19, v21
	v_max_u32_e32 v21, v6, v11
	v_min_u32_e32 v6, v6, v11
	v_max_u32_e32 v11, v27, v22
	v_min_u32_e32 v22, v27, v22
	v_max_u32_e32 v27, v5, v12
	v_min_u32_e32 v5, v5, v12
	v_max_u32_e32 v12, v26, v3
	v_min_u32_e32 v3, v26, v3
	v_max_u32_e32 v26, v17, v8
	v_min_u32_e32 v8, v17, v8
	v_max_u32_e32 v29, v16, v28
	v_min_u32_e32 v16, v16, v28
	v_max_u32_e32 v28, v31, v15
	v_min_u32_e32 v15, v31, v15
	v_max_u32_e32 v31, v34, v30
	v_min_u32_e32 v30, v34, v30
	v_max_u32_e32 v34, v13, v14
	v_min_u32_e32 v13, v13, v14
	v_max_u32_e32 v14, v20, v9
	v_min_u32_e32 v9, v20, v9
	v_max_u32_e32 v20, v32, v25
	v_min_u32_e32 v25, v32, v25
	v_max_u32_e32 v32, v4, v7
	v_min_u32_e32 v4, v4, v7
	v_max_u32_e32 v7, v23, v18
	v_min_u32_e32 v18, v23, v18
	v_max_u32_e32 v17, v42, v11
	v_min_u32_e32 v11, v42, v11
	v_max_u32_e32 v42, v33, v27
	v_min_u32_e32 v27, v33, v27
	v_max_u32_e32 v33, v10, v12
	v_min_u32_e32 v10, v10, v12
	v_max_u32_e32 v12, v21, v26
	v_min_u32_e32 v21, v21, v26
	v_max_u32_e32 v26, v24, v22
	v_min_u32_e32 v22, v24, v22
	v_max_u32_e32 v24, v2, v5
	v_min_u32_e32 v2, v2, v5
	v_max_u32_e32 v5, v19, v3
	v_min_u32_e32 v3, v19, v3
	v_max_u32_e32 v19, v6, v8
	v_min_u32_e32 v6, v6, v8
	v_max_u32_e32 v23, v29, v31
	v_min_u32_e32 v29, v29, v31
	v_max_u32_e32 v31, v28, v34
	v_min_u32_e32 v28, v28, v34
	v_max_u32_e32 v34, v16, v30
	v_min_u32_e32 v16, v16, v30
	v_max_u32_e32 v30, v15, v13
	v_min_u32_e32 v13, v15, v13
	v_max_u32_e32 v15, v14, v32
	v_min_u32_e32 v14, v14, v32
	v_max_u32_e32 v32, v20, v7
	v_min_u32_e32 v7, v20, v7
	v_max_u32_e32 v20, v9, v4
	v_min_u32_e32 v4, v9, v4
	v_max_u32_e32 v9, v25, v18
	v_min_u32_e32 v18, v25, v18
	v_max_u32_e32 v8, v17, v33
	v_min_u32_e32 v17, v17, v33
	v_max_u32_e32 v33, v42, v12
	v_min_u32_e32 v12, v42, v12
	v_max_u32_e32 v42, v11, v10
	v_min_u32_e32 v10, v11, v10
	v_max_u32_e32 v11, v27, v21
	v_min_u32_e32 v21, v27, v21
	v_max_u32_e32 v27, v26, v5
	v_min_u32_e32 v5, v26, v5
	v_max_u32_e32 v26, v24, v19
	v_min_u32_e32 v19, v24, v19
	v_max_u32_e32 v24, v22, v3
	v_min_u32_e32 v3, v22, v3
	v_max_u32_e32 v22, v2, v6
	v_min_u32_e32 v2, v2, v6
	v_min_u32_e32 v25, v23, v31
	v_min_u32_e32 v35, v29, v28
	v_min_u32_e32 v36, v34, v30
	v_min_u32_e32 v37, v16, v13
	v_min_u32_e32 v38, v15, v32
	v_min_u32_e32 v39, v14, v7
	v_min_u32_e32 v40, v20, v9
	v_min_u32_e32 v41, v4, v18
	v_min_u32_e32 v6, v8, v33
	v_min_u32_e32 v43, v17, v12
	v_min_u32_e32 v44, v42, v11
	v_min_u32_e32 v45, v10, v21
	v_min_u32_e32 v46, v27, v26
	v_min_u32_e32 v47, v5, v19
	v_min_u32_e32 v48, v24, v22
	v_min_u32_e32 v49, v3, v2
	v_max3_u32 v23, v23, v31, v49
	v_max3_u32 v2, v25, v3, v2
	v_max3_u32 v3, v29, v28, v48
	v_max3_u32 v22, v35, v24, v22
	v_max3_u32 v24, v34, v30, v47
	v_max3_u32 v5, v36, v5, v19
	v_max3_u32 v13, v16, v13, v46
	v_max3_u32 v16, v37, v27, v26
	v_max3_u32 v15, v15, v32, v45
	v_max3_u32 v10, v38, v10, v21
	v_max3_u32 v7, v14, v7, v44
	v_max3_u32 v11, v39, v42, v11
	v_max3_u32 v9, v20, v9, v43
	v_max3_u32 v12, v40, v17, v12
	v_max3_u32 v4, v4, v18, v6
	v_max3_u32 v6, v41, v8, v33
	v_max_u32_e32 v8, v23, v15
	v_min_u32_e32 v14, v23, v15
	v_max_u32_e32 v15, v2, v10
	v_min_u32_e32 v2, v2, v10
	v_max_u32_e32 v10, v3, v7
	v_min_u32_e32 v3, v3, v7
	v_max_u32_e32 v7, v22, v11
	v_min_u32_e32 v11, v22, v11
	v_max_u32_e32 v17, v24, v9
	v_min_u32_e32 v9, v24, v9
	v_max_u32_e32 v18, v5, v12
	v_min_u32_e32 v5, v5, v12
	v_max_u32_e32 v12, v13, v4
	v_min_u32_e32 v4, v13, v4
	v_max_u32_e32 v13, v16, v6
	v_min_u32_e32 v6, v16, v6
	v_max_u32_e32 v16, v8, v17
	v_min_u32_e32 v8, v8, v17
	v_max_u32_e32 v17, v15, v18
	v_min_u32_e32 v15, v15, v18
	v_max_u32_e32 v18, v10, v12
	v_min_u32_e32 v10, v10, v12
	v_max_u32_e32 v12, v7, v13
	v_min_u32_e32 v7, v7, v13
	v_max_u32_e32 v13, v14, v9
	v_min_u32_e32 v9, v14, v9
	v_max_u32_e32 v14, v2, v5
	v_min_u32_e32 v2, v2, v5
	v_max_u32_e32 v5, v3, v4
	v_min_u32_e32 v3, v3, v4
	v_max_u32_e32 v4, v11, v6
	v_min_u32_e32 v6, v11, v6
	v_max_u32_e32 v11, v16, v18
	v_min_u32_e32 v16, v16, v18
	v_max_u32_e32 v18, v17, v12
	v_min_u32_e32 v12, v17, v12
	v_max_u32_e32 v17, v8, v10
	v_min_u32_e32 v8, v8, v10
	v_max_u32_e32 v10, v15, v7
	v_min_u32_e32 v7, v15, v7
	v_max_u32_e32 v15, v13, v5
	v_min_u32_e32 v5, v13, v5
	v_max_u32_e32 v13, v14, v4
	v_min_u32_e32 v4, v14, v4
	v_max_u32_e32 v14, v9, v3
	v_min_u32_e32 v3, v9, v3
	v_max_u32_e32 v9, v2, v6
	v_min_u32_e32 v2, v2, v6
	v_max_u32_e32 v6, v11, v18
	v_min_u32_e32 v11, v11, v18
	v_max_u32_e32 v18, v16, v12
	v_min_u32_e32 v12, v16, v12
	v_max_u32_e32 v16, v17, v10
	v_min_u32_e32 v10, v17, v10
	v_max_u32_e32 v17, v8, v7
	v_min_u32_e32 v7, v8, v7
	v_max_u32_e32 v8, v15, v13
	v_min_u32_e32 v13, v15, v13
	v_max_u32_e32 v15, v5, v4
	ds_bpermute_b32 v23, v153, v15
	v_min_u32_e32 v19, v3, v2
	v_min_u32_e32 v4, v5, v4
	v_max_u32_e32 v5, v14, v9
	v_max_u32_e32 v2, v3, v2
	ds_bpermute_b32 v20, v153, v19
	v_min_u32_e32 v9, v14, v9
	ds_bpermute_b32 v14, v153, v2
	ds_bpermute_b32 v21, v153, v5
	ds_bpermute_b32 v22, v153, v4
	s_waitcnt lgkmcnt(4)
	v_max_u32_e32 v23, v10, v23
	ds_bpermute_b32 v10, v153, v10
	s_waitcnt lgkmcnt(4)
	v_max_u32_e32 v3, v6, v20
	ds_bpermute_b32 v20, v153, v9
	s_waitcnt lgkmcnt(4)
	v_max_u32_e32 v14, v11, v14
	s_waitcnt lgkmcnt(3)
	v_max_u32_e32 v21, v12, v21
	s_waitcnt lgkmcnt(2)
	v_max_u32_e32 v22, v16, v22
	ds_bpermute_b32 v24, v153, v13
	ds_bpermute_b32 v25, v153, v8
	ds_bpermute_b32 v26, v153, v7
	ds_bpermute_b32 v27, v153, v17
	s_waitcnt lgkmcnt(5)
	v_max_u32_e32 v10, v15, v10
	ds_bpermute_b32 v15, v153, v16
	ds_bpermute_b32 v12, v153, v12
	ds_bpermute_b32 v16, v153, v18
	ds_bpermute_b32 v11, v153, v11
	ds_bpermute_b32 v6, v153, v6
	s_waitcnt lgkmcnt(9)
	v_max_u32_e32 v20, v18, v20
	s_waitcnt lgkmcnt(8)
	v_max_u32_e32 v17, v17, v24
	s_waitcnt lgkmcnt(7)
	v_max_u32_e32 v7, v7, v25
	s_waitcnt lgkmcnt(6)
	v_max_u32_e32 v8, v8, v26
	s_waitcnt lgkmcnt(5)
	v_max_u32_e32 v13, v13, v27
	s_waitcnt lgkmcnt(4)
	v_max_u32_e32 v4, v4, v15
	s_waitcnt lgkmcnt(3)
	v_max_u32_e32 v5, v5, v12
	s_waitcnt lgkmcnt(2)
	v_max_u32_e32 v9, v9, v16
	s_waitcnt lgkmcnt(1)
	v_max_u32_e32 v2, v2, v11
	s_waitcnt lgkmcnt(0)
	v_max_u32_e32 v6, v19, v6
	v_max_u32_e32 v11, v3, v8
	v_min_u32_e32 v3, v3, v8
	v_max_u32_e32 v8, v14, v13
	v_min_u32_e32 v12, v14, v13
	v_max_u32_e32 v13, v20, v10
	v_min_u32_e32 v10, v20, v10
	v_max_u32_e32 v14, v21, v4
	v_min_u32_e32 v4, v21, v4
	v_max_u32_e32 v15, v22, v5
	v_min_u32_e32 v5, v22, v5
	v_max_u32_e32 v16, v23, v9
	v_min_u32_e32 v9, v23, v9
	v_max_u32_e32 v18, v17, v2
	v_min_u32_e32 v2, v17, v2
	v_max_u32_e32 v17, v7, v6
	v_min_u32_e32 v6, v7, v6
	v_max_u32_e32 v7, v11, v15
	v_min_u32_e32 v11, v11, v15
	v_max_u32_e32 v15, v8, v16
	v_min_u32_e32 v8, v8, v16
	v_max_u32_e32 v16, v13, v18
	v_min_u32_e32 v13, v13, v18
	v_max_u32_e32 v18, v14, v17
	v_min_u32_e32 v14, v14, v17
	v_max_u32_e32 v17, v3, v5
	v_min_u32_e32 v3, v3, v5
	v_max_u32_e32 v5, v12, v9
	v_min_u32_e32 v9, v12, v9
	v_max_u32_e32 v12, v10, v2
	v_min_u32_e32 v2, v10, v2
	v_max_u32_e32 v10, v4, v6
	v_min_u32_e32 v4, v4, v6
	v_max_u32_e32 v6, v7, v16
	v_min_u32_e32 v7, v7, v16
	v_max_u32_e32 v16, v15, v18
	s_waitcnt vmcnt(0)
	v_pk_mul_f32 v[200:201], v[200:201], s[96:97] op_sel_hi:[1,0]
	v_pk_mul_f32 v[202:203], v[202:203], s[96:97] op_sel_hi:[1,0]
	v_pk_mul_f32 v[204:205], v[204:205], s[96:97] op_sel_hi:[1,0]
	v_pk_mul_f32 v[206:207], v[206:207], s[96:97] op_sel_hi:[1,0]
	v_pk_mul_f32 v[208:209], v[208:209], s[96:97] op_sel_hi:[1,0]
	v_pk_mul_f32 v[210:211], v[210:211], s[96:97] op_sel_hi:[1,0]
	v_pk_mul_f32 v[212:213], v[212:213], s[96:97] op_sel_hi:[1,0]
	v_pk_mul_f32 v[214:215], v[214:215], s[96:97] op_sel_hi:[1,0]
	v_pk_mul_f32 v[216:217], v[216:217], s[96:97] op_sel_hi:[1,0]
	v_pk_mul_f32 v[218:219], v[218:219], s[96:97] op_sel_hi:[1,0]
	v_pk_mul_f32 v[220:221], v[220:221], s[96:97] op_sel_hi:[1,0]
	v_pk_mul_f32 v[222:223], v[222:223], s[96:97] op_sel_hi:[1,0]
	v_pk_mul_f32 v[224:225], v[224:225], s[96:97] op_sel_hi:[1,0]
	v_pk_mul_f32 v[226:227], v[226:227], s[96:97] op_sel_hi:[1,0]
	v_pk_mul_f32 v[228:229], v[228:229], s[96:97] op_sel_hi:[1,0]
	v_pk_mul_f32 v[230:231], v[230:231], s[96:97] op_sel_hi:[1,0]
	v_cvt_scalef32_pk_fp4_f32 v232, v200, v201, 1.0
	v_cvt_scalef32_pk_fp4_f32 v233, v208, v209, 1.0
	v_cvt_scalef32_pk_fp4_f32 v234, v216, v217, 1.0
	v_cvt_scalef32_pk_fp4_f32 v235, v224, v225, 1.0
	v_cvt_scalef32_pk_fp4_f32 v232, v202, v203, 1.0 op_sel:[0,0,1,0]
	v_cvt_scalef32_pk_fp4_f32 v233, v210, v211, 1.0 op_sel:[0,0,1,0]
	v_cvt_scalef32_pk_fp4_f32 v234, v218, v219, 1.0 op_sel:[0,0,1,0]
	v_cvt_scalef32_pk_fp4_f32 v235, v226, v227, 1.0 op_sel:[0,0,1,0]
	v_cvt_scalef32_pk_fp4_f32 v232, v204, v205, 1.0 op_sel:[0,0,0,1]
	v_cvt_scalef32_pk_fp4_f32 v233, v212, v213, 1.0 op_sel:[0,0,0,1]
	v_cvt_scalef32_pk_fp4_f32 v234, v220, v221, 1.0 op_sel:[0,0,0,1]
	v_cvt_scalef32_pk_fp4_f32 v235, v228, v229, 1.0 op_sel:[0,0,0,1]
	v_cvt_scalef32_pk_fp4_f32 v232, v206, v207, 1.0 op_sel:[0,0,1,1]
	v_cvt_scalef32_pk_fp4_f32 v233, v214, v215, 1.0 op_sel:[0,0,1,1]
	v_cvt_scalef32_pk_fp4_f32 v234, v222, v223, 1.0 op_sel:[0,0,1,1]
	v_cvt_scalef32_pk_fp4_f32 v235, v230, v231, 1.0 op_sel:[0,0,1,1]
	s_nop 0
	global_store_dwordx4 v[240:241], v[232:235], off
	v_lshl_add_u64 v[240:241], v[240:241], 0, v[246:247]
	global_load_dwordx4 v[200:203], v[236:237], off
	global_load_dwordx4 v[204:207], v[236:237], off offset:16
	global_load_dwordx4 v[208:211], v[236:237], off offset:32
	global_load_dwordx4 v[212:215], v[236:237], off offset:48
	global_load_dwordx4 v[216:219], v[238:239], off
	global_load_dwordx4 v[220:223], v[238:239], off offset:16
	global_load_dwordx4 v[224:227], v[238:239], off offset:32
	global_load_dwordx4 v[228:231], v[238:239], off offset:48
	v_lshl_add_u64 v[236:237], v[236:237], 0, v[244:245]
	v_lshl_add_u64 v[238:239], v[238:239], 0, v[244:245]
	v_max_u32_e32 v19, v17, v12
	v_min_u32_e32 v12, v17, v12
	v_max_u32_e32 v17, v5, v10
	v_min_u32_e32 v21, v3, v2
	v_max_u32_e32 v22, v9, v4
	v_min_u32_e32 v4, v9, v4
	v_min_u32_e32 v15, v15, v18
	v_max_u32_e32 v18, v11, v13
	v_min_u32_e32 v11, v11, v13
	v_max_u32_e32 v13, v8, v14
	v_min_u32_e32 v14, v8, v14
	v_min_u32_e32 v5, v5, v10
	v_max_u32_e32 v8, v6, v16
	v_min_u32_e32 v10, v6, v16
	v_max_u32_e32 v39, v19, v17
	v_min_u32_e32 v40, v19, v17
	v_max_u32_e32 v45, v21, v4
	v_min_u32_e32 v46, v21, v4
	v_bitop3_b32 v4, v82, s22, v82 bitop3:0xc
	v_lshl_add_u32 v19, v87, 2, s26
	v_bitop3_b32 v6, v152, s22, v152 bitop3:0xc
	v_max_u32_e32 v41, v12, v5
	v_min_u32_e32 v42, v12, v5
	v_bitop3_b32 v5, v8, s22, v8 bitop3:0xc
	ds_write2st64_b32 v19, v4, v6 offset1:1
	v_bitop3_b32 v4, v10, s22, v10 bitop3:0xc
	v_max_u32_e32 v20, v3, v2
	v_max_u32_e32 v3, v7, v15
	v_min_u32_e32 v2, v7, v15
	ds_write2st64_b32 v19, v5, v4 offset0:16 offset1:17
	v_bitop3_b32 v4, v156, s22, v156 bitop3:0xc
	v_bitop3_b32 v6, v157, s22, v157 bitop3:0xc
	v_bitop3_b32 v5, v3, s22, v3 bitop3:0xc
	ds_write2st64_b32 v19, v4, v6 offset0:2 offset1:3
	v_bitop3_b32 v4, v2, s22, v2 bitop3:0xc
	v_max_u32_e32 v35, v18, v13
	v_min_u32_e32 v36, v18, v13
	ds_write2st64_b32 v19, v5, v4 offset0:18 offset1:19
	v_bitop3_b32 v4, v158, s22, v158 bitop3:0xc
	v_bitop3_b32 v6, v159, s22, v159 bitop3:0xc
	v_bitop3_b32 v5, v35, s22, v35 bitop3:0xc
	ds_write2st64_b32 v19, v4, v6 offset0:4 offset1:5
	v_bitop3_b32 v4, v36, s22, v36 bitop3:0xc
	v_max_u32_e32 v37, v11, v14
	v_min_u32_e32 v38, v11, v14
	ds_write2st64_b32 v19, v5, v4 offset0:20 offset1:21
	v_bitop3_b32 v4, v160, s22, v160 bitop3:0xc
	v_bitop3_b32 v6, v161, s22, v161 bitop3:0xc
	v_bitop3_b32 v5, v37, s22, v37 bitop3:0xc
	ds_write2st64_b32 v19, v4, v6 offset0:6 offset1:7
	v_bitop3_b32 v4, v38, s22, v38 bitop3:0xc
	ds_write2st64_b32 v19, v5, v4 offset0:22 offset1:23
	v_bitop3_b32 v4, v83, s22, v83 bitop3:0xc
	v_bitop3_b32 v6, v147, s22, v147 bitop3:0xc
	v_bitop3_b32 v5, v39, s22, v39 bitop3:0xc
	ds_write2st64_b32 v19, v4, v6 offset0:8 offset1:9
	v_bitop3_b32 v4, v40, s22, v40 bitop3:0xc
	ds_write2st64_b32 v19, v5, v4 offset0:24 offset1:25
	v_bitop3_b32 v4, v148, s22, v148 bitop3:0xc
	v_bitop3_b32 v6, v149, s22, v149 bitop3:0xc
	v_bitop3_b32 v5, v41, s22, v41 bitop3:0xc
	ds_write2st64_b32 v19, v4, v6 offset0:10 offset1:11
	v_bitop3_b32 v4, v42, s22, v42 bitop3:0xc
	v_max_u32_e32 v43, v20, v22
	v_min_u32_e32 v44, v20, v22
	ds_write2st64_b32 v19, v5, v4 offset0:26 offset1:27
	v_bitop3_b32 v4, v150, s22, v150 bitop3:0xc
	v_bitop3_b32 v6, v151, s22, v151 bitop3:0xc
	v_bitop3_b32 v5, v43, s22, v43 bitop3:0xc
	ds_write2st64_b32 v19, v4, v6 offset0:12 offset1:13
	v_bitop3_b32 v4, v44, s22, v44 bitop3:0xc
	ds_write2st64_b32 v19, v5, v4 offset0:28 offset1:29
	v_bitop3_b32 v4, v154, s22, v154 bitop3:0xc
	v_bitop3_b32 v6, v155, s22, v155 bitop3:0xc
	v_bitop3_b32 v5, v45, s22, v45 bitop3:0xc
	ds_write2st64_b32 v19, v4, v6 offset0:14 offset1:15
	v_bitop3_b32 v4, v46, s22, v46 bitop3:0xc
	v_cmp_gt_u32_e32 vcc, 32, v87
	ds_write2st64_b32 v19, v5, v4 offset0:30 offset1:31
	s_and_saveexec_b64 s[16:17], vcc
	s_cbranch_execz .LBB0_795
	v_cmp_lt_i32_e32 vcc, -1, v161
	v_and_b32_e32 v6, 0xffffff80, v157
	v_and_b32_e32 v9, 0xffffff80, v8
	v_cndmask_b32_e64 v4, v86, -1, vcc
	v_cmp_lt_i32_e32 vcc, -1, v160
	v_bitop3_b32 v26, v4, v161, s23 bitop3:0x78
	v_and_b32_e32 v15, 0xffffff80, v152
	v_cndmask_b32_e64 v4, v86, -1, vcc
	v_cmp_lt_i32_e32 vcc, -1, v159
	v_bitop3_b32 v28, v4, v160, s23 bitop3:0x78
	v_and_b32_e32 v11, 0xffffff80, v155
	v_cndmask_b32_e64 v4, v86, -1, vcc
	v_cmp_lt_i32_e32 vcc, -1, v158
	v_bitop3_b32 v30, v4, v159, s23 bitop3:0x78
	v_and_b32_e32 v14, 0xffffff80, v154
	v_cndmask_b32_e64 v4, v86, -1, vcc
	v_cmp_lt_i32_e32 vcc, -1, v3
	v_bitop3_b32 v49, v4, v158, s23 bitop3:0x78
	v_and_b32_e32 v4, 0xffffff80, v3
	v_cndmask_b32_e64 v3, v86, -1, vcc
	v_cmp_lt_i32_e32 vcc, -1, v157
	v_xor_b32_e32 v5, v3, v4
	v_and_b32_e32 v3, 0xffffff80, v2
	v_cndmask_b32_e64 v7, v86, -1, vcc
	v_cmp_lt_i32_e32 vcc, -1, v2
	v_xor_b32_e32 v4, v7, v6
	v_and_b32_e32 v6, 0xffffff80, v156
	v_cndmask_b32_e64 v2, v86, -1, vcc
	v_cmp_lt_i32_e32 vcc, -1, v156
	v_xor_b32_e32 v7, v2, v3
	v_mov_b32_e32 v2, v5
	v_cndmask_b32_e64 v12, v86, -1, vcc
	v_xor_b32_e32 v6, v12, v6
	v_mov_b32_e32 v3, v7
	v_pk_add_f32 v[12:13], v[6:7], v[2:3] op_sel_hi:[0,1]
	v_not_b32_e32 v23, v13
	v_or_b32_e32 v24, 0x80000000, v13
	v_cmp_gt_i32_e32 vcc, 0, v13
	v_and_b32_e32 v16, 0xffffff80, v151
	v_and_b32_e32 v17, 0xffffff80, v150
	v_cndmask_b32_e32 v13, v24, v23, vcc
	v_and_b32_e32 v13, 0xffffff00, v13
	v_or_b32_e32 v31, 0xdc, v13
	v_not_b32_e32 v13, v12
	v_or_b32_e32 v23, 0x80000000, v12
	v_cmp_gt_i32_e32 vcc, 0, v12
	v_and_b32_e32 v18, 0xffffff80, v149
	v_and_b32_e32 v20, 0xffffff80, v148
	v_cndmask_b32_e32 v12, v23, v13, vcc
	v_cmp_lt_i32_e32 vcc, -1, v8
	v_and_b32_e32 v12, 0xffffff00, v12
	v_or_b32_e32 v32, 0xdd, v12
	v_cndmask_b32_e64 v8, v86, -1, vcc
	v_cmp_lt_i32_e32 vcc, -1, v152
	v_xor_b32_e32 v9, v8, v9
	v_and_b32_e32 v21, 0xffffff80, v147
	v_cndmask_b32_e64 v12, v86, -1, vcc
	v_cmp_lt_i32_e32 vcc, -1, v155
	v_xor_b32_e32 v8, v12, v15
	v_and_b32_e32 v22, 0xffffff80, v83
	v_cndmask_b32_e64 v12, v86, -1, vcc
	v_cmp_lt_i32_e32 vcc, -1, v154
	v_xor_b32_e32 v13, v12, v11
	v_mov_b32_e32 v48, v4
	v_cndmask_b32_e64 v15, v86, -1, vcc
	v_xor_b32_e32 v12, v15, v14
	v_pk_add_f32 v[12:13], v[8:9], v[12:13] op_sel:[1,0]
	v_and_b32_e32 v25, 0xffffff80, v10
	v_not_b32_e32 v11, v13
	v_or_b32_e32 v14, 0x80000000, v13
	v_cmp_gt_i32_e32 vcc, 0, v13
	v_or_b32_e32 v13, 0x80000000, v12
	v_and_b32_e32 v27, 0xffffff80, v82
	v_cndmask_b32_e32 v11, v14, v11, vcc
	v_and_or_b32 v14, v11, s33, 15
	v_not_b32_e32 v11, v12
	v_cmp_gt_i32_e32 vcc, 0, v12
	v_mov_b32_e32 v34, v49
	v_and_b32_e32 v54, 0xffffff80, v38
	v_cndmask_b32_e32 v11, v13, v11, vcc
	v_cmp_lt_i32_e32 vcc, -1, v151
	v_and_or_b32 v15, v11, s33, 31
	v_and_b32_e32 v55, 0xffffff80, v37
	v_cndmask_b32_e64 v11, v86, -1, vcc
	v_cmp_lt_i32_e32 vcc, -1, v150
	v_xor_b32_e32 v13, v11, v16
	v_and_b32_e32 v53, 0xffffff80, v35
	v_cndmask_b32_e64 v12, v86, -1, vcc
	v_xor_b32_e32 v12, v12, v17
	v_pk_add_f32 v[12:13], v[8:9], v[12:13] op_sel:[1,0]
	v_and_b32_e32 v52, 0xffffff80, v36
	v_not_b32_e32 v11, v13
	v_or_b32_e32 v16, 0x80000000, v13
	v_cmp_gt_i32_e32 vcc, 0, v13
	v_or_b32_e32 v13, 0x80000000, v12
	v_min_u32_e32 v88, v32, v31
	v_cndmask_b32_e32 v11, v16, v11, vcc
	v_and_or_b32 v16, v11, s33, 47
	v_not_b32_e32 v11, v12
	v_cmp_gt_i32_e32 vcc, 0, v12
	s_lshl_b32 s14, s35, 6
	s_nop 0
	v_cndmask_b32_e32 v11, v13, v11, vcc
	v_cmp_lt_i32_e32 vcc, -1, v149
	v_and_or_b32 v17, v11, s33, 63
	s_nop 0
	v_cndmask_b32_e64 v11, v86, -1, vcc
	v_cmp_lt_i32_e32 vcc, -1, v148
	v_xor_b32_e32 v13, v11, v18
	s_nop 0
	v_cndmask_b32_e64 v12, v86, -1, vcc
	v_xor_b32_e32 v12, v12, v20
	v_pk_add_f32 v[12:13], v[8:9], v[12:13] op_sel:[1,0]
	s_nop 0
	v_not_b32_e32 v11, v13
	v_or_b32_e32 v18, 0x80000000, v13
	v_cmp_gt_i32_e32 vcc, 0, v13
	v_or_b32_e32 v13, 0x80000000, v12
	s_nop 0
	v_cndmask_b32_e32 v11, v18, v11, vcc
	v_and_b32_e32 v11, 0xffffff00, v11
	v_or_b32_e32 v18, 0x4f, v11
	v_not_b32_e32 v11, v12
	v_cmp_gt_i32_e32 vcc, 0, v12
	s_nop 1
	v_cndmask_b32_e32 v11, v13, v11, vcc
	v_and_b32_e32 v11, 0xffffff00, v11
	v_cmp_lt_i32_e32 vcc, -1, v147
	v_or_b32_e32 v20, 0x5f, v11
	s_nop 0
	v_cndmask_b32_e64 v11, v86, -1, vcc
	v_cmp_lt_i32_e32 vcc, -1, v83
	v_xor_b32_e32 v13, v11, v21
	s_nop 0
	v_cndmask_b32_e64 v12, v86, -1, vcc
	v_xor_b32_e32 v12, v12, v22
	v_pk_add_f32 v[12:13], v[8:9], v[12:13] op_sel:[1,0]
	s_nop 0
	v_not_b32_e32 v11, v13
	v_or_b32_e32 v21, 0x80000000, v13
	v_cmp_gt_i32_e32 vcc, 0, v13
	v_or_b32_e32 v13, 0x80000000, v12
	s_nop 0
	v_cndmask_b32_e32 v11, v21, v11, vcc
	v_and_b32_e32 v11, 0xffffff00, v11
	v_or_b32_e32 v21, 0x6f, v11
	v_not_b32_e32 v11, v12
	v_cmp_gt_i32_e32 vcc, 0, v12
	v_mov_b32_e32 v12, v7
	s_nop 0
	v_cndmask_b32_e32 v11, v13, v11, vcc
	v_mov_b32_e32 v13, v9
	v_and_b32_e32 v11, 0xffffff00, v11
	v_pk_add_f32 v[12:13], v[48:49], v[12:13]
	v_or_b32_e32 v22, 0x7f, v11
	v_not_b32_e32 v11, v12
	v_or_b32_e32 v23, 0x80000000, v12
	v_cmp_gt_i32_e32 vcc, 0, v12
	v_or_b32_e32 v12, 0x80000000, v13
	v_mov_b32_e32 v49, v5
	v_cndmask_b32_e32 v11, v23, v11, vcc
	v_and_b32_e32 v11, 0xffffff00, v11
	v_or_b32_e32 v23, 0xcc, v11
	v_not_b32_e32 v11, v13
	v_cmp_gt_i32_e32 vcc, 0, v13
	s_nop 1
	v_cndmask_b32_e32 v11, v12, v11, vcc
	v_and_b32_e32 v11, 0xffffff00, v11
	v_pk_add_f32 v[12:13], v[8:9], v[2:3] op_sel_hi:[0,1]
	v_or_b32_e32 v24, 0xbf, v11
	v_not_b32_e32 v11, v13
	v_or_b32_e32 v29, 0x80000000, v13
	v_cmp_gt_i32_e32 vcc, 0, v13
	v_or_b32_e32 v13, 0x80000000, v12
	s_nop 0
	v_cndmask_b32_e32 v11, v29, v11, vcc
	v_and_b32_e32 v11, 0xffffff00, v11
	v_or_b32_e32 v56, 0xec, v11
	v_not_b32_e32 v11, v12
	v_cmp_gt_i32_e32 vcc, 0, v12
	s_nop 1
	v_cndmask_b32_e32 v11, v13, v11, vcc
	v_cmp_lt_i32_e32 vcc, -1, v10
	v_and_b32_e32 v11, 0xffffff00, v11
	v_or_b32_e32 v57, 0xed, v11
	v_cndmask_b32_e64 v10, v86, -1, vcc
	v_cmp_lt_i32_e32 vcc, -1, v82
	v_xor_b32_e32 v11, v10, v25
	v_mov_b32_e32 v13, v11
	v_cndmask_b32_e64 v12, v86, -1, vcc
	v_xor_b32_e32 v10, v12, v27
	v_mov_b32_e32 v12, v9
	v_pk_add_f32 v[26:27], v[26:27], v[12:13] op_sel_hi:[0,1]
	v_not_b32_e32 v25, v26
	v_or_b32_e32 v29, 0x80000000, v26
	v_cmp_gt_i32_e32 vcc, 0, v26
	v_not_b32_e32 v26, v27
	v_pk_add_f32 v[50:51], v[30:31], v[12:13] op_sel_hi:[0,1]
	v_cndmask_b32_e32 v25, v29, v25, vcc
	v_or_b32_e32 v29, 0x80000000, v27
	v_cmp_gt_i32_e32 vcc, 0, v27
	v_or_b32_e32 v30, 0x80000000, v50
	v_mov_b32_e32 v48, v11
	v_cndmask_b32_e32 v26, v29, v26, vcc
	v_pk_add_f32 v[28:29], v[28:29], v[12:13] op_sel_hi:[0,1]
	v_not_b32_e32 v27, v28
	v_or_b32_e32 v33, 0x80000000, v28
	v_cmp_gt_i32_e32 vcc, 0, v28
	v_not_b32_e32 v28, v29
	v_pk_add_f32 v[2:3], v[10:11], v[2:3] op_sel_hi:[0,1]
	v_cndmask_b32_e32 v27, v33, v27, vcc
	v_or_b32_e32 v33, 0x80000000, v29
	v_cmp_gt_i32_e32 vcc, 0, v29
	v_not_b32_e32 v29, v50
	v_min_u32_e32 v68, v57, v56
	v_cndmask_b32_e32 v28, v33, v28, vcc
	v_cmp_gt_i32_e32 vcc, 0, v50
	v_or_b32_e32 v33, 0x80000000, v51
	v_max_u32_e32 v31, v32, v31
	v_cndmask_b32_e32 v29, v30, v29, vcc
	v_not_b32_e32 v30, v51
	v_cmp_gt_i32_e32 vcc, 0, v51
	v_pk_add_f32 v[50:51], v[34:35], v[48:49] op_sel_hi:[0,1]
	v_or_b32_e32 v34, 0x80000000, v51
	v_cndmask_b32_e32 v30, v33, v30, vcc
	v_not_b32_e32 v33, v51
	v_cmp_gt_i32_e32 vcc, 0, v51
	v_or_b32_e32 v47, 0x80000000, v50
	v_pk_add_f32 v[48:49], v[4:5], v[48:49] op_sel_hi:[0,1]
	v_cndmask_b32_e32 v33, v34, v33, vcc
	v_not_b32_e32 v34, v50
	v_cmp_gt_i32_e32 vcc, 0, v50
	v_not_b32_e32 v5, v49
	v_and_b32_e32 v25, 0xffffff00, v25
	v_cndmask_b32_e32 v34, v47, v34, vcc
	v_or_b32_e32 v47, 0x80000000, v49
	v_cmp_gt_i32_e32 vcc, 0, v49
	v_and_b32_e32 v26, 0xffffff00, v26
	v_and_b32_e32 v27, 0xffffff00, v27
	v_cndmask_b32_e32 v5, v47, v5, vcc
	v_and_b32_e32 v5, 0xffffff00, v5
	v_or_b32_e32 v50, 0xcd, v5
	v_not_b32_e32 v5, v48
	v_or_b32_e32 v47, 0x80000000, v48
	v_cmp_gt_i32_e32 vcc, 0, v48
	v_pk_add_f32 v[48:49], v[6:7], v[12:13] op_sel_hi:[0,1]
	v_or_b32_e32 v7, 0x80000000, v48
	v_cndmask_b32_e32 v5, v47, v5, vcc
	v_and_b32_e32 v5, 0xffffff00, v5
	v_or_b32_e32 v51, 0xce, v5
	v_not_b32_e32 v5, v48
	v_cmp_gt_i32_e32 vcc, 0, v48
	v_min_u32_e32 v91, v51, v50
	v_and_b32_e32 v28, 0xffffff00, v28
	v_cndmask_b32_e32 v5, v7, v5, vcc
	v_and_b32_e32 v5, 0xffffff00, v5
	v_or_b32_e32 v58, 0xdf, v5
	v_not_b32_e32 v5, v49
	v_or_b32_e32 v7, 0x80000000, v49
	v_cmp_gt_i32_e32 vcc, 0, v49
	v_pk_add_f32 v[48:49], v[8:9], v[12:13] op_sel_hi:[0,1]
	v_and_b32_e32 v29, 0xffffff00, v29
	v_cndmask_b32_e32 v5, v7, v5, vcc
	v_and_b32_e32 v5, 0xffffff00, v5
	v_or_b32_e32 v59, 0xde, v5
	v_not_b32_e32 v5, v48
	v_or_b32_e32 v7, 0x80000000, v48
	v_cmp_gt_i32_e32 vcc, 0, v48
	v_max_u32_e32 v83, v58, v59
	v_min_u32_e32 v58, v58, v59
	v_cndmask_b32_e32 v5, v7, v5, vcc
	v_and_b32_e32 v5, 0xffffff00, v5
	v_or_b32_e32 v48, 0xef, v5
	v_not_b32_e32 v5, v49
	v_or_b32_e32 v7, 0x80000000, v49
	v_cmp_gt_i32_e32 vcc, 0, v49
	v_max_u32_e32 v89, v83, v88
	v_max_u32_e32 v32, v58, v31
	v_cndmask_b32_e32 v5, v7, v5, vcc
	v_and_b32_e32 v5, 0xffffff00, v5
	v_cmp_lt_i32_e32 vcc, -1, v46
	v_or_b32_e32 v49, 0xee, v5
	v_and_b32_e32 v5, 0xffffff80, v46
	v_cndmask_b32_e64 v46, v86, -1, vcc
	v_cmp_lt_i32_e32 vcc, -1, v45
	v_and_b32_e32 v7, 0xffffff80, v45
	v_xor_b32_e32 v47, v46, v5
	v_cndmask_b32_e64 v45, v86, -1, vcc
	v_xor_b32_e32 v46, v45, v7
	v_pk_add_f32 v[46:47], v[10:11], v[46:47] op_sel_hi:[0,1]
	v_not_b32_e32 v5, v47
	v_or_b32_e32 v7, 0x80000000, v47
	v_cmp_gt_i32_e32 vcc, 0, v47
	v_min_u32_e32 v83, v83, v88
	v_min_u32_e32 v31, v58, v31
	v_cndmask_b32_e32 v5, v7, v5, vcc
	v_and_b32_e32 v5, 0xffffff00, v5
	v_or_b32_e32 v47, 0xf0, v5
	v_not_b32_e32 v5, v46
	v_or_b32_e32 v7, 0x80000000, v46
	v_cmp_gt_i32_e32 vcc, 0, v46
	v_max_u32_e32 v59, v89, v32
	v_max_u32_e32 v58, v83, v31
	v_cndmask_b32_e32 v5, v7, v5, vcc
	v_and_b32_e32 v5, 0xffffff00, v5
	v_cmp_lt_i32_e32 vcc, -1, v44
	v_or_b32_e32 v46, 0xf1, v5
	v_and_b32_e32 v5, 0xffffff80, v44
	v_cndmask_b32_e64 v44, v86, -1, vcc
	v_cmp_lt_i32_e32 vcc, -1, v43
	v_and_b32_e32 v7, 0xffffff80, v43
	v_xor_b32_e32 v45, v44, v5
	v_cndmask_b32_e64 v43, v86, -1, vcc
	v_xor_b32_e32 v44, v43, v7
	v_pk_add_f32 v[44:45], v[10:11], v[44:45] op_sel_hi:[0,1]
	v_not_b32_e32 v5, v45
	v_or_b32_e32 v7, 0x80000000, v45
	v_cmp_gt_i32_e32 vcc, 0, v45
	v_min_u32_e32 v64, v46, v47
	v_min_u32_e32 v32, v89, v32
	v_cndmask_b32_e32 v5, v7, v5, vcc
	v_and_b32_e32 v5, 0xffffff00, v5
	v_or_b32_e32 v45, 0xf2, v5
	v_not_b32_e32 v5, v44
	v_or_b32_e32 v7, 0x80000000, v44
	v_cmp_gt_i32_e32 vcc, 0, v44
	v_min_u32_e32 v31, v83, v31
	v_and_b32_e32 v30, 0xffffff00, v30
	v_cndmask_b32_e32 v5, v7, v5, vcc
	v_and_b32_e32 v5, 0xffffff00, v5
	v_cmp_lt_i32_e32 vcc, -1, v42
	v_or_b32_e32 v44, 0xf3, v5
	v_and_b32_e32 v5, 0xffffff80, v42
	v_cndmask_b32_e64 v42, v86, -1, vcc
	v_cmp_lt_i32_e32 vcc, -1, v41
	v_and_b32_e32 v7, 0xffffff80, v41
	v_xor_b32_e32 v43, v42, v5
	v_cndmask_b32_e64 v41, v86, -1, vcc
	v_xor_b32_e32 v42, v41, v7
	v_pk_add_f32 v[42:43], v[10:11], v[42:43] op_sel_hi:[0,1]
	v_not_b32_e32 v5, v43
	v_or_b32_e32 v7, 0x80000000, v43
	v_cmp_gt_i32_e32 vcc, 0, v43
	v_max_u32_e32 v63, v44, v45
	v_min_u32_e32 v44, v44, v45
	v_cndmask_b32_e32 v5, v7, v5, vcc
	v_and_b32_e32 v5, 0xffffff00, v5
	v_or_b32_e32 v43, 0xf4, v5
	v_not_b32_e32 v5, v42
	v_or_b32_e32 v7, 0x80000000, v42
	v_cmp_gt_i32_e32 vcc, 0, v42
	v_max_u32_e32 v45, v46, v47
	v_min_u32_e32 v65, v63, v64
	v_cndmask_b32_e32 v5, v7, v5, vcc
	v_and_b32_e32 v5, 0xffffff00, v5
	v_cmp_lt_i32_e32 vcc, -1, v40
	v_or_b32_e32 v42, 0xf5, v5
	v_and_b32_e32 v5, 0xffffff80, v40
	v_cndmask_b32_e64 v40, v86, -1, vcc
	v_cmp_lt_i32_e32 vcc, -1, v39
	v_and_b32_e32 v7, 0xffffff80, v39
	v_xor_b32_e32 v41, v40, v5
	v_cndmask_b32_e64 v39, v86, -1, vcc
	v_xor_b32_e32 v40, v39, v7
	v_pk_add_f32 v[40:41], v[10:11], v[40:41] op_sel_hi:[0,1]
	v_not_b32_e32 v5, v41
	v_or_b32_e32 v7, 0x80000000, v41
	v_cmp_gt_i32_e32 vcc, 0, v41
	v_min_u32_e32 v46, v44, v45
	v_max_u32_e32 v44, v44, v45
	v_cndmask_b32_e32 v5, v7, v5, vcc
	v_and_b32_e32 v5, 0xffffff00, v5
	v_or_b32_e32 v60, 0xf6, v5
	v_not_b32_e32 v5, v40
	v_or_b32_e32 v7, 0x80000000, v40
	v_cmp_gt_i32_e32 vcc, 0, v40
	v_min_u32_e32 v47, v65, v46
	v_max_u32_e32 v46, v65, v46
	v_cndmask_b32_e32 v5, v7, v5, vcc
	v_and_b32_e32 v5, 0xffffff00, v5
	v_cmp_lt_i32_e32 vcc, -1, v38
	v_or_b32_e32 v61, 0xf7, v5
	v_and_b32_e32 v33, 0xffffff00, v33
	v_cndmask_b32_e64 v5, v86, -1, vcc
	v_cmp_lt_i32_e32 vcc, -1, v37
	v_xor_b32_e32 v39, v5, v54
	v_max_u32_e32 v54, v61, v60
	v_cndmask_b32_e64 v7, v86, -1, vcc
	v_xor_b32_e32 v38, v7, v55
	v_pk_add_f32 v[40:41], v[8:9], v[38:39] op_sel_hi:[0,1]
	v_not_b32_e32 v5, v41
	v_or_b32_e32 v7, 0x80000000, v41
	v_cmp_gt_i32_e32 vcc, 0, v41
	v_pk_add_f32 v[38:39], v[10:11], v[38:39] op_sel_hi:[0,1]
	v_min_u32_e32 v55, v42, v43
	v_cndmask_b32_e32 v5, v7, v5, vcc
	v_and_b32_e32 v5, 0xffffff00, v5
	v_or_b32_e32 v41, 0xe8, v5
	v_not_b32_e32 v5, v40
	v_or_b32_e32 v7, 0x80000000, v40
	v_cmp_gt_i32_e32 vcc, 0, v40
	v_min_u32_e32 v60, v61, v60
	v_max_u32_e32 v42, v42, v43
	v_cndmask_b32_e32 v5, v7, v5, vcc
	v_and_b32_e32 v5, 0xffffff00, v5
	v_or_b32_e32 v40, 0xe9, v5
	v_not_b32_e32 v5, v39
	v_or_b32_e32 v7, 0x80000000, v39
	v_cmp_gt_i32_e32 vcc, 0, v39
	v_max_u32_e32 v62, v54, v55
	v_max_u32_e32 v43, v60, v42
	v_cndmask_b32_e32 v5, v7, v5, vcc
	v_and_b32_e32 v5, 0xffffff00, v5
	v_or_b32_e32 v39, 0xf8, v5
	v_not_b32_e32 v5, v38
	v_or_b32_e32 v7, 0x80000000, v38
	v_cmp_gt_i32_e32 vcc, 0, v38
	v_min_u32_e32 v54, v54, v55
	v_min_u32_e32 v42, v60, v42
	v_cndmask_b32_e32 v5, v7, v5, vcc
	v_and_b32_e32 v5, 0xffffff00, v5
	v_cmp_lt_i32_e32 vcc, -1, v36
	v_or_b32_e32 v38, 0xf9, v5
	v_max_u32_e32 v60, v63, v64
	v_cndmask_b32_e64 v5, v86, -1, vcc
	v_cmp_lt_i32_e32 vcc, -1, v35
	v_xor_b32_e32 v37, v5, v52
	v_mov_b32_e32 v5, v9
	v_cndmask_b32_e64 v7, v86, -1, vcc
	v_xor_b32_e32 v36, v7, v53
	v_mov_b32_e32 v7, v4
	v_mov_b32_e32 v4, v36
	v_pk_add_f32 v[4:5], v[6:7], v[4:5]
	v_max_u32_e32 v61, v62, v43
	v_not_b32_e32 v6, v5
	v_or_b32_e32 v7, 0x80000000, v5
	v_cmp_gt_i32_e32 vcc, 0, v5
	v_max_u32_e32 v55, v54, v42
	v_min_u32_e32 v45, v60, v44
	v_cndmask_b32_e32 v5, v7, v6, vcc
	v_and_b32_e32 v5, 0xffffff00, v5
	v_or_b32_e32 v6, 0xcf, v5
	v_not_b32_e32 v5, v4
	v_or_b32_e32 v7, 0x80000000, v4
	v_cmp_gt_i32_e32 vcc, 0, v4
	v_min_u32_e32 v43, v62, v43
	v_min_u32_e32 v42, v54, v42
	v_cndmask_b32_e32 v4, v7, v5, vcc
	v_and_b32_e32 v4, 0xffffff00, v4
	v_or_b32_e32 v7, 0xdb, v4
	v_pk_add_f32 v[4:5], v[8:9], v[36:37] op_sel_hi:[0,1]
	v_not_b32_e32 v8, v5
	v_or_b32_e32 v9, 0x80000000, v5
	v_cmp_gt_i32_e32 vcc, 0, v5
	v_max_u32_e32 v44, v60, v44
	v_min_u32_e32 v66, v61, v47
	v_cndmask_b32_e32 v5, v9, v8, vcc
	v_and_b32_e32 v5, 0xffffff00, v5
	v_or_b32_e32 v8, 0xea, v5
	v_not_b32_e32 v5, v4
	v_or_b32_e32 v9, 0x80000000, v4
	v_cmp_gt_i32_e32 vcc, 0, v4
	v_min_u32_e32 v63, v55, v45
	v_min_u32_e32 v62, v43, v46
	v_cndmask_b32_e32 v4, v9, v5, vcc
	v_and_b32_e32 v4, 0xffffff00, v4
	v_or_b32_e32 v9, 0xeb, v4
	v_pk_add_f32 v[4:5], v[10:11], v[36:37] op_sel_hi:[0,1]
	v_not_b32_e32 v35, v5
	v_or_b32_e32 v36, 0x80000000, v5
	v_cmp_gt_i32_e32 vcc, 0, v5
	v_min_u32_e32 v37, v38, v39
	v_min_u32_e32 v54, v42, v44
	v_cndmask_b32_e32 v5, v36, v35, vcc
	v_not_b32_e32 v35, v4
	v_or_b32_e32 v36, 0x80000000, v4
	v_cmp_gt_i32_e32 vcc, 0, v4
	v_and_b32_e32 v5, 0xffffff00, v5
	v_or_b32_e32 v5, 0xfa, v5
	v_cndmask_b32_e32 v4, v36, v35, vcc
	v_not_b32_e32 v35, v3
	v_or_b32_e32 v36, 0x80000000, v3
	v_cmp_gt_i32_e32 vcc, 0, v3
	s_mov_b64 s[50:51], exec
	s_mov_b64 exec, -1
	s_waitcnt vmcnt(0)
	v_pk_mul_f32 v[200:201], v[200:201], s[96:97] op_sel_hi:[1,0]
	v_pk_mul_f32 v[202:203], v[202:203], s[96:97] op_sel_hi:[1,0]
	v_pk_mul_f32 v[204:205], v[204:205], s[96:97] op_sel_hi:[1,0]
	v_pk_mul_f32 v[206:207], v[206:207], s[96:97] op_sel_hi:[1,0]
	v_pk_mul_f32 v[208:209], v[208:209], s[96:97] op_sel_hi:[1,0]
	v_pk_mul_f32 v[210:211], v[210:211], s[96:97] op_sel_hi:[1,0]
	v_pk_mul_f32 v[212:213], v[212:213], s[96:97] op_sel_hi:[1,0]
	v_pk_mul_f32 v[214:215], v[214:215], s[96:97] op_sel_hi:[1,0]
	v_pk_mul_f32 v[216:217], v[216:217], s[96:97] op_sel_hi:[1,0]
	v_pk_mul_f32 v[218:219], v[218:219], s[96:97] op_sel_hi:[1,0]
	v_pk_mul_f32 v[220:221], v[220:221], s[96:97] op_sel_hi:[1,0]
	v_pk_mul_f32 v[222:223], v[222:223], s[96:97] op_sel_hi:[1,0]
	v_pk_mul_f32 v[224:225], v[224:225], s[96:97] op_sel_hi:[1,0]
	v_pk_mul_f32 v[226:227], v[226:227], s[96:97] op_sel_hi:[1,0]
	v_pk_mul_f32 v[228:229], v[228:229], s[96:97] op_sel_hi:[1,0]
	v_pk_mul_f32 v[230:231], v[230:231], s[96:97] op_sel_hi:[1,0]
	v_cvt_scalef32_pk_fp4_f32 v232, v200, v201, 1.0
	v_cvt_scalef32_pk_fp4_f32 v233, v208, v209, 1.0
	v_cvt_scalef32_pk_fp4_f32 v234, v216, v217, 1.0
	v_cvt_scalef32_pk_fp4_f32 v235, v224, v225, 1.0
	v_cvt_scalef32_pk_fp4_f32 v232, v202, v203, 1.0 op_sel:[0,0,1,0]
	v_cvt_scalef32_pk_fp4_f32 v233, v210, v211, 1.0 op_sel:[0,0,1,0]
	v_cvt_scalef32_pk_fp4_f32 v234, v218, v219, 1.0 op_sel:[0,0,1,0]
	v_cvt_scalef32_pk_fp4_f32 v235, v226, v227, 1.0 op_sel:[0,0,1,0]
	v_cvt_scalef32_pk_fp4_f32 v232, v204, v205, 1.0 op_sel:[0,0,0,1]
	v_cvt_scalef32_pk_fp4_f32 v233, v212, v213, 1.0 op_sel:[0,0,0,1]
	v_cvt_scalef32_pk_fp4_f32 v234, v220, v221, 1.0 op_sel:[0,0,0,1]
	v_cvt_scalef32_pk_fp4_f32 v235, v228, v229, 1.0 op_sel:[0,0,0,1]
	v_cvt_scalef32_pk_fp4_f32 v232, v206, v207, 1.0 op_sel:[0,0,1,1]
	v_cvt_scalef32_pk_fp4_f32 v233, v214, v215, 1.0 op_sel:[0,0,1,1]
	v_cvt_scalef32_pk_fp4_f32 v234, v222, v223, 1.0 op_sel:[0,0,1,1]
	v_cvt_scalef32_pk_fp4_f32 v235, v230, v231, 1.0 op_sel:[0,0,1,1]
	s_nop 0
	global_store_dwordx4 v[240:241], v[232:235], off
	v_lshl_add_u64 v[240:241], v[240:241], 0, v[246:247]
	global_load_dwordx4 v[200:203], v[236:237], off
	global_load_dwordx4 v[204:207], v[236:237], off offset:16
	global_load_dwordx4 v[208:211], v[236:237], off offset:32
	global_load_dwordx4 v[212:215], v[236:237], off offset:48
	global_load_dwordx4 v[216:219], v[238:239], off
	global_load_dwordx4 v[220:223], v[238:239], off offset:16
	global_load_dwordx4 v[224:227], v[238:239], off offset:32
	global_load_dwordx4 v[228:231], v[238:239], off offset:48
	v_lshl_add_u64 v[236:237], v[236:237], 0, v[244:245]
	v_lshl_add_u64 v[238:239], v[238:239], 0, v[244:245]
	s_mov_b64 exec, s[50:51]
	s_nop 4
	v_and_b32_e32 v4, 0xffffff00, v4
	v_or_b32_e32 v4, 0xfb, v4
	v_cndmask_b32_e32 v3, v36, v35, vcc
	v_and_b32_e32 v3, 0xffffff00, v3
	v_or_b32_e32 v35, 0xfc, v3
	v_not_b32_e32 v3, v2
	v_or_b32_e32 v36, 0x80000000, v2
	v_cmp_gt_i32_e32 vcc, 0, v2
	v_min_u32_e32 v64, v66, v63
	v_min_u32_e32 v60, v62, v54
	v_cndmask_b32_e32 v2, v36, v3, vcc
	v_and_b32_e32 v2, 0xffffff00, v2
	v_or_b32_e32 v36, 0xfd, v2
	v_pk_add_f32 v[2:3], v[10:11], v[12:13] op_sel_hi:[0,1]
	v_not_b32_e32 v10, v3
	v_or_b32_e32 v11, 0x80000000, v3
	v_cmp_gt_i32_e32 vcc, 0, v3
	v_min_u32_e32 v65, v64, v60
	v_max_u32_e32 v78, v9, v8
	v_cndmask_b32_e32 v3, v11, v10, vcc
	v_not_b32_e32 v10, v2
	v_or_b32_e32 v11, 0x80000000, v2
	v_cmp_gt_i32_e32 vcc, 0, v2
	v_and_b32_e32 v3, 0xffffff00, v3
	v_or_b32_e32 v3, 0xfe, v3
	v_cndmask_b32_e32 v2, v11, v10, vcc
	v_or_b32_e32 v2, 0xff, v2
	v_max_u32_e32 v10, v2, v3
	v_min_u32_e32 v11, v36, v35
	v_min_u32_e32 v2, v2, v3
	v_max_u32_e32 v3, v36, v35
	v_max_u32_e32 v36, v4, v5
	v_min_u32_e32 v4, v4, v5
	v_max_u32_e32 v5, v38, v39
	v_max_u32_e32 v12, v10, v11
	v_max_u32_e32 v13, v2, v3
	v_min_u32_e32 v52, v36, v37
	v_min_u32_e32 v38, v4, v5
	v_min_u32_e32 v10, v10, v11
	v_min_u32_e32 v2, v2, v3
	v_max_u32_e32 v11, v36, v37
	v_max_u32_e32 v4, v4, v5
	v_max_u32_e32 v35, v12, v13
	v_min_u32_e32 v39, v52, v38
	v_max_u32_e32 v3, v10, v2
	v_min_u32_e32 v5, v11, v4
	v_min_u32_e32 v12, v12, v13
	v_max_u32_e32 v13, v52, v38
	v_min_u32_e32 v2, v10, v2
	v_max_u32_e32 v4, v11, v4
	v_max_u32_e32 v53, v35, v39
	v_max_u32_e32 v36, v3, v5
	v_max_u32_e32 v38, v12, v13
	v_max_u32_e32 v10, v2, v4
	v_max_u32_e32 v37, v53, v36
	v_max_u32_e32 v11, v38, v10
	v_max_u32_e32 v52, v37, v11
	v_min_u32_e32 v11, v37, v11
	v_max_u32_e32 v37, v64, v60
	v_max_u32_e32 v64, v48, v49
	v_min_u32_e32 v48, v48, v49
	v_max_u32_e32 v49, v57, v56
	v_min_u32_e32 v80, v40, v41
	v_min_u32_e32 v8, v9, v8
	v_max_u32_e32 v9, v40, v41
	v_max_u32_e32 v90, v7, v6
	v_min_u32_e32 v6, v7, v6
	v_max_u32_e32 v7, v51, v50
	v_max_u32_e32 v69, v64, v68
	v_max_u32_e32 v56, v48, v49
	v_min_u32_e32 v81, v78, v80
	v_min_u32_e32 v40, v8, v9
	v_min_u32_e32 v64, v64, v68
	v_min_u32_e32 v48, v48, v49
	v_max_u32_e32 v68, v78, v80
	v_max_u32_e32 v8, v8, v9
	v_min_u32_e32 v92, v90, v91
	v_min_u32_e32 v50, v6, v7
	v_max_u32_e32 v88, v90, v91
	v_max_u32_e32 v6, v6, v7
	v_max_u32_e32 v57, v69, v56
	v_min_u32_e32 v41, v81, v40
	v_max_u32_e32 v49, v64, v48
	v_min_u32_e32 v9, v68, v8
	v_min_u32_e32 v56, v69, v56
	v_max_u32_e32 v40, v81, v40
	v_min_u32_e32 v48, v64, v48
	v_max_u32_e32 v8, v68, v8
	v_min_u32_e32 v51, v92, v50
	v_min_u32_e32 v7, v88, v6
	v_max_u32_e32 v50, v92, v50
	v_max_u32_e32 v6, v88, v6
	v_min_u32_e32 v35, v35, v39
	v_min_u32_e32 v3, v3, v5
	v_min_u32_e32 v12, v12, v13
	v_min_u32_e32 v2, v2, v4
	v_max_u32_e32 v39, v61, v47
	v_max_u32_e32 v45, v55, v45
	v_max_u32_e32 v43, v43, v46
	v_max_u32_e32 v42, v42, v44
	v_max_u32_e32 v82, v57, v41
	v_max_u32_e32 v78, v49, v9
	v_max_u32_e32 v69, v56, v40
	v_max_u32_e32 v64, v48, v8
	v_min_u32_e32 v93, v59, v51
	v_min_u32_e32 v90, v58, v7
	v_min_u32_e32 v89, v32, v50
	v_min_u32_e32 v83, v31, v6
	v_min_u32_e32 v41, v57, v41
	v_min_u32_e32 v9, v49, v9
	v_min_u32_e32 v40, v56, v40
	v_min_u32_e32 v8, v48, v8
	v_max_u32_e32 v51, v59, v51
	v_max_u32_e32 v7, v58, v7
	v_max_u32_e32 v32, v32, v50
	v_max_u32_e32 v6, v31, v6
	v_max_u32_e32 v5, v35, v3
	v_max_u32_e32 v4, v12, v2
	v_min_u32_e32 v47, v39, v45
	v_min_u32_e32 v44, v43, v42
	v_min_u32_e32 v36, v53, v36
	v_min_u32_e32 v10, v38, v10
	v_max_u32_e32 v53, v66, v63
	v_max_u32_e32 v54, v62, v54
	v_min_u32_e32 v3, v35, v3
	v_min_u32_e32 v2, v12, v2
	v_max_u32_e32 v35, v39, v45
	v_max_u32_e32 v39, v43, v42
	v_max_u32_e32 v80, v82, v78
	v_max_u32_e32 v68, v69, v64
	v_min_u32_e32 v91, v93, v90
	v_min_u32_e32 v88, v89, v83
	v_max_u32_e32 v49, v41, v9
	v_max_u32_e32 v48, v40, v8
	v_min_u32_e32 v57, v51, v7
	v_min_u32_e32 v31, v32, v6
	v_min_u32_e32 v78, v82, v78
	v_min_u32_e32 v64, v69, v64
	v_max_u32_e32 v82, v93, v90
	v_max_u32_e32 v83, v89, v83
	v_min_u32_e32 v9, v41, v9
	v_min_u32_e32 v8, v40, v8
	v_max_u32_e32 v7, v51, v7
	v_max_u32_e32 v6, v32, v6
	v_max_u32_e32 v13, v5, v4
	v_max_u32_e32 v38, v36, v10
	v_max_u32_e32 v12, v3, v2
	v_min_u32_e32 v4, v5, v4
	v_max_u32_e32 v5, v47, v44
	v_min_u32_e32 v10, v36, v10
	v_max_u32_e32 v36, v53, v54
	v_min_u32_e32 v2, v3, v2
	v_max_u32_e32 v3, v35, v39
	v_max_u32_e32 v81, v80, v68
	v_min_u32_e32 v92, v91, v88
	v_max_u32_e32 v56, v49, v48
	v_min_u32_e32 v50, v57, v31
	v_max_u32_e32 v69, v78, v64
	v_min_u32_e32 v89, v82, v83
	v_max_u32_e32 v40, v9, v8
	v_min_u32_e32 v32, v7, v6
	v_min_u32_e32 v68, v80, v68
	v_max_u32_e32 v80, v91, v88
	v_min_u32_e32 v48, v49, v48
	v_max_u32_e32 v31, v57, v31
	v_min_u32_e32 v64, v78, v64
	v_max_u32_e32 v78, v82, v83
	v_min_u32_e32 v8, v9, v8
	v_max_u32_e32 v6, v7, v6
	v_max_u32_e32 v67, v52, v65
	v_min_u32_e32 v46, v47, v44
	v_min_u32_e32 v62, v53, v54
	v_min_u32_e32 v42, v35, v39
	v_max_u32_e32 v60, v11, v37
	v_max_u32_e32 v44, v4, v5
	v_max_u32_e32 v53, v10, v36
	v_max_u32_e32 v35, v2, v3
	v_min_u32_e32 v58, v56, v50
	v_min_u32_e32 v41, v40, v32
	v_min_u32_e32 v88, v68, v80
	v_min_u32_e32 v49, v48, v31
	v_min_u32_e32 v82, v64, v78
	v_min_u32_e32 v7, v8, v6
	v_min_u32_e32 v52, v52, v65
	v_min_u32_e32 v11, v11, v37
	v_min_u32_e32 v4, v4, v5
	v_min_u32_e32 v10, v10, v36
	v_min_u32_e32 v2, v2, v3
	v_max_u32_e32 v37, v81, v92
	v_max_u32_e32 v50, v56, v50
	v_max_u32_e32 v65, v69, v89
	v_max_u32_e32 v32, v40, v32
	v_max_u32_e32 v68, v68, v80
	v_max_u32_e32 v31, v48, v31
	v_max_u32_e32 v64, v64, v78
	v_max_u32_e32 v6, v8, v6
	v_max_u32_e32 v55, v13, v46
	v_max_u32_e32 v63, v38, v62
	v_max_u32_e32 v43, v12, v42
	v_min_u32_e32 v94, v81, v92
	v_min_u32_e32 v90, v69, v89
	v_min_u32_e32 v13, v13, v46
	v_min_u32_e32 v38, v38, v62
	v_min_u32_e32 v12, v12, v42
	v_max_u32_e32 v5, v11, v4
	v_max_u32_e32 v3, v10, v2
	v_min_u32_e32 v56, v37, v50
	v_min_u32_e32 v40, v65, v32
	v_min_u32_e32 v48, v68, v31
	v_min_u32_e32 v8, v64, v6
	v_max_u32_e32 v47, v60, v44
	v_max_u32_e32 v39, v53, v35
	v_min_u32_e32 v59, v94, v58
	v_min_u32_e32 v51, v90, v41
	v_min_u32_e32 v57, v88, v49
	v_min_u32_e32 v9, v82, v7
	v_max_u32_e32 v46, v52, v13
	v_max_u32_e32 v42, v38, v12
	v_max_u32_e32 v36, v5, v3
	v_min_u32_e32 v78, v48, v8
	v_min_u32_e32 v4, v11, v4
	v_max_u32_e32 v11, v37, v50
	v_max_u32_e32 v32, v65, v32
	v_max_u32_e32 v31, v68, v31
	v_max_u32_e32 v6, v64, v6
	v_min_u32_e32 v3, v5, v3
	v_max_u32_e32 v5, v56, v40
	v_max_u32_e32 v8, v48, v8
	v_max_u32_e32 v61, v67, v55
	v_max_u32_e32 v45, v63, v43
	v_max_u32_e32 v54, v47, v39
	v_min_u32_e32 v83, v57, v9
	v_max_u32_e32 v62, v46, v42
	v_min_u32_e32 v69, v56, v40
	v_min_u32_e32 v55, v67, v55
	v_min_u32_e32 v43, v63, v43
	v_min_u32_e32 v44, v60, v44
	v_min_u32_e32 v35, v53, v35
	v_max_u32_e32 v58, v94, v58
	v_max_u32_e32 v41, v90, v41
	v_max_u32_e32 v49, v88, v49
	v_max_u32_e32 v7, v82, v7
	v_min_u32_e32 v13, v52, v13
	v_min_u32_e32 v12, v38, v12
	v_min_u32_e32 v2, v10, v2
	v_min_u32_e32 v37, v11, v32
	v_min_u32_e32 v50, v31, v6
	v_min_u32_e32 v39, v47, v39
	v_max_u32_e32 v47, v59, v51
	v_max_u32_e32 v9, v57, v9
	v_min_u32_e32 v42, v46, v42
	v_min_u32_e32 v40, v5, v8
	v_and_b32_e32 v34, 0xffffff00, v34
	v_max_u32_e32 v66, v61, v45
	v_min_u32_e32 v93, v59, v51
	v_max_u32_e32 v63, v55, v43
	v_max_u32_e32 v53, v44, v35
	v_min_u32_e32 v60, v58, v41
	v_min_u32_e32 v67, v49, v7
	v_max_u32_e32 v38, v13, v12
	v_max_u32_e32 v10, v4, v2
	v_min_u32_e32 v52, v37, v50
	v_min_u32_e32 v45, v61, v45
	v_min_u32_e32 v51, v47, v9
	v_max3_u32 v40, v42, v3, v40
	v_min_u32_e32 v43, v55, v43
	v_min_u32_e32 v35, v44, v35
	v_max_u32_e32 v41, v58, v41
	v_max_u32_e32 v7, v49, v7
	v_min_u32_e32 v2, v4, v2
	v_max_u32_e32 v4, v11, v32
	v_max_u32_e32 v6, v31, v6
	v_min_u32_e32 v3, v42, v3
	v_or_b32_e32 v25, 0x8f, v25
	v_or_b32_e32 v26, 0x8e, v26
	v_or_b32_e32 v27, 0x9f, v27
	v_or_b32_e32 v28, 0x9e, v28
	v_or_b32_e32 v29, 0xaf, v29
	v_or_b32_e32 v30, 0xae, v30
	v_or_b32_e32 v33, 0xbd, v33
	v_or_b32_e32 v34, 0xbe, v34
	v_max3_u32 v52, v38, v10, v52
	v_max3_u32 v51, v45, v39, v51
	v_min_u32_e32 v44, v41, v7
	v_min_u32_e32 v12, v13, v12
	v_min_u32_e32 v11, v4, v6
	v_min_u32_e32 v10, v38, v10
	v_min_u32_e32 v39, v45, v39
	v_max3_u32 v3, v3, v5, v8
	v_min_u32_e32 v8, v43, v35
	v_min_u32_e32 v91, v93, v83
	v_max3_u32 v44, v43, v35, v44
	v_max3_u32 v11, v12, v2, v11
	v_max3_u32 v10, v10, v37, v50
	v_max3_u32 v9, v39, v47, v9
	v_max3_u32 v7, v8, v41, v7
	v_min_u32_e32 v2, v12, v2
	v_max_u32_e32 v12, v23, v24
	v_min_u32_e32 v35, v34, v33
	v_min_u32_e32 v23, v23, v24
	v_max_u32_e32 v24, v34, v33
	v_max_u32_e32 v41, v29, v30
	v_min_u32_e32 v42, v27, v28
	v_min_u32_e32 v29, v29, v30
	v_max_u32_e32 v27, v27, v28
	v_max_u32_e32 v47, v25, v26
	v_min_u32_e32 v50, v22, v21
	v_min_u32_e32 v25, v25, v26
	v_max_u32_e32 v21, v22, v21
	v_max_u32_e32 v55, v20, v18
	v_min_u32_e32 v56, v17, v16
	v_min_u32_e32 v18, v20, v18
	v_max_u32_e32 v16, v17, v16
	v_max3_u32 v91, v66, v54, v91
	v_min_u32_e32 v48, v66, v54
	v_max_u32_e32 v39, v12, v35
	v_max_u32_e32 v33, v23, v24
	v_min_u32_e32 v43, v41, v42
	v_min_u32_e32 v28, v29, v27
	v_min_u32_e32 v12, v12, v35
	v_min_u32_e32 v23, v23, v24
	v_max_u32_e32 v35, v41, v42
	v_max_u32_e32 v27, v29, v27
	v_max_u32_e32 v54, v47, v50
	v_max_u32_e32 v22, v25, v21
	v_min_u32_e32 v57, v55, v56
	v_min_u32_e32 v17, v18, v16
	v_min_u32_e32 v47, v47, v50
	v_min_u32_e32 v21, v25, v21
	v_max_u32_e32 v50, v55, v56
	v_max_u32_e32 v16, v18, v16
	v_max_u32_e32 v34, v39, v33
	v_min_u32_e32 v30, v43, v28
	v_max_u32_e32 v24, v12, v23
	v_min_u32_e32 v29, v35, v27
	v_min_u32_e32 v33, v39, v33
	v_max_u32_e32 v28, v43, v28
	v_min_u32_e32 v12, v12, v23
	v_max_u32_e32 v23, v35, v27
	v_max_u32_e32 v26, v54, v22
	v_min_u32_e32 v20, v57, v17
	v_max_u32_e32 v25, v47, v21
	v_min_u32_e32 v18, v50, v16
	v_min_u32_e32 v22, v54, v22
	v_max_u32_e32 v17, v57, v17
	v_min_u32_e32 v21, v47, v21
	v_max_u32_e32 v16, v50, v16
	v_max_u32_e32 v45, v34, v30
	v_max_u32_e32 v41, v24, v29
	v_max_u32_e32 v39, v33, v28
	v_max_u32_e32 v27, v12, v23
	v_min_u32_e32 v58, v26, v20
	v_min_u32_e32 v55, v25, v18
	v_min_u32_e32 v54, v22, v17
	v_min_u32_e32 v47, v21, v16
	v_min_u32_e32 v30, v34, v30
	v_min_u32_e32 v24, v24, v29
	v_min_u32_e32 v28, v33, v28
	v_min_u32_e32 v12, v12, v23
	v_max_u32_e32 v20, v26, v20
	v_max_u32_e32 v18, v25, v18
	v_max_u32_e32 v17, v22, v17
	v_max_u32_e32 v16, v21, v16
	v_max_u32_e32 v42, v45, v41
	v_max_u32_e32 v35, v39, v27
	v_min_u32_e32 v56, v58, v55
	v_min_u32_e32 v50, v54, v47
	v_max_u32_e32 v29, v30, v24
	v_max_u32_e32 v23, v28, v12
	v_min_u32_e32 v25, v20, v18
	v_min_u32_e32 v21, v17, v16
	v_min_u32_e32 v41, v45, v41
	v_min_u32_e32 v27, v39, v27
	v_max_u32_e32 v45, v58, v55
	v_max_u32_e32 v47, v54, v47
	v_min_u32_e32 v24, v30, v24
	v_min_u32_e32 v12, v28, v12
	v_max_u32_e32 v18, v20, v18
	v_max_u32_e32 v16, v17, v16
	v_max_u32_e32 v43, v42, v35
	v_min_u32_e32 v57, v56, v50
	v_max_u32_e32 v33, v29, v23
	v_min_u32_e32 v22, v25, v21
	v_max_u32_e32 v39, v41, v27
	v_min_u32_e32 v54, v45, v47
	v_max_u32_e32 v28, v24, v12
	v_min_u32_e32 v17, v18, v16
	v_min_u32_e32 v35, v42, v35
	v_max_u32_e32 v42, v56, v50
	v_min_u32_e32 v23, v29, v23
	v_max_u32_e32 v21, v25, v21
	v_min_u32_e32 v27, v41, v27
	v_max_u32_e32 v41, v45, v47
	v_min_u32_e32 v12, v24, v12
	v_max_u32_e32 v16, v18, v16
	v_max_u32_e32 v59, v43, v57
	v_max_u32_e32 v26, v33, v22
	v_max_u32_e32 v55, v39, v54
	v_max_u32_e32 v20, v28, v17
	v_max_u32_e32 v50, v35, v42
	v_max_u32_e32 v25, v23, v21
	v_max_u32_e32 v45, v27, v41
	v_max_u32_e32 v18, v12, v16
	v_min_u32_e32 v43, v43, v57
	v_min_u32_e32 v22, v33, v22
	v_min_u32_e32 v39, v39, v54
	v_min_u32_e32 v17, v28, v17
	v_min_u32_e32 v35, v35, v42
	v_min_u32_e32 v21, v23, v21
	v_min_u32_e32 v27, v27, v41
	v_min_u32_e32 v12, v12, v16
	v_max_u32_e32 v33, v43, v22
	v_max_u32_e32 v28, v39, v17
	v_max_u32_e32 v23, v35, v21
	v_max_u32_e32 v16, v27, v12
	v_min_u32_e32 v22, v43, v22
	v_min_u32_e32 v17, v39, v17
	v_min_u32_e32 v21, v35, v21
	v_min_u32_e32 v12, v27, v12
	v_min_u32_e32 v80, v69, v78
	v_min_u32_e32 v82, v60, v67
	v_max_u32_e32 v34, v59, v26
	v_max_u32_e32 v30, v55, v20
	v_max_u32_e32 v29, v50, v25
	v_max_u32_e32 v24, v45, v18
	v_min_u32_e32 v26, v59, v26
	v_min_u32_e32 v20, v55, v20
	v_min_u32_e32 v25, v50, v25
	v_min_u32_e32 v18, v45, v18
	v_max_u32_e32 v39, v22, v17
	v_max_u32_e32 v27, v21, v12
	v_min_u32_e32 v17, v22, v17
	v_min_u32_e32 v12, v21, v12
	v_min_u32_e32 v21, v15, v14
	v_max3_u32 v80, v62, v36, v80
	v_max3_u32 v82, v63, v53, v82
	v_min_u32_e32 v36, v62, v36
	v_min_u32_e32 v53, v63, v53
	v_max_u32_e32 v58, v34, v30
	v_max_u32_e32 v47, v29, v24
	v_max_u32_e32 v54, v33, v28
	v_max_u32_e32 v41, v23, v16
	v_max_u32_e32 v55, v26, v20
	v_max_u32_e32 v45, v25, v18
	v_min_u32_e32 v30, v34, v30
	v_min_u32_e32 v24, v29, v24
	v_min_u32_e32 v28, v33, v28
	v_min_u32_e32 v16, v23, v16
	v_min_u32_e32 v20, v26, v20
	v_min_u32_e32 v18, v25, v18
	v_max3_u32 v21, v17, v12, v21
	v_min_u32_e32 v12, v17, v12
	v_max3_u32 v48, v48, v93, v83
	v_max3_u32 v36, v36, v69, v78
	v_max3_u32 v53, v53, v60, v67
	v_max3_u32 v2, v2, v4, v6
	v_max_u32_e32 v56, v58, v47
	v_max_u32_e32 v42, v54, v41
	v_max_u32_e32 v50, v55, v45
	v_max_u32_e32 v35, v39, v27
	v_max_u32_e32 v29, v30, v24
	v_max_u32_e32 v23, v28, v16
	v_max_u32_e32 v25, v20, v18
	v_min_u32_e32 v47, v58, v47
	v_min_u32_e32 v41, v54, v41
	v_min_u32_e32 v45, v55, v45
	v_min_u32_e32 v27, v39, v27
	v_min_u32_e32 v24, v30, v24
	v_min_u32_e32 v16, v28, v16
	v_min_u32_e32 v18, v20, v18
	v_max3_u32 v12, v12, v15, v14
	v_max_u32_e32 v49, v48, v36
	v_max_u32_e32 v37, v53, v10
	v_max_u32_e32 v5, v9, v3
	v_max_u32_e32 v4, v7, v2
	v_min_u32_e32 v57, v56, v42
	v_min_u32_e32 v43, v50, v35
	v_min_u32_e32 v33, v29, v23
	v_min_u32_e32 v22, v25, v21
	v_min_u32_e32 v54, v47, v41
	v_min_u32_e32 v39, v45, v27
	v_min_u32_e32 v28, v24, v16
	v_min_u32_e32 v14, v18, v12
	v_min_u32_e32 v36, v48, v36
	v_min_u32_e32 v10, v53, v10
	s_mov_b64 s[50:51], exec
	s_mov_b64 exec, -1
	s_waitcnt vmcnt(0)
	v_pk_mul_f32 v[200:201], v[200:201], s[96:97] op_sel_hi:[1,0]
	v_pk_mul_f32 v[202:203], v[202:203], s[96:97] op_sel_hi:[1,0]
	v_pk_mul_f32 v[204:205], v[204:205], s[96:97] op_sel_hi:[1,0]
	v_pk_mul_f32 v[206:207], v[206:207], s[96:97] op_sel_hi:[1,0]
	v_pk_mul_f32 v[208:209], v[208:209], s[96:97] op_sel_hi:[1,0]
	v_pk_mul_f32 v[210:211], v[210:211], s[96:97] op_sel_hi:[1,0]
	v_pk_mul_f32 v[212:213], v[212:213], s[96:97] op_sel_hi:[1,0]
	v_pk_mul_f32 v[214:215], v[214:215], s[96:97] op_sel_hi:[1,0]
	v_pk_mul_f32 v[216:217], v[216:217], s[96:97] op_sel_hi:[1,0]
	v_pk_mul_f32 v[218:219], v[218:219], s[96:97] op_sel_hi:[1,0]
	v_pk_mul_f32 v[220:221], v[220:221], s[96:97] op_sel_hi:[1,0]
	v_pk_mul_f32 v[222:223], v[222:223], s[96:97] op_sel_hi:[1,0]
	v_pk_mul_f32 v[224:225], v[224:225], s[96:97] op_sel_hi:[1,0]
	v_pk_mul_f32 v[226:227], v[226:227], s[96:97] op_sel_hi:[1,0]
	v_pk_mul_f32 v[228:229], v[228:229], s[96:97] op_sel_hi:[1,0]
	v_pk_mul_f32 v[230:231], v[230:231], s[96:97] op_sel_hi:[1,0]
	v_cvt_scalef32_pk_fp4_f32 v232, v200, v201, 1.0
	v_cvt_scalef32_pk_fp4_f32 v233, v208, v209, 1.0
	v_cvt_scalef32_pk_fp4_f32 v234, v216, v217, 1.0
	v_cvt_scalef32_pk_fp4_f32 v235, v224, v225, 1.0
	v_cvt_scalef32_pk_fp4_f32 v232, v202, v203, 1.0 op_sel:[0,0,1,0]
	v_cvt_scalef32_pk_fp4_f32 v233, v210, v211, 1.0 op_sel:[0,0,1,0]
	v_cvt_scalef32_pk_fp4_f32 v234, v218, v219, 1.0 op_sel:[0,0,1,0]
	v_cvt_scalef32_pk_fp4_f32 v235, v226, v227, 1.0 op_sel:[0,0,1,0]
	v_cvt_scalef32_pk_fp4_f32 v232, v204, v205, 1.0 op_sel:[0,0,0,1]
	v_cvt_scalef32_pk_fp4_f32 v233, v212, v213, 1.0 op_sel:[0,0,0,1]
	v_cvt_scalef32_pk_fp4_f32 v234, v220, v221, 1.0 op_sel:[0,0,0,1]
	v_cvt_scalef32_pk_fp4_f32 v235, v228, v229, 1.0 op_sel:[0,0,0,1]
	v_cvt_scalef32_pk_fp4_f32 v232, v206, v207, 1.0 op_sel:[0,0,1,1]
	v_cvt_scalef32_pk_fp4_f32 v233, v214, v215, 1.0 op_sel:[0,0,1,1]
	v_cvt_scalef32_pk_fp4_f32 v234, v222, v223, 1.0 op_sel:[0,0,1,1]
	v_cvt_scalef32_pk_fp4_f32 v235, v230, v231, 1.0 op_sel:[0,0,1,1]
	s_nop 0
	global_store_dwordx4 v[240:241], v[232:235], off
	v_lshl_add_u64 v[240:241], v[240:241], 0, v[246:247]
	s_mov_b64 exec, s[50:51]
	s_nop 4
	v_min_u32_e32 v3, v9, v3
	v_min_u32_e32 v2, v7, v2
	v_max_u32_e32 v42, v56, v42
	v_max_u32_e32 v35, v50, v35
	v_max_u32_e32 v23, v29, v23
	v_max_u32_e32 v21, v25, v21
	v_max_u32_e32 v41, v47, v41
	v_max_u32_e32 v27, v45, v27
	v_max_u32_e32 v16, v24, v16
	v_max_u32_e32 v12, v18, v12
	v_max_u32_e32 v81, v91, v80
	v_max_u32_e32 v64, v82, v52
	v_max_u32_e32 v46, v51, v40
	v_max_u32_e32 v13, v44, v11
	v_min_u32_e32 v59, v57, v43
	v_min_u32_e32 v26, v33, v22
	v_min_u32_e32 v55, v54, v39
	v_min_u32_e32 v15, v28, v14
	v_min_u32_e32 v30, v91, v80
	v_min_u32_e32 v52, v82, v52
	v_min_u32_e32 v40, v51, v40
	v_min_u32_e32 v11, v44, v11
	v_max_u32_e32 v48, v36, v10
	v_max_u32_e32 v7, v3, v2
	v_min_u32_e32 v50, v42, v35
	v_min_u32_e32 v25, v23, v21
	v_min_u32_e32 v45, v41, v27
	v_min_u32_e32 v18, v16, v12
	v_max_u32_e32 v43, v57, v43
	v_max_u32_e32 v22, v33, v22
	v_max_u32_e32 v39, v54, v39
	v_max_u32_e32 v14, v28, v14
	v_min_u32_e32 v10, v36, v10
	v_min_u32_e32 v2, v3, v2
	v_max_u32_e32 v35, v42, v35
	v_max_u32_e32 v21, v23, v21
	v_max_u32_e32 v27, v41, v27
	v_max_u32_e32 v12, v16, v12
	v_max_u32_e32 v65, v81, v64
	v_max_u32_e32 v31, v46, v13
	v_max_u32_e32 v38, v49, v37
	v_max_u32_e32 v6, v5, v4
	v_min_u32_e32 v34, v59, v26
	v_min_u32_e32 v17, v55, v15
	v_max_u32_e32 v58, v30, v52
	v_max_u32_e32 v44, v40, v11
	v_min_u32_e32 v29, v50, v25
	v_min_u32_e32 v24, v45, v18
	v_min_u32_e32 v56, v81, v64
	v_min_u32_e32 v13, v46, v13
	v_min_u32_e32 v37, v49, v37
	v_min_u32_e32 v4, v5, v4
	v_min_u32_e32 v33, v43, v22
	v_min_u32_e32 v28, v39, v14
	v_min_u32_e32 v30, v30, v52
	v_min_u32_e32 v11, v40, v11
	v_max_u32_e32 v3, v10, v2
	v_min_u32_e32 v23, v35, v21
	v_min_u32_e32 v16, v27, v12
	v_max_u32_e32 v26, v59, v26
	v_max_u32_e32 v15, v55, v15
	v_max_u32_e32 v25, v50, v25
	v_max_u32_e32 v18, v45, v18
	v_max_u32_e32 v22, v43, v22
	v_max_u32_e32 v14, v39, v14
	v_min_u32_e32 v2, v10, v2
	v_max_u32_e32 v10, v35, v21
	v_max_u32_e32 v12, v27, v12
	v_max_u32_e32 v32, v65, v31
	v_max_u32_e32 v8, v38, v6
	v_min_u32_e32 v20, v34, v17
	v_max_u32_e32 v51, v58, v44
	v_max_u32_e32 v9, v48, v7
	v_min_u32_e32 v47, v29, v24
	v_max_u32_e32 v46, v56, v13
	v_max_u32_e32 v5, v37, v4
	v_min_u32_e32 v49, v33, v28
	v_max_u32_e32 v40, v30, v11
	v_min_u32_e32 v36, v23, v16
	v_min_u32_e32 v31, v65, v31
	v_min_u32_e32 v6, v38, v6
	v_min_u32_e32 v38, v26, v15
	v_min_u32_e32 v44, v58, v44
	v_min_u32_e32 v7, v48, v7
	v_min_u32_e32 v45, v25, v18
	v_min_u32_e32 v13, v56, v13
	v_min_u32_e32 v4, v37, v4
	v_min_u32_e32 v37, v22, v14
	v_min_u32_e32 v11, v30, v11
	v_min_u32_e32 v21, v10, v12
	v_max3_u32 v20, v32, v8, v20
	v_max3_u32 v47, v51, v9, v47
	v_max3_u32 v49, v46, v5, v49
	v_max3_u32 v36, v40, v3, v36
	v_max3_u32 v38, v31, v6, v38
	v_max3_u32 v45, v44, v7, v45
	v_max3_u32 v37, v13, v4, v37
	v_max3_u32 v21, v11, v2, v21
	v_min_u32_e32 v8, v32, v8
	v_min_u32_e32 v9, v51, v9
	v_min_u32_e32 v5, v46, v5
	v_min_u32_e32 v3, v40, v3
	v_min_u32_e32 v6, v31, v6
	v_min_u32_e32 v7, v44, v7
	v_min_u32_e32 v4, v13, v4
	v_min_u32_e32 v2, v11, v2
	v_max3_u32 v8, v8, v34, v17
	v_max3_u32 v9, v9, v29, v24
	v_max3_u32 v5, v5, v33, v28
	v_max3_u32 v3, v3, v23, v16
	v_max3_u32 v6, v6, v26, v15
	v_max3_u32 v7, v7, v25, v18
	v_max3_u32 v4, v4, v22, v14
	v_max3_u32 v2, v2, v10, v12
	v_max_u32_e32 v53, v20, v47
	v_max_u32_e32 v41, v49, v36
	v_max_u32_e32 v48, v38, v45
	v_max_u32_e32 v27, v37, v21
	v_max_u32_e32 v17, v8, v9
	v_max_u32_e32 v16, v5, v3
	v_max_u32_e32 v15, v6, v7
	v_max_u32_e32 v10, v4, v2
	v_max_u32_e32 v42, v53, v41
	v_max_u32_e32 v30, v48, v27
	v_max_u32_e32 v23, v17, v16
	v_max_u32_e32 v11, v15, v10
	v_max_u32_e32 v35, v42, v30
	v_max_u32_e32 v12, v23, v11
	v_max_u32_e32 v13, v35, v12
	v_min_u32_e32 v12, v35, v12
	v_cmp_lt_i32_e32 vcc, -1, v12
	v_not_b32_e32 v32, v12
	v_min_u32_e32 v11, v23, v11
	v_cndmask_b32_e64 v14, v86, -1, vcc
	v_bitop3_b32 v12, v14, v12, s33 bitop3:0x78
	v_min_u32_e32 v14, v42, v30
	v_max_u32_e32 v18, v14, v11
	v_cmp_lt_i32_e32 vcc, -1, v18
	v_min_u32_e32 v11, v14, v11
	v_not_b32_e32 v33, v18
	v_cndmask_b32_e64 v22, v86, -1, vcc
	v_cmp_lt_i32_e32 vcc, -1, v11
	v_bitop3_b32 v18, v22, v18, s33 bitop3:0x78
	v_not_b32_e32 v34, v11
	v_cndmask_b32_e64 v14, v86, -1, vcc
	v_bitop3_b32 v11, v14, v11, s33 bitop3:0x78
	v_min_u32_e32 v14, v53, v41
	v_min_u32_e32 v22, v48, v27
	v_min_u32_e32 v16, v17, v16
	v_min_u32_e32 v10, v15, v10
	v_max_u32_e32 v23, v14, v22
	v_max_u32_e32 v15, v16, v10
	v_max_u32_e32 v17, v23, v15
	v_cmp_lt_i32_e32 vcc, -1, v17
	v_min_u32_e32 v15, v23, v15
	v_min_u32_e32 v14, v14, v22
	v_min_u32_e32 v10, v16, v10
	v_cndmask_b32_e64 v24, v86, -1, vcc
	v_cmp_lt_i32_e32 vcc, -1, v15
	v_max_u32_e32 v16, v14, v10
	v_min_u32_e32 v10, v14, v10
	v_cndmask_b32_e64 v23, v86, -1, vcc
	v_cmp_lt_i32_e32 vcc, -1, v16
	v_not_b32_e32 v30, v15
	v_bitop3_b32 v15, v23, v15, s33 bitop3:0x78
	v_cndmask_b32_e64 v22, v86, -1, vcc
	v_cmp_lt_i32_e32 vcc, -1, v10
	v_not_b32_e32 v35, v10
	v_min_u32_e32 v23, v38, v45
	v_cndmask_b32_e64 v14, v86, -1, vcc
	v_bitop3_b32 v14, v14, v10, s33 bitop3:0x78
	v_min_u32_e32 v10, v20, v47
	v_min_u32_e32 v20, v49, v36
	v_min_u32_e32 v21, v37, v21
	v_min_u32_e32 v8, v8, v9
	v_min_u32_e32 v3, v5, v3
	v_min_u32_e32 v6, v6, v7
	v_min_u32_e32 v2, v4, v2
	v_not_b32_e32 v29, v17
	v_bitop3_b32 v17, v24, v17, s33 bitop3:0x78
	v_not_b32_e32 v31, v16
	v_bitop3_b32 v16, v22, v16, s33 bitop3:0x78
	v_max_u32_e32 v22, v10, v20
	v_max_u32_e32 v24, v23, v21
	v_max_u32_e32 v5, v8, v3
	v_max_u32_e32 v4, v6, v2
	v_max_u32_e32 v25, v22, v24
	v_max_u32_e32 v7, v5, v4
	v_max_u32_e32 v9, v25, v7
	v_cmp_lt_i32_e32 vcc, -1, v9
	v_min_u32_e32 v7, v25, v7
	v_min_u32_e32 v22, v22, v24
	v_min_u32_e32 v4, v5, v4
	v_cndmask_b32_e64 v27, v86, -1, vcc
	v_cmp_lt_i32_e32 vcc, -1, v7
	v_max_u32_e32 v5, v22, v4
	v_not_b32_e32 v26, v9
	v_bitop3_b32 v9, v27, v9, s33 bitop3:0x78
	v_cndmask_b32_e64 v27, v86, -1, vcc
	v_cmp_lt_i32_e32 vcc, -1, v5
	v_min_u32_e32 v4, v22, v4
	v_not_b32_e32 v25, v7
	v_bitop3_b32 v7, v27, v7, s33 bitop3:0x78
	v_cndmask_b32_e64 v27, v86, -1, vcc
	v_cmp_lt_i32_e32 vcc, -1, v4
	v_not_b32_e32 v24, v5
	v_bitop3_b32 v27, v27, v5, s33 bitop3:0x78
	v_cndmask_b32_e64 v5, v86, -1, vcc
	v_not_b32_e32 v36, v4
	v_bitop3_b32 v22, v5, v4, s33 bitop3:0x78
	v_min_u32_e32 v4, v10, v20
	v_min_u32_e32 v5, v23, v21
	v_min_u32_e32 v3, v8, v3
	v_min_u32_e32 v2, v6, v2
	v_max_u32_e32 v10, v4, v5
	v_max_u32_e32 v6, v3, v2
	v_max_u32_e32 v8, v10, v6
	v_cmp_lt_i32_e32 vcc, -1, v8
	v_not_b32_e32 v20, v8
	v_min_u32_e32 v4, v4, v5
	v_cndmask_b32_e64 v21, v86, -1, vcc
	v_bitop3_b32 v8, v21, v8, s33 bitop3:0x78
	v_min_u32_e32 v21, v10, v6
	v_min_u32_e32 v2, v3, v2
	v_cmp_lt_i32_e32 vcc, -1, v21
	v_max_u32_e32 v37, v4, v2
	v_min_u32_e32 v39, v4, v2
	v_cndmask_b32_e64 v6, v86, -1, vcc
	v_cmp_lt_i32_e32 vcc, -1, v37
	v_and_b32_e32 v4, 0xffffff00, v13
	v_and_b32_e32 v5, 0xffffff00, v39
	v_cndmask_b32_e64 v3, v86, -1, vcc
	v_cmp_lt_i32_e32 vcc, -1, v13
	v_bitop3_b32 v38, v3, v37, s33 bitop3:0x78
	v_bitop3_b32 v23, v6, v21, s33 bitop3:0x78
	v_cndmask_b32_e64 v2, v86, -1, vcc
	v_cmp_lt_i32_e32 vcc, -1, v39
	v_xor_b32_e32 v40, v2, v4
	v_sub_f32_e32 v2, v40, v40
	v_cndmask_b32_e64 v3, v86, -1, vcc
	v_xor_b32_e32 v41, v3, v5
	v_mul_f32_e32 v2, 0x3fb8aa3b, v2
	v_sub_f32_e32 v3, v12, v40
	v_sub_f32_e32 v4, v18, v40
	v_exp_f32_e32 v2, v2
	v_mul_f32_e32 v3, 0x3fb8aa3b, v3
	v_mul_f32_e32 v4, 0x3fb8aa3b, v4
	v_exp_f32_e32 v3, v3
	v_exp_f32_e32 v10, v4
	v_sub_f32_e32 v4, v11, v40
	v_mul_f32_e32 v4, 0x3fb8aa3b, v4
	v_exp_f32_e32 v11, v4
	v_add_f32_e32 v4, 0, v2
	v_add_f32_e32 v4, v3, v4
	v_add_f32_e32 v4, v10, v4
	v_add_f32_e32 v6, v11, v4
	v_sub_f32_e32 v4, v17, v40
	v_mul_f32_e32 v4, 0x3fb8aa3b, v4
	v_sub_f32_e32 v5, v15, v40
	v_exp_f32_e32 v4, v4
	v_mul_f32_e32 v5, 0x3fb8aa3b, v5
	v_sub_f32_e32 v12, v16, v40
	v_not_b32_e32 v28, v13
	v_exp_f32_e32 v5, v5
	v_mul_f32_e32 v12, 0x3fb8aa3b, v12
	v_sub_f32_e32 v13, v14, v40
	v_exp_f32_e32 v12, v12
	v_mul_f32_e32 v13, 0x3fb8aa3b, v13
	v_exp_f32_e32 v13, v13
	v_add_f32_e32 v6, v4, v6
	v_add_f32_e32 v6, v5, v6
	v_add_f32_e32 v6, v12, v6
	v_add_f32_e32 v16, v13, v6
	v_sub_f32_e32 v6, v9, v40
	v_mul_f32_e32 v6, 0x3fb8aa3b, v6
	v_sub_f32_e32 v7, v7, v40
	v_sub_f32_e32 v9, v27, v40
	v_exp_f32_e32 v6, v6
	v_mul_f32_e32 v7, 0x3fb8aa3b, v7
	v_mul_f32_e32 v9, 0x3fb8aa3b, v9
	v_exp_f32_e32 v7, v7
	v_exp_f32_e32 v14, v9
	v_sub_f32_e32 v9, v22, v40
	v_mul_f32_e32 v9, 0x3fb8aa3b, v9
	v_exp_f32_e32 v15, v9
	v_add_f32_e32 v9, v6, v16
	v_add_f32_e32 v9, v7, v9
	v_add_f32_e32 v9, v14, v9
	v_sub_f32_e32 v8, v8, v40
	v_add_f32_e32 v18, v15, v9
	v_mul_f32_e32 v8, 0x3fb8aa3b, v8
	v_sub_f32_e32 v9, v23, v40
	v_exp_f32_e32 v8, v8
	v_mul_f32_e32 v9, 0x3fb8aa3b, v9
	v_sub_f32_e32 v16, v38, v40
	v_exp_f32_e32 v9, v9
	v_mul_f32_e32 v16, 0x3fb8aa3b, v16
	v_sub_f32_e32 v17, v41, v40
	v_exp_f32_e32 v16, v16
	v_mul_f32_e32 v17, 0x3fb8aa3b, v17
	v_exp_f32_e32 v17, v17
	v_add_f32_e32 v18, v8, v18
	v_add_f32_e32 v18, v9, v18
	v_add_f32_e32 v18, v16, v18
	v_add_f32_e32 v18, v17, v18
	v_div_scale_f32 v22, s[38:39], v18, v18, 1.0
	v_rcp_f32_e32 v23, v22
	v_not_b32_e32 v27, v37
	v_not_b32_e32 v37, v39
	v_not_b32_e32 v21, v21
	v_fma_f32 v38, -v22, v23, 1.0
	v_fmac_f32_e32 v23, v38, v23
	v_div_scale_f32 v38, vcc, 1.0, v18, 1.0
	v_mul_f32_e32 v39, v38, v23
	v_fma_f32 v40, -v22, v39, v38
	v_fmac_f32_e32 v39, v40, v23
	v_fma_f32 v22, -v22, v39, v38
	v_div_fmas_f32 v22, v22, v23, v39
	v_div_fixup_f32 v18, v22, v18, 1.0
	v_lshlrev_b32_e32 v22, 4, v37
	v_lshlrev_b32_e32 v23, 8, v37
	v_lshlrev_b32_e32 v38, 4, v27
	v_lshlrev_b32_e32 v27, 8, v27
	v_lshlrev_b32_e32 v39, 4, v21
	v_lshlrev_b32_e32 v21, 8, v21
	v_lshlrev_b32_e32 v40, 4, v20
	v_lshlrev_b32_e32 v20, 8, v20
	v_and_b32_e32 v22, 0xf00, v22
	v_and_b32_e32 v23, 0xf00, v23
	v_lshlrev_b32_e32 v37, 2, v87
	v_and_b32_e32 v38, 0xf00, v38
	v_and_b32_e32 v27, 0xf00, v27
	v_and_b32_e32 v39, 0xf00, v39
	v_and_b32_e32 v21, 0xf00, v21
	v_and_b32_e32 v40, 0xf00, v40
	v_and_b32_e32 v20, 0xf00, v20
	v_add_u32_e32 v22, v19, v22
	v_add3_u32 v23, s26, v23, v37
	v_add_u32_e32 v38, v19, v38
	v_add3_u32 v27, s26, v27, v37
	v_add_u32_e32 v39, v19, v39
	v_add3_u32 v21, s26, v21, v37
	v_add_u32_e32 v40, v19, v40
	v_add3_u32 v20, s26, v20, v37
	ds_read_b32 v22, v22
	ds_read_b32 v23, v23 offset:4096
	ds_read_b32 v38, v38
	ds_read_b32 v27, v27 offset:4096
	ds_read_b32 v39, v39
	ds_read_b32 v21, v21 offset:4096
	ds_read_b32 v40, v40
	ds_read_b32 v20, v20 offset:4096
	s_waitcnt lgkmcnt(6)
	v_lshl_add_u32 v23, v22, 7, v23
	s_waitcnt lgkmcnt(4)
	v_lshl_add_u32 v22, v38, 7, v27
	s_waitcnt lgkmcnt(2)
	v_lshl_add_u32 v21, v39, 7, v21
	v_lshlrev_b32_e32 v27, 4, v36
	v_lshlrev_b32_e32 v36, 8, v36
	v_lshlrev_b32_e32 v38, 4, v24
	v_lshlrev_b32_e32 v24, 8, v24
	v_lshlrev_b32_e32 v39, 4, v25
	v_lshlrev_b32_e32 v25, 8, v25
	v_lshlrev_b32_e32 v41, 4, v26
	v_and_b32_e32 v27, 0xf00, v27
	v_and_b32_e32 v36, 0xf00, v36
	v_and_b32_e32 v38, 0xf00, v38
	v_and_b32_e32 v24, 0xf00, v24
	v_and_b32_e32 v39, 0xf00, v39
	v_and_b32_e32 v25, 0xf00, v25
	v_and_b32_e32 v41, 0xf00, v41
	v_lshlrev_b32_e32 v26, 8, v26
	v_add_u32_e32 v27, v19, v27
	v_add3_u32 v36, s26, v36, v37
	v_add_u32_e32 v38, v19, v38
	v_add3_u32 v24, s26, v24, v37
	v_add_u32_e32 v39, v19, v39
	v_add3_u32 v25, s26, v25, v37
	v_add_u32_e32 v41, v19, v41
	v_and_b32_e32 v26, 0xf00, v26
	v_add3_u32 v26, s26, v26, v37
	ds_read_b32 v27, v27
	ds_read_b32 v36, v36 offset:4096
	ds_read_b32 v38, v38
	ds_read_b32 v24, v24 offset:4096
	ds_read_b32 v39, v39
	ds_read_b32 v25, v25 offset:4096
	ds_read_b32 v41, v41
	ds_read_b32 v42, v26 offset:4096
	s_waitcnt lgkmcnt(8)
	v_lshl_add_u32 v20, v40, 7, v20
	s_waitcnt lgkmcnt(6)
	v_lshl_add_u32 v27, v27, 7, v36
	s_waitcnt lgkmcnt(4)
	v_lshl_add_u32 v26, v38, 7, v24
	s_waitcnt lgkmcnt(2)
	v_lshl_add_u32 v25, v39, 7, v25
	v_lshlrev_b32_e32 v36, 4, v35
	v_lshlrev_b32_e32 v35, 8, v35
	v_lshlrev_b32_e32 v38, 4, v31
	v_lshlrev_b32_e32 v39, 4, v30
	v_lshlrev_b32_e32 v40, 4, v29
	v_and_b32_e32 v36, 0xf00, v36
	v_and_b32_e32 v35, 0xf00, v35
	v_and_b32_e32 v38, 0xf00, v38
	v_lshlrev_b32_e32 v31, 8, v31
	v_and_b32_e32 v39, 0xf00, v39
	v_lshlrev_b32_e32 v30, 8, v30
	v_and_b32_e32 v40, 0xf00, v40
	v_lshlrev_b32_e32 v29, 8, v29
	v_add_u32_e32 v36, v19, v36
	v_add3_u32 v35, s26, v35, v37
	v_add_u32_e32 v38, v19, v38
	v_and_b32_e32 v31, 0xf00, v31
	v_add_u32_e32 v39, v19, v39
	v_and_b32_e32 v30, 0xf00, v30
	v_add_u32_e32 v40, v19, v40
	v_and_b32_e32 v29, 0xf00, v29
	s_waitcnt lgkmcnt(0)
	v_lshl_add_u32 v24, v41, 7, v42
	v_add3_u32 v31, s26, v31, v37
	v_add3_u32 v30, s26, v30, v37
	v_add3_u32 v29, s26, v29, v37
	ds_read_b32 v36, v36
	ds_read_b32 v35, v35 offset:4096
	ds_read_b32 v38, v38
	ds_read_b32 v41, v31 offset:4096
	ds_read_b32 v39, v39
	ds_read_b32 v42, v30 offset:4096
	ds_read_b32 v40, v40
	ds_read_b32 v43, v29 offset:4096
	s_waitcnt lgkmcnt(6)
	v_lshl_add_u32 v31, v36, 7, v35
	s_waitcnt lgkmcnt(4)
	v_lshl_add_u32 v30, v38, 7, v41
	s_waitcnt lgkmcnt(2)
	v_lshl_add_u32 v29, v39, 7, v42
	v_lshlrev_b32_e32 v35, 4, v34
	v_lshlrev_b32_e32 v34, 8, v34
	v_lshlrev_b32_e32 v36, 4, v33
	v_lshlrev_b32_e32 v33, 8, v33
	v_lshlrev_b32_e32 v38, 4, v32
	v_lshlrev_b32_e32 v32, 8, v32
	v_lshlrev_b32_e32 v39, 4, v28
	v_and_b32_e32 v35, 0xf00, v35
	v_and_b32_e32 v34, 0xf00, v34
	v_and_b32_e32 v36, 0xf00, v36
	v_and_b32_e32 v33, 0xf00, v33
	v_and_b32_e32 v38, 0xf00, v38
	v_and_b32_e32 v32, 0xf00, v32
	v_and_b32_e32 v39, 0xf00, v39
	v_lshlrev_b32_e32 v28, 8, v28
	v_add_u32_e32 v35, v19, v35
	v_add3_u32 v34, s26, v34, v37
	v_add_u32_e32 v36, v19, v36
	v_add3_u32 v33, s26, v33, v37
	v_add_u32_e32 v38, v19, v38
	v_add3_u32 v32, s26, v32, v37
	v_add_u32_e32 v19, v19, v39
	v_and_b32_e32 v28, 0xf00, v28
	v_add3_u32 v28, s26, v28, v37
	ds_read_b32 v35, v35
	ds_read_b32 v34, v34 offset:4096
	ds_read_b32 v36, v36
	ds_read_b32 v33, v33 offset:4096
	ds_read_b32 v37, v38
	ds_read_b32 v32, v32 offset:4096
	ds_read_b32 v19, v19
	ds_read_b32 v38, v28 offset:4096
	s_waitcnt lgkmcnt(6)
	v_lshl_add_u32 v35, v35, 7, v34
	s_waitcnt lgkmcnt(4)
	v_lshl_add_u32 v34, v36, 7, v33
	v_or_b32_e32 v36, s36, v87
	s_waitcnt lgkmcnt(2)
	v_lshl_add_u32 v33, v37, 7, v32
	v_ashrrev_i32_e32 v37, 31, v36
	v_lshlrev_b64 v[36:37], 9, v[36:37]
	s_waitcnt lgkmcnt(0)
	v_lshl_add_u32 v32, v19, 7, v38
	v_lshl_add_u64 v[38:39], s[8:9], 0, v[36:37]
	v_lshl_add_u64 v[38:39], v[38:39], 0, s[14:15]
	v_lshl_add_u64 v[36:37], s[10:11], 0, v[36:37]
	v_lshl_add_u64 v[36:37], v[36:37], 0, s[14:15]
	global_store_dwordx4 v[38:39], v[32:35], off
	v_pk_mul_f32 v[12:13], v[12:13], v[18:19] op_sel_hi:[1,0]
	v_lshl_add_u32 v28, v40, 7, v43
	v_pk_mul_f32 v[34:35], v[10:11], v[18:19] op_sel_hi:[1,0]
	v_pk_mul_f32 v[32:33], v[2:3], v[18:19] op_sel_hi:[1,0]
	v_pk_mul_f32 v[10:11], v[4:5], v[18:19] op_sel_hi:[1,0]
	v_pk_mul_f32 v[4:5], v[14:15], v[18:19] op_sel_hi:[1,0]
	v_pk_mul_f32 v[2:3], v[6:7], v[18:19] op_sel_hi:[1,0]
	global_store_dwordx4 v[36:37], v[32:35], off
	global_store_dwordx4 v[38:39], v[28:31], off offset:16
	global_store_dwordx4 v[36:37], v[10:13], off offset:16
	global_store_dwordx4 v[38:39], v[24:27], off offset:32
	global_store_dwordx4 v[36:37], v[2:5], off offset:32
	global_store_dwordx4 v[38:39], v[20:23], off offset:48
	s_nop 0
	v_pk_mul_f32 v[4:5], v[16:17], v[18:19] op_sel_hi:[1,0]
	v_pk_mul_f32 v[2:3], v[8:9], v[18:19] op_sel_hi:[1,0]
	global_store_dwordx4 v[36:37], v[2:5], off offset:48
	s_branch .LBB0_795

.LBB0_802:
	s_bitcmp1_b32 s98, 0
	s_cselect_b32 s52, s94, s92
	s_cselect_b32 s53, s95, s93
	s_cselect_b32 s54, s48, s46
	s_cselect_b32 s55, s49, s47
	s_mov_b32 s96, 0x42580000
	s_cselect_b32 s96, 0x40b66666, s96
	s_add_i32 s98, s98, 1
	v_mbcnt_lo_u32_b32 v248, -1, 0
	v_mbcnt_hi_u32_b32 v248, -1, v248
	v_lshlrev_b32_e32 v236, 6, v248
	v_mov_b32_e32 v237, 0
	v_lshl_add_u64 v[236:237], s[52:53], 0, v[236:237]
	v_lshl_add_u64 v[238:239], v[236:237], 0, v[250:251]
	v_lshlrev_b32_e32 v240, 4, v248
	v_mov_b32_e32 v241, 0
	v_lshl_add_u64 v[240:241], s[54:55], 0, v[240:241]
	s_lshr_b32 s12, s19, 3
	s_and_b32 s12, s12, 0x7fffff8
	v_mov_b32_e32 v87, v1
	s_or_b32 s12, s12, s91
	s_lshl_b32 s31, s12, 5
	v_and_b32_e32 v4, 31, v87
	v_or_b32_e32 v2, s31, v4
	v_ashrrev_i32_e32 v3, 31, v2
	v_ashrrev_i32_e32 v118, 5, v87
	v_lshlrev_b64 v[2:3], 12, v[2:3]
	v_lshl_add_u64 v[6:7], s[2:3], 0, v[2:3]
	v_lshlrev_b32_e32 v2, 3, v118
	v_ashrrev_i32_e32 v3, 31, v2
	s_bfe_u32 s30, s19, 0x30003
	v_lshlrev_b64 v[8:9], 1, v[2:3]
	v_lshlrev_b32_e32 v4, 8, v4
	v_lshl_add_u64 v[2:3], s[6:7], 0, v[8:9]
	v_lshl_or_b32 v78, s30, 16, v4
	v_lshl_add_u64 v[80:81], v[2:3], 0, v[78:79]
	global_load_dwordx4 v[2:5], v[80:81], off
	s_lshl_b32 s12, s30, 9
	v_lshl_add_u64 v[6:7], v[6:7], 0, s[12:13]
	v_lshl_add_u64 v[82:83], v[6:7], 0, v[8:9]
	global_load_dwordx4 v[34:37], v[82:83], off
	global_load_dwordx4 v[88:91], v[80:81], off offset:32
	global_load_dwordx4 v[92:95], v[80:81], off offset:64
	global_load_dwordx4 v[96:99], v[80:81], off offset:96
	global_load_dwordx4 v[100:103], v[80:81], off offset:128
	global_load_dwordx4 v[104:107], v[80:81], off offset:160
	global_load_dwordx4 v[108:111], v[80:81], off offset:192
	global_load_dwordx4 v[66:69], v[80:81], off offset:224
	global_load_dwordx4 v[62:65], v[82:83], off offset:32
	global_load_dwordx4 v[58:61], v[82:83], off offset:64
	global_load_dwordx4 v[54:57], v[82:83], off offset:96
	global_load_dwordx4 v[50:53], v[82:83], off offset:128
	global_load_dwordx4 v[46:49], v[82:83], off offset:160
	global_load_dwordx4 v[42:45], v[82:83], off offset:192
	global_load_dwordx4 v[38:41], v[82:83], off offset:224
	v_add_co_u32_e32 v116, vcc, s20, v80
	v_lshlrev_b32_e32 v146, 2, v118
	s_nop 0
	v_addc_co_u32_e32 v117, vcc, 0, v81, vcc
	global_load_dwordx4 v[6:9], v[116:117], off
	global_load_dwordx4 v[112:115], v[116:117], off offset:32
	v_add_co_u32_e32 v136, vcc, s22, v80
	v_sub_u32_e32 v78, 0x66, v146
	s_nop 0
	v_addc_co_u32_e32 v137, vcc, 0, v81, vcc
	v_sub_u32_e32 v144, 6, v146
	v_sub_u32_e32 v145, 5, v146
	s_waitcnt vmcnt(0)
	v_mfma_f32_32x32x16_bf16 v[18:33], v[2:5], v[34:37], 0
	v_mfma_f32_32x32x16_bf16 v[18:33], v[88:91], v[62:65], v[18:33]
	global_load_dwordx4 v[88:91], v[116:117], off offset:64
	v_mfma_f32_32x32x16_bf16 v[2:17], v[6:9], v[34:37], 0
	v_mfma_f32_32x32x16_bf16 v[2:17], v[112:115], v[62:65], v[2:17]
	global_load_dwordx4 v[112:115], v[116:117], off offset:160
	v_mfma_f32_32x32x16_bf16 v[18:33], v[92:95], v[58:61], v[18:33]
	global_load_dwordx4 v[92:95], v[116:117], off offset:96
	s_waitcnt vmcnt(0)
	v_mfma_f32_32x32x16_bf16 v[2:17], v[88:91], v[58:61], v[2:17]
	global_load_dwordx4 v[88:91], v[116:117], off offset:128
	v_mfma_f32_32x32x16_bf16 v[18:33], v[96:99], v[54:57], v[18:33]
	v_sub_u32_e32 v98, 0x7e, v146
	v_or_b32_e32 v99, 3, v146
	v_sub_u32_e32 v97, 0x77, v146
	v_sub_u32_e32 v96, 0x76, v146
	v_sub_u32_e32 v99, 0x7f, v99
	v_mfma_f32_32x32x16_bf16 v[18:33], v[100:103], v[50:53], v[18:33]
	v_sub_u32_e32 v100, 0x7f, v146
	v_mfma_f32_32x32x16_bf16 v[18:33], v[104:107], v[46:49], v[18:33]
	v_mfma_f32_32x32x16_bf16 v[18:33], v[108:111], v[42:45], v[18:33]
	global_load_dwordx4 v[104:107], v[116:117], off offset:192
	global_load_dwordx4 v[108:111], v[116:117], off offset:224
	v_mfma_f32_32x32x16_bf16 v[2:17], v[92:95], v[54:57], v[2:17]
	v_sub_u32_e32 v95, 0x75, v146
	v_sub_u32_e32 v94, 0x74, v146
	v_sub_u32_e32 v93, 0x6f, v146
	v_sub_u32_e32 v92, 0x6e, v146
	v_mfma_f32_32x32x16_bf16 v[18:33], v[66:69], v[38:41], v[18:33]
	s_waitcnt vmcnt(0)
	v_mfma_f32_32x32x16_bf16 v[2:17], v[88:91], v[50:53], v[2:17]
	s_nop 9
	v_not_b32_e32 v66, v18
	v_or_b32_e32 v67, 0x80000000, v18
	v_cmp_gt_i32_e32 vcc, 0, v18
	v_or_b32_e32 v91, 2, v146
	v_not_b32_e32 v68, v19
	v_or_b32_e32 v69, 0x80000000, v19
	v_cndmask_b32_e32 v18, v67, v66, vcc
	v_mfma_f32_32x32x16_bf16 v[2:17], v[112:115], v[46:49], v[2:17]
	global_load_dwordx4 v[112:115], v[136:137], off
	v_cmp_gt_i32_e32 vcc, 0, v19
	v_sub_u32_e32 v101, 0x7f, v91
	v_not_b32_e32 v91, v20
	v_or_b32_e32 v102, 0x80000000, v20
	v_cndmask_b32_e32 v19, v69, v68, vcc
	v_cmp_gt_i32_e32 vcc, 0, v20
	v_not_b32_e32 v103, v21
	v_or_b32_e32 v116, 0x80000000, v21
	v_cndmask_b32_e32 v20, v102, v91, vcc
	v_cmp_gt_i32_e32 vcc, 0, v21
	v_not_b32_e32 v117, v22
	v_or_b32_e32 v118, 0x80000000, v22
	v_cndmask_b32_e32 v21, v116, v103, vcc
	v_cmp_gt_i32_e32 vcc, 0, v22
	v_not_b32_e32 v119, v23
	v_or_b32_e32 v120, 0x80000000, v23
	v_cndmask_b32_e32 v22, v118, v117, vcc
	v_cmp_gt_i32_e32 vcc, 0, v23
	v_not_b32_e32 v121, v24
	v_or_b32_e32 v122, 0x80000000, v24
	v_cndmask_b32_e32 v23, v120, v119, vcc
	global_load_dwordx4 v[116:119], v[136:137], off offset:32
	v_cmp_gt_i32_e32 vcc, 0, v24
	v_not_b32_e32 v123, v25
	v_or_b32_e32 v124, 0x80000000, v25
	v_cndmask_b32_e32 v24, v122, v121, vcc
	v_cmp_gt_i32_e32 vcc, 0, v25
	v_not_b32_e32 v125, v26
	v_or_b32_e32 v126, 0x80000000, v26
	v_cndmask_b32_e32 v25, v124, v123, vcc
	global_load_dwordx4 v[120:123], v[136:137], off offset:64
	v_cmp_gt_i32_e32 vcc, 0, v26
	v_not_b32_e32 v127, v27
	v_or_b32_e32 v128, 0x80000000, v27
	v_cndmask_b32_e32 v26, v126, v125, vcc
	v_cmp_gt_i32_e32 vcc, 0, v27
	v_mfma_f32_32x32x16_bf16 v[2:17], v[104:107], v[42:45], v[2:17]
	v_not_b32_e32 v129, v28
	v_cndmask_b32_e32 v27, v128, v127, vcc
	global_load_dwordx4 v[124:127], v[136:137], off offset:96
	v_or_b32_e32 v130, 0x80000000, v28
	v_cmp_gt_i32_e32 vcc, 0, v28
	v_not_b32_e32 v131, v29
	v_or_b32_e32 v132, 0x80000000, v29
	v_cndmask_b32_e32 v28, v130, v129, vcc
	v_cmp_gt_i32_e32 vcc, 0, v29
	v_mfma_f32_32x32x16_bf16 v[2:17], v[108:111], v[38:41], v[2:17]
	v_not_b32_e32 v133, v30
	v_cndmask_b32_e32 v29, v132, v131, vcc
	global_load_dwordx4 v[128:131], v[136:137], off offset:128
	v_or_b32_e32 v134, 0x80000000, v30
	v_cmp_gt_i32_e32 vcc, 0, v30
	v_not_b32_e32 v135, v31
	v_or_b32_e32 v138, 0x80000000, v31
	v_cndmask_b32_e32 v30, v134, v133, vcc
	v_cmp_gt_i32_e32 vcc, 0, v31
	v_and_or_b32 v159, v18, s17, v100
	v_and_or_b32 v168, v19, s17, v98
	v_cndmask_b32_e32 v31, v138, v135, vcc
	v_not_b32_e32 v18, v32
	v_or_b32_e32 v19, 0x80000000, v32
	v_cmp_gt_i32_e32 vcc, 0, v32
	v_sub_u32_e32 v102, 0x65, v146
	v_sub_u32_e32 v103, 0x64, v146
	v_cndmask_b32_e32 v18, v19, v18, vcc
	v_and_or_b32 v181, v18, s17, v102
	v_not_b32_e32 v18, v33
	v_or_b32_e32 v19, 0x80000000, v33
	v_cmp_gt_i32_e32 vcc, 0, v33
	global_load_dwordx4 v[132:135], v[136:137], off offset:160
	v_sub_u32_e32 v104, 0x5f, v146
	v_cndmask_b32_e32 v18, v19, v18, vcc
	v_and_or_b32 v182, v18, s17, v103
	v_not_b32_e32 v18, v2
	v_or_b32_e32 v19, 0x80000000, v2
	v_cmp_gt_i32_e32 vcc, 0, v2
	v_sub_u32_e32 v105, 0x5e, v146
	v_sub_u32_e32 v107, 0x5d, v146
	v_cndmask_b32_e32 v2, v19, v18, vcc
	v_and_or_b32 v147, v2, s17, v104
	v_not_b32_e32 v2, v3
	v_or_b32_e32 v18, 0x80000000, v3
	v_cmp_gt_i32_e32 vcc, 0, v3
	v_or_b32_e32 v3, 0x80000000, v4
	v_sub_u32_e32 v106, 0x5c, v146
	v_cndmask_b32_e32 v2, v18, v2, vcc
	v_and_or_b32 v148, v2, s17, v105
	v_not_b32_e32 v2, v4
	v_cmp_gt_i32_e32 vcc, 0, v4
	v_or_b32_e32 v19, 0x80000000, v6
	v_sub_u32_e32 v108, 0x57, v146
	v_cndmask_b32_e32 v2, v3, v2, vcc
	v_and_or_b32 v149, v2, s17, v107
	v_not_b32_e32 v2, v5
	v_or_b32_e32 v3, 0x80000000, v5
	v_cmp_gt_i32_e32 vcc, 0, v5
	v_sub_u32_e32 v90, 0x6d, v146
	v_sub_u32_e32 v89, 0x6c, v146
	v_cndmask_b32_e32 v18, v3, v2, vcc
	global_load_dwordx4 v[2:5], v[136:137], off offset:192
	v_and_or_b32 v150, v18, s17, v106
	global_load_dwordx4 v[136:139], v[136:137], off offset:224
	v_not_b32_e32 v18, v6
	v_cmp_gt_i32_e32 vcc, 0, v6
	v_sub_u32_e32 v88, 0x67, v146
	v_and_or_b32 v169, v20, s17, v101
	v_cndmask_b32_e32 v6, v19, v18, vcc
	v_and_or_b32 v151, v6, s17, v108
	v_not_b32_e32 v6, v7
	v_or_b32_e32 v18, 0x80000000, v7
	v_cmp_gt_i32_e32 vcc, 0, v7
	v_and_or_b32 v170, v21, s17, v99
	v_and_or_b32 v171, v22, s17, v97
	v_and_or_b32 v172, v23, s17, v96
	v_and_or_b32 v173, v24, s17, v95
	v_and_or_b32 v174, v25, s17, v94
	v_and_or_b32 v175, v26, s17, v93
	v_and_or_b32 v176, v27, s17, v92
	v_and_or_b32 v177, v28, s17, v90
	v_and_or_b32 v178, v29, s17, v89
	v_and_or_b32 v179, v30, s17, v88
	v_and_or_b32 v180, v31, s17, v78
	v_cndmask_b32_e32 v6, v18, v6, vcc
	v_sub_u32_e32 v109, 0x56, v146
	s_waitcnt vmcnt(0)
	v_mfma_f32_32x32x16_bf16 v[18:33], v[112:115], v[34:37], 0
	v_and_or_b32 v152, v6, s17, v109
	v_not_b32_e32 v6, v8
	v_or_b32_e32 v7, 0x80000000, v8
	v_cmp_gt_i32_e32 vcc, 0, v8
	v_sub_u32_e32 v110, 0x55, v146
	v_sub_u32_e32 v111, 0x54, v146
	v_cndmask_b32_e32 v6, v7, v6, vcc
	v_and_or_b32 v153, v6, s17, v110
	v_not_b32_e32 v6, v9
	v_or_b32_e32 v7, 0x80000000, v9
	v_cmp_gt_i32_e32 vcc, 0, v9
	v_sub_u32_e32 v68, 0x4f, v146
	v_sub_u32_e32 v91, 0x4e, v146
	v_cndmask_b32_e32 v6, v7, v6, vcc
	v_and_or_b32 v154, v6, s17, v111
	v_not_b32_e32 v6, v10
	v_or_b32_e32 v7, 0x80000000, v10
	v_cmp_gt_i32_e32 vcc, 0, v10
	v_mfma_f32_32x32x16_bf16 v[18:33], v[116:119], v[62:65], v[18:33]
	v_sub_u32_e32 v69, 0x4d, v146
	v_cndmask_b32_e32 v6, v7, v6, vcc
	v_and_or_b32 v155, v6, s17, v68
	v_not_b32_e32 v6, v11
	v_or_b32_e32 v7, 0x80000000, v11
	v_cmp_gt_i32_e32 vcc, 0, v11
	v_sub_u32_e32 v67, 0x4c, v146
	v_mfma_f32_32x32x16_bf16 v[18:33], v[120:123], v[58:61], v[18:33]
	v_cndmask_b32_e32 v6, v7, v6, vcc
	v_and_or_b32 v156, v6, s17, v91
	v_not_b32_e32 v6, v12
	v_or_b32_e32 v7, 0x80000000, v12
	v_cmp_gt_i32_e32 vcc, 0, v12
	v_sub_u32_e32 v66, 0x47, v146
	v_sub_u32_e32 v112, 0x46, v146
	v_cndmask_b32_e32 v6, v7, v6, vcc
	v_and_or_b32 v157, v6, s17, v69
	v_not_b32_e32 v6, v13
	v_or_b32_e32 v7, 0x80000000, v13
	v_cmp_gt_i32_e32 vcc, 0, v13
	v_mfma_f32_32x32x16_bf16 v[18:33], v[124:127], v[54:57], v[18:33]
	v_or_b32_e32 v13, 0x80000000, v15
	v_cndmask_b32_e32 v6, v7, v6, vcc
	v_and_or_b32 v158, v6, s17, v67
	v_not_b32_e32 v6, v14
	v_or_b32_e32 v7, 0x80000000, v14
	v_cmp_gt_i32_e32 vcc, 0, v14
	v_sub_u32_e32 v113, 0x45, v146
	v_mfma_f32_32x32x16_bf16 v[18:33], v[128:131], v[50:53], v[18:33]
	v_cndmask_b32_e32 v12, v7, v6, vcc
	v_add_co_u32_e32 v10, vcc, s23, v80
	v_and_or_b32 v183, v12, s17, v66
	s_nop 0
	v_addc_co_u32_e32 v11, vcc, 0, v81, vcc
	global_load_dwordx4 v[6:9], v[10:11], off
	global_load_dwordx4 v[124:127], v[10:11], off offset:32
	global_load_dwordx4 v[128:131], v[10:11], off offset:64
	v_mfma_f32_32x32x16_bf16 v[18:33], v[132:135], v[46:49], v[18:33]
	global_load_dwordx4 v[132:135], v[10:11], off offset:96
	global_load_dwordx4 v[140:143], v[10:11], off offset:128
	global_load_dwordx4 v[160:163], v[10:11], off offset:192
	global_load_dwordx4 v[164:167], v[10:11], off offset:224
	v_not_b32_e32 v12, v15
	v_cmp_gt_i32_e32 vcc, 0, v15
	v_sub_u32_e32 v114, 0x44, v146
	v_mfma_f32_32x32x16_bf16 v[18:33], v[2:5], v[42:45], v[18:33]
	v_cndmask_b32_e32 v12, v13, v12, vcc
	v_and_or_b32 v184, v12, s17, v112
	v_not_b32_e32 v12, v16
	v_or_b32_e32 v13, 0x80000000, v16
	v_cmp_gt_i32_e32 vcc, 0, v16
	v_or_b32_e32 v2, 0x80000000, v17
	v_sub_u32_e32 v115, 63, v146
	v_mfma_f32_32x32x16_bf16 v[18:33], v[136:139], v[38:41], v[18:33]
	global_load_dwordx4 v[136:139], v[10:11], off offset:160
	v_cndmask_b32_e32 v12, v13, v12, vcc
	v_and_or_b32 v185, v12, s17, v113
	v_not_b32_e32 v12, v17
	v_cmp_gt_i32_e32 vcc, 0, v17
	v_sub_u32_e32 v116, 62, v146
	v_sub_u32_e32 v117, 61, v146
	v_cndmask_b32_e32 v2, v2, v12, vcc
	v_and_or_b32 v186, v2, s17, v114
	s_nop 2
	v_not_b32_e32 v2, v18
	v_or_b32_e32 v3, 0x80000000, v18
	v_cmp_gt_i32_e32 vcc, 0, v18
	v_sub_u32_e32 v118, 60, v146
	v_sub_u32_e32 v119, 55, v146
	v_cndmask_b32_e32 v2, v3, v2, vcc
	v_and_or_b32 v18, v2, s17, v115
	v_not_b32_e32 v2, v19
	v_or_b32_e32 v3, 0x80000000, v19
	v_cmp_gt_i32_e32 vcc, 0, v19
	v_sub_u32_e32 v120, 54, v146
	v_sub_u32_e32 v121, 53, v146
	v_cndmask_b32_e32 v2, v3, v2, vcc
	v_and_or_b32 v19, v2, s17, v116
	v_not_b32_e32 v2, v20
	v_or_b32_e32 v3, 0x80000000, v20
	v_cmp_gt_i32_e32 vcc, 0, v20
	v_sub_u32_e32 v122, 52, v146
	v_sub_u32_e32 v123, 47, v146
	v_cndmask_b32_e32 v2, v3, v2, vcc
	v_and_or_b32 v20, v2, s17, v117
	v_not_b32_e32 v2, v21
	v_or_b32_e32 v3, 0x80000000, v21
	v_cmp_gt_i32_e32 vcc, 0, v21
	s_nop 1
	v_cndmask_b32_e32 v2, v3, v2, vcc
	v_and_or_b32 v21, v2, s17, v118
	v_not_b32_e32 v2, v22
	v_or_b32_e32 v3, 0x80000000, v22
	v_cmp_gt_i32_e32 vcc, 0, v22
	s_nop 1
	v_cndmask_b32_e32 v2, v3, v2, vcc
	v_and_or_b32 v22, v2, s17, v119
	v_not_b32_e32 v2, v23
	v_or_b32_e32 v3, 0x80000000, v23
	v_cmp_gt_i32_e32 vcc, 0, v23
	s_nop 1
	v_cndmask_b32_e32 v2, v3, v2, vcc
	v_and_or_b32 v23, v2, s17, v120
	v_not_b32_e32 v2, v24
	v_or_b32_e32 v3, 0x80000000, v24
	v_cmp_gt_i32_e32 vcc, 0, v24
	s_nop 1
	v_cndmask_b32_e32 v2, v3, v2, vcc
	v_and_or_b32 v24, v2, s17, v121
	v_not_b32_e32 v2, v25
	v_or_b32_e32 v3, 0x80000000, v25
	v_cmp_gt_i32_e32 vcc, 0, v25
	s_nop 1
	v_cndmask_b32_e32 v25, v3, v2, vcc
	s_waitcnt vmcnt(0)
	v_mfma_f32_32x32x16_bf16 v[2:17], v[6:9], v[34:37], 0
	v_not_b32_e32 v34, v26
	v_or_b32_e32 v35, 0x80000000, v26
	v_cmp_gt_i32_e32 vcc, 0, v26
	v_and_or_b32 v25, v25, s17, v122
	v_max_u32_e32 v36, v169, v170
	v_cndmask_b32_e32 v26, v35, v34, vcc
	v_not_b32_e32 v34, v27
	v_mfma_f32_32x32x16_bf16 v[2:17], v[124:127], v[62:65], v[2:17]
	v_or_b32_e32 v35, 0x80000000, v27
	v_cmp_gt_i32_e32 vcc, 0, v27
	v_sub_u32_e32 v124, 46, v146
	v_sub_u32_e32 v125, 45, v146
	v_cndmask_b32_e32 v27, v35, v34, vcc
	v_not_b32_e32 v34, v28
	v_or_b32_e32 v35, 0x80000000, v28
	v_mfma_f32_32x32x16_bf16 v[2:17], v[128:131], v[58:61], v[2:17]
	v_cmp_gt_i32_e32 vcc, 0, v28
	v_sub_u32_e32 v126, 44, v146
	v_sub_u32_e32 v127, 39, v146
	v_cndmask_b32_e32 v28, v35, v34, vcc
	v_not_b32_e32 v34, v29
	v_or_b32_e32 v35, 0x80000000, v29
	v_cmp_gt_i32_e32 vcc, 0, v29
	v_mfma_f32_32x32x16_bf16 v[2:17], v[132:135], v[54:57], v[2:17]
	v_sub_u32_e32 v128, 38, v146
	v_cndmask_b32_e32 v29, v35, v34, vcc
	v_not_b32_e32 v34, v30
	v_or_b32_e32 v35, 0x80000000, v30
	v_cmp_gt_i32_e32 vcc, 0, v30
	v_sub_u32_e32 v129, 37, v146
	v_sub_u32_e32 v130, 36, v146
	v_mfma_f32_32x32x16_bf16 v[2:17], v[140:143], v[50:53], v[2:17]
	v_cndmask_b32_e32 v30, v35, v34, vcc
	v_not_b32_e32 v34, v31
	v_or_b32_e32 v35, 0x80000000, v31
	v_cmp_gt_i32_e32 vcc, 0, v31
	v_sub_u32_e32 v131, 31, v146
	v_sub_u32_e32 v132, 30, v146
	v_cndmask_b32_e32 v31, v35, v34, vcc
	v_mfma_f32_32x32x16_bf16 v[2:17], v[136:139], v[46:49], v[2:17]
	v_not_b32_e32 v34, v32
	v_or_b32_e32 v35, 0x80000000, v32
	v_cmp_gt_i32_e32 vcc, 0, v32
	v_sub_u32_e32 v133, 29, v146
	v_sub_u32_e32 v134, 28, v146
	v_cndmask_b32_e32 v32, v35, v34, vcc
	v_not_b32_e32 v34, v33
	v_mfma_f32_32x32x16_bf16 v[2:17], v[160:163], v[42:45], v[2:17]
	v_or_b32_e32 v35, 0x80000000, v33
	v_cmp_gt_i32_e32 vcc, 0, v33
	v_sub_u32_e32 v135, 23, v146
	v_sub_u32_e32 v136, 22, v146
	v_cndmask_b32_e32 v33, v35, v34, vcc
	v_sub_u32_e32 v137, 21, v146
	v_sub_u32_e32 v138, 20, v146
	v_mfma_f32_32x32x16_bf16 v[2:17], v[164:167], v[38:41], v[2:17]
	v_sub_u32_e32 v139, 15, v146
	v_sub_u32_e32 v140, 14, v146
	v_sub_u32_e32 v141, 13, v146
	v_sub_u32_e32 v142, 12, v146
	v_sub_u32_e32 v143, 7, v146
	v_sub_u32_e32 v146, 4, v146
	v_and_or_b32 v26, v26, s17, v123
	s_nop 4
	v_not_b32_e32 v34, v2
	v_or_b32_e32 v35, 0x80000000, v2
	v_cmp_gt_i32_e32 vcc, 0, v2
	v_and_or_b32 v27, v27, s17, v124
	global_load_dwordx4 v[200:203], v[236:237], off
	global_load_dwordx4 v[204:207], v[236:237], off offset:16
	global_load_dwordx4 v[208:211], v[236:237], off offset:32
	global_load_dwordx4 v[212:215], v[236:237], off offset:48
	global_load_dwordx4 v[216:219], v[238:239], off
	global_load_dwordx4 v[220:223], v[238:239], off offset:16
	global_load_dwordx4 v[224:227], v[238:239], off offset:32
	global_load_dwordx4 v[228:231], v[238:239], off offset:48
	v_lshl_add_u64 v[236:237], v[236:237], 0, v[244:245]
	v_lshl_add_u64 v[238:239], v[238:239], 0, v[244:245]
	v_and_or_b32 v28, v28, s17, v125
	v_cndmask_b32_e32 v2, v35, v34, vcc
	v_not_b32_e32 v34, v3
	v_or_b32_e32 v35, 0x80000000, v3
	v_cmp_gt_i32_e32 vcc, 0, v3
	v_and_or_b32 v29, v29, s17, v126
	v_and_or_b32 v30, v30, s17, v127
	v_cndmask_b32_e32 v3, v35, v34, vcc
	v_not_b32_e32 v34, v4
	v_or_b32_e32 v35, 0x80000000, v4
	v_cmp_gt_i32_e32 vcc, 0, v4
	v_and_or_b32 v31, v31, s17, v128
	v_and_or_b32 v32, v32, s17, v129
	v_cndmask_b32_e32 v4, v35, v34, vcc
	v_not_b32_e32 v34, v5
	v_or_b32_e32 v35, 0x80000000, v5
	v_cmp_gt_i32_e32 vcc, 0, v5
	v_and_or_b32 v33, v33, s17, v130
	v_and_or_b32 v2, v2, s17, v131
	v_cndmask_b32_e32 v5, v35, v34, vcc
	v_not_b32_e32 v34, v6
	v_or_b32_e32 v35, 0x80000000, v6
	v_cmp_gt_i32_e32 vcc, 0, v6
	v_and_or_b32 v3, v3, s17, v132
	v_and_or_b32 v4, v4, s17, v133
	v_cndmask_b32_e32 v6, v35, v34, vcc
	v_not_b32_e32 v34, v7
	v_or_b32_e32 v35, 0x80000000, v7
	v_cmp_gt_i32_e32 vcc, 0, v7
	v_and_or_b32 v5, v5, s17, v134
	v_and_or_b32 v6, v6, s17, v135
	v_cndmask_b32_e32 v7, v35, v34, vcc
	v_not_b32_e32 v34, v8
	v_or_b32_e32 v35, 0x80000000, v8
	v_cmp_gt_i32_e32 vcc, 0, v8
	v_and_or_b32 v7, v7, s17, v136
	v_min_u32_e32 v37, v169, v170
	v_cndmask_b32_e32 v8, v35, v34, vcc
	v_not_b32_e32 v34, v9
	v_or_b32_e32 v35, 0x80000000, v9
	v_cmp_gt_i32_e32 vcc, 0, v9
	v_and_or_b32 v8, v8, s17, v137
	v_max_u32_e32 v38, v171, v172
	v_cndmask_b32_e32 v9, v35, v34, vcc
	v_not_b32_e32 v34, v10
	v_or_b32_e32 v35, 0x80000000, v10
	v_cmp_gt_i32_e32 vcc, 0, v10
	v_and_or_b32 v9, v9, s17, v138
	v_min_u32_e32 v39, v171, v172
	v_cndmask_b32_e32 v10, v35, v34, vcc
	v_not_b32_e32 v34, v11
	v_or_b32_e32 v35, 0x80000000, v11
	v_cmp_gt_i32_e32 vcc, 0, v11
	v_and_or_b32 v10, v10, s17, v139
	v_max_u32_e32 v40, v173, v174
	v_cndmask_b32_e32 v11, v35, v34, vcc
	v_not_b32_e32 v34, v12
	v_or_b32_e32 v35, 0x80000000, v12
	v_cmp_gt_i32_e32 vcc, 0, v12
	v_and_or_b32 v11, v11, s17, v140
	v_min_u32_e32 v41, v173, v174
	v_cndmask_b32_e32 v12, v35, v34, vcc
	v_not_b32_e32 v34, v13
	v_or_b32_e32 v35, 0x80000000, v13
	v_cmp_gt_i32_e32 vcc, 0, v13
	v_and_or_b32 v12, v12, s17, v141
	v_max_u32_e32 v42, v175, v176
	v_cndmask_b32_e32 v13, v35, v34, vcc
	v_not_b32_e32 v34, v14
	v_or_b32_e32 v35, 0x80000000, v14
	v_cmp_gt_i32_e32 vcc, 0, v14
	v_and_or_b32 v13, v13, s17, v142
	v_min_u32_e32 v43, v175, v176
	v_cndmask_b32_e32 v14, v35, v34, vcc
	v_not_b32_e32 v34, v15
	v_or_b32_e32 v35, 0x80000000, v15
	v_cmp_gt_i32_e32 vcc, 0, v15
	v_and_or_b32 v14, v14, s17, v143
	v_max_u32_e32 v44, v177, v178
	v_cndmask_b32_e32 v15, v35, v34, vcc
	v_not_b32_e32 v34, v16
	v_or_b32_e32 v35, 0x80000000, v16
	v_cmp_gt_i32_e32 vcc, 0, v16
	v_and_or_b32 v15, v15, s17, v144
	v_min_u32_e32 v45, v177, v178
	v_cndmask_b32_e32 v16, v35, v34, vcc
	v_not_b32_e32 v34, v17
	v_or_b32_e32 v35, 0x80000000, v17
	v_cmp_gt_i32_e32 vcc, 0, v17
	v_and_or_b32 v16, v16, s17, v145
	v_max_u32_e32 v46, v179, v180
	v_cndmask_b32_e32 v17, v35, v34, vcc
	v_and_or_b32 v17, v17, s17, v146
	v_max_u32_e32 v34, v159, v168
	v_min_u32_e32 v35, v159, v168
	v_min_u32_e32 v47, v179, v180
	v_max_u32_e32 v48, v181, v182
	v_min_u32_e32 v49, v181, v182
	v_max_u32_e32 v58, v147, v148
	v_min_u32_e32 v59, v147, v148
	v_max_u32_e32 v60, v149, v150
	v_min_u32_e32 v61, v149, v150
	v_max_u32_e32 v62, v151, v152
	v_min_u32_e32 v63, v151, v152
	v_max_u32_e32 v64, v153, v154
	v_min_u32_e32 v65, v153, v154
	v_max_u32_e32 v147, v155, v156
	v_min_u32_e32 v148, v155, v156
	v_max_u32_e32 v149, v157, v158
	v_min_u32_e32 v150, v157, v158
	v_max_u32_e32 v151, v183, v184
	v_min_u32_e32 v152, v183, v184
	v_max_u32_e32 v153, v185, v186
	v_min_u32_e32 v154, v185, v186
	v_max_u32_e32 v163, v18, v19
	v_min_u32_e32 v18, v18, v19
	v_max_u32_e32 v19, v20, v21
	v_min_u32_e32 v20, v20, v21
	v_max_u32_e32 v21, v22, v23
	v_min_u32_e32 v22, v22, v23
	v_max_u32_e32 v23, v24, v25
	v_min_u32_e32 v24, v24, v25
	v_max_u32_e32 v25, v26, v27
	v_min_u32_e32 v26, v26, v27
	v_max_u32_e32 v27, v28, v29
	v_min_u32_e32 v28, v28, v29
	v_max_u32_e32 v29, v30, v31
	v_min_u32_e32 v30, v30, v31
	v_max_u32_e32 v31, v32, v33
	v_min_u32_e32 v32, v32, v33
	v_max_u32_e32 v171, v2, v3
	v_min_u32_e32 v2, v2, v3
	v_max_u32_e32 v3, v4, v5
	v_min_u32_e32 v4, v4, v5
	v_max_u32_e32 v5, v6, v7
	v_min_u32_e32 v6, v6, v7
	v_max_u32_e32 v7, v8, v9
	v_min_u32_e32 v8, v8, v9
	v_max_u32_e32 v9, v10, v11
	v_min_u32_e32 v10, v10, v11
	v_max_u32_e32 v11, v12, v13
	v_min_u32_e32 v12, v12, v13
	v_max_u32_e32 v13, v14, v15
	v_min_u32_e32 v14, v14, v15
	v_max_u32_e32 v15, v16, v17
	v_min_u32_e32 v16, v16, v17
	v_max_u32_e32 v50, v34, v37
	v_min_u32_e32 v34, v34, v37
	v_max_u32_e32 v37, v35, v36
	v_min_u32_e32 v35, v35, v36
	v_max_u32_e32 v36, v38, v41
	v_min_u32_e32 v38, v38, v41
	v_max_u32_e32 v41, v39, v40
	v_min_u32_e32 v39, v39, v40
	v_max_u32_e32 v40, v42, v45
	v_min_u32_e32 v42, v42, v45
	v_max_u32_e32 v45, v43, v44
	v_min_u32_e32 v43, v43, v44
	v_max_u32_e32 v44, v46, v49
	v_min_u32_e32 v46, v46, v49
	v_max_u32_e32 v49, v47, v48
	v_min_u32_e32 v47, v47, v48
	v_max_u32_e32 v155, v58, v61
	v_min_u32_e32 v58, v58, v61
	v_max_u32_e32 v61, v59, v60
	v_min_u32_e32 v59, v59, v60
	v_max_u32_e32 v60, v62, v65
	v_min_u32_e32 v62, v62, v65
	v_max_u32_e32 v65, v63, v64
	v_min_u32_e32 v63, v63, v64
	v_max_u32_e32 v64, v147, v150
	v_min_u32_e32 v147, v147, v150
	v_max_u32_e32 v150, v148, v149
	v_min_u32_e32 v148, v148, v149
	v_max_u32_e32 v149, v151, v154
	v_min_u32_e32 v151, v151, v154
	v_max_u32_e32 v154, v152, v153
	v_min_u32_e32 v152, v152, v153
	v_max_u32_e32 v33, v163, v20
	v_min_u32_e32 v20, v163, v20
	v_max_u32_e32 v163, v18, v19
	v_min_u32_e32 v18, v18, v19
	v_max_u32_e32 v19, v21, v24
	v_min_u32_e32 v21, v21, v24
	v_max_u32_e32 v24, v22, v23
	v_min_u32_e32 v22, v22, v23
	v_max_u32_e32 v23, v25, v28
	v_min_u32_e32 v25, v25, v28
	v_max_u32_e32 v28, v26, v27
	v_min_u32_e32 v26, v26, v27
	v_max_u32_e32 v27, v29, v32
	v_min_u32_e32 v29, v29, v32
	v_max_u32_e32 v32, v30, v31
	v_min_u32_e32 v30, v30, v31
	v_max_u32_e32 v17, v171, v4
	v_min_u32_e32 v4, v171, v4
	v_max_u32_e32 v171, v2, v3
	v_min_u32_e32 v2, v2, v3
	v_max_u32_e32 v3, v5, v8
	v_min_u32_e32 v5, v5, v8
	v_max_u32_e32 v8, v6, v7
	v_min_u32_e32 v6, v6, v7
	v_max_u32_e32 v7, v9, v12
	v_min_u32_e32 v9, v9, v12
	v_max_u32_e32 v12, v10, v11
	v_min_u32_e32 v10, v10, v11
	v_max_u32_e32 v11, v13, v16
	v_min_u32_e32 v13, v13, v16
	v_max_u32_e32 v16, v14, v15
	v_min_u32_e32 v14, v14, v15
	v_max_u32_e32 v48, v50, v37
	v_min_u32_e32 v37, v50, v37
	v_max_u32_e32 v50, v34, v35
	v_min_u32_e32 v34, v34, v35
	v_max_u32_e32 v35, v38, v39
	v_min_u32_e32 v38, v38, v39
	v_max_u32_e32 v39, v36, v41
	v_min_u32_e32 v36, v36, v41
	v_max_u32_e32 v41, v40, v45
	v_min_u32_e32 v40, v40, v45
	v_max_u32_e32 v45, v42, v43
	v_min_u32_e32 v42, v42, v43
	v_max_u32_e32 v43, v46, v47
	v_min_u32_e32 v46, v46, v47
	v_max_u32_e32 v47, v44, v49
	v_min_u32_e32 v44, v44, v49
	v_max_u32_e32 v153, v155, v61
	v_min_u32_e32 v61, v155, v61
	v_max_u32_e32 v155, v58, v59
	v_min_u32_e32 v58, v58, v59
	v_max_u32_e32 v59, v62, v63
	v_min_u32_e32 v62, v62, v63
	v_max_u32_e32 v63, v60, v65
	v_min_u32_e32 v60, v60, v65
	v_max_u32_e32 v65, v64, v150
	v_min_u32_e32 v64, v64, v150
	v_max_u32_e32 v150, v147, v148
	v_min_u32_e32 v147, v147, v148
	v_max_u32_e32 v148, v151, v152
	v_min_u32_e32 v151, v151, v152
	v_max_u32_e32 v152, v149, v154
	v_min_u32_e32 v149, v149, v154
	v_max_u32_e32 v31, v33, v163
	v_min_u32_e32 v33, v33, v163
	v_max_u32_e32 v163, v20, v18
	v_min_u32_e32 v18, v20, v18
	v_max_u32_e32 v20, v21, v22
	v_min_u32_e32 v21, v21, v22
	v_max_u32_e32 v22, v19, v24
	v_min_u32_e32 v19, v19, v24
	v_max_u32_e32 v24, v23, v28
	v_min_u32_e32 v23, v23, v28
	v_max_u32_e32 v28, v25, v26
	v_min_u32_e32 v25, v25, v26
	v_max_u32_e32 v26, v29, v30
	v_min_u32_e32 v29, v29, v30
	v_max_u32_e32 v30, v27, v32
	v_min_u32_e32 v27, v27, v32
	v_max_u32_e32 v15, v17, v171
	v_min_u32_e32 v17, v17, v171
	v_max_u32_e32 v171, v4, v2
	v_min_u32_e32 v2, v4, v2
	v_max_u32_e32 v4, v5, v6
	v_min_u32_e32 v5, v5, v6
	v_max_u32_e32 v6, v3, v8
	v_min_u32_e32 v3, v3, v8
	v_max_u32_e32 v8, v7, v12
	v_min_u32_e32 v7, v7, v12
	v_max_u32_e32 v12, v9, v10
	v_min_u32_e32 v9, v9, v10
	v_max_u32_e32 v10, v13, v14
	v_min_u32_e32 v13, v13, v14
	v_max_u32_e32 v14, v11, v16
	v_min_u32_e32 v11, v11, v16
	v_max_u32_e32 v49, v48, v38
	v_min_u32_e32 v38, v48, v38
	v_max_u32_e32 v48, v37, v35
	v_min_u32_e32 v35, v37, v35
	v_max_u32_e32 v37, v50, v36
	v_min_u32_e32 v36, v50, v36
	v_max_u32_e32 v50, v34, v39
	v_min_u32_e32 v34, v34, v39
	v_max_u32_e32 v39, v41, v46
	v_min_u32_e32 v41, v41, v46
	v_max_u32_e32 v46, v40, v43
	v_min_u32_e32 v40, v40, v43
	v_max_u32_e32 v43, v45, v44
	v_min_u32_e32 v44, v45, v44
	v_max_u32_e32 v45, v42, v47
	v_min_u32_e32 v42, v42, v47
	v_max_u32_e32 v154, v153, v62
	v_min_u32_e32 v62, v153, v62
	v_max_u32_e32 v153, v61, v59
	s_waitcnt vmcnt(0)
	v_pk_mul_f32 v[200:201], v[200:201], s[96:97] op_sel_hi:[1,0]
	v_pk_mul_f32 v[202:203], v[202:203], s[96:97] op_sel_hi:[1,0]
	v_pk_mul_f32 v[204:205], v[204:205], s[96:97] op_sel_hi:[1,0]
	v_pk_mul_f32 v[206:207], v[206:207], s[96:97] op_sel_hi:[1,0]
	v_pk_mul_f32 v[208:209], v[208:209], s[96:97] op_sel_hi:[1,0]
	v_pk_mul_f32 v[210:211], v[210:211], s[96:97] op_sel_hi:[1,0]
	v_pk_mul_f32 v[212:213], v[212:213], s[96:97] op_sel_hi:[1,0]
	v_pk_mul_f32 v[214:215], v[214:215], s[96:97] op_sel_hi:[1,0]
	v_pk_mul_f32 v[216:217], v[216:217], s[96:97] op_sel_hi:[1,0]
	v_pk_mul_f32 v[218:219], v[218:219], s[96:97] op_sel_hi:[1,0]
	v_pk_mul_f32 v[220:221], v[220:221], s[96:97] op_sel_hi:[1,0]
	v_pk_mul_f32 v[222:223], v[222:223], s[96:97] op_sel_hi:[1,0]
	v_pk_mul_f32 v[224:225], v[224:225], s[96:97] op_sel_hi:[1,0]
	v_pk_mul_f32 v[226:227], v[226:227], s[96:97] op_sel_hi:[1,0]
	v_pk_mul_f32 v[228:229], v[228:229], s[96:97] op_sel_hi:[1,0]
	v_pk_mul_f32 v[230:231], v[230:231], s[96:97] op_sel_hi:[1,0]
	v_cvt_scalef32_pk_fp4_f32 v232, v200, v201, 1.0
	v_cvt_scalef32_pk_fp4_f32 v233, v208, v209, 1.0
	v_cvt_scalef32_pk_fp4_f32 v234, v216, v217, 1.0
	v_cvt_scalef32_pk_fp4_f32 v235, v224, v225, 1.0
	v_cvt_scalef32_pk_fp4_f32 v232, v202, v203, 1.0 op_sel:[0,0,1,0]
	v_cvt_scalef32_pk_fp4_f32 v233, v210, v211, 1.0 op_sel:[0,0,1,0]
	v_cvt_scalef32_pk_fp4_f32 v234, v218, v219, 1.0 op_sel:[0,0,1,0]
	v_cvt_scalef32_pk_fp4_f32 v235, v226, v227, 1.0 op_sel:[0,0,1,0]
	v_cvt_scalef32_pk_fp4_f32 v232, v204, v205, 1.0 op_sel:[0,0,0,1]
	v_cvt_scalef32_pk_fp4_f32 v233, v212, v213, 1.0 op_sel:[0,0,0,1]
	v_cvt_scalef32_pk_fp4_f32 v234, v220, v221, 1.0 op_sel:[0,0,0,1]
	v_cvt_scalef32_pk_fp4_f32 v235, v228, v229, 1.0 op_sel:[0,0,0,1]
	v_cvt_scalef32_pk_fp4_f32 v232, v206, v207, 1.0 op_sel:[0,0,1,1]
	v_cvt_scalef32_pk_fp4_f32 v233, v214, v215, 1.0 op_sel:[0,0,1,1]
	v_cvt_scalef32_pk_fp4_f32 v234, v222, v223, 1.0 op_sel:[0,0,1,1]
	v_cvt_scalef32_pk_fp4_f32 v235, v230, v231, 1.0 op_sel:[0,0,1,1]
	s_nop 0
	global_store_dwordx4 v[240:241], v[232:235], off
	v_lshl_add_u64 v[240:241], v[240:241], 0, v[246:247]
	global_load_dwordx4 v[200:203], v[236:237], off
	global_load_dwordx4 v[204:207], v[236:237], off offset:16
	global_load_dwordx4 v[208:211], v[236:237], off offset:32
	global_load_dwordx4 v[212:215], v[236:237], off offset:48
	global_load_dwordx4 v[216:219], v[238:239], off
	global_load_dwordx4 v[220:223], v[238:239], off offset:16
	global_load_dwordx4 v[224:227], v[238:239], off offset:32
	global_load_dwordx4 v[228:231], v[238:239], off offset:48
	v_lshl_add_u64 v[236:237], v[236:237], 0, v[244:245]
	v_lshl_add_u64 v[238:239], v[238:239], 0, v[244:245]
	v_min_u32_e32 v59, v61, v59
	v_max_u32_e32 v61, v155, v60
	v_min_u32_e32 v60, v155, v60
	v_max_u32_e32 v155, v58, v63
	v_min_u32_e32 v58, v58, v63
	v_max_u32_e32 v63, v65, v151
	v_min_u32_e32 v65, v65, v151
	v_max_u32_e32 v151, v64, v148
	v_min_u32_e32 v64, v64, v148
	v_max_u32_e32 v148, v150, v149
	v_min_u32_e32 v149, v150, v149
	v_max_u32_e32 v150, v147, v152
	v_min_u32_e32 v147, v147, v152
	v_max_u32_e32 v32, v31, v21
	v_min_u32_e32 v21, v31, v21
	v_max_u32_e32 v31, v33, v20
	v_min_u32_e32 v20, v33, v20
	v_max_u32_e32 v33, v163, v19
	v_min_u32_e32 v19, v163, v19
	v_max_u32_e32 v163, v18, v22
	v_min_u32_e32 v18, v18, v22
	v_max_u32_e32 v22, v24, v29
	v_min_u32_e32 v24, v24, v29
	v_max_u32_e32 v29, v23, v26
	v_min_u32_e32 v23, v23, v26
	v_max_u32_e32 v26, v28, v27
	v_min_u32_e32 v27, v28, v27
	v_max_u32_e32 v28, v25, v30
	v_min_u32_e32 v25, v25, v30
	v_max_u32_e32 v16, v15, v5
	v_min_u32_e32 v5, v15, v5
	v_max_u32_e32 v15, v17, v4
	v_min_u32_e32 v4, v17, v4
	v_max_u32_e32 v17, v171, v3
	v_min_u32_e32 v3, v171, v3
	v_max_u32_e32 v171, v2, v6
	v_min_u32_e32 v2, v2, v6
	v_max_u32_e32 v6, v8, v13
	v_min_u32_e32 v8, v8, v13
	v_max_u32_e32 v13, v7, v10
	v_min_u32_e32 v7, v7, v10
	v_max_u32_e32 v10, v12, v11
	v_min_u32_e32 v11, v12, v11
	v_max_u32_e32 v12, v9, v14
	v_min_u32_e32 v9, v9, v14
	v_max_u32_e32 v47, v49, v37
	v_min_u32_e32 v37, v49, v37
	v_max_u32_e32 v49, v48, v50
	v_min_u32_e32 v48, v48, v50
	v_max_u32_e32 v50, v38, v36
	v_min_u32_e32 v36, v38, v36
	v_max_u32_e32 v38, v35, v34
	v_min_u32_e32 v34, v35, v34
	v_max_u32_e32 v35, v41, v44
	v_min_u32_e32 v41, v41, v44
	v_max_u32_e32 v44, v40, v42
	v_min_u32_e32 v40, v40, v42
	v_max_u32_e32 v42, v39, v43
	v_min_u32_e32 v39, v39, v43
	v_max_u32_e32 v43, v46, v45
	v_min_u32_e32 v45, v46, v45
	v_max_u32_e32 v152, v154, v61
	v_min_u32_e32 v61, v154, v61
	v_max_u32_e32 v154, v153, v155
	v_min_u32_e32 v153, v153, v155
	v_max_u32_e32 v155, v62, v60
	v_min_u32_e32 v60, v62, v60
	v_max_u32_e32 v62, v59, v58
	v_min_u32_e32 v58, v59, v58
	v_max_u32_e32 v59, v65, v149
	v_min_u32_e32 v65, v65, v149
	v_max_u32_e32 v149, v64, v147
	v_min_u32_e32 v64, v64, v147
	v_max_u32_e32 v147, v63, v148
	v_min_u32_e32 v63, v63, v148
	v_max_u32_e32 v148, v151, v150
	v_min_u32_e32 v150, v151, v150
	v_max_u32_e32 v30, v32, v33
	v_min_u32_e32 v32, v32, v33
	v_max_u32_e32 v33, v31, v163
	v_min_u32_e32 v31, v31, v163
	v_max_u32_e32 v163, v21, v19
	v_min_u32_e32 v19, v21, v19
	v_max_u32_e32 v21, v20, v18
	v_min_u32_e32 v18, v20, v18
	v_max_u32_e32 v20, v24, v27
	v_min_u32_e32 v24, v24, v27
	v_max_u32_e32 v27, v23, v25
	v_min_u32_e32 v23, v23, v25
	v_max_u32_e32 v25, v22, v26
	v_min_u32_e32 v22, v22, v26
	v_max_u32_e32 v26, v29, v28
	v_min_u32_e32 v28, v29, v28
	v_max_u32_e32 v14, v16, v17
	v_min_u32_e32 v16, v16, v17
	v_max_u32_e32 v17, v15, v171
	v_min_u32_e32 v15, v15, v171
	v_max_u32_e32 v171, v5, v3
	v_min_u32_e32 v3, v5, v3
	v_max_u32_e32 v5, v4, v2
	v_min_u32_e32 v2, v4, v2
	v_max_u32_e32 v4, v8, v11
	v_min_u32_e32 v8, v8, v11
	v_max_u32_e32 v11, v7, v9
	v_min_u32_e32 v7, v7, v9
	v_max_u32_e32 v9, v6, v10
	v_min_u32_e32 v6, v6, v10
	v_max_u32_e32 v10, v13, v12
	v_min_u32_e32 v12, v13, v12
	v_max_u32_e32 v46, v47, v49
	v_min_u32_e32 v47, v47, v49
	v_max_u32_e32 v49, v37, v48
	v_min_u32_e32 v37, v37, v48
	v_max_u32_e32 v48, v50, v38
	v_min_u32_e32 v38, v50, v38
	v_max_u32_e32 v50, v36, v34
	v_min_u32_e32 v34, v36, v34
	v_max_u32_e32 v36, v41, v40
	v_min_u32_e32 v40, v41, v40
	v_max_u32_e32 v41, v35, v44
	v_min_u32_e32 v35, v35, v44
	v_max_u32_e32 v44, v39, v45
	v_min_u32_e32 v39, v39, v45
	v_max_u32_e32 v45, v42, v43
	v_min_u32_e32 v42, v42, v43
	v_max_u32_e32 v151, v152, v154
	v_min_u32_e32 v152, v152, v154
	v_max_u32_e32 v154, v61, v153
	v_min_u32_e32 v61, v61, v153
	v_max_u32_e32 v153, v155, v62
	v_min_u32_e32 v62, v155, v62
	v_max_u32_e32 v155, v60, v58
	v_min_u32_e32 v58, v60, v58
	v_max_u32_e32 v60, v65, v64
	v_min_u32_e32 v64, v65, v64
	v_max_u32_e32 v65, v59, v149
	v_min_u32_e32 v59, v59, v149
	v_max_u32_e32 v149, v63, v150
	v_min_u32_e32 v63, v63, v150
	v_max_u32_e32 v150, v147, v148
	v_min_u32_e32 v147, v147, v148
	v_max_u32_e32 v29, v30, v33
	v_min_u32_e32 v30, v30, v33
	v_max_u32_e32 v33, v32, v31
	v_min_u32_e32 v31, v32, v31
	v_max_u32_e32 v32, v163, v21
	v_min_u32_e32 v21, v163, v21
	v_max_u32_e32 v163, v19, v18
	v_min_u32_e32 v18, v19, v18
	v_max_u32_e32 v19, v24, v23
	v_min_u32_e32 v23, v24, v23
	v_max_u32_e32 v24, v20, v27
	v_min_u32_e32 v20, v20, v27
	v_max_u32_e32 v27, v22, v28
	v_min_u32_e32 v22, v22, v28
	v_max_u32_e32 v28, v25, v26
	v_min_u32_e32 v25, v25, v26
	v_max_u32_e32 v13, v14, v17
	v_min_u32_e32 v14, v14, v17
	v_max_u32_e32 v17, v16, v15
	v_min_u32_e32 v15, v16, v15
	v_max_u32_e32 v16, v171, v5
	v_min_u32_e32 v5, v171, v5
	v_max_u32_e32 v171, v3, v2
	v_min_u32_e32 v2, v3, v2
	v_max_u32_e32 v3, v8, v7
	v_min_u32_e32 v7, v8, v7
	v_max_u32_e32 v8, v4, v11
	v_min_u32_e32 v4, v4, v11
	v_max_u32_e32 v11, v6, v12
	v_min_u32_e32 v6, v6, v12
	v_max_u32_e32 v12, v9, v10
	v_min_u32_e32 v9, v9, v10
	v_max_u32_e32 v43, v46, v40
	v_min_u32_e32 v40, v46, v40
	v_max_u32_e32 v46, v47, v36
	v_min_u32_e32 v36, v47, v36
	v_max_u32_e32 v47, v49, v35
	v_min_u32_e32 v35, v49, v35
	v_max_u32_e32 v49, v37, v41
	v_min_u32_e32 v37, v37, v41
	v_max_u32_e32 v41, v48, v39
	v_min_u32_e32 v39, v48, v39
	v_max_u32_e32 v48, v38, v44
	v_min_u32_e32 v38, v38, v44
	v_max_u32_e32 v44, v50, v42
	v_min_u32_e32 v42, v50, v42
	v_max_u32_e32 v50, v34, v45
	v_min_u32_e32 v34, v34, v45
	v_max_u32_e32 v148, v151, v64
	v_min_u32_e32 v64, v151, v64
	v_max_u32_e32 v151, v152, v60
	v_min_u32_e32 v60, v152, v60
	v_max_u32_e32 v152, v154, v59
	v_min_u32_e32 v59, v154, v59
	v_max_u32_e32 v154, v61, v65
	v_min_u32_e32 v61, v61, v65
	v_max_u32_e32 v65, v153, v63
	v_min_u32_e32 v63, v153, v63
	v_max_u32_e32 v153, v62, v149
	v_min_u32_e32 v62, v62, v149
	v_max_u32_e32 v149, v155, v147
	v_min_u32_e32 v147, v155, v147
	v_max_u32_e32 v155, v58, v150
	v_min_u32_e32 v58, v58, v150
	v_max_u32_e32 v26, v29, v23
	v_min_u32_e32 v23, v29, v23
	v_max_u32_e32 v29, v30, v19
	v_min_u32_e32 v19, v30, v19
	v_max_u32_e32 v30, v33, v20
	v_min_u32_e32 v20, v33, v20
	v_max_u32_e32 v33, v31, v24
	v_min_u32_e32 v24, v31, v24
	v_max_u32_e32 v31, v32, v22
	v_min_u32_e32 v22, v32, v22
	v_max_u32_e32 v32, v21, v27
	v_min_u32_e32 v21, v21, v27
	v_max_u32_e32 v27, v163, v25
	v_min_u32_e32 v25, v163, v25
	v_max_u32_e32 v163, v18, v28
	v_min_u32_e32 v18, v18, v28
	v_max_u32_e32 v10, v13, v7
	v_min_u32_e32 v7, v13, v7
	v_max_u32_e32 v13, v14, v3
	v_min_u32_e32 v3, v14, v3
	v_max_u32_e32 v14, v17, v4
	v_min_u32_e32 v4, v17, v4
	v_max_u32_e32 v17, v15, v8
	v_min_u32_e32 v8, v15, v8
	v_max_u32_e32 v15, v16, v6
	v_min_u32_e32 v6, v16, v6
	v_max_u32_e32 v16, v5, v11
	v_min_u32_e32 v5, v5, v11
	v_max_u32_e32 v11, v171, v9
	v_min_u32_e32 v9, v171, v9
	v_max_u32_e32 v171, v2, v12
	v_min_u32_e32 v2, v2, v12
	v_max_u32_e32 v45, v43, v41
	v_min_u32_e32 v41, v43, v41
	v_max_u32_e32 v43, v46, v48
	v_min_u32_e32 v46, v46, v48
	v_max_u32_e32 v48, v47, v44
	v_min_u32_e32 v44, v47, v44
	v_max_u32_e32 v47, v49, v50
	v_min_u32_e32 v49, v49, v50
	v_max_u32_e32 v50, v40, v39
	v_min_u32_e32 v39, v40, v39
	v_max_u32_e32 v40, v36, v38
	v_min_u32_e32 v36, v36, v38
	v_max_u32_e32 v38, v35, v42
	v_min_u32_e32 v35, v35, v42
	v_max_u32_e32 v42, v37, v34
	v_min_u32_e32 v34, v37, v34
	v_max_u32_e32 v150, v148, v65
	v_min_u32_e32 v65, v148, v65
	v_max_u32_e32 v148, v151, v153
	v_min_u32_e32 v151, v151, v153
	v_max_u32_e32 v153, v152, v149
	v_min_u32_e32 v149, v152, v149
	v_max_u32_e32 v152, v154, v155
	v_min_u32_e32 v154, v154, v155
	v_max_u32_e32 v155, v64, v63
	v_min_u32_e32 v63, v64, v63
	v_max_u32_e32 v64, v60, v62
	v_min_u32_e32 v60, v60, v62
	v_max_u32_e32 v62, v59, v147
	v_min_u32_e32 v59, v59, v147
	v_max_u32_e32 v147, v61, v58
	v_min_u32_e32 v58, v61, v58
	v_max_u32_e32 v28, v26, v31
	v_min_u32_e32 v26, v26, v31
	v_max_u32_e32 v31, v29, v32
	v_min_u32_e32 v29, v29, v32
	v_max_u32_e32 v32, v30, v27
	v_min_u32_e32 v27, v30, v27
	v_max_u32_e32 v30, v33, v163
	v_min_u32_e32 v33, v33, v163
	v_max_u32_e32 v163, v23, v22
	v_min_u32_e32 v22, v23, v22
	v_max_u32_e32 v23, v19, v21
	v_min_u32_e32 v19, v19, v21
	v_max_u32_e32 v21, v20, v25
	v_min_u32_e32 v20, v20, v25
	v_max_u32_e32 v25, v24, v18
	v_min_u32_e32 v18, v24, v18
	v_max_u32_e32 v12, v10, v15
	v_min_u32_e32 v10, v10, v15
	v_max_u32_e32 v15, v13, v16
	v_min_u32_e32 v13, v13, v16
	v_max_u32_e32 v16, v14, v11
	v_min_u32_e32 v11, v14, v11
	v_max_u32_e32 v14, v17, v171
	v_min_u32_e32 v17, v17, v171
	v_max_u32_e32 v171, v7, v6
	v_min_u32_e32 v6, v7, v6
	v_max_u32_e32 v7, v3, v5
	v_min_u32_e32 v3, v3, v5
	v_max_u32_e32 v5, v4, v9
	v_min_u32_e32 v4, v4, v9
	v_max_u32_e32 v9, v8, v2
	v_min_u32_e32 v2, v8, v2
	v_max_u32_e32 v37, v45, v48
	v_min_u32_e32 v45, v45, v48
	v_max_u32_e32 v48, v43, v47
	v_min_u32_e32 v43, v43, v47
	s_waitcnt vmcnt(0)
	v_pk_mul_f32 v[200:201], v[200:201], s[96:97] op_sel_hi:[1,0]
	v_pk_mul_f32 v[202:203], v[202:203], s[96:97] op_sel_hi:[1,0]
	v_pk_mul_f32 v[204:205], v[204:205], s[96:97] op_sel_hi:[1,0]
	v_pk_mul_f32 v[206:207], v[206:207], s[96:97] op_sel_hi:[1,0]
	v_pk_mul_f32 v[208:209], v[208:209], s[96:97] op_sel_hi:[1,0]
	v_pk_mul_f32 v[210:211], v[210:211], s[96:97] op_sel_hi:[1,0]
	v_pk_mul_f32 v[212:213], v[212:213], s[96:97] op_sel_hi:[1,0]
	v_pk_mul_f32 v[214:215], v[214:215], s[96:97] op_sel_hi:[1,0]
	v_pk_mul_f32 v[216:217], v[216:217], s[96:97] op_sel_hi:[1,0]
	v_pk_mul_f32 v[218:219], v[218:219], s[96:97] op_sel_hi:[1,0]
	v_pk_mul_f32 v[220:221], v[220:221], s[96:97] op_sel_hi:[1,0]
	v_pk_mul_f32 v[222:223], v[222:223], s[96:97] op_sel_hi:[1,0]
	v_pk_mul_f32 v[224:225], v[224:225], s[96:97] op_sel_hi:[1,0]
	v_pk_mul_f32 v[226:227], v[226:227], s[96:97] op_sel_hi:[1,0]
	v_pk_mul_f32 v[228:229], v[228:229], s[96:97] op_sel_hi:[1,0]
	v_pk_mul_f32 v[230:231], v[230:231], s[96:97] op_sel_hi:[1,0]
	v_cvt_scalef32_pk_fp4_f32 v232, v200, v201, 1.0
	v_cvt_scalef32_pk_fp4_f32 v233, v208, v209, 1.0
	v_cvt_scalef32_pk_fp4_f32 v234, v216, v217, 1.0
	v_cvt_scalef32_pk_fp4_f32 v235, v224, v225, 1.0
	v_cvt_scalef32_pk_fp4_f32 v232, v202, v203, 1.0 op_sel:[0,0,1,0]
	v_cvt_scalef32_pk_fp4_f32 v233, v210, v211, 1.0 op_sel:[0,0,1,0]
	v_cvt_scalef32_pk_fp4_f32 v234, v218, v219, 1.0 op_sel:[0,0,1,0]
	v_cvt_scalef32_pk_fp4_f32 v235, v226, v227, 1.0 op_sel:[0,0,1,0]
	v_cvt_scalef32_pk_fp4_f32 v232, v204, v205, 1.0 op_sel:[0,0,0,1]
	v_cvt_scalef32_pk_fp4_f32 v233, v212, v213, 1.0 op_sel:[0,0,0,1]
	v_cvt_scalef32_pk_fp4_f32 v234, v220, v221, 1.0 op_sel:[0,0,0,1]
	v_cvt_scalef32_pk_fp4_f32 v235, v228, v229, 1.0 op_sel:[0,0,0,1]
	v_cvt_scalef32_pk_fp4_f32 v232, v206, v207, 1.0 op_sel:[0,0,1,1]
	v_cvt_scalef32_pk_fp4_f32 v233, v214, v215, 1.0 op_sel:[0,0,1,1]
	v_cvt_scalef32_pk_fp4_f32 v234, v222, v223, 1.0 op_sel:[0,0,1,1]
	v_cvt_scalef32_pk_fp4_f32 v235, v230, v231, 1.0 op_sel:[0,0,1,1]
	s_nop 0
	global_store_dwordx4 v[240:241], v[232:235], off
	v_lshl_add_u64 v[240:241], v[240:241], 0, v[246:247]
	global_load_dwordx4 v[200:203], v[236:237], off
	global_load_dwordx4 v[204:207], v[236:237], off offset:16
	global_load_dwordx4 v[208:211], v[236:237], off offset:32
	global_load_dwordx4 v[212:215], v[236:237], off offset:48
	global_load_dwordx4 v[216:219], v[238:239], off
	global_load_dwordx4 v[220:223], v[238:239], off offset:16
	global_load_dwordx4 v[224:227], v[238:239], off offset:32
	global_load_dwordx4 v[228:231], v[238:239], off offset:48
	v_lshl_add_u64 v[236:237], v[236:237], 0, v[244:245]
	v_lshl_add_u64 v[238:239], v[238:239], 0, v[244:245]
	v_max_u32_e32 v47, v41, v44
	v_min_u32_e32 v41, v41, v44
	v_max_u32_e32 v44, v46, v49
	v_min_u32_e32 v46, v46, v49
	v_max_u32_e32 v49, v50, v38
	v_min_u32_e32 v38, v50, v38
	v_max_u32_e32 v50, v40, v42
	v_min_u32_e32 v40, v40, v42
	v_max_u32_e32 v42, v39, v35
	v_min_u32_e32 v35, v39, v35
	v_max_u32_e32 v39, v36, v34
	v_min_u32_e32 v34, v36, v34
	v_max_u32_e32 v61, v150, v153
	v_min_u32_e32 v150, v150, v153
	v_max_u32_e32 v153, v148, v152
	v_min_u32_e32 v148, v148, v152
	v_max_u32_e32 v152, v65, v149
	v_min_u32_e32 v65, v65, v149
	v_max_u32_e32 v149, v151, v154
	v_min_u32_e32 v151, v151, v154
	v_max_u32_e32 v154, v155, v62
	v_min_u32_e32 v62, v155, v62
	v_max_u32_e32 v155, v64, v147
	v_min_u32_e32 v64, v64, v147
	v_max_u32_e32 v147, v63, v59
	v_min_u32_e32 v59, v63, v59
	v_max_u32_e32 v63, v60, v58
	v_min_u32_e32 v58, v60, v58
	v_max_u32_e32 v24, v28, v32
	v_min_u32_e32 v28, v28, v32
	v_max_u32_e32 v32, v31, v30
	v_min_u32_e32 v30, v31, v30
	v_max_u32_e32 v31, v26, v27
	v_min_u32_e32 v26, v26, v27
	v_max_u32_e32 v27, v29, v33
	v_min_u32_e32 v29, v29, v33
	v_max_u32_e32 v33, v163, v21
	v_min_u32_e32 v21, v163, v21
	v_max_u32_e32 v163, v23, v25
	v_min_u32_e32 v23, v23, v25
	v_max_u32_e32 v25, v22, v20
	v_min_u32_e32 v20, v22, v20
	v_max_u32_e32 v22, v19, v18
	v_min_u32_e32 v18, v19, v18
	v_max_u32_e32 v8, v12, v16
	v_min_u32_e32 v12, v12, v16
	v_max_u32_e32 v16, v15, v14
	v_min_u32_e32 v14, v15, v14
	v_max_u32_e32 v15, v10, v11
	v_min_u32_e32 v10, v10, v11
	v_max_u32_e32 v11, v13, v17
	v_min_u32_e32 v13, v13, v17
	v_max_u32_e32 v17, v171, v5
	v_min_u32_e32 v5, v171, v5
	v_max_u32_e32 v171, v7, v9
	v_min_u32_e32 v7, v7, v9
	v_max_u32_e32 v9, v6, v4
	v_min_u32_e32 v4, v6, v4
	v_max_u32_e32 v6, v3, v2
	v_min_u32_e32 v2, v3, v2
	v_min_u32_e32 v36, v37, v48
	v_min_u32_e32 v51, v45, v43
	v_min_u32_e32 v52, v47, v44
	v_min_u32_e32 v53, v41, v46
	v_min_u32_e32 v54, v49, v50
	v_min_u32_e32 v55, v38, v40
	v_min_u32_e32 v56, v42, v39
	v_min_u32_e32 v57, v35, v34
	v_min_u32_e32 v60, v61, v153
	v_min_u32_e32 v156, v150, v148
	v_min_u32_e32 v157, v152, v149
	v_min_u32_e32 v158, v65, v151
	v_min_u32_e32 v159, v154, v155
	v_min_u32_e32 v160, v62, v64
	v_min_u32_e32 v161, v147, v63
	v_min_u32_e32 v162, v59, v58
	v_min_u32_e32 v19, v24, v32
	v_min_u32_e32 v164, v28, v30
	v_min_u32_e32 v165, v31, v27
	v_min_u32_e32 v166, v26, v29
	v_min_u32_e32 v167, v33, v163
	v_min_u32_e32 v168, v21, v23
	v_min_u32_e32 v169, v25, v22
	v_min_u32_e32 v170, v20, v18
	v_min_u32_e32 v3, v8, v16
	v_min_u32_e32 v172, v12, v14
	v_min_u32_e32 v173, v15, v11
	v_min_u32_e32 v174, v10, v13
	v_min_u32_e32 v175, v17, v171
	v_min_u32_e32 v176, v5, v7
	v_min_u32_e32 v177, v9, v6
	v_min_u32_e32 v178, v4, v2
	v_max3_u32 v37, v37, v48, v162
	v_max3_u32 v24, v24, v32, v178
	v_max3_u32 v32, v36, v59, v58
	v_max3_u32 v2, v19, v4, v2
	v_max3_u32 v4, v45, v43, v161
	v_max3_u32 v19, v28, v30, v177
	v_max3_u32 v28, v51, v147, v63
	v_max3_u32 v6, v164, v9, v6
	v_max3_u32 v9, v47, v44, v160
	v_max3_u32 v27, v31, v27, v176
	v_max3_u32 v30, v52, v62, v64
	v_max3_u32 v5, v165, v5, v7
	v_max3_u32 v7, v41, v46, v159
	v_max3_u32 v26, v26, v29, v175
	v_max3_u32 v29, v53, v154, v155
	v_max3_u32 v17, v166, v17, v171
	v_max3_u32 v31, v49, v50, v158
	v_max3_u32 v33, v33, v163, v174
	v_max3_u32 v36, v54, v65, v151
	v_max3_u32 v10, v167, v10, v13
	v_max3_u32 v13, v38, v40, v157
	v_max3_u32 v21, v21, v23, v173
	v_max3_u32 v23, v55, v152, v149
	v_max3_u32 v11, v168, v15, v11
	v_max3_u32 v15, v42, v39, v156
	v_max3_u32 v22, v25, v22, v172
	v_max3_u32 v25, v56, v150, v148
	v_max3_u32 v12, v169, v12, v14
	v_max3_u32 v14, v35, v34, v60
	v_max3_u32 v3, v20, v18, v3
	v_max3_u32 v18, v57, v61, v153
	v_max3_u32 v8, v170, v8, v16
	v_max_u32_e32 v16, v37, v31
	v_min_u32_e32 v20, v37, v31
	v_max_u32_e32 v31, v32, v36
	v_min_u32_e32 v32, v32, v36
	v_max_u32_e32 v34, v4, v13
	v_min_u32_e32 v4, v4, v13
	v_max_u32_e32 v13, v28, v23
	v_min_u32_e32 v23, v28, v23
	v_max_u32_e32 v28, v9, v15
	v_min_u32_e32 v9, v9, v15
	v_max_u32_e32 v15, v30, v25
	v_min_u32_e32 v25, v30, v25
	v_max_u32_e32 v30, v7, v14
	v_min_u32_e32 v7, v7, v14
	v_max_u32_e32 v14, v29, v18
	v_min_u32_e32 v18, v29, v18
	v_max_u32_e32 v42, v24, v33
	v_min_u32_e32 v24, v24, v33
	v_max_u32_e32 v33, v2, v10
	v_min_u32_e32 v2, v2, v10
	v_max_u32_e32 v10, v19, v21
	v_min_u32_e32 v19, v19, v21
	v_max_u32_e32 v21, v6, v11
	v_min_u32_e32 v6, v6, v11
	v_max_u32_e32 v11, v27, v22
	v_min_u32_e32 v22, v27, v22
	v_max_u32_e32 v27, v5, v12
	v_min_u32_e32 v5, v5, v12
	v_max_u32_e32 v12, v26, v3
	v_min_u32_e32 v3, v26, v3
	v_max_u32_e32 v26, v17, v8
	v_min_u32_e32 v8, v17, v8
	v_max_u32_e32 v29, v16, v28
	v_min_u32_e32 v16, v16, v28
	v_max_u32_e32 v28, v31, v15
	v_min_u32_e32 v15, v31, v15
	v_max_u32_e32 v31, v34, v30
	v_min_u32_e32 v30, v34, v30
	v_max_u32_e32 v34, v13, v14
	v_min_u32_e32 v13, v13, v14
	v_max_u32_e32 v14, v20, v9
	v_min_u32_e32 v9, v20, v9
	v_max_u32_e32 v20, v32, v25
	v_min_u32_e32 v25, v32, v25
	v_max_u32_e32 v32, v4, v7
	v_min_u32_e32 v4, v4, v7
	v_max_u32_e32 v7, v23, v18
	v_min_u32_e32 v18, v23, v18
	v_max_u32_e32 v17, v42, v11
	v_min_u32_e32 v11, v42, v11
	v_max_u32_e32 v42, v33, v27
	v_min_u32_e32 v27, v33, v27
	v_max_u32_e32 v33, v10, v12
	v_min_u32_e32 v10, v10, v12
	v_max_u32_e32 v12, v21, v26
	v_min_u32_e32 v21, v21, v26
	v_max_u32_e32 v26, v24, v22
	v_min_u32_e32 v22, v24, v22
	v_max_u32_e32 v24, v2, v5
	v_min_u32_e32 v2, v2, v5
	v_max_u32_e32 v5, v19, v3
	v_min_u32_e32 v3, v19, v3
	v_max_u32_e32 v19, v6, v8
	v_min_u32_e32 v6, v6, v8
	v_max_u32_e32 v23, v29, v31
	v_min_u32_e32 v29, v29, v31
	v_max_u32_e32 v31, v28, v34
	v_min_u32_e32 v28, v28, v34
	v_max_u32_e32 v34, v16, v30
	v_min_u32_e32 v16, v16, v30
	v_max_u32_e32 v30, v15, v13
	v_min_u32_e32 v13, v15, v13
	v_max_u32_e32 v15, v14, v32
	v_min_u32_e32 v14, v14, v32
	v_max_u32_e32 v32, v20, v7
	v_min_u32_e32 v7, v20, v7
	v_max_u32_e32 v20, v9, v4
	v_min_u32_e32 v4, v9, v4
	v_max_u32_e32 v9, v25, v18
	v_min_u32_e32 v18, v25, v18
	v_max_u32_e32 v8, v17, v33
	v_min_u32_e32 v17, v17, v33
	v_max_u32_e32 v33, v42, v12
	v_min_u32_e32 v12, v42, v12
	v_max_u32_e32 v42, v11, v10
	v_min_u32_e32 v10, v11, v10
	v_max_u32_e32 v11, v27, v21
	v_min_u32_e32 v21, v27, v21
	v_max_u32_e32 v27, v26, v5
	v_min_u32_e32 v5, v26, v5
	v_max_u32_e32 v26, v24, v19
	v_min_u32_e32 v19, v24, v19
	v_max_u32_e32 v24, v22, v3
	v_min_u32_e32 v3, v22, v3
	v_max_u32_e32 v22, v2, v6
	v_min_u32_e32 v2, v2, v6
	v_min_u32_e32 v25, v23, v31
	v_min_u32_e32 v35, v29, v28
	v_min_u32_e32 v36, v34, v30
	v_min_u32_e32 v37, v16, v13
	v_min_u32_e32 v38, v15, v32
	v_min_u32_e32 v39, v14, v7
	v_min_u32_e32 v40, v20, v9
	v_min_u32_e32 v41, v4, v18
	v_min_u32_e32 v6, v8, v33
	v_min_u32_e32 v43, v17, v12
	v_min_u32_e32 v44, v42, v11
	v_min_u32_e32 v45, v10, v21
	v_min_u32_e32 v46, v27, v26
	v_min_u32_e32 v47, v5, v19
	v_min_u32_e32 v48, v24, v22
	v_min_u32_e32 v49, v3, v2
	v_max3_u32 v23, v23, v31, v49
	v_max3_u32 v2, v25, v3, v2
	v_max3_u32 v3, v29, v28, v48
	v_max3_u32 v22, v35, v24, v22
	v_max3_u32 v24, v34, v30, v47
	v_max3_u32 v5, v36, v5, v19
	v_max3_u32 v13, v16, v13, v46
	v_max3_u32 v16, v37, v27, v26
	v_max3_u32 v15, v15, v32, v45
	s_waitcnt vmcnt(0)
	v_pk_mul_f32 v[200:201], v[200:201], s[96:97] op_sel_hi:[1,0]
	v_pk_mul_f32 v[202:203], v[202:203], s[96:97] op_sel_hi:[1,0]
	v_pk_mul_f32 v[204:205], v[204:205], s[96:97] op_sel_hi:[1,0]
	v_pk_mul_f32 v[206:207], v[206:207], s[96:97] op_sel_hi:[1,0]
	v_pk_mul_f32 v[208:209], v[208:209], s[96:97] op_sel_hi:[1,0]
	v_pk_mul_f32 v[210:211], v[210:211], s[96:97] op_sel_hi:[1,0]
	v_pk_mul_f32 v[212:213], v[212:213], s[96:97] op_sel_hi:[1,0]
	v_pk_mul_f32 v[214:215], v[214:215], s[96:97] op_sel_hi:[1,0]
	v_pk_mul_f32 v[216:217], v[216:217], s[96:97] op_sel_hi:[1,0]
	v_pk_mul_f32 v[218:219], v[218:219], s[96:97] op_sel_hi:[1,0]
	v_pk_mul_f32 v[220:221], v[220:221], s[96:97] op_sel_hi:[1,0]
	v_pk_mul_f32 v[222:223], v[222:223], s[96:97] op_sel_hi:[1,0]
	v_pk_mul_f32 v[224:225], v[224:225], s[96:97] op_sel_hi:[1,0]
	v_pk_mul_f32 v[226:227], v[226:227], s[96:97] op_sel_hi:[1,0]
	v_pk_mul_f32 v[228:229], v[228:229], s[96:97] op_sel_hi:[1,0]
	v_pk_mul_f32 v[230:231], v[230:231], s[96:97] op_sel_hi:[1,0]
	v_cvt_scalef32_pk_fp4_f32 v232, v200, v201, 1.0
	v_cvt_scalef32_pk_fp4_f32 v233, v208, v209, 1.0
	v_cvt_scalef32_pk_fp4_f32 v234, v216, v217, 1.0
	v_cvt_scalef32_pk_fp4_f32 v235, v224, v225, 1.0
	v_cvt_scalef32_pk_fp4_f32 v232, v202, v203, 1.0 op_sel:[0,0,1,0]
	v_cvt_scalef32_pk_fp4_f32 v233, v210, v211, 1.0 op_sel:[0,0,1,0]
	v_cvt_scalef32_pk_fp4_f32 v234, v218, v219, 1.0 op_sel:[0,0,1,0]
	v_cvt_scalef32_pk_fp4_f32 v235, v226, v227, 1.0 op_sel:[0,0,1,0]
	v_cvt_scalef32_pk_fp4_f32 v232, v204, v205, 1.0 op_sel:[0,0,0,1]
	v_cvt_scalef32_pk_fp4_f32 v233, v212, v213, 1.0 op_sel:[0,0,0,1]
	v_cvt_scalef32_pk_fp4_f32 v234, v220, v221, 1.0 op_sel:[0,0,0,1]
	v_cvt_scalef32_pk_fp4_f32 v235, v228, v229, 1.0 op_sel:[0,0,0,1]
	v_cvt_scalef32_pk_fp4_f32 v232, v206, v207, 1.0 op_sel:[0,0,1,1]
	v_cvt_scalef32_pk_fp4_f32 v233, v214, v215, 1.0 op_sel:[0,0,1,1]
	v_cvt_scalef32_pk_fp4_f32 v234, v222, v223, 1.0 op_sel:[0,0,1,1]
	v_cvt_scalef32_pk_fp4_f32 v235, v230, v231, 1.0 op_sel:[0,0,1,1]
	s_nop 0
	global_store_dwordx4 v[240:241], v[232:235], off
	v_lshl_add_u64 v[240:241], v[240:241], 0, v[246:247]
	v_max3_u32 v10, v38, v10, v21
	v_max3_u32 v7, v14, v7, v44
	v_max3_u32 v11, v39, v42, v11
	v_max3_u32 v9, v20, v9, v43
	v_max3_u32 v12, v40, v17, v12
	v_max3_u32 v4, v4, v18, v6
	v_max3_u32 v6, v41, v8, v33
	v_max_u32_e32 v8, v23, v15
	v_min_u32_e32 v14, v23, v15
	v_max_u32_e32 v15, v2, v10
	v_min_u32_e32 v2, v2, v10
	v_max_u32_e32 v10, v3, v7
	v_min_u32_e32 v3, v3, v7
	v_max_u32_e32 v7, v22, v11
	v_max_u32_e32 v17, v24, v9
	v_max_u32_e32 v18, v5, v12
	v_min_u32_e32 v5, v5, v12
	v_max_u32_e32 v12, v13, v4
	v_min_u32_e32 v4, v13, v4
	v_max_u32_e32 v13, v16, v6
	v_min_u32_e32 v11, v22, v11
	v_min_u32_e32 v9, v24, v9
	v_min_u32_e32 v6, v16, v6
	v_max_u32_e32 v16, v8, v17
	v_min_u32_e32 v8, v8, v17
	v_max_u32_e32 v17, v15, v18
	v_min_u32_e32 v15, v15, v18
	v_max_u32_e32 v18, v10, v12
	v_min_u32_e32 v10, v10, v12
	v_max_u32_e32 v12, v7, v13
	v_min_u32_e32 v7, v7, v13
	v_max_u32_e32 v13, v14, v9
	v_min_u32_e32 v9, v14, v9
	v_max_u32_e32 v14, v2, v5
	v_min_u32_e32 v2, v2, v5
	v_max_u32_e32 v5, v3, v4
	v_min_u32_e32 v3, v3, v4
	v_max_u32_e32 v4, v11, v6
	v_min_u32_e32 v6, v11, v6
	v_max_u32_e32 v11, v16, v18
	v_min_u32_e32 v16, v16, v18
	v_max_u32_e32 v18, v17, v12
	v_min_u32_e32 v12, v17, v12
	v_max_u32_e32 v17, v8, v10
	v_min_u32_e32 v8, v8, v10
	v_add_co_u32_e32 v10, vcc, s24, v80
	v_max_u32_e32 v25, v11, v18
	v_min_u32_e32 v18, v11, v18
	v_addc_co_u32_e32 v11, vcc, 0, v81, vcc
	v_max_u32_e32 v19, v15, v7
	v_min_u32_e32 v7, v15, v7
	v_max_u32_e32 v15, v13, v5
	v_min_u32_e32 v13, v13, v5
	v_max_u32_e32 v20, v14, v4
	v_min_u32_e32 v14, v14, v4
	v_max_u32_e32 v21, v9, v3
	v_min_u32_e32 v22, v9, v3
	v_max_u32_e32 v23, v2, v6
	v_min_u32_e32 v24, v2, v6
	global_load_dwordx4 v[2:5], v[10:11], off
	global_load_dwordx4 v[34:37], v[82:83], off offset:256
	global_load_dwordx4 v[38:41], v[82:83], off offset:288
	v_max_u32_e32 v26, v16, v12
	v_min_u32_e32 v12, v16, v12
	v_max_u32_e32 v16, v17, v19
	v_min_u32_e32 v17, v17, v19
	v_max_u32_e32 v19, v8, v7
	v_min_u32_e32 v27, v8, v7
	global_load_dwordx4 v[6:9], v[10:11], off offset:32
	global_load_dwordx4 v[28:31], v[10:11], off offset:64
	global_load_dwordx4 v[148:151], v[10:11], off offset:96
	v_cmp_lt_i32_e32 vcc, v84, v85
	global_load_dwordx4 v[42:45], v[82:83], off offset:320
	v_max_u32_e32 v33, v22, v24
	v_min_u32_e32 v22, v22, v24
	v_cndmask_b32_e32 v24, v77, v84, vcc
	v_max_u32_e32 v32, v15, v20
	v_min_u32_e32 v15, v15, v20
	v_max_u32_e32 v20, v13, v14
	v_min_u32_e32 v13, v13, v14
	v_min_u32_e32 v14, v21, v23
	v_lshlrev_b32_e32 v153, 2, v24
	ds_bpermute_b32 v46, v153, v33
	ds_bpermute_b32 v47, v153, v14
	ds_bpermute_b32 v50, v153, v13
	ds_bpermute_b32 v51, v153, v20
	ds_bpermute_b32 v52, v153, v15
	s_waitcnt lgkmcnt(0)
	v_max_u32_e32 v147, v18, v46
	v_max_u32_e32 v152, v26, v47
	global_load_dwordx4 v[46:49], v[82:83], off offset:352
	ds_bpermute_b32 v53, v153, v32
	global_load_dwordx4 v[154:157], v[10:11], off offset:128
	global_load_dwordx4 v[158:161], v[10:11], off offset:160
	v_max_u32_e32 v170, v16, v50
	v_max_u32_e32 v171, v17, v51
	v_max_u32_e32 v172, v19, v52
	s_waitcnt lgkmcnt(0)
	v_max_u32_e32 v173, v27, v53
	global_load_dwordx4 v[50:53], v[82:83], off offset:384
	global_load_dwordx4 v[54:57], v[82:83], off offset:416
	global_load_dwordx4 v[162:165], v[10:11], off offset:192
	global_load_dwordx4 v[166:169], v[10:11], off offset:224
	global_load_dwordx4 v[58:61], v[82:83], off offset:448
	global_load_dwordx4 v[62:65], v[82:83], off offset:480
	v_max_u32_e32 v21, v21, v23
	ds_bpermute_b32 v23, v153, v21
	ds_bpermute_b32 v16, v153, v16
	ds_bpermute_b32 v19, v153, v19
	ds_bpermute_b32 v24, v153, v22
	ds_bpermute_b32 v27, v153, v27
	s_waitcnt lgkmcnt(4)
	v_max_u32_e32 v23, v12, v23
	ds_bpermute_b32 v17, v153, v17
	s_waitcnt lgkmcnt(4)
	v_max_u32_e32 v13, v13, v16
	ds_bpermute_b32 v12, v153, v12
	ds_bpermute_b32 v16, v153, v26
	ds_bpermute_b32 v18, v153, v18
	s_waitcnt lgkmcnt(6)
	v_max_u32_e32 v15, v15, v19
	ds_bpermute_b32 v19, v153, v25
	s_waitcnt lgkmcnt(6)
	v_max_u32_e32 v24, v25, v24
	s_waitcnt lgkmcnt(5)
	v_max_u32_e32 v27, v32, v27
	s_waitcnt lgkmcnt(4)
	v_max_u32_e32 v17, v20, v17
	s_waitcnt lgkmcnt(3)
	v_max_u32_e32 v12, v21, v12
	s_waitcnt lgkmcnt(2)
	v_max_u32_e32 v14, v14, v16
	s_waitcnt lgkmcnt(1)
	v_max_u32_e32 v16, v33, v18
	s_waitcnt lgkmcnt(0)
	v_max_u32_e32 v10, v22, v19
	v_max_u32_e32 v11, v24, v27
	v_max_u32_e32 v18, v147, v15
	v_min_u32_e32 v33, v147, v15
	v_max_u32_e32 v15, v152, v17
	v_min_u32_e32 v82, v152, v17
	v_max_u32_e32 v83, v23, v13
	v_min_u32_e32 v147, v23, v13
	v_max_u32_e32 v13, v170, v12
	v_min_u32_e32 v152, v170, v12
	v_max_u32_e32 v12, v171, v14
	v_min_u32_e32 v170, v171, v14
	v_max_u32_e32 v14, v172, v16
	v_min_u32_e32 v32, v24, v27
	v_min_u32_e32 v171, v172, v16
	v_max_u32_e32 v172, v173, v10
	v_min_u32_e32 v10, v173, v10
	v_max_u32_e32 v173, v11, v13
	v_min_u32_e32 v11, v11, v13
	v_max_u32_e32 v174, v18, v12
	v_min_u32_e32 v175, v18, v12
	v_max_u32_e32 v176, v15, v14
	v_min_u32_e32 v177, v15, v14
	s_waitcnt vmcnt(14)
	v_mfma_f32_32x32x16_bf16 v[12:27], v[2:5], v[34:37], 0
	v_max_u32_e32 v2, v83, v172
	v_max_u32_e32 v178, v174, v2
	v_min_u32_e32 v174, v174, v2
	v_min_u32_e32 v83, v83, v172
	v_max_u32_e32 v172, v32, v152
	v_min_u32_e32 v32, v32, v152
	s_waitcnt vmcnt(12)
	v_mfma_f32_32x32x16_bf16 v[12:27], v[6:9], v[38:41], v[12:27]
	v_add_co_u32_e32 v6, vcc, s25, v80
	v_max_u32_e32 v152, v33, v170
	s_nop 0
	v_addc_co_u32_e32 v7, vcc, 0, v81, vcc
	global_load_dwordx4 v[2:5], v[6:7], off
	v_min_u32_e32 v33, v33, v170
	s_waitcnt vmcnt(10)
	v_mfma_f32_32x32x16_bf16 v[12:27], v[28:31], v[42:45], v[12:27]
	global_load_dwordx4 v[28:31], v[6:7], off offset:32
	v_max_u32_e32 v170, v82, v171
	v_min_u32_e32 v8, v82, v171
	v_max_u32_e32 v9, v147, v10
	v_min_u32_e32 v10, v147, v10
	v_max_u32_e32 v147, v173, v176
	v_min_u32_e32 v176, v173, v176
	s_waitcnt vmcnt(10)
	v_mfma_f32_32x32x16_bf16 v[12:27], v[148:151], v[46:49], v[12:27]
	v_max_u32_e32 v148, v172, v170
	v_min_u32_e32 v149, v172, v170
	global_load_dwordx4 v[170:173], v[6:7], off offset:64
	v_max_u32_e32 v179, v11, v177
	v_min_u32_e32 v11, v11, v177
	v_max_u32_e32 v177, v175, v83
	v_min_u32_e32 v83, v175, v83
	s_waitcnt vmcnt(8)
	v_mfma_f32_32x32x16_bf16 v[12:27], v[154:157], v[50:53], v[12:27]
	v_max_u32_e32 v156, v176, v174
	v_min_u32_e32 v157, v176, v174
	v_max_u32_e32 v150, v152, v9
	v_min_u32_e32 v9, v152, v9
	v_max_u32_e32 v82, v147, v178
	v_min_u32_e32 v152, v147, v178
	global_load_dwordx4 v[182:185], v[6:7], off offset:224
	s_waitcnt vmcnt(8)
	v_mfma_f32_32x32x16_bf16 v[12:27], v[158:161], v[54:57], v[12:27]
	v_max_u32_e32 v158, v179, v177
	v_min_u32_e32 v159, v179, v177
	global_load_dwordx4 v[174:177], v[6:7], off offset:96
	global_load_dwordx4 v[178:181], v[6:7], off offset:192
	v_max_u32_e32 v151, v32, v8
	v_min_u32_e32 v8, v32, v8
	v_max_u32_e32 v32, v33, v10
	s_waitcnt vmcnt(7)
	v_mfma_f32_32x32x16_bf16 v[12:27], v[162:165], v[58:61], v[12:27]
	global_load_dwordx4 v[162:165], v[6:7], off offset:128
	v_min_u32_e32 v10, v33, v10
	v_max_u32_e32 v160, v11, v83
	v_min_u32_e32 v161, v11, v83
	v_max_u32_e32 v83, v148, v150
	v_min_u32_e32 v147, v148, v150
	v_max_u32_e32 v148, v149, v9
	s_waitcnt vmcnt(7)
	v_mfma_f32_32x32x16_bf16 v[12:27], v[166:169], v[62:65], v[12:27]
	global_load_dwordx4 v[166:169], v[6:7], off offset:160
	v_min_u32_e32 v149, v149, v9
	v_max_u32_e32 v154, v8, v10
	v_min_u32_e32 v155, v8, v10
	v_max_u32_e32 v150, v151, v32
	v_min_u32_e32 v151, v151, v32
	s_nop 5
	v_not_b32_e32 v8, v12
	v_or_b32_e32 v9, 0x80000000, v12
	v_cmp_gt_i32_e32 vcc, 0, v12
	v_not_b32_e32 v6, v15
	v_or_b32_e32 v7, 0x80000000, v15
	v_cndmask_b32_e32 v8, v9, v8, vcc
	v_and_or_b32 v100, v8, s17, v100
	v_not_b32_e32 v8, v13
	v_or_b32_e32 v9, 0x80000000, v13
	v_cmp_gt_i32_e32 vcc, 0, v13
	v_or_b32_e32 v32, 0x80000000, v19
	s_nop 0
	v_cndmask_b32_e32 v8, v9, v8, vcc
	v_and_or_b32 v98, v8, s17, v98
	v_not_b32_e32 v8, v14
	v_or_b32_e32 v9, 0x80000000, v14
	v_cmp_gt_i32_e32 vcc, 0, v14
	s_nop 1
	v_cndmask_b32_e32 v8, v9, v8, vcc
	v_cmp_gt_i32_e32 vcc, 0, v15
	v_and_or_b32 v101, v8, s17, v101
	s_nop 0
	v_cndmask_b32_e32 v6, v7, v6, vcc
	v_and_or_b32 v99, v6, s17, v99
	v_not_b32_e32 v6, v16
	v_or_b32_e32 v7, 0x80000000, v16
	v_cmp_gt_i32_e32 vcc, 0, v16
	s_nop 1
	v_cndmask_b32_e32 v6, v7, v6, vcc
	v_and_or_b32 v97, v6, s17, v97
	v_not_b32_e32 v6, v17
	v_or_b32_e32 v7, 0x80000000, v17
	v_cmp_gt_i32_e32 vcc, 0, v17
	s_nop 1
	v_cndmask_b32_e32 v6, v7, v6, vcc
	v_and_or_b32 v96, v6, s17, v96
	v_not_b32_e32 v6, v18
	v_or_b32_e32 v7, 0x80000000, v18
	v_cmp_gt_i32_e32 vcc, 0, v18
	v_not_b32_e32 v18, v19
	s_nop 0
	v_cndmask_b32_e32 v6, v7, v6, vcc
	v_and_or_b32 v95, v6, s17, v95
	s_waitcnt vmcnt(7)
	v_mfma_f32_32x32x16_bf16 v[2:17], v[2:5], v[34:37], 0
	v_cmp_gt_i32_e32 vcc, 0, v19
	v_or_b32_e32 v19, 0x80000000, v20
	s_nop 0
	v_cndmask_b32_e32 v18, v32, v18, vcc
	v_and_or_b32 v94, v18, s17, v94
	v_not_b32_e32 v18, v20
	v_cmp_gt_i32_e32 vcc, 0, v20
	s_waitcnt vmcnt(6)
	v_mfma_f32_32x32x16_bf16 v[2:17], v[28:31], v[38:41], v[2:17]
	v_not_b32_e32 v30, v22
	v_cndmask_b32_e32 v18, v19, v18, vcc
	v_and_or_b32 v93, v18, s17, v93
	v_not_b32_e32 v18, v21
	v_or_b32_e32 v19, 0x80000000, v21
	v_cmp_gt_i32_e32 vcc, 0, v21
	v_or_b32_e32 v31, 0x80000000, v22
	s_waitcnt vmcnt(5)
	v_mfma_f32_32x32x16_bf16 v[2:17], v[170:173], v[42:45], v[2:17]
	v_cndmask_b32_e32 v18, v19, v18, vcc
	v_add_co_u32_e32 v28, vcc, s27, v80
	v_and_or_b32 v92, v18, s17, v92
	s_nop 0
	v_addc_co_u32_e32 v29, vcc, 0, v81, vcc
	global_load_dwordx4 v[18:21], v[28:29], off
	global_load_dwordx4 v[170:173], v[28:29], off offset:32
	s_waitcnt vmcnt(5)
	v_mfma_f32_32x32x16_bf16 v[2:17], v[174:177], v[46:49], v[2:17]
	global_load_dwordx4 v[174:177], v[28:29], off offset:128
	v_cmp_gt_i32_e32 vcc, 0, v22
	s_nop 1
	v_cndmask_b32_e32 v22, v31, v30, vcc
	v_and_or_b32 v90, v22, s17, v90
	v_not_b32_e32 v22, v23
	s_waitcnt vmcnt(4)
	v_mfma_f32_32x32x16_bf16 v[2:17], v[162:165], v[50:53], v[2:17]
	global_load_dwordx4 v[162:165], v[28:29], off offset:64
	v_or_b32_e32 v30, 0x80000000, v23
	v_cmp_gt_i32_e32 vcc, 0, v23
	v_or_b32_e32 v23, 0x80000000, v24
	s_nop 0
	v_cndmask_b32_e32 v22, v30, v22, vcc
	v_and_or_b32 v186, v22, s17, v89
	s_waitcnt vmcnt(4)
	v_mfma_f32_32x32x16_bf16 v[2:17], v[166:169], v[54:57], v[2:17]
	global_load_dwordx4 v[166:169], v[28:29], off offset:96
	v_not_b32_e32 v22, v24
	v_cmp_gt_i32_e32 vcc, 0, v24
	s_nop 1
	v_cndmask_b32_e32 v22, v23, v22, vcc
	v_and_or_b32 v187, v22, s17, v88
	v_mfma_f32_32x32x16_bf16 v[2:17], v[178:181], v[58:61], v[2:17]
	global_load_dwordx4 v[178:181], v[28:29], off offset:160
	v_not_b32_e32 v22, v25
	v_or_b32_e32 v23, 0x80000000, v25
	v_cmp_gt_i32_e32 vcc, 0, v25
	s_nop 1
	v_cndmask_b32_e32 v22, v23, v22, vcc
	v_mfma_f32_32x32x16_bf16 v[2:17], v[182:185], v[62:65], v[2:17]
	v_and_or_b32 v188, v22, s17, v78
	v_not_b32_e32 v22, v26
	v_or_b32_e32 v23, 0x80000000, v26
	v_cmp_gt_i32_e32 vcc, 0, v26
	global_load_dwordx4 v[182:185], v[28:29], off offset:192
	s_nop 0
	v_cndmask_b32_e32 v22, v23, v22, vcc
	v_and_or_b32 v189, v22, s17, v102
	v_not_b32_e32 v22, v27
	v_or_b32_e32 v23, 0x80000000, v27
	v_cmp_gt_i32_e32 vcc, 0, v27
	s_nop 1
	v_cndmask_b32_e32 v22, v23, v22, vcc
	v_and_or_b32 v190, v22, s17, v103
	v_not_b32_e32 v22, v2
	v_or_b32_e32 v23, 0x80000000, v2
	v_cmp_gt_i32_e32 vcc, 0, v2
	s_nop 1
	v_cndmask_b32_e32 v2, v23, v22, vcc
	v_and_or_b32 v78, v2, s17, v104
	v_not_b32_e32 v2, v3
	v_or_b32_e32 v22, 0x80000000, v3
	v_cmp_gt_i32_e32 vcc, 0, v3
	v_or_b32_e32 v3, 0x80000000, v4
	s_nop 0
	v_cndmask_b32_e32 v2, v22, v2, vcc
	v_and_or_b32 v88, v2, s17, v105
	global_load_dwordx4 v[102:105], v[28:29], off offset:224
	v_not_b32_e32 v2, v4
	v_cmp_gt_i32_e32 vcc, 0, v4
	s_waitcnt vmcnt(7)
	v_mfma_f32_32x32x16_bf16 v[18:33], v[18:21], v[34:37], 0
	v_cndmask_b32_e32 v2, v3, v2, vcc
	v_and_or_b32 v89, v2, s17, v107
	v_not_b32_e32 v2, v5
	v_or_b32_e32 v3, 0x80000000, v5
	v_cmp_gt_i32_e32 vcc, 0, v5
	s_nop 1
	v_cndmask_b32_e32 v2, v3, v2, vcc
	v_and_or_b32 v191, v2, s17, v106
	v_not_b32_e32 v2, v6
	v_or_b32_e32 v3, 0x80000000, v6
	v_cmp_gt_i32_e32 vcc, 0, v6
	s_waitcnt vmcnt(6)
	v_mfma_f32_32x32x16_bf16 v[18:33], v[170:173], v[38:41], v[18:33]
	v_cndmask_b32_e32 v2, v3, v2, vcc
	v_and_or_b32 v192, v2, s17, v108
	v_not_b32_e32 v2, v7
	v_or_b32_e32 v3, 0x80000000, v7
	v_cmp_gt_i32_e32 vcc, 0, v7
	s_waitcnt vmcnt(4)
	v_mfma_f32_32x32x16_bf16 v[18:33], v[162:165], v[42:45], v[18:33]
	v_cndmask_b32_e32 v2, v3, v2, vcc
	v_and_or_b32 v193, v2, s17, v109
	v_not_b32_e32 v2, v8
	v_or_b32_e32 v3, 0x80000000, v8
	v_cmp_gt_i32_e32 vcc, 0, v8
	s_nop 1
	v_cndmask_b32_e32 v2, v3, v2, vcc
	v_and_or_b32 v194, v2, s17, v110
	v_not_b32_e32 v2, v9
	v_or_b32_e32 v3, 0x80000000, v9
	v_cmp_gt_i32_e32 vcc, 0, v9
	v_or_b32_e32 v9, 0x80000000, v11
	s_waitcnt vmcnt(3)
	v_mfma_f32_32x32x16_bf16 v[18:33], v[166:169], v[46:49], v[18:33]
	v_cndmask_b32_e32 v2, v3, v2, vcc
	v_and_or_b32 v195, v2, s17, v111
	v_not_b32_e32 v2, v10
	v_or_b32_e32 v3, 0x80000000, v10
	v_cmp_gt_i32_e32 vcc, 0, v10
	s_nop 1
	v_cndmask_b32_e32 v8, v3, v2, vcc
	v_add_co_u32_e32 v6, vcc, s28, v80
	v_and_or_b32 v80, v8, s17, v68
	s_nop 0
	v_addc_co_u32_e32 v7, vcc, 0, v81, vcc
	global_load_dwordx4 v[2:5], v[6:7], off
	global_load_dwordx4 v[106:109], v[6:7], off offset:32
	global_load_dwordx4 v[162:165], v[6:7], off offset:64
	global_load_dwordx4 v[166:169], v[6:7], off offset:96
	v_not_b32_e32 v8, v11
	v_cmp_gt_i32_e32 vcc, 0, v11
	v_mfma_f32_32x32x16_bf16 v[18:33], v[174:177], v[50:53], v[18:33]
	global_load_dwordx4 v[170:173], v[6:7], off offset:192
	v_cndmask_b32_e32 v8, v9, v8, vcc
	v_and_or_b32 v81, v8, s17, v91
	v_not_b32_e32 v8, v12
	v_or_b32_e32 v9, 0x80000000, v12
	v_cmp_gt_i32_e32 vcc, 0, v12
	s_waitcnt vmcnt(7)
	v_mfma_f32_32x32x16_bf16 v[18:33], v[178:181], v[54:57], v[18:33]
	v_cndmask_b32_e32 v8, v9, v8, vcc
	v_and_or_b32 v91, v8, s17, v69
	v_not_b32_e32 v8, v13
	v_or_b32_e32 v9, 0x80000000, v13
	v_cmp_gt_i32_e32 vcc, 0, v13
	s_nop 1
	v_cndmask_b32_e32 v8, v9, v8, vcc
	v_and_or_b32 v196, v8, s17, v67
	v_not_b32_e32 v8, v14
	v_or_b32_e32 v9, 0x80000000, v14
	v_cmp_gt_i32_e32 vcc, 0, v14
	s_waitcnt vmcnt(6)
	v_mfma_f32_32x32x16_bf16 v[18:33], v[182:185], v[58:61], v[18:33]
	v_cndmask_b32_e32 v8, v9, v8, vcc
	v_and_or_b32 v174, v8, s17, v66
	global_load_dwordx4 v[66:69], v[6:7], off offset:128
	v_not_b32_e32 v8, v15
	v_or_b32_e32 v9, 0x80000000, v15
	v_cmp_gt_i32_e32 vcc, 0, v15
	s_waitcnt vmcnt(6)
	v_mfma_f32_32x32x16_bf16 v[18:33], v[102:105], v[62:65], v[18:33]
	global_load_dwordx4 v[102:105], v[6:7], off offset:224
	v_cndmask_b32_e32 v8, v9, v8, vcc
	v_and_or_b32 v175, v8, s17, v112
	v_not_b32_e32 v8, v16
	v_or_b32_e32 v9, 0x80000000, v16
	v_cmp_gt_i32_e32 vcc, 0, v16
	s_nop 1
	v_cndmask_b32_e32 v8, v9, v8, vcc
	v_and_or_b32 v176, v8, s17, v113
	global_load_dwordx4 v[110:113], v[6:7], off offset:160
	v_not_b32_e32 v8, v17
	v_or_b32_e32 v9, 0x80000000, v17
	v_cmp_gt_i32_e32 vcc, 0, v17
	v_not_b32_e32 v6, v19
	v_or_b32_e32 v7, 0x80000000, v19
	v_cndmask_b32_e32 v8, v9, v8, vcc
	v_and_or_b32 v114, v8, s17, v114
	v_not_b32_e32 v8, v18
	v_or_b32_e32 v9, 0x80000000, v18
	v_cmp_gt_i32_e32 vcc, 0, v18
	s_nop 1
	v_cndmask_b32_e32 v8, v9, v8, vcc
	v_cmp_gt_i32_e32 vcc, 0, v19
	v_and_or_b32 v18, v8, s17, v115
	v_not_b32_e32 v115, v23
	v_cndmask_b32_e32 v6, v7, v6, vcc
	v_and_or_b32 v19, v6, s17, v116
	v_not_b32_e32 v6, v20
	v_or_b32_e32 v7, 0x80000000, v20
	v_cmp_gt_i32_e32 vcc, 0, v20
	v_or_b32_e32 v116, 0x80000000, v23
	s_nop 0
	v_cndmask_b32_e32 v6, v7, v6, vcc
	v_and_or_b32 v20, v6, s17, v117
	v_not_b32_e32 v6, v21
	v_or_b32_e32 v7, 0x80000000, v21
	v_cmp_gt_i32_e32 vcc, 0, v21
	s_nop 1
	v_cndmask_b32_e32 v6, v7, v6, vcc
	v_and_or_b32 v21, v6, s17, v118
	v_not_b32_e32 v6, v22
	v_or_b32_e32 v7, 0x80000000, v22
	v_cmp_gt_i32_e32 vcc, 0, v22
	s_nop 1
	v_cndmask_b32_e32 v6, v7, v6, vcc
	v_and_or_b32 v22, v6, s17, v119
	s_waitcnt vmcnt(7)
	v_mfma_f32_32x32x16_bf16 v[2:17], v[2:5], v[34:37], 0
	v_cmp_gt_i32_e32 vcc, 0, v23
	v_not_b32_e32 v34, v24
	v_or_b32_e32 v35, 0x80000000, v24
	v_cndmask_b32_e32 v23, v116, v115, vcc
	v_cmp_gt_i32_e32 vcc, 0, v24
	v_and_or_b32 v23, v23, s17, v120
	v_max_u32_e32 v36, v101, v99
	s_waitcnt vmcnt(6)
	v_mfma_f32_32x32x16_bf16 v[2:17], v[106:109], v[38:41], v[2:17]
	v_cndmask_b32_e32 v24, v35, v34, vcc
	v_not_b32_e32 v34, v25
	v_or_b32_e32 v35, 0x80000000, v25
	v_cmp_gt_i32_e32 vcc, 0, v25
	v_and_or_b32 v24, v24, s17, v121
	v_min_u32_e32 v37, v101, v99
	v_cndmask_b32_e32 v25, v35, v34, vcc
	s_waitcnt vmcnt(5)
	v_mfma_f32_32x32x16_bf16 v[2:17], v[162:165], v[42:45], v[2:17]
	v_not_b32_e32 v34, v26
	v_or_b32_e32 v35, 0x80000000, v26
	v_cmp_gt_i32_e32 vcc, 0, v26
	v_and_or_b32 v25, v25, s17, v122
	v_max_u32_e32 v38, v97, v96
	v_cndmask_b32_e32 v26, v35, v34, vcc
	v_not_b32_e32 v34, v27
	s_waitcnt vmcnt(4)
	v_mfma_f32_32x32x16_bf16 v[2:17], v[166:169], v[46:49], v[2:17]
	v_or_b32_e32 v35, 0x80000000, v27
	v_cmp_gt_i32_e32 vcc, 0, v27
	v_and_or_b32 v26, v26, s17, v123
	v_min_u32_e32 v39, v97, v96
	v_cndmask_b32_e32 v27, v35, v34, vcc
	v_not_b32_e32 v34, v28
	v_or_b32_e32 v35, 0x80000000, v28
	s_waitcnt vmcnt(2)
	v_mfma_f32_32x32x16_bf16 v[2:17], v[66:69], v[50:53], v[2:17]
	v_cmp_gt_i32_e32 vcc, 0, v28
	v_and_or_b32 v27, v27, s17, v124
	v_max_u32_e32 v40, v95, v94
	v_cndmask_b32_e32 v28, v35, v34, vcc
	v_not_b32_e32 v34, v29
	v_or_b32_e32 v35, 0x80000000, v29
	v_cmp_gt_i32_e32 vcc, 0, v29
	s_waitcnt vmcnt(0)
	v_mfma_f32_32x32x16_bf16 v[2:17], v[110:113], v[54:57], v[2:17]
	v_cndmask_b32_e32 v29, v35, v34, vcc
	v_not_b32_e32 v34, v30
	v_or_b32_e32 v35, 0x80000000, v30
	v_cmp_gt_i32_e32 vcc, 0, v30
	v_and_or_b32 v28, v28, s17, v125
	v_and_or_b32 v29, v29, s17, v126
	v_cndmask_b32_e32 v30, v35, v34, vcc
	v_mfma_f32_32x32x16_bf16 v[2:17], v[170:173], v[58:61], v[2:17]
	v_not_b32_e32 v34, v31
	v_or_b32_e32 v35, 0x80000000, v31
	v_cmp_gt_i32_e32 vcc, 0, v31
	v_and_or_b32 v30, v30, s17, v127
	v_min_u32_e32 v41, v95, v94
	v_cndmask_b32_e32 v31, v35, v34, vcc
	v_not_b32_e32 v34, v32
	v_mfma_f32_32x32x16_bf16 v[2:17], v[102:105], v[62:65], v[2:17]
	v_or_b32_e32 v35, 0x80000000, v32
	v_cmp_gt_i32_e32 vcc, 0, v32
	v_and_or_b32 v31, v31, s17, v128
	v_max_u32_e32 v42, v93, v92
	v_cndmask_b32_e32 v32, v35, v34, vcc
	v_not_b32_e32 v34, v33
	v_or_b32_e32 v35, 0x80000000, v33
	v_cmp_gt_i32_e32 vcc, 0, v33
	v_and_or_b32 v32, v32, s17, v129
	v_min_u32_e32 v43, v93, v92
	v_cndmask_b32_e32 v33, v35, v34, vcc
	s_nop 0
	v_not_b32_e32 v34, v2
	v_or_b32_e32 v35, 0x80000000, v2
	v_cmp_gt_i32_e32 vcc, 0, v2
	global_load_dwordx4 v[200:203], v[236:237], off
	global_load_dwordx4 v[204:207], v[236:237], off offset:16
	global_load_dwordx4 v[208:211], v[236:237], off offset:32
	global_load_dwordx4 v[212:215], v[236:237], off offset:48
	global_load_dwordx4 v[216:219], v[238:239], off
	global_load_dwordx4 v[220:223], v[238:239], off offset:16
	global_load_dwordx4 v[224:227], v[238:239], off offset:32
	global_load_dwordx4 v[228:231], v[238:239], off offset:48
	v_lshl_add_u64 v[236:237], v[236:237], 0, v[244:245]
	v_lshl_add_u64 v[238:239], v[238:239], 0, v[244:245]
	v_and_or_b32 v33, v33, s17, v130
	v_max_u32_e32 v44, v90, v186
	v_cndmask_b32_e32 v2, v35, v34, vcc
	v_not_b32_e32 v34, v3
	v_or_b32_e32 v35, 0x80000000, v3
	v_cmp_gt_i32_e32 vcc, 0, v3
	v_and_or_b32 v2, v2, s17, v131
	v_min_u32_e32 v45, v90, v186
	v_cndmask_b32_e32 v3, v35, v34, vcc
	v_not_b32_e32 v34, v4
	v_or_b32_e32 v35, 0x80000000, v4
	v_cmp_gt_i32_e32 vcc, 0, v4
	v_and_or_b32 v3, v3, s17, v132
	v_max_u32_e32 v46, v187, v188
	v_cndmask_b32_e32 v4, v35, v34, vcc
	v_not_b32_e32 v34, v5
	v_or_b32_e32 v35, 0x80000000, v5
	v_cmp_gt_i32_e32 vcc, 0, v5
	v_and_or_b32 v4, v4, s17, v133
	v_min_u32_e32 v47, v187, v188
	v_cndmask_b32_e32 v5, v35, v34, vcc
	v_not_b32_e32 v34, v6
	v_or_b32_e32 v35, 0x80000000, v6
	v_cmp_gt_i32_e32 vcc, 0, v6
	v_and_or_b32 v5, v5, s17, v134
	v_max_u32_e32 v48, v189, v190
	v_cndmask_b32_e32 v6, v35, v34, vcc
	v_not_b32_e32 v34, v7
	v_or_b32_e32 v35, 0x80000000, v7
	v_cmp_gt_i32_e32 vcc, 0, v7
	v_and_or_b32 v6, v6, s17, v135
	v_min_u32_e32 v49, v189, v190
	v_cndmask_b32_e32 v7, v35, v34, vcc
	v_not_b32_e32 v34, v8
	v_or_b32_e32 v35, 0x80000000, v8
	v_cmp_gt_i32_e32 vcc, 0, v8
	v_and_or_b32 v7, v7, s17, v136
	v_max_u32_e32 v58, v78, v88
	v_cndmask_b32_e32 v8, v35, v34, vcc
	v_not_b32_e32 v34, v9
	v_or_b32_e32 v35, 0x80000000, v9
	v_cmp_gt_i32_e32 vcc, 0, v9
	v_and_or_b32 v8, v8, s17, v137
	v_min_u32_e32 v59, v78, v88
	v_cndmask_b32_e32 v9, v35, v34, vcc
	v_not_b32_e32 v34, v10
	v_or_b32_e32 v35, 0x80000000, v10
	v_cmp_gt_i32_e32 vcc, 0, v10
	v_and_or_b32 v9, v9, s17, v138
	v_max_u32_e32 v60, v89, v191
	v_cndmask_b32_e32 v10, v35, v34, vcc
	v_not_b32_e32 v34, v11
	v_or_b32_e32 v35, 0x80000000, v11
	v_cmp_gt_i32_e32 vcc, 0, v11
	v_and_or_b32 v10, v10, s17, v139
	v_min_u32_e32 v61, v89, v191
	v_cndmask_b32_e32 v11, v35, v34, vcc
	v_not_b32_e32 v34, v12
	v_or_b32_e32 v35, 0x80000000, v12
	v_cmp_gt_i32_e32 vcc, 0, v12
	v_and_or_b32 v11, v11, s17, v140
	v_max_u32_e32 v62, v192, v193
	v_cndmask_b32_e32 v12, v35, v34, vcc
	v_not_b32_e32 v34, v13
	v_or_b32_e32 v35, 0x80000000, v13
	v_cmp_gt_i32_e32 vcc, 0, v13
	v_and_or_b32 v12, v12, s17, v141
	v_min_u32_e32 v63, v192, v193
	v_cndmask_b32_e32 v13, v35, v34, vcc
	v_not_b32_e32 v34, v14
	v_or_b32_e32 v35, 0x80000000, v14
	v_cmp_gt_i32_e32 vcc, 0, v14
	v_and_or_b32 v13, v13, s17, v142
	v_max_u32_e32 v64, v194, v195
	v_cndmask_b32_e32 v14, v35, v34, vcc
	v_not_b32_e32 v34, v15
	v_or_b32_e32 v35, 0x80000000, v15
	v_cmp_gt_i32_e32 vcc, 0, v15
	v_and_or_b32 v14, v14, s17, v143
	v_min_u32_e32 v65, v194, v195
	v_cndmask_b32_e32 v15, v35, v34, vcc
	v_not_b32_e32 v34, v16
	v_or_b32_e32 v35, 0x80000000, v16
	v_cmp_gt_i32_e32 vcc, 0, v16
	v_and_or_b32 v15, v15, s17, v144
	v_max_u32_e32 v66, v80, v81
	v_cndmask_b32_e32 v16, v35, v34, vcc
	v_not_b32_e32 v34, v17
	v_or_b32_e32 v35, 0x80000000, v17
	v_cmp_gt_i32_e32 vcc, 0, v17
	v_and_or_b32 v16, v16, s17, v145
	v_min_u32_e32 v67, v80, v81
	v_cndmask_b32_e32 v17, v35, v34, vcc
	v_and_or_b32 v17, v17, s17, v146
	v_max_u32_e32 v34, v100, v98
	v_min_u32_e32 v35, v100, v98
	v_max_u32_e32 v68, v91, v196
	v_min_u32_e32 v69, v91, v196
	v_max_u32_e32 v78, v174, v175
	v_min_u32_e32 v80, v174, v175
	v_max_u32_e32 v81, v176, v114
	v_min_u32_e32 v88, v176, v114
	v_max_u32_e32 v97, v18, v19
	v_min_u32_e32 v18, v18, v19
	v_max_u32_e32 v19, v20, v21
	v_min_u32_e32 v20, v20, v21
	v_max_u32_e32 v21, v22, v23
	v_min_u32_e32 v22, v22, v23
	v_max_u32_e32 v23, v24, v25
	v_min_u32_e32 v24, v24, v25
	v_max_u32_e32 v25, v26, v27
	v_min_u32_e32 v26, v26, v27
	v_max_u32_e32 v27, v28, v29
	v_min_u32_e32 v28, v28, v29
	v_max_u32_e32 v29, v30, v31
	v_min_u32_e32 v30, v30, v31
	v_max_u32_e32 v31, v32, v33
	v_min_u32_e32 v32, v32, v33
	v_max_u32_e32 v105, v2, v3
	v_min_u32_e32 v2, v2, v3
	v_max_u32_e32 v3, v4, v5
	v_min_u32_e32 v4, v4, v5
	v_max_u32_e32 v5, v6, v7
	v_min_u32_e32 v6, v6, v7
	v_max_u32_e32 v7, v8, v9
	v_min_u32_e32 v8, v8, v9
	v_max_u32_e32 v9, v10, v11
	v_min_u32_e32 v10, v10, v11
	v_max_u32_e32 v11, v12, v13
	v_min_u32_e32 v12, v12, v13
	v_max_u32_e32 v13, v14, v15
	v_min_u32_e32 v14, v14, v15
	v_max_u32_e32 v15, v16, v17
	v_min_u32_e32 v16, v16, v17
	v_max_u32_e32 v50, v34, v37
	v_min_u32_e32 v34, v34, v37
	v_max_u32_e32 v37, v35, v36
	v_min_u32_e32 v35, v35, v36
	v_max_u32_e32 v36, v38, v41
	v_min_u32_e32 v38, v38, v41
	v_max_u32_e32 v41, v39, v40
	v_min_u32_e32 v39, v39, v40
	v_max_u32_e32 v40, v42, v45
	v_min_u32_e32 v42, v42, v45
	v_max_u32_e32 v45, v43, v44
	v_min_u32_e32 v43, v43, v44
	v_max_u32_e32 v44, v46, v49
	v_min_u32_e32 v46, v46, v49
	v_max_u32_e32 v49, v47, v48
	v_min_u32_e32 v47, v47, v48
	v_max_u32_e32 v89, v58, v61
	v_min_u32_e32 v58, v58, v61
	v_max_u32_e32 v61, v59, v60
	v_min_u32_e32 v59, v59, v60
	v_max_u32_e32 v60, v62, v65
	v_min_u32_e32 v62, v62, v65
	v_max_u32_e32 v65, v63, v64
	v_min_u32_e32 v63, v63, v64
	v_max_u32_e32 v64, v66, v69
	v_min_u32_e32 v66, v66, v69
	v_max_u32_e32 v69, v67, v68
	v_min_u32_e32 v67, v67, v68
	v_max_u32_e32 v68, v78, v88
	v_min_u32_e32 v78, v78, v88
	v_max_u32_e32 v88, v80, v81
	v_min_u32_e32 v80, v80, v81
	v_max_u32_e32 v33, v97, v20
	v_min_u32_e32 v20, v97, v20
	v_max_u32_e32 v97, v18, v19
	v_min_u32_e32 v18, v18, v19
	v_max_u32_e32 v19, v21, v24
	v_min_u32_e32 v21, v21, v24
	v_max_u32_e32 v24, v22, v23
	v_min_u32_e32 v22, v22, v23
	v_max_u32_e32 v23, v25, v28
	v_min_u32_e32 v25, v25, v28
	v_max_u32_e32 v28, v26, v27
	v_min_u32_e32 v26, v26, v27
	v_max_u32_e32 v27, v29, v32
	v_min_u32_e32 v29, v29, v32
	v_max_u32_e32 v32, v30, v31
	v_min_u32_e32 v30, v30, v31
	v_max_u32_e32 v17, v105, v4
	v_min_u32_e32 v4, v105, v4
	v_max_u32_e32 v105, v2, v3
	v_min_u32_e32 v2, v2, v3
	v_max_u32_e32 v3, v5, v8
	v_min_u32_e32 v5, v5, v8
	v_max_u32_e32 v8, v6, v7
	v_min_u32_e32 v6, v6, v7
	v_max_u32_e32 v7, v9, v12
	v_min_u32_e32 v9, v9, v12
	v_max_u32_e32 v12, v10, v11
	v_min_u32_e32 v10, v10, v11
	v_max_u32_e32 v11, v13, v16
	v_min_u32_e32 v13, v13, v16
	v_max_u32_e32 v16, v14, v15
	v_min_u32_e32 v14, v14, v15
	v_max_u32_e32 v48, v50, v37
	v_min_u32_e32 v37, v50, v37
	v_max_u32_e32 v50, v34, v35
	v_min_u32_e32 v34, v34, v35
	v_max_u32_e32 v35, v38, v39
	v_min_u32_e32 v38, v38, v39
	v_max_u32_e32 v39, v36, v41
	v_min_u32_e32 v36, v36, v41
	v_max_u32_e32 v41, v40, v45
	v_min_u32_e32 v40, v40, v45
	v_max_u32_e32 v45, v42, v43
	v_min_u32_e32 v42, v42, v43
	v_max_u32_e32 v43, v46, v47
	v_min_u32_e32 v46, v46, v47
	v_max_u32_e32 v47, v44, v49
	v_min_u32_e32 v44, v44, v49
	v_max_u32_e32 v81, v89, v61
	v_min_u32_e32 v61, v89, v61
	v_max_u32_e32 v89, v58, v59
	v_min_u32_e32 v58, v58, v59
	v_max_u32_e32 v59, v62, v63
	v_min_u32_e32 v62, v62, v63
	v_max_u32_e32 v63, v60, v65
	v_min_u32_e32 v60, v60, v65
	v_max_u32_e32 v65, v64, v69
	v_min_u32_e32 v64, v64, v69
	v_max_u32_e32 v69, v66, v67
	v_min_u32_e32 v66, v66, v67
	v_max_u32_e32 v67, v78, v80
	v_min_u32_e32 v78, v78, v80
	v_max_u32_e32 v80, v68, v88
	v_min_u32_e32 v68, v68, v88
	v_max_u32_e32 v31, v33, v97
	v_min_u32_e32 v33, v33, v97
	v_max_u32_e32 v97, v20, v18
	v_min_u32_e32 v18, v20, v18
	v_max_u32_e32 v20, v21, v22
	v_min_u32_e32 v21, v21, v22
	v_max_u32_e32 v22, v19, v24
	v_min_u32_e32 v19, v19, v24
	v_max_u32_e32 v24, v23, v28
	v_min_u32_e32 v23, v23, v28
	v_max_u32_e32 v28, v25, v26
	v_min_u32_e32 v25, v25, v26
	v_max_u32_e32 v26, v29, v30
	v_min_u32_e32 v29, v29, v30
	v_max_u32_e32 v30, v27, v32
	v_min_u32_e32 v27, v27, v32
	v_max_u32_e32 v15, v17, v105
	v_min_u32_e32 v17, v17, v105
	v_max_u32_e32 v105, v4, v2
	v_min_u32_e32 v2, v4, v2
	v_max_u32_e32 v4, v5, v6
	v_min_u32_e32 v5, v5, v6
	v_max_u32_e32 v6, v3, v8
	v_min_u32_e32 v3, v3, v8
	v_max_u32_e32 v8, v7, v12
	v_min_u32_e32 v7, v7, v12
	v_max_u32_e32 v12, v9, v10
	v_min_u32_e32 v9, v9, v10
	v_max_u32_e32 v10, v13, v14
	v_min_u32_e32 v13, v13, v14
	v_max_u32_e32 v14, v11, v16
	v_min_u32_e32 v11, v11, v16
	v_max_u32_e32 v49, v48, v38
	v_min_u32_e32 v38, v48, v38
	v_max_u32_e32 v48, v37, v35
	v_min_u32_e32 v35, v37, v35
	v_max_u32_e32 v37, v50, v36
	v_min_u32_e32 v36, v50, v36
	v_max_u32_e32 v50, v34, v39
	v_min_u32_e32 v34, v34, v39
	v_max_u32_e32 v39, v41, v46
	v_min_u32_e32 v41, v41, v46
	v_max_u32_e32 v46, v40, v43
	v_min_u32_e32 v40, v40, v43
	v_max_u32_e32 v43, v45, v44
	v_min_u32_e32 v44, v45, v44
	v_max_u32_e32 v45, v42, v47
	v_min_u32_e32 v42, v42, v47
	v_max_u32_e32 v88, v81, v62
	v_min_u32_e32 v62, v81, v62
	v_max_u32_e32 v81, v61, v59
	v_min_u32_e32 v59, v61, v59
	v_max_u32_e32 v61, v89, v60
	v_min_u32_e32 v60, v89, v60
	v_max_u32_e32 v89, v58, v63
	v_min_u32_e32 v58, v58, v63
	v_max_u32_e32 v63, v65, v78
	v_min_u32_e32 v65, v65, v78
	v_max_u32_e32 v78, v64, v67
	v_min_u32_e32 v64, v64, v67
	v_max_u32_e32 v67, v69, v68
	v_min_u32_e32 v68, v69, v68
	v_max_u32_e32 v69, v66, v80
	v_min_u32_e32 v66, v66, v80
	v_max_u32_e32 v32, v31, v21
	v_min_u32_e32 v21, v31, v21
	v_max_u32_e32 v31, v33, v20
	v_min_u32_e32 v20, v33, v20
	v_max_u32_e32 v33, v97, v19
	v_min_u32_e32 v19, v97, v19
	v_max_u32_e32 v97, v18, v22
	v_min_u32_e32 v18, v18, v22
	v_max_u32_e32 v22, v24, v29
	v_min_u32_e32 v24, v24, v29
	v_max_u32_e32 v29, v23, v26
	v_min_u32_e32 v23, v23, v26
	v_max_u32_e32 v26, v28, v27
	v_min_u32_e32 v27, v28, v27
	v_max_u32_e32 v28, v25, v30
	v_min_u32_e32 v25, v25, v30
	v_max_u32_e32 v16, v15, v5
	v_min_u32_e32 v5, v15, v5
	v_max_u32_e32 v15, v17, v4
	v_min_u32_e32 v4, v17, v4
	v_max_u32_e32 v17, v105, v3
	v_min_u32_e32 v3, v105, v3
	v_max_u32_e32 v105, v2, v6
	v_min_u32_e32 v2, v2, v6
	v_max_u32_e32 v6, v8, v13
	v_min_u32_e32 v8, v8, v13
	v_max_u32_e32 v13, v7, v10
	v_min_u32_e32 v7, v7, v10
	v_max_u32_e32 v10, v12, v11
	v_min_u32_e32 v11, v12, v11
	v_max_u32_e32 v12, v9, v14
	v_min_u32_e32 v9, v9, v14
	v_max_u32_e32 v47, v49, v37
	v_min_u32_e32 v37, v49, v37
	v_max_u32_e32 v49, v48, v50
	v_min_u32_e32 v48, v48, v50
	v_max_u32_e32 v50, v38, v36
	v_min_u32_e32 v36, v38, v36
	v_max_u32_e32 v38, v35, v34
	v_min_u32_e32 v34, v35, v34
	v_max_u32_e32 v35, v41, v44
	v_min_u32_e32 v41, v41, v44
	v_max_u32_e32 v44, v40, v42
	v_min_u32_e32 v40, v40, v42
	v_max_u32_e32 v42, v39, v43
	v_min_u32_e32 v39, v39, v43
	v_max_u32_e32 v43, v46, v45
	v_min_u32_e32 v45, v46, v45
	v_max_u32_e32 v80, v88, v61
	v_min_u32_e32 v61, v88, v61
	v_max_u32_e32 v88, v81, v89
	s_waitcnt vmcnt(0)
	v_pk_mul_f32 v[200:201], v[200:201], s[96:97] op_sel_hi:[1,0]
	v_pk_mul_f32 v[202:203], v[202:203], s[96:97] op_sel_hi:[1,0]
	v_pk_mul_f32 v[204:205], v[204:205], s[96:97] op_sel_hi:[1,0]
	v_pk_mul_f32 v[206:207], v[206:207], s[96:97] op_sel_hi:[1,0]
	v_pk_mul_f32 v[208:209], v[208:209], s[96:97] op_sel_hi:[1,0]
	v_pk_mul_f32 v[210:211], v[210:211], s[96:97] op_sel_hi:[1,0]
	v_pk_mul_f32 v[212:213], v[212:213], s[96:97] op_sel_hi:[1,0]
	v_pk_mul_f32 v[214:215], v[214:215], s[96:97] op_sel_hi:[1,0]
	v_pk_mul_f32 v[216:217], v[216:217], s[96:97] op_sel_hi:[1,0]
	v_pk_mul_f32 v[218:219], v[218:219], s[96:97] op_sel_hi:[1,0]
	v_pk_mul_f32 v[220:221], v[220:221], s[96:97] op_sel_hi:[1,0]
	v_pk_mul_f32 v[222:223], v[222:223], s[96:97] op_sel_hi:[1,0]
	v_pk_mul_f32 v[224:225], v[224:225], s[96:97] op_sel_hi:[1,0]
	v_pk_mul_f32 v[226:227], v[226:227], s[96:97] op_sel_hi:[1,0]
	v_pk_mul_f32 v[228:229], v[228:229], s[96:97] op_sel_hi:[1,0]
	v_pk_mul_f32 v[230:231], v[230:231], s[96:97] op_sel_hi:[1,0]
	v_cvt_scalef32_pk_fp4_f32 v232, v200, v201, 1.0
	v_cvt_scalef32_pk_fp4_f32 v233, v208, v209, 1.0
	v_cvt_scalef32_pk_fp4_f32 v234, v216, v217, 1.0
	v_cvt_scalef32_pk_fp4_f32 v235, v224, v225, 1.0
	v_cvt_scalef32_pk_fp4_f32 v232, v202, v203, 1.0 op_sel:[0,0,1,0]
	v_cvt_scalef32_pk_fp4_f32 v233, v210, v211, 1.0 op_sel:[0,0,1,0]
	v_cvt_scalef32_pk_fp4_f32 v234, v218, v219, 1.0 op_sel:[0,0,1,0]
	v_cvt_scalef32_pk_fp4_f32 v235, v226, v227, 1.0 op_sel:[0,0,1,0]
	v_cvt_scalef32_pk_fp4_f32 v232, v204, v205, 1.0 op_sel:[0,0,0,1]
	v_cvt_scalef32_pk_fp4_f32 v233, v212, v213, 1.0 op_sel:[0,0,0,1]
	v_cvt_scalef32_pk_fp4_f32 v234, v220, v221, 1.0 op_sel:[0,0,0,1]
	v_cvt_scalef32_pk_fp4_f32 v235, v228, v229, 1.0 op_sel:[0,0,0,1]
	v_cvt_scalef32_pk_fp4_f32 v232, v206, v207, 1.0 op_sel:[0,0,1,1]
	v_cvt_scalef32_pk_fp4_f32 v233, v214, v215, 1.0 op_sel:[0,0,1,1]
	v_cvt_scalef32_pk_fp4_f32 v234, v222, v223, 1.0 op_sel:[0,0,1,1]
	v_cvt_scalef32_pk_fp4_f32 v235, v230, v231, 1.0 op_sel:[0,0,1,1]
	s_nop 0
	global_store_dwordx4 v[240:241], v[232:235], off
	v_lshl_add_u64 v[240:241], v[240:241], 0, v[246:247]
	global_load_dwordx4 v[200:203], v[236:237], off
	global_load_dwordx4 v[204:207], v[236:237], off offset:16
	global_load_dwordx4 v[208:211], v[236:237], off offset:32
	global_load_dwordx4 v[212:215], v[236:237], off offset:48
	global_load_dwordx4 v[216:219], v[238:239], off
	global_load_dwordx4 v[220:223], v[238:239], off offset:16
	global_load_dwordx4 v[224:227], v[238:239], off offset:32
	global_load_dwordx4 v[228:231], v[238:239], off offset:48
	v_lshl_add_u64 v[236:237], v[236:237], 0, v[244:245]
	v_lshl_add_u64 v[238:239], v[238:239], 0, v[244:245]
	v_min_u32_e32 v81, v81, v89
	v_max_u32_e32 v89, v62, v60
	v_min_u32_e32 v60, v62, v60
	v_max_u32_e32 v62, v59, v58
	v_min_u32_e32 v58, v59, v58
	v_max_u32_e32 v59, v65, v68
	v_min_u32_e32 v65, v65, v68
	v_max_u32_e32 v68, v64, v66
	v_min_u32_e32 v64, v64, v66
	v_max_u32_e32 v66, v63, v67
	v_min_u32_e32 v63, v63, v67
	v_max_u32_e32 v67, v78, v69
	v_min_u32_e32 v69, v78, v69
	v_max_u32_e32 v30, v32, v33
	v_min_u32_e32 v32, v32, v33
	v_max_u32_e32 v33, v31, v97
	v_min_u32_e32 v31, v31, v97
	v_max_u32_e32 v97, v21, v19
	v_min_u32_e32 v19, v21, v19
	v_max_u32_e32 v21, v20, v18
	v_min_u32_e32 v18, v20, v18
	v_max_u32_e32 v20, v24, v27
	v_min_u32_e32 v24, v24, v27
	v_max_u32_e32 v27, v23, v25
	v_min_u32_e32 v23, v23, v25
	v_max_u32_e32 v25, v22, v26
	v_min_u32_e32 v22, v22, v26
	v_max_u32_e32 v26, v29, v28
	v_min_u32_e32 v28, v29, v28
	v_max_u32_e32 v14, v16, v17
	v_min_u32_e32 v16, v16, v17
	v_max_u32_e32 v17, v15, v105
	v_min_u32_e32 v15, v15, v105
	v_max_u32_e32 v105, v5, v3
	v_min_u32_e32 v3, v5, v3
	v_max_u32_e32 v5, v4, v2
	v_min_u32_e32 v2, v4, v2
	v_max_u32_e32 v4, v8, v11
	v_min_u32_e32 v8, v8, v11
	v_max_u32_e32 v11, v7, v9
	v_min_u32_e32 v7, v7, v9
	v_max_u32_e32 v9, v6, v10
	v_min_u32_e32 v6, v6, v10
	v_max_u32_e32 v10, v13, v12
	v_min_u32_e32 v12, v13, v12
	v_max_u32_e32 v46, v47, v49
	v_min_u32_e32 v47, v47, v49
	v_max_u32_e32 v49, v37, v48
	v_min_u32_e32 v37, v37, v48
	v_max_u32_e32 v48, v50, v38
	v_min_u32_e32 v38, v50, v38
	v_max_u32_e32 v50, v36, v34
	v_min_u32_e32 v34, v36, v34
	v_max_u32_e32 v36, v41, v40
	v_min_u32_e32 v40, v41, v40
	v_max_u32_e32 v41, v35, v44
	v_min_u32_e32 v35, v35, v44
	v_max_u32_e32 v44, v39, v45
	v_min_u32_e32 v39, v39, v45
	v_max_u32_e32 v45, v42, v43
	v_min_u32_e32 v42, v42, v43
	v_max_u32_e32 v78, v80, v88
	v_min_u32_e32 v80, v80, v88
	v_max_u32_e32 v88, v61, v81
	v_min_u32_e32 v61, v61, v81
	v_max_u32_e32 v81, v89, v62
	v_min_u32_e32 v62, v89, v62
	v_max_u32_e32 v89, v60, v58
	v_min_u32_e32 v58, v60, v58
	v_max_u32_e32 v60, v65, v64
	v_min_u32_e32 v64, v65, v64
	v_max_u32_e32 v65, v59, v68
	v_min_u32_e32 v59, v59, v68
	v_max_u32_e32 v68, v63, v69
	v_min_u32_e32 v63, v63, v69
	v_max_u32_e32 v69, v66, v67
	v_min_u32_e32 v66, v66, v67
	v_max_u32_e32 v29, v30, v33
	v_min_u32_e32 v30, v30, v33
	v_max_u32_e32 v33, v32, v31
	v_min_u32_e32 v31, v32, v31
	v_max_u32_e32 v32, v97, v21
	v_min_u32_e32 v21, v97, v21
	v_max_u32_e32 v97, v19, v18
	v_min_u32_e32 v18, v19, v18
	v_max_u32_e32 v19, v24, v23
	v_min_u32_e32 v23, v24, v23
	v_max_u32_e32 v24, v20, v27
	v_min_u32_e32 v20, v20, v27
	v_max_u32_e32 v27, v22, v28
	v_min_u32_e32 v22, v22, v28
	v_max_u32_e32 v28, v25, v26
	v_min_u32_e32 v25, v25, v26
	v_max_u32_e32 v13, v14, v17
	v_min_u32_e32 v14, v14, v17
	v_max_u32_e32 v17, v16, v15
	v_min_u32_e32 v15, v16, v15
	v_max_u32_e32 v16, v105, v5
	v_min_u32_e32 v5, v105, v5
	v_max_u32_e32 v105, v3, v2
	v_min_u32_e32 v2, v3, v2
	v_max_u32_e32 v3, v8, v7
	v_min_u32_e32 v7, v8, v7
	v_max_u32_e32 v8, v4, v11
	v_min_u32_e32 v4, v4, v11
	v_max_u32_e32 v11, v6, v12
	v_min_u32_e32 v6, v6, v12
	v_max_u32_e32 v12, v9, v10
	v_min_u32_e32 v9, v9, v10
	v_max_u32_e32 v43, v46, v40
	v_min_u32_e32 v40, v46, v40
	v_max_u32_e32 v46, v47, v36
	v_min_u32_e32 v36, v47, v36
	v_max_u32_e32 v47, v49, v35
	v_min_u32_e32 v35, v49, v35
	v_max_u32_e32 v49, v37, v41
	v_min_u32_e32 v37, v37, v41
	v_max_u32_e32 v41, v48, v39
	v_min_u32_e32 v39, v48, v39
	v_max_u32_e32 v48, v38, v44
	v_min_u32_e32 v38, v38, v44
	v_max_u32_e32 v44, v50, v42
	v_min_u32_e32 v42, v50, v42
	v_max_u32_e32 v50, v34, v45
	v_min_u32_e32 v34, v34, v45
	v_max_u32_e32 v67, v78, v64
	v_min_u32_e32 v64, v78, v64
	v_max_u32_e32 v78, v80, v60
	v_min_u32_e32 v60, v80, v60
	v_max_u32_e32 v80, v88, v59
	v_min_u32_e32 v59, v88, v59
	v_max_u32_e32 v88, v61, v65
	v_min_u32_e32 v61, v61, v65
	v_max_u32_e32 v65, v81, v63
	v_min_u32_e32 v63, v81, v63
	v_max_u32_e32 v81, v62, v68
	v_min_u32_e32 v62, v62, v68
	v_max_u32_e32 v68, v89, v66
	v_min_u32_e32 v66, v89, v66
	v_max_u32_e32 v89, v58, v69
	v_min_u32_e32 v58, v58, v69
	v_max_u32_e32 v26, v29, v23
	v_min_u32_e32 v23, v29, v23
	v_max_u32_e32 v29, v30, v19
	v_min_u32_e32 v19, v30, v19
	v_max_u32_e32 v30, v33, v20
	v_min_u32_e32 v20, v33, v20
	v_max_u32_e32 v33, v31, v24
	v_min_u32_e32 v24, v31, v24
	v_max_u32_e32 v31, v32, v22
	v_min_u32_e32 v22, v32, v22
	v_max_u32_e32 v32, v21, v27
	v_min_u32_e32 v21, v21, v27
	v_max_u32_e32 v27, v97, v25
	v_min_u32_e32 v25, v97, v25
	v_max_u32_e32 v97, v18, v28
	v_min_u32_e32 v18, v18, v28
	v_max_u32_e32 v10, v13, v7
	v_min_u32_e32 v7, v13, v7
	v_max_u32_e32 v13, v14, v3
	v_min_u32_e32 v3, v14, v3
	v_max_u32_e32 v14, v17, v4
	v_min_u32_e32 v4, v17, v4
	v_max_u32_e32 v17, v15, v8
	v_min_u32_e32 v8, v15, v8
	v_max_u32_e32 v15, v16, v6
	v_min_u32_e32 v6, v16, v6
	v_max_u32_e32 v16, v5, v11
	v_min_u32_e32 v5, v5, v11
	v_max_u32_e32 v11, v105, v9
	v_min_u32_e32 v9, v105, v9
	v_max_u32_e32 v105, v2, v12
	v_min_u32_e32 v2, v2, v12
	v_max_u32_e32 v45, v43, v41
	v_min_u32_e32 v41, v43, v41
	v_max_u32_e32 v43, v46, v48
	v_min_u32_e32 v46, v46, v48
	v_max_u32_e32 v48, v47, v44
	v_min_u32_e32 v44, v47, v44
	v_max_u32_e32 v47, v49, v50
	v_min_u32_e32 v49, v49, v50
	v_max_u32_e32 v50, v40, v39
	v_min_u32_e32 v39, v40, v39
	v_max_u32_e32 v40, v36, v38
	v_min_u32_e32 v36, v36, v38
	v_max_u32_e32 v38, v35, v42
	v_min_u32_e32 v35, v35, v42
	v_max_u32_e32 v42, v37, v34
	v_min_u32_e32 v34, v37, v34
	v_max_u32_e32 v69, v67, v65
	v_min_u32_e32 v65, v67, v65
	v_max_u32_e32 v67, v78, v81
	v_min_u32_e32 v78, v78, v81
	v_max_u32_e32 v81, v80, v68
	v_min_u32_e32 v68, v80, v68
	v_max_u32_e32 v80, v88, v89
	v_min_u32_e32 v88, v88, v89
	v_max_u32_e32 v89, v64, v63
	v_min_u32_e32 v63, v64, v63
	v_max_u32_e32 v64, v60, v62
	v_min_u32_e32 v60, v60, v62
	v_max_u32_e32 v62, v59, v66
	v_min_u32_e32 v59, v59, v66
	v_max_u32_e32 v66, v61, v58
	v_min_u32_e32 v58, v61, v58
	v_max_u32_e32 v28, v26, v31
	v_min_u32_e32 v26, v26, v31
	v_max_u32_e32 v31, v29, v32
	v_min_u32_e32 v29, v29, v32
	v_max_u32_e32 v32, v30, v27
	v_min_u32_e32 v27, v30, v27
	v_max_u32_e32 v30, v33, v97
	v_min_u32_e32 v33, v33, v97
	v_max_u32_e32 v97, v23, v22
	v_min_u32_e32 v22, v23, v22
	v_max_u32_e32 v23, v19, v21
	v_min_u32_e32 v19, v19, v21
	v_max_u32_e32 v21, v20, v25
	v_min_u32_e32 v20, v20, v25
	v_max_u32_e32 v25, v24, v18
	v_min_u32_e32 v18, v24, v18
	v_max_u32_e32 v12, v10, v15
	v_min_u32_e32 v10, v10, v15
	v_max_u32_e32 v15, v13, v16
	v_min_u32_e32 v13, v13, v16
	v_max_u32_e32 v16, v14, v11
	v_min_u32_e32 v11, v14, v11
	v_max_u32_e32 v14, v17, v105
	v_min_u32_e32 v17, v17, v105
	v_max_u32_e32 v105, v7, v6
	v_min_u32_e32 v6, v7, v6
	v_max_u32_e32 v7, v3, v5
	v_min_u32_e32 v3, v3, v5
	v_max_u32_e32 v5, v4, v9
	v_min_u32_e32 v4, v4, v9
	v_max_u32_e32 v9, v8, v2
	v_min_u32_e32 v2, v8, v2
	v_max_u32_e32 v37, v45, v48
	v_min_u32_e32 v45, v45, v48
	v_max_u32_e32 v48, v43, v47
	v_min_u32_e32 v43, v43, v47
	v_max_u32_e32 v47, v41, v44
	v_min_u32_e32 v41, v41, v44
	v_max_u32_e32 v44, v46, v49
	v_min_u32_e32 v46, v46, v49
	v_max_u32_e32 v49, v50, v38
	v_min_u32_e32 v38, v50, v38
	v_max_u32_e32 v50, v40, v42
	v_min_u32_e32 v40, v40, v42
	v_max_u32_e32 v42, v39, v35
	v_min_u32_e32 v35, v39, v35
	v_max_u32_e32 v39, v36, v34
	v_min_u32_e32 v34, v36, v34
	v_max_u32_e32 v61, v69, v81
	v_min_u32_e32 v69, v69, v81
	v_max_u32_e32 v81, v67, v80
	v_min_u32_e32 v67, v67, v80
	v_max_u32_e32 v80, v65, v68
	v_min_u32_e32 v65, v65, v68
	v_max_u32_e32 v68, v78, v88
	v_min_u32_e32 v78, v78, v88
	v_max_u32_e32 v88, v89, v62
	v_min_u32_e32 v62, v89, v62
	v_max_u32_e32 v89, v64, v66
	v_min_u32_e32 v64, v64, v66
	v_max_u32_e32 v66, v63, v59
	v_min_u32_e32 v59, v63, v59
	v_max_u32_e32 v63, v60, v58
	v_min_u32_e32 v58, v60, v58
	v_max_u32_e32 v24, v28, v32
	v_min_u32_e32 v28, v28, v32
	v_max_u32_e32 v32, v31, v30
	v_min_u32_e32 v30, v31, v30
	v_max_u32_e32 v31, v26, v27
	v_min_u32_e32 v26, v26, v27
	v_max_u32_e32 v27, v29, v33
	v_min_u32_e32 v29, v29, v33
	v_max_u32_e32 v33, v97, v21
	v_min_u32_e32 v21, v97, v21
	v_max_u32_e32 v97, v23, v25
	v_min_u32_e32 v23, v23, v25
	v_max_u32_e32 v25, v22, v20
	v_min_u32_e32 v20, v22, v20
	v_max_u32_e32 v22, v19, v18
	v_min_u32_e32 v18, v19, v18
	v_max_u32_e32 v8, v12, v16
	v_min_u32_e32 v12, v12, v16
	v_max_u32_e32 v16, v15, v14
	v_min_u32_e32 v14, v15, v14
	v_max_u32_e32 v15, v10, v11
	v_min_u32_e32 v10, v10, v11
	v_max_u32_e32 v11, v13, v17
	v_min_u32_e32 v13, v13, v17
	v_max_u32_e32 v17, v105, v5
	v_min_u32_e32 v5, v105, v5
	v_max_u32_e32 v105, v7, v9
	v_min_u32_e32 v7, v7, v9
	v_max_u32_e32 v9, v6, v4
	v_min_u32_e32 v4, v6, v4
	v_max_u32_e32 v6, v3, v2
	v_min_u32_e32 v2, v3, v2
	v_min_u32_e32 v36, v37, v48
	v_min_u32_e32 v51, v45, v43
	v_min_u32_e32 v52, v47, v44
	v_min_u32_e32 v53, v41, v46
	v_min_u32_e32 v54, v49, v50
	v_min_u32_e32 v55, v38, v40
	v_min_u32_e32 v56, v42, v39
	v_min_u32_e32 v57, v35, v34
	v_min_u32_e32 v60, v61, v81
	v_min_u32_e32 v90, v69, v67
	v_min_u32_e32 v91, v80, v68
	v_min_u32_e32 v92, v65, v78
	v_min_u32_e32 v93, v88, v89
	v_min_u32_e32 v94, v62, v64
	v_min_u32_e32 v95, v66, v63
	v_min_u32_e32 v96, v59, v58
	v_min_u32_e32 v19, v24, v32
	v_min_u32_e32 v98, v28, v30
	v_min_u32_e32 v99, v31, v27
	v_min_u32_e32 v100, v26, v29
	v_min_u32_e32 v101, v33, v97
	v_min_u32_e32 v102, v21, v23
	v_min_u32_e32 v103, v25, v22
	v_min_u32_e32 v104, v20, v18
	v_min_u32_e32 v3, v8, v16
	v_min_u32_e32 v106, v12, v14
	v_min_u32_e32 v107, v15, v11
	v_min_u32_e32 v108, v10, v13
	v_min_u32_e32 v109, v17, v105
	v_min_u32_e32 v110, v5, v7
	v_min_u32_e32 v111, v9, v6
	v_min_u32_e32 v112, v4, v2
	v_max3_u32 v37, v37, v48, v96
	v_max3_u32 v24, v24, v32, v112
	v_max3_u32 v32, v36, v59, v58
	v_max3_u32 v2, v19, v4, v2
	v_max3_u32 v4, v45, v43, v95
	v_max3_u32 v19, v28, v30, v111
	v_max3_u32 v28, v51, v66, v63
	v_max3_u32 v6, v98, v9, v6
	v_max3_u32 v9, v47, v44, v94
	v_max3_u32 v27, v31, v27, v110
	v_max3_u32 v30, v52, v62, v64
	v_max3_u32 v5, v99, v5, v7
	v_max3_u32 v7, v41, v46, v93
	v_max3_u32 v26, v26, v29, v109
	v_max3_u32 v29, v53, v88, v89
	v_max3_u32 v17, v100, v17, v105
	v_max3_u32 v31, v49, v50, v92
	v_max3_u32 v33, v33, v97, v108
	v_max3_u32 v36, v54, v65, v78
	v_max3_u32 v10, v101, v10, v13
	v_max3_u32 v13, v38, v40, v91
	v_max3_u32 v21, v21, v23, v107
	v_max3_u32 v23, v55, v80, v68
	v_max3_u32 v11, v102, v15, v11
	v_max3_u32 v15, v42, v39, v90
	v_max3_u32 v22, v25, v22, v106
	v_max3_u32 v25, v56, v69, v67
	s_waitcnt vmcnt(0)
	v_pk_mul_f32 v[200:201], v[200:201], s[96:97] op_sel_hi:[1,0]
	v_pk_mul_f32 v[202:203], v[202:203], s[96:97] op_sel_hi:[1,0]
	v_pk_mul_f32 v[204:205], v[204:205], s[96:97] op_sel_hi:[1,0]
	v_pk_mul_f32 v[206:207], v[206:207], s[96:97] op_sel_hi:[1,0]
	v_pk_mul_f32 v[208:209], v[208:209], s[96:97] op_sel_hi:[1,0]
	v_pk_mul_f32 v[210:211], v[210:211], s[96:97] op_sel_hi:[1,0]
	v_pk_mul_f32 v[212:213], v[212:213], s[96:97] op_sel_hi:[1,0]
	v_pk_mul_f32 v[214:215], v[214:215], s[96:97] op_sel_hi:[1,0]
	v_pk_mul_f32 v[216:217], v[216:217], s[96:97] op_sel_hi:[1,0]
	v_pk_mul_f32 v[218:219], v[218:219], s[96:97] op_sel_hi:[1,0]
	v_pk_mul_f32 v[220:221], v[220:221], s[96:97] op_sel_hi:[1,0]
	v_pk_mul_f32 v[222:223], v[222:223], s[96:97] op_sel_hi:[1,0]
	v_pk_mul_f32 v[224:225], v[224:225], s[96:97] op_sel_hi:[1,0]
	v_pk_mul_f32 v[226:227], v[226:227], s[96:97] op_sel_hi:[1,0]
	v_pk_mul_f32 v[228:229], v[228:229], s[96:97] op_sel_hi:[1,0]
	v_pk_mul_f32 v[230:231], v[230:231], s[96:97] op_sel_hi:[1,0]
	v_cvt_scalef32_pk_fp4_f32 v232, v200, v201, 1.0
	v_cvt_scalef32_pk_fp4_f32 v233, v208, v209, 1.0
	v_cvt_scalef32_pk_fp4_f32 v234, v216, v217, 1.0
	v_cvt_scalef32_pk_fp4_f32 v235, v224, v225, 1.0
	v_cvt_scalef32_pk_fp4_f32 v232, v202, v203, 1.0 op_sel:[0,0,1,0]
	v_cvt_scalef32_pk_fp4_f32 v233, v210, v211, 1.0 op_sel:[0,0,1,0]
	v_cvt_scalef32_pk_fp4_f32 v234, v218, v219, 1.0 op_sel:[0,0,1,0]
	v_cvt_scalef32_pk_fp4_f32 v235, v226, v227, 1.0 op_sel:[0,0,1,0]
	v_cvt_scalef32_pk_fp4_f32 v232, v204, v205, 1.0 op_sel:[0,0,0,1]
	v_cvt_scalef32_pk_fp4_f32 v233, v212, v213, 1.0 op_sel:[0,0,0,1]
	v_cvt_scalef32_pk_fp4_f32 v234, v220, v221, 1.0 op_sel:[0,0,0,1]
	v_cvt_scalef32_pk_fp4_f32 v235, v228, v229, 1.0 op_sel:[0,0,0,1]
	v_cvt_scalef32_pk_fp4_f32 v232, v206, v207, 1.0 op_sel:[0,0,1,1]
	v_cvt_scalef32_pk_fp4_f32 v233, v214, v215, 1.0 op_sel:[0,0,1,1]
	v_cvt_scalef32_pk_fp4_f32 v234, v222, v223, 1.0 op_sel:[0,0,1,1]
	v_cvt_scalef32_pk_fp4_f32 v235, v230, v231, 1.0 op_sel:[0,0,1,1]
	s_nop 0
	global_store_dwordx4 v[240:241], v[232:235], off
	v_lshl_add_u64 v[240:241], v[240:241], 0, v[246:247]
	global_load_dwordx4 v[200:203], v[236:237], off
	global_load_dwordx4 v[204:207], v[236:237], off offset:16
	global_load_dwordx4 v[208:211], v[236:237], off offset:32
	global_load_dwordx4 v[212:215], v[236:237], off offset:48
	global_load_dwordx4 v[216:219], v[238:239], off
	global_load_dwordx4 v[220:223], v[238:239], off offset:16
	global_load_dwordx4 v[224:227], v[238:239], off offset:32
	global_load_dwordx4 v[228:231], v[238:239], off offset:48
	v_lshl_add_u64 v[236:237], v[236:237], 0, v[244:245]
	v_lshl_add_u64 v[238:239], v[238:239], 0, v[244:245]
	v_max3_u32 v12, v103, v12, v14
	v_max3_u32 v14, v35, v34, v60
	v_max3_u32 v3, v20, v18, v3
	v_max3_u32 v18, v57, v61, v81
	v_max3_u32 v8, v104, v8, v16
	v_max_u32_e32 v16, v37, v31
	v_min_u32_e32 v20, v37, v31
	v_max_u32_e32 v31, v32, v36
	v_min_u32_e32 v32, v32, v36
	v_max_u32_e32 v34, v4, v13
	v_min_u32_e32 v4, v4, v13
	v_max_u32_e32 v13, v28, v23
	v_min_u32_e32 v23, v28, v23
	v_max_u32_e32 v28, v9, v15
	v_min_u32_e32 v9, v9, v15
	v_max_u32_e32 v15, v30, v25
	v_min_u32_e32 v25, v30, v25
	v_max_u32_e32 v30, v7, v14
	v_min_u32_e32 v7, v7, v14
	v_max_u32_e32 v14, v29, v18
	v_min_u32_e32 v18, v29, v18
	v_max_u32_e32 v42, v24, v33
	v_min_u32_e32 v24, v24, v33
	v_max_u32_e32 v33, v2, v10
	v_min_u32_e32 v2, v2, v10
	v_max_u32_e32 v10, v19, v21
	v_min_u32_e32 v19, v19, v21
	v_max_u32_e32 v21, v6, v11
	v_min_u32_e32 v6, v6, v11
	v_max_u32_e32 v11, v27, v22
	v_min_u32_e32 v22, v27, v22
	v_max_u32_e32 v27, v5, v12
	v_min_u32_e32 v5, v5, v12
	v_max_u32_e32 v12, v26, v3
	v_min_u32_e32 v3, v26, v3
	v_max_u32_e32 v26, v17, v8
	v_min_u32_e32 v8, v17, v8
	v_max_u32_e32 v29, v16, v28
	v_min_u32_e32 v16, v16, v28
	v_max_u32_e32 v28, v31, v15
	v_min_u32_e32 v15, v31, v15
	v_max_u32_e32 v31, v34, v30
	v_min_u32_e32 v30, v34, v30
	v_max_u32_e32 v34, v13, v14
	v_min_u32_e32 v13, v13, v14
	v_max_u32_e32 v14, v20, v9
	v_min_u32_e32 v9, v20, v9
	v_max_u32_e32 v20, v32, v25
	v_min_u32_e32 v25, v32, v25
	v_max_u32_e32 v32, v4, v7
	v_min_u32_e32 v4, v4, v7
	v_max_u32_e32 v7, v23, v18
	v_min_u32_e32 v18, v23, v18
	v_max_u32_e32 v17, v42, v11
	v_min_u32_e32 v11, v42, v11
	v_max_u32_e32 v42, v33, v27
	v_min_u32_e32 v27, v33, v27
	v_max_u32_e32 v33, v10, v12
	v_min_u32_e32 v10, v10, v12
	v_max_u32_e32 v12, v21, v26
	v_min_u32_e32 v21, v21, v26
	v_max_u32_e32 v26, v24, v22
	v_min_u32_e32 v22, v24, v22
	v_max_u32_e32 v24, v2, v5
	v_min_u32_e32 v2, v2, v5
	v_max_u32_e32 v5, v19, v3
	v_min_u32_e32 v3, v19, v3
	v_max_u32_e32 v19, v6, v8
	v_min_u32_e32 v6, v6, v8
	v_max_u32_e32 v23, v29, v31
	v_min_u32_e32 v29, v29, v31
	v_max_u32_e32 v31, v28, v34
	v_min_u32_e32 v28, v28, v34
	v_max_u32_e32 v34, v16, v30
	v_min_u32_e32 v16, v16, v30
	v_max_u32_e32 v30, v15, v13
	v_min_u32_e32 v13, v15, v13
	v_max_u32_e32 v15, v14, v32
	v_min_u32_e32 v14, v14, v32
	v_max_u32_e32 v32, v20, v7
	v_min_u32_e32 v7, v20, v7
	v_max_u32_e32 v20, v9, v4
	v_min_u32_e32 v4, v9, v4
	v_max_u32_e32 v9, v25, v18
	v_min_u32_e32 v18, v25, v18
	v_max_u32_e32 v8, v17, v33
	v_min_u32_e32 v17, v17, v33
	v_max_u32_e32 v33, v42, v12
	v_min_u32_e32 v12, v42, v12
	v_max_u32_e32 v42, v11, v10
	v_min_u32_e32 v10, v11, v10
	v_max_u32_e32 v11, v27, v21
	v_min_u32_e32 v21, v27, v21
	v_max_u32_e32 v27, v26, v5
	v_min_u32_e32 v5, v26, v5
	v_max_u32_e32 v26, v24, v19
	v_min_u32_e32 v19, v24, v19
	v_max_u32_e32 v24, v22, v3
	v_min_u32_e32 v3, v22, v3
	v_max_u32_e32 v22, v2, v6
	v_min_u32_e32 v2, v2, v6
	v_min_u32_e32 v25, v23, v31
	v_min_u32_e32 v35, v29, v28
	v_min_u32_e32 v36, v34, v30
	v_min_u32_e32 v37, v16, v13
	v_min_u32_e32 v38, v15, v32
	v_min_u32_e32 v39, v14, v7
	v_min_u32_e32 v40, v20, v9
	v_min_u32_e32 v41, v4, v18
	v_min_u32_e32 v6, v8, v33
	v_min_u32_e32 v43, v17, v12
	v_min_u32_e32 v44, v42, v11
	v_min_u32_e32 v45, v10, v21
	v_min_u32_e32 v46, v27, v26
	v_min_u32_e32 v47, v5, v19
	v_min_u32_e32 v48, v24, v22
	v_min_u32_e32 v49, v3, v2
	v_max3_u32 v23, v23, v31, v49
	v_max3_u32 v2, v25, v3, v2
	v_max3_u32 v3, v29, v28, v48
	v_max3_u32 v22, v35, v24, v22
	v_max3_u32 v24, v34, v30, v47
	v_max3_u32 v5, v36, v5, v19
	v_max3_u32 v13, v16, v13, v46
	v_max3_u32 v16, v37, v27, v26
	v_max3_u32 v15, v15, v32, v45
	v_max3_u32 v10, v38, v10, v21
	v_max3_u32 v7, v14, v7, v44
	v_max3_u32 v11, v39, v42, v11
	v_max3_u32 v9, v20, v9, v43
	v_max3_u32 v12, v40, v17, v12
	v_max3_u32 v4, v4, v18, v6
	v_max3_u32 v6, v41, v8, v33
	v_max_u32_e32 v8, v23, v15
	v_min_u32_e32 v14, v23, v15
	v_max_u32_e32 v15, v2, v10
	v_min_u32_e32 v2, v2, v10
	v_max_u32_e32 v10, v3, v7
	v_min_u32_e32 v3, v3, v7
	v_max_u32_e32 v7, v22, v11
	v_min_u32_e32 v11, v22, v11
	v_max_u32_e32 v17, v24, v9
	v_min_u32_e32 v9, v24, v9
	v_max_u32_e32 v18, v5, v12
	v_min_u32_e32 v5, v5, v12
	v_max_u32_e32 v12, v13, v4
	v_min_u32_e32 v4, v13, v4
	v_max_u32_e32 v13, v16, v6
	v_min_u32_e32 v6, v16, v6
	v_max_u32_e32 v16, v8, v17
	v_min_u32_e32 v8, v8, v17
	v_max_u32_e32 v17, v15, v18
	v_min_u32_e32 v15, v15, v18
	v_max_u32_e32 v18, v10, v12
	v_min_u32_e32 v10, v10, v12
	v_max_u32_e32 v12, v7, v13
	v_min_u32_e32 v7, v7, v13
	v_max_u32_e32 v13, v14, v9
	v_min_u32_e32 v9, v14, v9
	v_max_u32_e32 v14, v2, v5
	v_min_u32_e32 v2, v2, v5
	v_max_u32_e32 v5, v3, v4
	v_min_u32_e32 v3, v3, v4
	v_max_u32_e32 v4, v11, v6
	v_min_u32_e32 v6, v11, v6
	v_max_u32_e32 v11, v16, v18
	v_min_u32_e32 v16, v16, v18
	v_max_u32_e32 v18, v17, v12
	v_min_u32_e32 v12, v17, v12
	v_max_u32_e32 v17, v8, v10
	v_min_u32_e32 v8, v8, v10
	v_max_u32_e32 v10, v15, v7
	v_min_u32_e32 v7, v15, v7
	v_max_u32_e32 v15, v13, v5
	v_min_u32_e32 v5, v13, v5
	v_max_u32_e32 v13, v14, v4
	v_min_u32_e32 v4, v14, v4
	v_max_u32_e32 v14, v9, v3
	v_min_u32_e32 v3, v9, v3
	v_max_u32_e32 v9, v2, v6
	v_min_u32_e32 v2, v2, v6
	v_max_u32_e32 v6, v11, v18
	v_min_u32_e32 v11, v11, v18
	v_max_u32_e32 v18, v16, v12
	v_min_u32_e32 v12, v16, v12
	v_max_u32_e32 v16, v17, v10
	v_min_u32_e32 v10, v17, v10
	v_max_u32_e32 v17, v8, v7
	v_min_u32_e32 v7, v8, v7
	v_max_u32_e32 v8, v15, v13
	v_min_u32_e32 v13, v15, v13
	v_max_u32_e32 v15, v5, v4
	ds_bpermute_b32 v23, v153, v15
	v_min_u32_e32 v19, v3, v2
	v_min_u32_e32 v4, v5, v4
	v_max_u32_e32 v5, v14, v9
	v_max_u32_e32 v2, v3, v2
	ds_bpermute_b32 v20, v153, v19
	v_min_u32_e32 v9, v14, v9
	ds_bpermute_b32 v14, v153, v2
	ds_bpermute_b32 v21, v153, v5
	ds_bpermute_b32 v22, v153, v4
	s_waitcnt lgkmcnt(4)
	v_max_u32_e32 v23, v10, v23
	ds_bpermute_b32 v10, v153, v10
	s_waitcnt lgkmcnt(4)
	v_max_u32_e32 v3, v6, v20
	ds_bpermute_b32 v20, v153, v9
	s_waitcnt lgkmcnt(4)
	v_max_u32_e32 v14, v11, v14
	s_waitcnt lgkmcnt(3)
	v_max_u32_e32 v21, v12, v21
	s_waitcnt lgkmcnt(2)
	v_max_u32_e32 v22, v16, v22
	ds_bpermute_b32 v24, v153, v13
	ds_bpermute_b32 v25, v153, v8
	ds_bpermute_b32 v26, v153, v7
	ds_bpermute_b32 v27, v153, v17
	s_waitcnt lgkmcnt(5)
	v_max_u32_e32 v10, v15, v10
	ds_bpermute_b32 v15, v153, v16
	ds_bpermute_b32 v12, v153, v12
	ds_bpermute_b32 v16, v153, v18
	ds_bpermute_b32 v11, v153, v11
	ds_bpermute_b32 v6, v153, v6
	s_waitcnt lgkmcnt(9)
	v_max_u32_e32 v20, v18, v20
	s_waitcnt lgkmcnt(8)
	v_max_u32_e32 v17, v17, v24
	s_waitcnt lgkmcnt(7)
	v_max_u32_e32 v7, v7, v25
	s_waitcnt lgkmcnt(6)
	v_max_u32_e32 v8, v8, v26
	s_waitcnt lgkmcnt(5)
	v_max_u32_e32 v13, v13, v27
	s_waitcnt lgkmcnt(4)
	v_max_u32_e32 v4, v4, v15
	s_waitcnt lgkmcnt(3)
	v_max_u32_e32 v5, v5, v12
	s_waitcnt lgkmcnt(2)
	v_max_u32_e32 v9, v9, v16
	s_waitcnt lgkmcnt(1)
	v_max_u32_e32 v2, v2, v11
	s_waitcnt lgkmcnt(0)
	v_max_u32_e32 v6, v19, v6
	v_max_u32_e32 v11, v3, v8
	v_min_u32_e32 v3, v3, v8
	v_max_u32_e32 v8, v14, v13
	v_min_u32_e32 v12, v14, v13
	v_max_u32_e32 v13, v20, v10
	v_min_u32_e32 v10, v20, v10
	v_max_u32_e32 v14, v21, v4
	v_min_u32_e32 v4, v21, v4
	v_max_u32_e32 v15, v22, v5
	v_min_u32_e32 v5, v22, v5
	v_max_u32_e32 v16, v23, v9
	v_min_u32_e32 v9, v23, v9
	v_max_u32_e32 v18, v17, v2
	v_min_u32_e32 v2, v17, v2
	v_max_u32_e32 v17, v7, v6
	v_min_u32_e32 v6, v7, v6
	v_max_u32_e32 v7, v11, v15
	v_min_u32_e32 v11, v11, v15
	v_max_u32_e32 v15, v8, v16
	v_min_u32_e32 v8, v8, v16
	v_max_u32_e32 v16, v13, v18
	v_min_u32_e32 v13, v13, v18
	v_max_u32_e32 v18, v14, v17
	v_min_u32_e32 v14, v14, v17
	v_max_u32_e32 v17, v3, v5
	v_min_u32_e32 v3, v3, v5
	v_max_u32_e32 v5, v12, v9
	v_min_u32_e32 v9, v12, v9
	v_max_u32_e32 v12, v10, v2
	v_min_u32_e32 v2, v10, v2
	v_max_u32_e32 v10, v4, v6
	v_min_u32_e32 v4, v4, v6
	v_max_u32_e32 v6, v7, v16
	v_min_u32_e32 v7, v7, v16
	v_max_u32_e32 v16, v15, v18
	s_waitcnt vmcnt(0)
	v_pk_mul_f32 v[200:201], v[200:201], s[96:97] op_sel_hi:[1,0]
	v_pk_mul_f32 v[202:203], v[202:203], s[96:97] op_sel_hi:[1,0]
	v_pk_mul_f32 v[204:205], v[204:205], s[96:97] op_sel_hi:[1,0]
	v_pk_mul_f32 v[206:207], v[206:207], s[96:97] op_sel_hi:[1,0]
	v_pk_mul_f32 v[208:209], v[208:209], s[96:97] op_sel_hi:[1,0]
	v_pk_mul_f32 v[210:211], v[210:211], s[96:97] op_sel_hi:[1,0]
	v_pk_mul_f32 v[212:213], v[212:213], s[96:97] op_sel_hi:[1,0]
	v_pk_mul_f32 v[214:215], v[214:215], s[96:97] op_sel_hi:[1,0]
	v_pk_mul_f32 v[216:217], v[216:217], s[96:97] op_sel_hi:[1,0]
	v_pk_mul_f32 v[218:219], v[218:219], s[96:97] op_sel_hi:[1,0]
	v_pk_mul_f32 v[220:221], v[220:221], s[96:97] op_sel_hi:[1,0]
	v_pk_mul_f32 v[222:223], v[222:223], s[96:97] op_sel_hi:[1,0]
	v_pk_mul_f32 v[224:225], v[224:225], s[96:97] op_sel_hi:[1,0]
	v_pk_mul_f32 v[226:227], v[226:227], s[96:97] op_sel_hi:[1,0]
	v_pk_mul_f32 v[228:229], v[228:229], s[96:97] op_sel_hi:[1,0]
	v_pk_mul_f32 v[230:231], v[230:231], s[96:97] op_sel_hi:[1,0]
	v_cvt_scalef32_pk_fp4_f32 v232, v200, v201, 1.0
	v_cvt_scalef32_pk_fp4_f32 v233, v208, v209, 1.0
	v_cvt_scalef32_pk_fp4_f32 v234, v216, v217, 1.0
	v_cvt_scalef32_pk_fp4_f32 v235, v224, v225, 1.0
	v_cvt_scalef32_pk_fp4_f32 v232, v202, v203, 1.0 op_sel:[0,0,1,0]
	v_cvt_scalef32_pk_fp4_f32 v233, v210, v211, 1.0 op_sel:[0,0,1,0]
	v_cvt_scalef32_pk_fp4_f32 v234, v218, v219, 1.0 op_sel:[0,0,1,0]
	v_cvt_scalef32_pk_fp4_f32 v235, v226, v227, 1.0 op_sel:[0,0,1,0]
	v_cvt_scalef32_pk_fp4_f32 v232, v204, v205, 1.0 op_sel:[0,0,0,1]
	v_cvt_scalef32_pk_fp4_f32 v233, v212, v213, 1.0 op_sel:[0,0,0,1]
	v_cvt_scalef32_pk_fp4_f32 v234, v220, v221, 1.0 op_sel:[0,0,0,1]
	v_cvt_scalef32_pk_fp4_f32 v235, v228, v229, 1.0 op_sel:[0,0,0,1]
	v_cvt_scalef32_pk_fp4_f32 v232, v206, v207, 1.0 op_sel:[0,0,1,1]
	v_cvt_scalef32_pk_fp4_f32 v233, v214, v215, 1.0 op_sel:[0,0,1,1]
	v_cvt_scalef32_pk_fp4_f32 v234, v222, v223, 1.0 op_sel:[0,0,1,1]
	v_cvt_scalef32_pk_fp4_f32 v235, v230, v231, 1.0 op_sel:[0,0,1,1]
	s_nop 0
	global_store_dwordx4 v[240:241], v[232:235], off
	v_lshl_add_u64 v[240:241], v[240:241], 0, v[246:247]
	global_load_dwordx4 v[200:203], v[236:237], off
	global_load_dwordx4 v[204:207], v[236:237], off offset:16
	global_load_dwordx4 v[208:211], v[236:237], off offset:32
	global_load_dwordx4 v[212:215], v[236:237], off offset:48
	global_load_dwordx4 v[216:219], v[238:239], off
	global_load_dwordx4 v[220:223], v[238:239], off offset:16
	global_load_dwordx4 v[224:227], v[238:239], off offset:32
	global_load_dwordx4 v[228:231], v[238:239], off offset:48
	v_lshl_add_u64 v[236:237], v[236:237], 0, v[244:245]
	v_lshl_add_u64 v[238:239], v[238:239], 0, v[244:245]
	v_max_u32_e32 v19, v17, v12
	v_min_u32_e32 v12, v17, v12
	v_max_u32_e32 v17, v5, v10
	v_min_u32_e32 v21, v3, v2
	v_max_u32_e32 v22, v9, v4
	v_min_u32_e32 v4, v9, v4
	v_min_u32_e32 v15, v15, v18
	v_max_u32_e32 v18, v11, v13
	v_min_u32_e32 v11, v11, v13
	v_max_u32_e32 v13, v8, v14
	v_min_u32_e32 v14, v8, v14
	v_min_u32_e32 v5, v5, v10
	v_max_u32_e32 v8, v6, v16
	v_min_u32_e32 v10, v6, v16
	v_max_u32_e32 v39, v19, v17
	v_min_u32_e32 v40, v19, v17
	v_max_u32_e32 v45, v21, v4
	v_min_u32_e32 v46, v21, v4
	v_bitop3_b32 v4, v82, s16, v82 bitop3:0xc
	v_lshl_add_u32 v19, v87, 2, s26
	v_bitop3_b32 v6, v152, s16, v152 bitop3:0xc
	v_max_u32_e32 v41, v12, v5
	v_min_u32_e32 v42, v12, v5
	v_bitop3_b32 v5, v8, s16, v8 bitop3:0xc
	ds_write2st64_b32 v19, v4, v6 offset1:1
	v_bitop3_b32 v4, v10, s16, v10 bitop3:0xc
	v_max_u32_e32 v20, v3, v2
	v_max_u32_e32 v3, v7, v15
	v_min_u32_e32 v2, v7, v15
	ds_write2st64_b32 v19, v5, v4 offset0:16 offset1:17
	v_bitop3_b32 v4, v156, s16, v156 bitop3:0xc
	v_bitop3_b32 v6, v157, s16, v157 bitop3:0xc
	v_bitop3_b32 v5, v3, s16, v3 bitop3:0xc
	ds_write2st64_b32 v19, v4, v6 offset0:2 offset1:3
	v_bitop3_b32 v4, v2, s16, v2 bitop3:0xc
	v_max_u32_e32 v35, v18, v13
	v_min_u32_e32 v36, v18, v13
	ds_write2st64_b32 v19, v5, v4 offset0:18 offset1:19
	v_bitop3_b32 v4, v158, s16, v158 bitop3:0xc
	v_bitop3_b32 v6, v159, s16, v159 bitop3:0xc
	v_bitop3_b32 v5, v35, s16, v35 bitop3:0xc
	ds_write2st64_b32 v19, v4, v6 offset0:4 offset1:5
	v_bitop3_b32 v4, v36, s16, v36 bitop3:0xc
	v_max_u32_e32 v37, v11, v14
	v_min_u32_e32 v38, v11, v14
	ds_write2st64_b32 v19, v5, v4 offset0:20 offset1:21
	v_bitop3_b32 v4, v160, s16, v160 bitop3:0xc
	v_bitop3_b32 v6, v161, s16, v161 bitop3:0xc
	v_bitop3_b32 v5, v37, s16, v37 bitop3:0xc
	ds_write2st64_b32 v19, v4, v6 offset0:6 offset1:7
	v_bitop3_b32 v4, v38, s16, v38 bitop3:0xc
	ds_write2st64_b32 v19, v5, v4 offset0:22 offset1:23
	v_bitop3_b32 v4, v83, s16, v83 bitop3:0xc
	v_bitop3_b32 v6, v147, s16, v147 bitop3:0xc
	v_bitop3_b32 v5, v39, s16, v39 bitop3:0xc
	ds_write2st64_b32 v19, v4, v6 offset0:8 offset1:9
	v_bitop3_b32 v4, v40, s16, v40 bitop3:0xc
	ds_write2st64_b32 v19, v5, v4 offset0:24 offset1:25
	v_bitop3_b32 v4, v148, s16, v148 bitop3:0xc
	v_bitop3_b32 v6, v149, s16, v149 bitop3:0xc
	v_bitop3_b32 v5, v41, s16, v41 bitop3:0xc
	ds_write2st64_b32 v19, v4, v6 offset0:10 offset1:11
	v_bitop3_b32 v4, v42, s16, v42 bitop3:0xc
	v_max_u32_e32 v43, v20, v22
	v_min_u32_e32 v44, v20, v22
	ds_write2st64_b32 v19, v5, v4 offset0:26 offset1:27
	v_bitop3_b32 v4, v150, s16, v150 bitop3:0xc
	v_bitop3_b32 v6, v151, s16, v151 bitop3:0xc
	v_bitop3_b32 v5, v43, s16, v43 bitop3:0xc
	ds_write2st64_b32 v19, v4, v6 offset0:12 offset1:13
	v_bitop3_b32 v4, v44, s16, v44 bitop3:0xc
	ds_write2st64_b32 v19, v5, v4 offset0:28 offset1:29
	v_bitop3_b32 v4, v154, s16, v154 bitop3:0xc
	v_bitop3_b32 v6, v155, s16, v155 bitop3:0xc
	v_bitop3_b32 v5, v45, s16, v45 bitop3:0xc
	ds_write2st64_b32 v19, v4, v6 offset0:14 offset1:15
	v_bitop3_b32 v4, v46, s16, v46 bitop3:0xc
	v_cmp_gt_u32_e32 vcc, 32, v87
	ds_write2st64_b32 v19, v5, v4 offset0:30 offset1:31
	s_and_saveexec_b64 s[14:15], vcc
	s_cbranch_execz .LBB0_801
	v_cmp_lt_i32_e32 vcc, -1, v161
	v_and_b32_e32 v6, 0xffffff80, v157
	v_and_b32_e32 v9, 0xffffff80, v8
	v_cndmask_b32_e64 v4, v86, -1, vcc
	v_cmp_lt_i32_e32 vcc, -1, v160
	v_bitop3_b32 v26, v4, v161, s17 bitop3:0x78
	v_and_b32_e32 v15, 0xffffff80, v152
	v_cndmask_b32_e64 v4, v86, -1, vcc
	v_cmp_lt_i32_e32 vcc, -1, v159
	v_bitop3_b32 v28, v4, v160, s17 bitop3:0x78
	v_and_b32_e32 v11, 0xffffff80, v155
	v_cndmask_b32_e64 v4, v86, -1, vcc
	v_cmp_lt_i32_e32 vcc, -1, v158
	v_bitop3_b32 v30, v4, v159, s17 bitop3:0x78
	v_and_b32_e32 v14, 0xffffff80, v154
	v_cndmask_b32_e64 v4, v86, -1, vcc
	v_cmp_lt_i32_e32 vcc, -1, v3
	v_bitop3_b32 v49, v4, v158, s17 bitop3:0x78
	v_and_b32_e32 v4, 0xffffff80, v3
	v_cndmask_b32_e64 v3, v86, -1, vcc
	v_cmp_lt_i32_e32 vcc, -1, v157
	v_xor_b32_e32 v5, v3, v4
	v_and_b32_e32 v3, 0xffffff80, v2
	v_cndmask_b32_e64 v7, v86, -1, vcc
	v_cmp_lt_i32_e32 vcc, -1, v2
	v_xor_b32_e32 v4, v7, v6
	v_and_b32_e32 v6, 0xffffff80, v156
	v_cndmask_b32_e64 v2, v86, -1, vcc
	v_cmp_lt_i32_e32 vcc, -1, v156
	v_xor_b32_e32 v7, v2, v3
	v_mov_b32_e32 v2, v5
	v_cndmask_b32_e64 v12, v86, -1, vcc
	v_xor_b32_e32 v6, v12, v6
	v_mov_b32_e32 v3, v7
	v_pk_add_f32 v[12:13], v[6:7], v[2:3] op_sel_hi:[0,1]
	v_not_b32_e32 v23, v13
	v_or_b32_e32 v24, 0x80000000, v13
	v_cmp_gt_i32_e32 vcc, 0, v13
	v_and_b32_e32 v16, 0xffffff80, v151
	v_and_b32_e32 v17, 0xffffff80, v150
	v_cndmask_b32_e32 v13, v24, v23, vcc
	v_and_b32_e32 v13, 0xffffff00, v13
	v_or_b32_e32 v31, 0xdc, v13
	v_not_b32_e32 v13, v12
	v_or_b32_e32 v23, 0x80000000, v12
	v_cmp_gt_i32_e32 vcc, 0, v12
	v_and_b32_e32 v18, 0xffffff80, v149
	v_and_b32_e32 v20, 0xffffff80, v148
	v_cndmask_b32_e32 v12, v23, v13, vcc
	v_cmp_lt_i32_e32 vcc, -1, v8
	v_and_b32_e32 v12, 0xffffff00, v12
	v_or_b32_e32 v32, 0xdd, v12
	v_cndmask_b32_e64 v8, v86, -1, vcc
	v_cmp_lt_i32_e32 vcc, -1, v152
	v_xor_b32_e32 v9, v8, v9
	v_and_b32_e32 v21, 0xffffff80, v147
	v_cndmask_b32_e64 v12, v86, -1, vcc
	v_cmp_lt_i32_e32 vcc, -1, v155
	v_xor_b32_e32 v8, v12, v15
	v_and_b32_e32 v22, 0xffffff80, v83
	v_cndmask_b32_e64 v12, v86, -1, vcc
	v_cmp_lt_i32_e32 vcc, -1, v154
	v_xor_b32_e32 v13, v12, v11
	v_mov_b32_e32 v48, v4
	v_cndmask_b32_e64 v15, v86, -1, vcc
	v_xor_b32_e32 v12, v15, v14
	v_pk_add_f32 v[12:13], v[8:9], v[12:13] op_sel:[1,0]
	v_and_b32_e32 v25, 0xffffff80, v10
	v_not_b32_e32 v11, v13
	v_or_b32_e32 v14, 0x80000000, v13
	v_cmp_gt_i32_e32 vcc, 0, v13
	v_or_b32_e32 v13, 0x80000000, v12
	v_and_b32_e32 v27, 0xffffff80, v82
	v_cndmask_b32_e32 v11, v14, v11, vcc
	v_and_or_b32 v14, v11, s29, 15
	v_not_b32_e32 v11, v12
	v_cmp_gt_i32_e32 vcc, 0, v12
	v_mov_b32_e32 v34, v49
	v_and_b32_e32 v54, 0xffffff80, v38
	v_cndmask_b32_e32 v11, v13, v11, vcc
	v_cmp_lt_i32_e32 vcc, -1, v151
	v_and_or_b32 v15, v11, s29, 31
	v_and_b32_e32 v55, 0xffffff80, v37
	v_cndmask_b32_e64 v11, v86, -1, vcc
	v_cmp_lt_i32_e32 vcc, -1, v150
	v_xor_b32_e32 v13, v11, v16
	v_and_b32_e32 v53, 0xffffff80, v35
	v_cndmask_b32_e64 v12, v86, -1, vcc
	v_xor_b32_e32 v12, v12, v17
	v_pk_add_f32 v[12:13], v[8:9], v[12:13] op_sel:[1,0]
	v_and_b32_e32 v52, 0xffffff80, v36
	v_not_b32_e32 v11, v13
	v_or_b32_e32 v16, 0x80000000, v13
	v_cmp_gt_i32_e32 vcc, 0, v13
	v_or_b32_e32 v13, 0x80000000, v12
	v_min_u32_e32 v88, v32, v31
	v_cndmask_b32_e32 v11, v16, v11, vcc
	v_and_or_b32 v16, v11, s29, 47
	v_not_b32_e32 v11, v12
	v_cmp_gt_i32_e32 vcc, 0, v12
	s_lshl_b32 s12, s30, 6
	s_nop 0
	v_cndmask_b32_e32 v11, v13, v11, vcc
	v_cmp_lt_i32_e32 vcc, -1, v149
	v_and_or_b32 v17, v11, s29, 63
	s_nop 0
	v_cndmask_b32_e64 v11, v86, -1, vcc
	v_cmp_lt_i32_e32 vcc, -1, v148
	v_xor_b32_e32 v13, v11, v18
	s_nop 0
	v_cndmask_b32_e64 v12, v86, -1, vcc
	v_xor_b32_e32 v12, v12, v20
	v_pk_add_f32 v[12:13], v[8:9], v[12:13] op_sel:[1,0]
	s_nop 0
	v_not_b32_e32 v11, v13
	v_or_b32_e32 v18, 0x80000000, v13
	v_cmp_gt_i32_e32 vcc, 0, v13
	v_or_b32_e32 v13, 0x80000000, v12
	s_nop 0
	v_cndmask_b32_e32 v11, v18, v11, vcc
	v_and_b32_e32 v11, 0xffffff00, v11
	v_or_b32_e32 v18, 0x4f, v11
	v_not_b32_e32 v11, v12
	v_cmp_gt_i32_e32 vcc, 0, v12
	s_nop 1
	v_cndmask_b32_e32 v11, v13, v11, vcc
	v_and_b32_e32 v11, 0xffffff00, v11
	v_cmp_lt_i32_e32 vcc, -1, v147
	v_or_b32_e32 v20, 0x5f, v11
	s_nop 0
	v_cndmask_b32_e64 v11, v86, -1, vcc
	v_cmp_lt_i32_e32 vcc, -1, v83
	v_xor_b32_e32 v13, v11, v21
	s_nop 0
	v_cndmask_b32_e64 v12, v86, -1, vcc
	v_xor_b32_e32 v12, v12, v22
	v_pk_add_f32 v[12:13], v[8:9], v[12:13] op_sel:[1,0]
	s_nop 0
	v_not_b32_e32 v11, v13
	v_or_b32_e32 v21, 0x80000000, v13
	v_cmp_gt_i32_e32 vcc, 0, v13
	v_or_b32_e32 v13, 0x80000000, v12
	s_nop 0
	v_cndmask_b32_e32 v11, v21, v11, vcc
	v_and_b32_e32 v11, 0xffffff00, v11
	v_or_b32_e32 v21, 0x6f, v11
	v_not_b32_e32 v11, v12
	v_cmp_gt_i32_e32 vcc, 0, v12
	v_mov_b32_e32 v12, v7
	s_nop 0
	v_cndmask_b32_e32 v11, v13, v11, vcc
	v_mov_b32_e32 v13, v9
	v_and_b32_e32 v11, 0xffffff00, v11
	v_pk_add_f32 v[12:13], v[48:49], v[12:13]
	v_or_b32_e32 v22, 0x7f, v11
	v_not_b32_e32 v11, v12
	v_or_b32_e32 v23, 0x80000000, v12
	v_cmp_gt_i32_e32 vcc, 0, v12
	v_or_b32_e32 v12, 0x80000000, v13
	v_mov_b32_e32 v49, v5
	v_cndmask_b32_e32 v11, v23, v11, vcc
	v_and_b32_e32 v11, 0xffffff00, v11
	v_or_b32_e32 v23, 0xcc, v11
	v_not_b32_e32 v11, v13
	v_cmp_gt_i32_e32 vcc, 0, v13
	s_nop 1
	v_cndmask_b32_e32 v11, v12, v11, vcc
	v_and_b32_e32 v11, 0xffffff00, v11
	v_pk_add_f32 v[12:13], v[8:9], v[2:3] op_sel_hi:[0,1]
	v_or_b32_e32 v24, 0xbf, v11
	v_not_b32_e32 v11, v13
	v_or_b32_e32 v29, 0x80000000, v13
	v_cmp_gt_i32_e32 vcc, 0, v13
	v_or_b32_e32 v13, 0x80000000, v12
	s_nop 0
	v_cndmask_b32_e32 v11, v29, v11, vcc
	v_and_b32_e32 v11, 0xffffff00, v11
	v_or_b32_e32 v56, 0xec, v11
	v_not_b32_e32 v11, v12
	v_cmp_gt_i32_e32 vcc, 0, v12
	s_nop 1
	v_cndmask_b32_e32 v11, v13, v11, vcc
	v_cmp_lt_i32_e32 vcc, -1, v10
	v_and_b32_e32 v11, 0xffffff00, v11
	v_or_b32_e32 v57, 0xed, v11
	v_cndmask_b32_e64 v10, v86, -1, vcc
	v_cmp_lt_i32_e32 vcc, -1, v82
	v_xor_b32_e32 v11, v10, v25
	v_mov_b32_e32 v13, v11
	v_cndmask_b32_e64 v12, v86, -1, vcc
	v_xor_b32_e32 v10, v12, v27
	v_mov_b32_e32 v12, v9
	v_pk_add_f32 v[26:27], v[26:27], v[12:13] op_sel_hi:[0,1]
	v_not_b32_e32 v25, v26
	v_or_b32_e32 v29, 0x80000000, v26
	v_cmp_gt_i32_e32 vcc, 0, v26
	v_not_b32_e32 v26, v27
	v_pk_add_f32 v[50:51], v[30:31], v[12:13] op_sel_hi:[0,1]
	v_cndmask_b32_e32 v25, v29, v25, vcc
	v_or_b32_e32 v29, 0x80000000, v27
	v_cmp_gt_i32_e32 vcc, 0, v27
	v_or_b32_e32 v30, 0x80000000, v50
	v_mov_b32_e32 v48, v11
	v_cndmask_b32_e32 v26, v29, v26, vcc
	v_pk_add_f32 v[28:29], v[28:29], v[12:13] op_sel_hi:[0,1]
	v_not_b32_e32 v27, v28
	v_or_b32_e32 v33, 0x80000000, v28
	v_cmp_gt_i32_e32 vcc, 0, v28
	v_not_b32_e32 v28, v29
	v_pk_add_f32 v[2:3], v[10:11], v[2:3] op_sel_hi:[0,1]
	v_cndmask_b32_e32 v27, v33, v27, vcc
	v_or_b32_e32 v33, 0x80000000, v29
	v_cmp_gt_i32_e32 vcc, 0, v29
	v_not_b32_e32 v29, v50
	v_min_u32_e32 v68, v57, v56
	v_cndmask_b32_e32 v28, v33, v28, vcc
	v_cmp_gt_i32_e32 vcc, 0, v50
	v_or_b32_e32 v33, 0x80000000, v51
	v_max_u32_e32 v31, v32, v31
	v_cndmask_b32_e32 v29, v30, v29, vcc
	v_not_b32_e32 v30, v51
	v_cmp_gt_i32_e32 vcc, 0, v51
	v_pk_add_f32 v[50:51], v[34:35], v[48:49] op_sel_hi:[0,1]
	v_or_b32_e32 v34, 0x80000000, v51
	v_cndmask_b32_e32 v30, v33, v30, vcc
	v_not_b32_e32 v33, v51
	v_cmp_gt_i32_e32 vcc, 0, v51
	v_or_b32_e32 v47, 0x80000000, v50
	v_pk_add_f32 v[48:49], v[4:5], v[48:49] op_sel_hi:[0,1]
	v_cndmask_b32_e32 v33, v34, v33, vcc
	v_not_b32_e32 v34, v50
	v_cmp_gt_i32_e32 vcc, 0, v50
	v_not_b32_e32 v5, v49
	v_and_b32_e32 v25, 0xffffff00, v25
	v_cndmask_b32_e32 v34, v47, v34, vcc
	v_or_b32_e32 v47, 0x80000000, v49
	v_cmp_gt_i32_e32 vcc, 0, v49
	v_and_b32_e32 v26, 0xffffff00, v26
	v_and_b32_e32 v27, 0xffffff00, v27
	v_cndmask_b32_e32 v5, v47, v5, vcc
	v_and_b32_e32 v5, 0xffffff00, v5
	v_or_b32_e32 v50, 0xcd, v5
	v_not_b32_e32 v5, v48
	v_or_b32_e32 v47, 0x80000000, v48
	v_cmp_gt_i32_e32 vcc, 0, v48
	v_pk_add_f32 v[48:49], v[6:7], v[12:13] op_sel_hi:[0,1]
	v_or_b32_e32 v7, 0x80000000, v48
	v_cndmask_b32_e32 v5, v47, v5, vcc
	v_and_b32_e32 v5, 0xffffff00, v5
	v_or_b32_e32 v51, 0xce, v5
	v_not_b32_e32 v5, v48
	v_cmp_gt_i32_e32 vcc, 0, v48
	v_min_u32_e32 v91, v51, v50
	v_and_b32_e32 v28, 0xffffff00, v28
	v_cndmask_b32_e32 v5, v7, v5, vcc
	v_and_b32_e32 v5, 0xffffff00, v5
	v_or_b32_e32 v58, 0xdf, v5
	v_not_b32_e32 v5, v49
	v_or_b32_e32 v7, 0x80000000, v49
	v_cmp_gt_i32_e32 vcc, 0, v49
	v_pk_add_f32 v[48:49], v[8:9], v[12:13] op_sel_hi:[0,1]
	v_and_b32_e32 v29, 0xffffff00, v29
	v_cndmask_b32_e32 v5, v7, v5, vcc
	v_and_b32_e32 v5, 0xffffff00, v5
	v_or_b32_e32 v59, 0xde, v5
	v_not_b32_e32 v5, v48
	v_or_b32_e32 v7, 0x80000000, v48
	v_cmp_gt_i32_e32 vcc, 0, v48
	v_max_u32_e32 v83, v58, v59
	v_min_u32_e32 v58, v58, v59
	v_cndmask_b32_e32 v5, v7, v5, vcc
	v_and_b32_e32 v5, 0xffffff00, v5
	v_or_b32_e32 v48, 0xef, v5
	v_not_b32_e32 v5, v49
	v_or_b32_e32 v7, 0x80000000, v49
	v_cmp_gt_i32_e32 vcc, 0, v49
	v_max_u32_e32 v89, v83, v88
	v_max_u32_e32 v32, v58, v31
	v_cndmask_b32_e32 v5, v7, v5, vcc
	v_and_b32_e32 v5, 0xffffff00, v5
	v_cmp_lt_i32_e32 vcc, -1, v46
	v_or_b32_e32 v49, 0xee, v5
	v_and_b32_e32 v5, 0xffffff80, v46
	v_cndmask_b32_e64 v46, v86, -1, vcc
	v_cmp_lt_i32_e32 vcc, -1, v45
	v_and_b32_e32 v7, 0xffffff80, v45
	v_xor_b32_e32 v47, v46, v5
	v_cndmask_b32_e64 v45, v86, -1, vcc
	v_xor_b32_e32 v46, v45, v7
	v_pk_add_f32 v[46:47], v[10:11], v[46:47] op_sel_hi:[0,1]
	v_not_b32_e32 v5, v47
	v_or_b32_e32 v7, 0x80000000, v47
	v_cmp_gt_i32_e32 vcc, 0, v47
	v_min_u32_e32 v83, v83, v88
	v_min_u32_e32 v31, v58, v31
	v_cndmask_b32_e32 v5, v7, v5, vcc
	v_and_b32_e32 v5, 0xffffff00, v5
	v_or_b32_e32 v47, 0xf0, v5
	v_not_b32_e32 v5, v46
	v_or_b32_e32 v7, 0x80000000, v46
	v_cmp_gt_i32_e32 vcc, 0, v46
	v_max_u32_e32 v59, v89, v32
	v_max_u32_e32 v58, v83, v31
	v_cndmask_b32_e32 v5, v7, v5, vcc
	v_and_b32_e32 v5, 0xffffff00, v5
	v_cmp_lt_i32_e32 vcc, -1, v44
	v_or_b32_e32 v46, 0xf1, v5
	v_and_b32_e32 v5, 0xffffff80, v44
	v_cndmask_b32_e64 v44, v86, -1, vcc
	v_cmp_lt_i32_e32 vcc, -1, v43
	v_and_b32_e32 v7, 0xffffff80, v43
	v_xor_b32_e32 v45, v44, v5
	v_cndmask_b32_e64 v43, v86, -1, vcc
	v_xor_b32_e32 v44, v43, v7
	v_pk_add_f32 v[44:45], v[10:11], v[44:45] op_sel_hi:[0,1]
	v_not_b32_e32 v5, v45
	v_or_b32_e32 v7, 0x80000000, v45
	v_cmp_gt_i32_e32 vcc, 0, v45
	v_min_u32_e32 v64, v46, v47
	v_min_u32_e32 v32, v89, v32
	v_cndmask_b32_e32 v5, v7, v5, vcc
	v_and_b32_e32 v5, 0xffffff00, v5
	v_or_b32_e32 v45, 0xf2, v5
	v_not_b32_e32 v5, v44
	v_or_b32_e32 v7, 0x80000000, v44
	v_cmp_gt_i32_e32 vcc, 0, v44
	v_min_u32_e32 v31, v83, v31
	v_and_b32_e32 v30, 0xffffff00, v30
	v_cndmask_b32_e32 v5, v7, v5, vcc
	v_and_b32_e32 v5, 0xffffff00, v5
	v_cmp_lt_i32_e32 vcc, -1, v42
	v_or_b32_e32 v44, 0xf3, v5
	v_and_b32_e32 v5, 0xffffff80, v42
	v_cndmask_b32_e64 v42, v86, -1, vcc
	v_cmp_lt_i32_e32 vcc, -1, v41
	v_and_b32_e32 v7, 0xffffff80, v41
	v_xor_b32_e32 v43, v42, v5
	v_cndmask_b32_e64 v41, v86, -1, vcc
	v_xor_b32_e32 v42, v41, v7
	v_pk_add_f32 v[42:43], v[10:11], v[42:43] op_sel_hi:[0,1]
	v_not_b32_e32 v5, v43
	v_or_b32_e32 v7, 0x80000000, v43
	v_cmp_gt_i32_e32 vcc, 0, v43
	v_max_u32_e32 v63, v44, v45
	v_min_u32_e32 v44, v44, v45
	v_cndmask_b32_e32 v5, v7, v5, vcc
	v_and_b32_e32 v5, 0xffffff00, v5
	v_or_b32_e32 v43, 0xf4, v5
	v_not_b32_e32 v5, v42
	v_or_b32_e32 v7, 0x80000000, v42
	v_cmp_gt_i32_e32 vcc, 0, v42
	v_max_u32_e32 v45, v46, v47
	v_min_u32_e32 v65, v63, v64
	v_cndmask_b32_e32 v5, v7, v5, vcc
	v_and_b32_e32 v5, 0xffffff00, v5
	v_cmp_lt_i32_e32 vcc, -1, v40
	v_or_b32_e32 v42, 0xf5, v5
	v_and_b32_e32 v5, 0xffffff80, v40
	v_cndmask_b32_e64 v40, v86, -1, vcc
	v_cmp_lt_i32_e32 vcc, -1, v39
	v_and_b32_e32 v7, 0xffffff80, v39
	v_xor_b32_e32 v41, v40, v5
	v_cndmask_b32_e64 v39, v86, -1, vcc
	v_xor_b32_e32 v40, v39, v7
	v_pk_add_f32 v[40:41], v[10:11], v[40:41] op_sel_hi:[0,1]
	v_not_b32_e32 v5, v41
	v_or_b32_e32 v7, 0x80000000, v41
	v_cmp_gt_i32_e32 vcc, 0, v41
	v_min_u32_e32 v46, v44, v45
	v_max_u32_e32 v44, v44, v45
	v_cndmask_b32_e32 v5, v7, v5, vcc
	v_and_b32_e32 v5, 0xffffff00, v5
	v_or_b32_e32 v60, 0xf6, v5
	v_not_b32_e32 v5, v40
	v_or_b32_e32 v7, 0x80000000, v40
	v_cmp_gt_i32_e32 vcc, 0, v40
	v_min_u32_e32 v47, v65, v46
	v_max_u32_e32 v46, v65, v46
	v_cndmask_b32_e32 v5, v7, v5, vcc
	v_and_b32_e32 v5, 0xffffff00, v5
	v_cmp_lt_i32_e32 vcc, -1, v38
	v_or_b32_e32 v61, 0xf7, v5
	v_and_b32_e32 v33, 0xffffff00, v33
	v_cndmask_b32_e64 v5, v86, -1, vcc
	v_cmp_lt_i32_e32 vcc, -1, v37
	v_xor_b32_e32 v39, v5, v54
	v_max_u32_e32 v54, v61, v60
	v_cndmask_b32_e64 v7, v86, -1, vcc
	v_xor_b32_e32 v38, v7, v55
	v_pk_add_f32 v[40:41], v[8:9], v[38:39] op_sel_hi:[0,1]
	v_not_b32_e32 v5, v41
	v_or_b32_e32 v7, 0x80000000, v41
	v_cmp_gt_i32_e32 vcc, 0, v41
	v_pk_add_f32 v[38:39], v[10:11], v[38:39] op_sel_hi:[0,1]
	v_min_u32_e32 v55, v42, v43
	v_cndmask_b32_e32 v5, v7, v5, vcc
	v_and_b32_e32 v5, 0xffffff00, v5
	v_or_b32_e32 v41, 0xe8, v5
	v_not_b32_e32 v5, v40
	v_or_b32_e32 v7, 0x80000000, v40
	v_cmp_gt_i32_e32 vcc, 0, v40
	v_min_u32_e32 v60, v61, v60
	v_max_u32_e32 v42, v42, v43
	v_cndmask_b32_e32 v5, v7, v5, vcc
	v_and_b32_e32 v5, 0xffffff00, v5
	v_or_b32_e32 v40, 0xe9, v5
	v_not_b32_e32 v5, v39
	v_or_b32_e32 v7, 0x80000000, v39
	v_cmp_gt_i32_e32 vcc, 0, v39
	v_max_u32_e32 v62, v54, v55
	v_max_u32_e32 v43, v60, v42
	v_cndmask_b32_e32 v5, v7, v5, vcc
	v_and_b32_e32 v5, 0xffffff00, v5
	v_or_b32_e32 v39, 0xf8, v5
	v_not_b32_e32 v5, v38
	v_or_b32_e32 v7, 0x80000000, v38
	v_cmp_gt_i32_e32 vcc, 0, v38
	v_min_u32_e32 v54, v54, v55
	v_min_u32_e32 v42, v60, v42
	v_cndmask_b32_e32 v5, v7, v5, vcc
	v_and_b32_e32 v5, 0xffffff00, v5
	v_cmp_lt_i32_e32 vcc, -1, v36
	v_or_b32_e32 v38, 0xf9, v5
	v_max_u32_e32 v60, v63, v64
	v_cndmask_b32_e64 v5, v86, -1, vcc
	v_cmp_lt_i32_e32 vcc, -1, v35
	v_xor_b32_e32 v37, v5, v52
	v_mov_b32_e32 v5, v9
	v_cndmask_b32_e64 v7, v86, -1, vcc
	v_xor_b32_e32 v36, v7, v53
	v_mov_b32_e32 v7, v4
	v_mov_b32_e32 v4, v36
	v_pk_add_f32 v[4:5], v[6:7], v[4:5]
	v_max_u32_e32 v61, v62, v43
	v_not_b32_e32 v6, v5
	v_or_b32_e32 v7, 0x80000000, v5
	v_cmp_gt_i32_e32 vcc, 0, v5
	v_max_u32_e32 v55, v54, v42
	v_min_u32_e32 v45, v60, v44
	v_cndmask_b32_e32 v5, v7, v6, vcc
	v_and_b32_e32 v5, 0xffffff00, v5
	v_or_b32_e32 v6, 0xcf, v5
	v_not_b32_e32 v5, v4
	v_or_b32_e32 v7, 0x80000000, v4
	v_cmp_gt_i32_e32 vcc, 0, v4
	v_min_u32_e32 v43, v62, v43
	v_min_u32_e32 v42, v54, v42
	v_cndmask_b32_e32 v4, v7, v5, vcc
	v_and_b32_e32 v4, 0xffffff00, v4
	v_or_b32_e32 v7, 0xdb, v4
	v_pk_add_f32 v[4:5], v[8:9], v[36:37] op_sel_hi:[0,1]
	v_not_b32_e32 v8, v5
	v_or_b32_e32 v9, 0x80000000, v5
	v_cmp_gt_i32_e32 vcc, 0, v5
	v_max_u32_e32 v44, v60, v44
	v_min_u32_e32 v66, v61, v47
	v_cndmask_b32_e32 v5, v9, v8, vcc
	v_and_b32_e32 v5, 0xffffff00, v5
	v_or_b32_e32 v8, 0xea, v5
	v_not_b32_e32 v5, v4
	v_or_b32_e32 v9, 0x80000000, v4
	v_cmp_gt_i32_e32 vcc, 0, v4
	v_min_u32_e32 v63, v55, v45
	v_min_u32_e32 v62, v43, v46
	v_cndmask_b32_e32 v4, v9, v5, vcc
	v_and_b32_e32 v4, 0xffffff00, v4
	v_or_b32_e32 v9, 0xeb, v4
	v_pk_add_f32 v[4:5], v[10:11], v[36:37] op_sel_hi:[0,1]
	v_not_b32_e32 v35, v5
	v_or_b32_e32 v36, 0x80000000, v5
	v_cmp_gt_i32_e32 vcc, 0, v5
	v_min_u32_e32 v37, v38, v39
	v_min_u32_e32 v54, v42, v44
	v_cndmask_b32_e32 v5, v36, v35, vcc
	v_not_b32_e32 v35, v4
	v_or_b32_e32 v36, 0x80000000, v4
	v_cmp_gt_i32_e32 vcc, 0, v4
	v_and_b32_e32 v5, 0xffffff00, v5
	v_or_b32_e32 v5, 0xfa, v5
	v_cndmask_b32_e32 v4, v36, v35, vcc
	v_not_b32_e32 v35, v3
	v_or_b32_e32 v36, 0x80000000, v3
	v_cmp_gt_i32_e32 vcc, 0, v3
	s_mov_b64 s[50:51], exec
	s_mov_b64 exec, -1
	s_waitcnt vmcnt(0)
	v_pk_mul_f32 v[200:201], v[200:201], s[96:97] op_sel_hi:[1,0]
	v_pk_mul_f32 v[202:203], v[202:203], s[96:97] op_sel_hi:[1,0]
	v_pk_mul_f32 v[204:205], v[204:205], s[96:97] op_sel_hi:[1,0]
	v_pk_mul_f32 v[206:207], v[206:207], s[96:97] op_sel_hi:[1,0]
	v_pk_mul_f32 v[208:209], v[208:209], s[96:97] op_sel_hi:[1,0]
	v_pk_mul_f32 v[210:211], v[210:211], s[96:97] op_sel_hi:[1,0]
	v_pk_mul_f32 v[212:213], v[212:213], s[96:97] op_sel_hi:[1,0]
	v_pk_mul_f32 v[214:215], v[214:215], s[96:97] op_sel_hi:[1,0]
	v_pk_mul_f32 v[216:217], v[216:217], s[96:97] op_sel_hi:[1,0]
	v_pk_mul_f32 v[218:219], v[218:219], s[96:97] op_sel_hi:[1,0]
	v_pk_mul_f32 v[220:221], v[220:221], s[96:97] op_sel_hi:[1,0]
	v_pk_mul_f32 v[222:223], v[222:223], s[96:97] op_sel_hi:[1,0]
	v_pk_mul_f32 v[224:225], v[224:225], s[96:97] op_sel_hi:[1,0]
	v_pk_mul_f32 v[226:227], v[226:227], s[96:97] op_sel_hi:[1,0]
	v_pk_mul_f32 v[228:229], v[228:229], s[96:97] op_sel_hi:[1,0]
	v_pk_mul_f32 v[230:231], v[230:231], s[96:97] op_sel_hi:[1,0]
	v_cvt_scalef32_pk_fp4_f32 v232, v200, v201, 1.0
	v_cvt_scalef32_pk_fp4_f32 v233, v208, v209, 1.0
	v_cvt_scalef32_pk_fp4_f32 v234, v216, v217, 1.0
	v_cvt_scalef32_pk_fp4_f32 v235, v224, v225, 1.0
	v_cvt_scalef32_pk_fp4_f32 v232, v202, v203, 1.0 op_sel:[0,0,1,0]
	v_cvt_scalef32_pk_fp4_f32 v233, v210, v211, 1.0 op_sel:[0,0,1,0]
	v_cvt_scalef32_pk_fp4_f32 v234, v218, v219, 1.0 op_sel:[0,0,1,0]
	v_cvt_scalef32_pk_fp4_f32 v235, v226, v227, 1.0 op_sel:[0,0,1,0]
	v_cvt_scalef32_pk_fp4_f32 v232, v204, v205, 1.0 op_sel:[0,0,0,1]
	v_cvt_scalef32_pk_fp4_f32 v233, v212, v213, 1.0 op_sel:[0,0,0,1]
	v_cvt_scalef32_pk_fp4_f32 v234, v220, v221, 1.0 op_sel:[0,0,0,1]
	v_cvt_scalef32_pk_fp4_f32 v235, v228, v229, 1.0 op_sel:[0,0,0,1]
	v_cvt_scalef32_pk_fp4_f32 v232, v206, v207, 1.0 op_sel:[0,0,1,1]
	v_cvt_scalef32_pk_fp4_f32 v233, v214, v215, 1.0 op_sel:[0,0,1,1]
	v_cvt_scalef32_pk_fp4_f32 v234, v222, v223, 1.0 op_sel:[0,0,1,1]
	v_cvt_scalef32_pk_fp4_f32 v235, v230, v231, 1.0 op_sel:[0,0,1,1]
	s_nop 0
	global_store_dwordx4 v[240:241], v[232:235], off
	v_lshl_add_u64 v[240:241], v[240:241], 0, v[246:247]
	global_load_dwordx4 v[200:203], v[236:237], off
	global_load_dwordx4 v[204:207], v[236:237], off offset:16
	global_load_dwordx4 v[208:211], v[236:237], off offset:32
	global_load_dwordx4 v[212:215], v[236:237], off offset:48
	global_load_dwordx4 v[216:219], v[238:239], off
	global_load_dwordx4 v[220:223], v[238:239], off offset:16
	global_load_dwordx4 v[224:227], v[238:239], off offset:32
	global_load_dwordx4 v[228:231], v[238:239], off offset:48
	v_lshl_add_u64 v[236:237], v[236:237], 0, v[244:245]
	v_lshl_add_u64 v[238:239], v[238:239], 0, v[244:245]
	s_mov_b64 exec, s[50:51]
	s_nop 4
	v_and_b32_e32 v4, 0xffffff00, v4
	v_or_b32_e32 v4, 0xfb, v4
	v_cndmask_b32_e32 v3, v36, v35, vcc
	v_and_b32_e32 v3, 0xffffff00, v3
	v_or_b32_e32 v35, 0xfc, v3
	v_not_b32_e32 v3, v2
	v_or_b32_e32 v36, 0x80000000, v2
	v_cmp_gt_i32_e32 vcc, 0, v2
	v_min_u32_e32 v64, v66, v63
	v_min_u32_e32 v60, v62, v54
	v_cndmask_b32_e32 v2, v36, v3, vcc
	v_and_b32_e32 v2, 0xffffff00, v2
	v_or_b32_e32 v36, 0xfd, v2
	v_pk_add_f32 v[2:3], v[10:11], v[12:13] op_sel_hi:[0,1]
	v_not_b32_e32 v10, v3
	v_or_b32_e32 v11, 0x80000000, v3
	v_cmp_gt_i32_e32 vcc, 0, v3
	v_min_u32_e32 v65, v64, v60
	v_max_u32_e32 v78, v9, v8
	v_cndmask_b32_e32 v3, v11, v10, vcc
	v_not_b32_e32 v10, v2
	v_or_b32_e32 v11, 0x80000000, v2
	v_cmp_gt_i32_e32 vcc, 0, v2
	v_and_b32_e32 v3, 0xffffff00, v3
	v_or_b32_e32 v3, 0xfe, v3
	v_cndmask_b32_e32 v2, v11, v10, vcc
	v_or_b32_e32 v2, 0xff, v2
	v_max_u32_e32 v10, v2, v3
	v_min_u32_e32 v11, v36, v35
	v_min_u32_e32 v2, v2, v3
	v_max_u32_e32 v3, v36, v35
	v_max_u32_e32 v36, v4, v5
	v_min_u32_e32 v4, v4, v5
	v_max_u32_e32 v5, v38, v39
	v_max_u32_e32 v12, v10, v11
	v_max_u32_e32 v13, v2, v3
	v_min_u32_e32 v52, v36, v37
	v_min_u32_e32 v38, v4, v5
	v_min_u32_e32 v10, v10, v11
	v_min_u32_e32 v2, v2, v3
	v_max_u32_e32 v11, v36, v37
	v_max_u32_e32 v4, v4, v5
	v_max_u32_e32 v35, v12, v13
	v_min_u32_e32 v39, v52, v38
	v_max_u32_e32 v3, v10, v2
	v_min_u32_e32 v5, v11, v4
	v_min_u32_e32 v12, v12, v13
	v_max_u32_e32 v13, v52, v38
	v_min_u32_e32 v2, v10, v2
	v_max_u32_e32 v4, v11, v4
	v_max_u32_e32 v53, v35, v39
	v_max_u32_e32 v36, v3, v5
	v_max_u32_e32 v38, v12, v13
	v_max_u32_e32 v10, v2, v4
	v_max_u32_e32 v37, v53, v36
	v_max_u32_e32 v11, v38, v10
	v_max_u32_e32 v52, v37, v11
	v_min_u32_e32 v11, v37, v11
	v_max_u32_e32 v37, v64, v60
	v_max_u32_e32 v64, v48, v49
	v_min_u32_e32 v48, v48, v49
	v_max_u32_e32 v49, v57, v56
	v_min_u32_e32 v80, v40, v41
	v_min_u32_e32 v8, v9, v8
	v_max_u32_e32 v9, v40, v41
	v_max_u32_e32 v90, v7, v6
	v_min_u32_e32 v6, v7, v6
	v_max_u32_e32 v7, v51, v50
	v_max_u32_e32 v69, v64, v68
	v_max_u32_e32 v56, v48, v49
	v_min_u32_e32 v81, v78, v80
	v_min_u32_e32 v40, v8, v9
	v_min_u32_e32 v64, v64, v68
	v_min_u32_e32 v48, v48, v49
	v_max_u32_e32 v68, v78, v80
	v_max_u32_e32 v8, v8, v9
	v_min_u32_e32 v92, v90, v91
	v_min_u32_e32 v50, v6, v7
	v_max_u32_e32 v88, v90, v91
	v_max_u32_e32 v6, v6, v7
	v_max_u32_e32 v57, v69, v56
	v_min_u32_e32 v41, v81, v40
	v_max_u32_e32 v49, v64, v48
	v_min_u32_e32 v9, v68, v8
	v_min_u32_e32 v56, v69, v56
	v_max_u32_e32 v40, v81, v40
	v_min_u32_e32 v48, v64, v48
	v_max_u32_e32 v8, v68, v8
	v_min_u32_e32 v51, v92, v50
	v_min_u32_e32 v7, v88, v6
	v_max_u32_e32 v50, v92, v50
	v_max_u32_e32 v6, v88, v6
	v_min_u32_e32 v35, v35, v39
	v_min_u32_e32 v3, v3, v5
	v_min_u32_e32 v12, v12, v13
	v_min_u32_e32 v2, v2, v4
	v_max_u32_e32 v39, v61, v47
	v_max_u32_e32 v45, v55, v45
	v_max_u32_e32 v43, v43, v46
	v_max_u32_e32 v42, v42, v44
	v_max_u32_e32 v82, v57, v41
	v_max_u32_e32 v78, v49, v9
	v_max_u32_e32 v69, v56, v40
	v_max_u32_e32 v64, v48, v8
	v_min_u32_e32 v93, v59, v51
	v_min_u32_e32 v90, v58, v7
	v_min_u32_e32 v89, v32, v50
	v_min_u32_e32 v83, v31, v6
	v_min_u32_e32 v41, v57, v41
	v_min_u32_e32 v9, v49, v9
	v_min_u32_e32 v40, v56, v40
	v_min_u32_e32 v8, v48, v8
	v_max_u32_e32 v51, v59, v51
	v_max_u32_e32 v7, v58, v7
	v_max_u32_e32 v32, v32, v50
	v_max_u32_e32 v6, v31, v6
	v_max_u32_e32 v5, v35, v3
	v_max_u32_e32 v4, v12, v2
	v_min_u32_e32 v47, v39, v45
	v_min_u32_e32 v44, v43, v42
	v_min_u32_e32 v36, v53, v36
	v_min_u32_e32 v10, v38, v10
	v_max_u32_e32 v53, v66, v63
	v_max_u32_e32 v54, v62, v54
	v_min_u32_e32 v3, v35, v3
	v_min_u32_e32 v2, v12, v2
	v_max_u32_e32 v35, v39, v45
	v_max_u32_e32 v39, v43, v42
	v_max_u32_e32 v80, v82, v78
	v_max_u32_e32 v68, v69, v64
	v_min_u32_e32 v91, v93, v90
	v_min_u32_e32 v88, v89, v83
	v_max_u32_e32 v49, v41, v9
	v_max_u32_e32 v48, v40, v8
	v_min_u32_e32 v57, v51, v7
	v_min_u32_e32 v31, v32, v6
	v_min_u32_e32 v78, v82, v78
	v_min_u32_e32 v64, v69, v64
	v_max_u32_e32 v82, v93, v90
	v_max_u32_e32 v83, v89, v83
	v_min_u32_e32 v9, v41, v9
	v_min_u32_e32 v8, v40, v8
	v_max_u32_e32 v7, v51, v7
	v_max_u32_e32 v6, v32, v6
	v_max_u32_e32 v13, v5, v4
	v_max_u32_e32 v38, v36, v10
	v_max_u32_e32 v12, v3, v2
	v_min_u32_e32 v4, v5, v4
	v_max_u32_e32 v5, v47, v44
	v_min_u32_e32 v10, v36, v10
	v_max_u32_e32 v36, v53, v54
	v_min_u32_e32 v2, v3, v2
	v_max_u32_e32 v3, v35, v39
	v_max_u32_e32 v81, v80, v68
	v_min_u32_e32 v92, v91, v88
	v_max_u32_e32 v56, v49, v48
	v_min_u32_e32 v50, v57, v31
	v_max_u32_e32 v69, v78, v64
	v_min_u32_e32 v89, v82, v83
	v_max_u32_e32 v40, v9, v8
	v_min_u32_e32 v32, v7, v6
	v_min_u32_e32 v68, v80, v68
	v_max_u32_e32 v80, v91, v88
	v_min_u32_e32 v48, v49, v48
	v_max_u32_e32 v31, v57, v31
	v_min_u32_e32 v64, v78, v64
	v_max_u32_e32 v78, v82, v83
	v_min_u32_e32 v8, v9, v8
	v_max_u32_e32 v6, v7, v6
	v_max_u32_e32 v67, v52, v65
	v_min_u32_e32 v46, v47, v44
	v_min_u32_e32 v62, v53, v54
	v_min_u32_e32 v42, v35, v39
	v_max_u32_e32 v60, v11, v37
	v_max_u32_e32 v44, v4, v5
	v_max_u32_e32 v53, v10, v36
	v_max_u32_e32 v35, v2, v3
	v_min_u32_e32 v58, v56, v50
	v_min_u32_e32 v41, v40, v32
	v_min_u32_e32 v88, v68, v80
	v_min_u32_e32 v49, v48, v31
	v_min_u32_e32 v82, v64, v78
	v_min_u32_e32 v7, v8, v6
	v_min_u32_e32 v52, v52, v65
	v_min_u32_e32 v11, v11, v37
	v_min_u32_e32 v4, v4, v5
	v_min_u32_e32 v10, v10, v36
	v_min_u32_e32 v2, v2, v3
	v_max_u32_e32 v37, v81, v92
	v_max_u32_e32 v50, v56, v50
	v_max_u32_e32 v65, v69, v89
	v_max_u32_e32 v32, v40, v32
	v_max_u32_e32 v68, v68, v80
	v_max_u32_e32 v31, v48, v31
	v_max_u32_e32 v64, v64, v78
	v_max_u32_e32 v6, v8, v6
	v_max_u32_e32 v55, v13, v46
	v_max_u32_e32 v63, v38, v62
	v_max_u32_e32 v43, v12, v42
	v_min_u32_e32 v94, v81, v92
	v_min_u32_e32 v90, v69, v89
	v_min_u32_e32 v13, v13, v46
	v_min_u32_e32 v38, v38, v62
	v_min_u32_e32 v12, v12, v42
	v_max_u32_e32 v5, v11, v4
	v_max_u32_e32 v3, v10, v2
	v_min_u32_e32 v56, v37, v50
	v_min_u32_e32 v40, v65, v32
	v_min_u32_e32 v48, v68, v31
	v_min_u32_e32 v8, v64, v6
	v_max_u32_e32 v47, v60, v44
	v_max_u32_e32 v39, v53, v35
	v_min_u32_e32 v59, v94, v58
	v_min_u32_e32 v51, v90, v41
	v_min_u32_e32 v57, v88, v49
	v_min_u32_e32 v9, v82, v7
	v_max_u32_e32 v46, v52, v13
	v_max_u32_e32 v42, v38, v12
	v_max_u32_e32 v36, v5, v3
	v_min_u32_e32 v78, v48, v8
	v_min_u32_e32 v4, v11, v4
	v_max_u32_e32 v11, v37, v50
	v_max_u32_e32 v32, v65, v32
	v_max_u32_e32 v31, v68, v31
	v_max_u32_e32 v6, v64, v6
	v_min_u32_e32 v3, v5, v3
	v_max_u32_e32 v5, v56, v40
	v_max_u32_e32 v8, v48, v8
	v_max_u32_e32 v61, v67, v55
	v_max_u32_e32 v45, v63, v43
	v_max_u32_e32 v54, v47, v39
	v_min_u32_e32 v83, v57, v9
	v_max_u32_e32 v62, v46, v42
	v_min_u32_e32 v69, v56, v40
	v_min_u32_e32 v55, v67, v55
	v_min_u32_e32 v43, v63, v43
	v_min_u32_e32 v44, v60, v44
	v_min_u32_e32 v35, v53, v35
	v_max_u32_e32 v58, v94, v58
	v_max_u32_e32 v41, v90, v41
	v_max_u32_e32 v49, v88, v49
	v_max_u32_e32 v7, v82, v7
	v_min_u32_e32 v13, v52, v13
	v_min_u32_e32 v12, v38, v12
	v_min_u32_e32 v2, v10, v2
	v_min_u32_e32 v37, v11, v32
	v_min_u32_e32 v50, v31, v6
	v_min_u32_e32 v39, v47, v39
	v_max_u32_e32 v47, v59, v51
	v_max_u32_e32 v9, v57, v9
	v_min_u32_e32 v42, v46, v42
	v_min_u32_e32 v40, v5, v8
	v_and_b32_e32 v34, 0xffffff00, v34
	v_max_u32_e32 v66, v61, v45
	v_min_u32_e32 v93, v59, v51
	v_max_u32_e32 v63, v55, v43
	v_max_u32_e32 v53, v44, v35
	v_min_u32_e32 v60, v58, v41
	v_min_u32_e32 v67, v49, v7
	v_max_u32_e32 v38, v13, v12
	v_max_u32_e32 v10, v4, v2
	v_min_u32_e32 v52, v37, v50
	v_min_u32_e32 v45, v61, v45
	v_min_u32_e32 v51, v47, v9
	v_max3_u32 v40, v42, v3, v40
	v_min_u32_e32 v43, v55, v43
	v_min_u32_e32 v35, v44, v35
	v_max_u32_e32 v41, v58, v41
	v_max_u32_e32 v7, v49, v7
	v_min_u32_e32 v2, v4, v2
	v_max_u32_e32 v4, v11, v32
	v_max_u32_e32 v6, v31, v6
	v_min_u32_e32 v3, v42, v3
	v_or_b32_e32 v25, 0x8f, v25
	v_or_b32_e32 v26, 0x8e, v26
	v_or_b32_e32 v27, 0x9f, v27
	v_or_b32_e32 v28, 0x9e, v28
	v_or_b32_e32 v29, 0xaf, v29
	v_or_b32_e32 v30, 0xae, v30
	v_or_b32_e32 v33, 0xbd, v33
	v_or_b32_e32 v34, 0xbe, v34
	v_max3_u32 v52, v38, v10, v52
	v_max3_u32 v51, v45, v39, v51
	v_min_u32_e32 v44, v41, v7
	v_min_u32_e32 v12, v13, v12
	v_min_u32_e32 v11, v4, v6
	v_min_u32_e32 v10, v38, v10
	v_min_u32_e32 v39, v45, v39
	v_max3_u32 v3, v3, v5, v8
	v_min_u32_e32 v8, v43, v35
	v_min_u32_e32 v91, v93, v83
	v_max3_u32 v44, v43, v35, v44
	v_max3_u32 v11, v12, v2, v11
	v_max3_u32 v10, v10, v37, v50
	v_max3_u32 v9, v39, v47, v9
	v_max3_u32 v7, v8, v41, v7
	v_min_u32_e32 v2, v12, v2
	v_max_u32_e32 v12, v23, v24
	v_min_u32_e32 v35, v34, v33
	v_min_u32_e32 v23, v23, v24
	v_max_u32_e32 v24, v34, v33
	v_max_u32_e32 v41, v29, v30
	v_min_u32_e32 v42, v27, v28
	v_min_u32_e32 v29, v29, v30
	v_max_u32_e32 v27, v27, v28
	v_max_u32_e32 v47, v25, v26
	v_min_u32_e32 v50, v22, v21
	v_min_u32_e32 v25, v25, v26
	v_max_u32_e32 v21, v22, v21
	v_max_u32_e32 v55, v20, v18
	v_min_u32_e32 v56, v17, v16
	v_min_u32_e32 v18, v20, v18
	v_max_u32_e32 v16, v17, v16
	v_max3_u32 v91, v66, v54, v91
	v_min_u32_e32 v48, v66, v54
	v_max_u32_e32 v39, v12, v35
	v_max_u32_e32 v33, v23, v24
	v_min_u32_e32 v43, v41, v42
	v_min_u32_e32 v28, v29, v27
	v_min_u32_e32 v12, v12, v35
	v_min_u32_e32 v23, v23, v24
	v_max_u32_e32 v35, v41, v42
	v_max_u32_e32 v27, v29, v27
	v_max_u32_e32 v54, v47, v50
	v_max_u32_e32 v22, v25, v21
	v_min_u32_e32 v57, v55, v56
	v_min_u32_e32 v17, v18, v16
	v_min_u32_e32 v47, v47, v50
	v_min_u32_e32 v21, v25, v21
	v_max_u32_e32 v50, v55, v56
	v_max_u32_e32 v16, v18, v16
	v_max_u32_e32 v34, v39, v33
	v_min_u32_e32 v30, v43, v28
	v_max_u32_e32 v24, v12, v23
	v_min_u32_e32 v29, v35, v27
	v_min_u32_e32 v33, v39, v33
	v_max_u32_e32 v28, v43, v28
	v_min_u32_e32 v12, v12, v23
	v_max_u32_e32 v23, v35, v27
	v_max_u32_e32 v26, v54, v22
	v_min_u32_e32 v20, v57, v17
	v_max_u32_e32 v25, v47, v21
	v_min_u32_e32 v18, v50, v16
	v_min_u32_e32 v22, v54, v22
	v_max_u32_e32 v17, v57, v17
	v_min_u32_e32 v21, v47, v21
	v_max_u32_e32 v16, v50, v16
	v_max_u32_e32 v45, v34, v30
	v_max_u32_e32 v41, v24, v29
	v_max_u32_e32 v39, v33, v28
	v_max_u32_e32 v27, v12, v23
	v_min_u32_e32 v58, v26, v20
	v_min_u32_e32 v55, v25, v18
	v_min_u32_e32 v54, v22, v17
	v_min_u32_e32 v47, v21, v16
	v_min_u32_e32 v30, v34, v30
	v_min_u32_e32 v24, v24, v29
	v_min_u32_e32 v28, v33, v28
	v_min_u32_e32 v12, v12, v23
	v_max_u32_e32 v20, v26, v20
	v_max_u32_e32 v18, v25, v18
	v_max_u32_e32 v17, v22, v17
	v_max_u32_e32 v16, v21, v16
	v_max_u32_e32 v42, v45, v41
	v_max_u32_e32 v35, v39, v27
	v_min_u32_e32 v56, v58, v55
	v_min_u32_e32 v50, v54, v47
	v_max_u32_e32 v29, v30, v24
	v_max_u32_e32 v23, v28, v12
	v_min_u32_e32 v25, v20, v18
	v_min_u32_e32 v21, v17, v16
	v_min_u32_e32 v41, v45, v41
	v_min_u32_e32 v27, v39, v27
	v_max_u32_e32 v45, v58, v55
	v_max_u32_e32 v47, v54, v47
	v_min_u32_e32 v24, v30, v24
	v_min_u32_e32 v12, v28, v12
	v_max_u32_e32 v18, v20, v18
	v_max_u32_e32 v16, v17, v16
	v_max_u32_e32 v43, v42, v35
	v_min_u32_e32 v57, v56, v50
	v_max_u32_e32 v33, v29, v23
	v_min_u32_e32 v22, v25, v21
	v_max_u32_e32 v39, v41, v27
	v_min_u32_e32 v54, v45, v47
	v_max_u32_e32 v28, v24, v12
	v_min_u32_e32 v17, v18, v16
	v_min_u32_e32 v35, v42, v35
	v_max_u32_e32 v42, v56, v50
	v_min_u32_e32 v23, v29, v23
	v_max_u32_e32 v21, v25, v21
	v_min_u32_e32 v27, v41, v27
	v_max_u32_e32 v41, v45, v47
	v_min_u32_e32 v12, v24, v12
	v_max_u32_e32 v16, v18, v16
	v_max_u32_e32 v59, v43, v57
	v_max_u32_e32 v26, v33, v22
	v_max_u32_e32 v55, v39, v54
	v_max_u32_e32 v20, v28, v17
	v_max_u32_e32 v50, v35, v42
	v_max_u32_e32 v25, v23, v21
	v_max_u32_e32 v45, v27, v41
	v_max_u32_e32 v18, v12, v16
	v_min_u32_e32 v43, v43, v57
	v_min_u32_e32 v22, v33, v22
	v_min_u32_e32 v39, v39, v54
	v_min_u32_e32 v17, v28, v17
	v_min_u32_e32 v35, v35, v42
	v_min_u32_e32 v21, v23, v21
	v_min_u32_e32 v27, v27, v41
	v_min_u32_e32 v12, v12, v16
	v_max_u32_e32 v33, v43, v22
	v_max_u32_e32 v28, v39, v17
	v_max_u32_e32 v23, v35, v21
	v_max_u32_e32 v16, v27, v12
	v_min_u32_e32 v22, v43, v22
	v_min_u32_e32 v17, v39, v17
	v_min_u32_e32 v21, v35, v21
	v_min_u32_e32 v12, v27, v12
	v_min_u32_e32 v80, v69, v78
	v_min_u32_e32 v82, v60, v67
	v_max_u32_e32 v34, v59, v26
	v_max_u32_e32 v30, v55, v20
	v_max_u32_e32 v29, v50, v25
	v_max_u32_e32 v24, v45, v18
	v_min_u32_e32 v26, v59, v26
	v_min_u32_e32 v20, v55, v20
	v_min_u32_e32 v25, v50, v25
	v_min_u32_e32 v18, v45, v18
	v_max_u32_e32 v39, v22, v17
	v_max_u32_e32 v27, v21, v12
	v_min_u32_e32 v17, v22, v17
	v_min_u32_e32 v12, v21, v12
	v_min_u32_e32 v21, v15, v14
	v_max3_u32 v80, v62, v36, v80
	v_max3_u32 v82, v63, v53, v82
	v_min_u32_e32 v36, v62, v36
	v_min_u32_e32 v53, v63, v53
	v_max_u32_e32 v58, v34, v30
	v_max_u32_e32 v47, v29, v24
	v_max_u32_e32 v54, v33, v28
	v_max_u32_e32 v41, v23, v16
	v_max_u32_e32 v55, v26, v20
	v_max_u32_e32 v45, v25, v18
	v_min_u32_e32 v30, v34, v30
	v_min_u32_e32 v24, v29, v24
	v_min_u32_e32 v28, v33, v28
	v_min_u32_e32 v16, v23, v16
	v_min_u32_e32 v20, v26, v20
	v_min_u32_e32 v18, v25, v18
	v_max3_u32 v21, v17, v12, v21
	v_min_u32_e32 v12, v17, v12
	v_max3_u32 v48, v48, v93, v83
	v_max3_u32 v36, v36, v69, v78
	v_max3_u32 v53, v53, v60, v67
	v_max3_u32 v2, v2, v4, v6
	v_max_u32_e32 v56, v58, v47
	v_max_u32_e32 v42, v54, v41
	v_max_u32_e32 v50, v55, v45
	v_max_u32_e32 v35, v39, v27
	v_max_u32_e32 v29, v30, v24
	v_max_u32_e32 v23, v28, v16
	v_max_u32_e32 v25, v20, v18
	v_min_u32_e32 v47, v58, v47
	v_min_u32_e32 v41, v54, v41
	v_min_u32_e32 v45, v55, v45
	v_min_u32_e32 v27, v39, v27
	v_min_u32_e32 v24, v30, v24
	v_min_u32_e32 v16, v28, v16
	v_min_u32_e32 v18, v20, v18
	v_max3_u32 v12, v12, v15, v14
	v_max_u32_e32 v49, v48, v36
	v_max_u32_e32 v37, v53, v10
	v_max_u32_e32 v5, v9, v3
	v_max_u32_e32 v4, v7, v2
	v_min_u32_e32 v57, v56, v42
	v_min_u32_e32 v43, v50, v35
	v_min_u32_e32 v33, v29, v23
	v_min_u32_e32 v22, v25, v21
	v_min_u32_e32 v54, v47, v41
	v_min_u32_e32 v39, v45, v27
	v_min_u32_e32 v28, v24, v16
	v_min_u32_e32 v14, v18, v12
	v_min_u32_e32 v36, v48, v36
	v_min_u32_e32 v10, v53, v10
	s_mov_b64 s[50:51], exec
	s_mov_b64 exec, -1
	s_waitcnt vmcnt(0)
	v_pk_mul_f32 v[200:201], v[200:201], s[96:97] op_sel_hi:[1,0]
	v_pk_mul_f32 v[202:203], v[202:203], s[96:97] op_sel_hi:[1,0]
	v_pk_mul_f32 v[204:205], v[204:205], s[96:97] op_sel_hi:[1,0]
	v_pk_mul_f32 v[206:207], v[206:207], s[96:97] op_sel_hi:[1,0]
	v_pk_mul_f32 v[208:209], v[208:209], s[96:97] op_sel_hi:[1,0]
	v_pk_mul_f32 v[210:211], v[210:211], s[96:97] op_sel_hi:[1,0]
	v_pk_mul_f32 v[212:213], v[212:213], s[96:97] op_sel_hi:[1,0]
	v_pk_mul_f32 v[214:215], v[214:215], s[96:97] op_sel_hi:[1,0]
	v_pk_mul_f32 v[216:217], v[216:217], s[96:97] op_sel_hi:[1,0]
	v_pk_mul_f32 v[218:219], v[218:219], s[96:97] op_sel_hi:[1,0]
	v_pk_mul_f32 v[220:221], v[220:221], s[96:97] op_sel_hi:[1,0]
	v_pk_mul_f32 v[222:223], v[222:223], s[96:97] op_sel_hi:[1,0]
	v_pk_mul_f32 v[224:225], v[224:225], s[96:97] op_sel_hi:[1,0]
	v_pk_mul_f32 v[226:227], v[226:227], s[96:97] op_sel_hi:[1,0]
	v_pk_mul_f32 v[228:229], v[228:229], s[96:97] op_sel_hi:[1,0]
	v_pk_mul_f32 v[230:231], v[230:231], s[96:97] op_sel_hi:[1,0]
	v_cvt_scalef32_pk_fp4_f32 v232, v200, v201, 1.0
	v_cvt_scalef32_pk_fp4_f32 v233, v208, v209, 1.0
	v_cvt_scalef32_pk_fp4_f32 v234, v216, v217, 1.0
	v_cvt_scalef32_pk_fp4_f32 v235, v224, v225, 1.0
	v_cvt_scalef32_pk_fp4_f32 v232, v202, v203, 1.0 op_sel:[0,0,1,0]
	v_cvt_scalef32_pk_fp4_f32 v233, v210, v211, 1.0 op_sel:[0,0,1,0]
	v_cvt_scalef32_pk_fp4_f32 v234, v218, v219, 1.0 op_sel:[0,0,1,0]
	v_cvt_scalef32_pk_fp4_f32 v235, v226, v227, 1.0 op_sel:[0,0,1,0]
	v_cvt_scalef32_pk_fp4_f32 v232, v204, v205, 1.0 op_sel:[0,0,0,1]
	v_cvt_scalef32_pk_fp4_f32 v233, v212, v213, 1.0 op_sel:[0,0,0,1]
	v_cvt_scalef32_pk_fp4_f32 v234, v220, v221, 1.0 op_sel:[0,0,0,1]
	v_cvt_scalef32_pk_fp4_f32 v235, v228, v229, 1.0 op_sel:[0,0,0,1]
	v_cvt_scalef32_pk_fp4_f32 v232, v206, v207, 1.0 op_sel:[0,0,1,1]
	v_cvt_scalef32_pk_fp4_f32 v233, v214, v215, 1.0 op_sel:[0,0,1,1]
	v_cvt_scalef32_pk_fp4_f32 v234, v222, v223, 1.0 op_sel:[0,0,1,1]
	v_cvt_scalef32_pk_fp4_f32 v235, v230, v231, 1.0 op_sel:[0,0,1,1]
	s_nop 0
	global_store_dwordx4 v[240:241], v[232:235], off
	v_lshl_add_u64 v[240:241], v[240:241], 0, v[246:247]
	s_mov_b64 exec, s[50:51]
	s_nop 4
	v_min_u32_e32 v3, v9, v3
	v_min_u32_e32 v2, v7, v2
	v_max_u32_e32 v42, v56, v42
	v_max_u32_e32 v35, v50, v35
	v_max_u32_e32 v23, v29, v23
	v_max_u32_e32 v21, v25, v21
	v_max_u32_e32 v41, v47, v41
	v_max_u32_e32 v27, v45, v27
	v_max_u32_e32 v16, v24, v16
	v_max_u32_e32 v12, v18, v12
	v_max_u32_e32 v81, v91, v80
	v_max_u32_e32 v64, v82, v52
	v_max_u32_e32 v46, v51, v40
	v_max_u32_e32 v13, v44, v11
	v_min_u32_e32 v59, v57, v43
	v_min_u32_e32 v26, v33, v22
	v_min_u32_e32 v55, v54, v39
	v_min_u32_e32 v15, v28, v14
	v_min_u32_e32 v30, v91, v80
	v_min_u32_e32 v52, v82, v52
	v_min_u32_e32 v40, v51, v40
	v_min_u32_e32 v11, v44, v11
	v_max_u32_e32 v48, v36, v10
	v_max_u32_e32 v7, v3, v2
	v_min_u32_e32 v50, v42, v35
	v_min_u32_e32 v25, v23, v21
	v_min_u32_e32 v45, v41, v27
	v_min_u32_e32 v18, v16, v12
	v_max_u32_e32 v43, v57, v43
	v_max_u32_e32 v22, v33, v22
	v_max_u32_e32 v39, v54, v39
	v_max_u32_e32 v14, v28, v14
	v_min_u32_e32 v10, v36, v10
	v_min_u32_e32 v2, v3, v2
	v_max_u32_e32 v35, v42, v35
	v_max_u32_e32 v21, v23, v21
	v_max_u32_e32 v27, v41, v27
	v_max_u32_e32 v12, v16, v12
	v_max_u32_e32 v65, v81, v64
	v_max_u32_e32 v31, v46, v13
	v_max_u32_e32 v38, v49, v37
	v_max_u32_e32 v6, v5, v4
	v_min_u32_e32 v34, v59, v26
	v_min_u32_e32 v17, v55, v15
	v_max_u32_e32 v58, v30, v52
	v_max_u32_e32 v44, v40, v11
	v_min_u32_e32 v29, v50, v25
	v_min_u32_e32 v24, v45, v18
	v_min_u32_e32 v56, v81, v64
	v_min_u32_e32 v13, v46, v13
	v_min_u32_e32 v37, v49, v37
	v_min_u32_e32 v4, v5, v4
	v_min_u32_e32 v33, v43, v22
	v_min_u32_e32 v28, v39, v14
	v_min_u32_e32 v30, v30, v52
	v_min_u32_e32 v11, v40, v11
	v_max_u32_e32 v3, v10, v2
	v_min_u32_e32 v23, v35, v21
	v_min_u32_e32 v16, v27, v12
	v_max_u32_e32 v26, v59, v26
	v_max_u32_e32 v15, v55, v15
	v_max_u32_e32 v25, v50, v25
	v_max_u32_e32 v18, v45, v18
	v_max_u32_e32 v22, v43, v22
	v_max_u32_e32 v14, v39, v14
	v_min_u32_e32 v2, v10, v2
	v_max_u32_e32 v10, v35, v21
	v_max_u32_e32 v12, v27, v12
	v_max_u32_e32 v32, v65, v31
	v_max_u32_e32 v8, v38, v6
	v_min_u32_e32 v20, v34, v17
	v_max_u32_e32 v51, v58, v44
	v_max_u32_e32 v9, v48, v7
	v_min_u32_e32 v47, v29, v24
	v_max_u32_e32 v46, v56, v13
	v_max_u32_e32 v5, v37, v4
	v_min_u32_e32 v49, v33, v28
	v_max_u32_e32 v40, v30, v11
	v_min_u32_e32 v36, v23, v16
	v_min_u32_e32 v31, v65, v31
	v_min_u32_e32 v6, v38, v6
	v_min_u32_e32 v38, v26, v15
	v_min_u32_e32 v44, v58, v44
	v_min_u32_e32 v7, v48, v7
	v_min_u32_e32 v45, v25, v18
	v_min_u32_e32 v13, v56, v13
	v_min_u32_e32 v4, v37, v4
	v_min_u32_e32 v37, v22, v14
	v_min_u32_e32 v11, v30, v11
	v_min_u32_e32 v21, v10, v12
	v_max3_u32 v20, v32, v8, v20
	v_max3_u32 v47, v51, v9, v47
	v_max3_u32 v49, v46, v5, v49
	v_max3_u32 v36, v40, v3, v36
	v_max3_u32 v38, v31, v6, v38
	v_max3_u32 v45, v44, v7, v45
	v_max3_u32 v37, v13, v4, v37
	v_max3_u32 v21, v11, v2, v21
	v_min_u32_e32 v8, v32, v8
	v_min_u32_e32 v9, v51, v9
	v_min_u32_e32 v5, v46, v5
	v_min_u32_e32 v3, v40, v3
	v_min_u32_e32 v6, v31, v6
	v_min_u32_e32 v7, v44, v7
	v_min_u32_e32 v4, v13, v4
	v_min_u32_e32 v2, v11, v2
	v_max3_u32 v8, v8, v34, v17
	v_max3_u32 v9, v9, v29, v24
	v_max3_u32 v5, v5, v33, v28
	v_max3_u32 v3, v3, v23, v16
	v_max3_u32 v6, v6, v26, v15
	v_max3_u32 v7, v7, v25, v18
	v_max3_u32 v4, v4, v22, v14
	v_max3_u32 v2, v2, v10, v12
	v_max_u32_e32 v53, v20, v47
	v_max_u32_e32 v41, v49, v36
	v_max_u32_e32 v48, v38, v45
	v_max_u32_e32 v27, v37, v21
	v_max_u32_e32 v17, v8, v9
	v_max_u32_e32 v16, v5, v3
	v_max_u32_e32 v15, v6, v7
	v_max_u32_e32 v10, v4, v2
	v_max_u32_e32 v42, v53, v41
	v_max_u32_e32 v30, v48, v27
	v_max_u32_e32 v23, v17, v16
	v_max_u32_e32 v11, v15, v10
	v_max_u32_e32 v35, v42, v30
	v_max_u32_e32 v12, v23, v11
	v_max_u32_e32 v13, v35, v12
	v_min_u32_e32 v12, v35, v12
	v_cmp_lt_i32_e32 vcc, -1, v12
	v_not_b32_e32 v32, v12
	v_min_u32_e32 v11, v23, v11
	v_cndmask_b32_e64 v14, v86, -1, vcc
	v_bitop3_b32 v12, v14, v12, s29 bitop3:0x78
	v_min_u32_e32 v14, v42, v30
	v_max_u32_e32 v18, v14, v11
	v_cmp_lt_i32_e32 vcc, -1, v18
	v_min_u32_e32 v11, v14, v11
	v_not_b32_e32 v33, v18
	v_cndmask_b32_e64 v22, v86, -1, vcc
	v_cmp_lt_i32_e32 vcc, -1, v11
	v_bitop3_b32 v18, v22, v18, s29 bitop3:0x78
	v_not_b32_e32 v34, v11
	v_cndmask_b32_e64 v14, v86, -1, vcc
	v_bitop3_b32 v11, v14, v11, s29 bitop3:0x78
	v_min_u32_e32 v14, v53, v41
	v_min_u32_e32 v22, v48, v27
	v_min_u32_e32 v16, v17, v16
	v_min_u32_e32 v10, v15, v10
	v_max_u32_e32 v23, v14, v22
	v_max_u32_e32 v15, v16, v10
	v_max_u32_e32 v17, v23, v15
	v_cmp_lt_i32_e32 vcc, -1, v17
	v_min_u32_e32 v15, v23, v15
	v_min_u32_e32 v14, v14, v22
	v_min_u32_e32 v10, v16, v10
	v_cndmask_b32_e64 v24, v86, -1, vcc
	v_cmp_lt_i32_e32 vcc, -1, v15
	v_max_u32_e32 v16, v14, v10
	v_min_u32_e32 v10, v14, v10
	v_cndmask_b32_e64 v23, v86, -1, vcc
	v_cmp_lt_i32_e32 vcc, -1, v16
	v_not_b32_e32 v30, v15
	v_bitop3_b32 v15, v23, v15, s29 bitop3:0x78
	v_cndmask_b32_e64 v22, v86, -1, vcc
	v_cmp_lt_i32_e32 vcc, -1, v10
	v_not_b32_e32 v35, v10
	v_min_u32_e32 v23, v38, v45
	v_cndmask_b32_e64 v14, v86, -1, vcc
	v_bitop3_b32 v14, v14, v10, s29 bitop3:0x78
	v_min_u32_e32 v10, v20, v47
	v_min_u32_e32 v20, v49, v36
	v_min_u32_e32 v21, v37, v21
	v_min_u32_e32 v8, v8, v9
	v_min_u32_e32 v3, v5, v3
	v_min_u32_e32 v6, v6, v7
	v_min_u32_e32 v2, v4, v2
	v_not_b32_e32 v29, v17
	v_bitop3_b32 v17, v24, v17, s29 bitop3:0x78
	v_not_b32_e32 v31, v16
	v_bitop3_b32 v16, v22, v16, s29 bitop3:0x78
	v_max_u32_e32 v22, v10, v20
	v_max_u32_e32 v24, v23, v21
	v_max_u32_e32 v5, v8, v3
	v_max_u32_e32 v4, v6, v2
	v_max_u32_e32 v25, v22, v24
	v_max_u32_e32 v7, v5, v4
	v_max_u32_e32 v9, v25, v7
	v_cmp_lt_i32_e32 vcc, -1, v9
	v_min_u32_e32 v7, v25, v7
	v_min_u32_e32 v22, v22, v24
	v_min_u32_e32 v4, v5, v4
	v_cndmask_b32_e64 v27, v86, -1, vcc
	v_cmp_lt_i32_e32 vcc, -1, v7
	v_max_u32_e32 v5, v22, v4
	v_not_b32_e32 v26, v9
	v_bitop3_b32 v9, v27, v9, s29 bitop3:0x78
	v_cndmask_b32_e64 v27, v86, -1, vcc
	v_cmp_lt_i32_e32 vcc, -1, v5
	v_min_u32_e32 v4, v22, v4
	v_not_b32_e32 v25, v7
	v_bitop3_b32 v7, v27, v7, s29 bitop3:0x78
	v_cndmask_b32_e64 v27, v86, -1, vcc
	v_cmp_lt_i32_e32 vcc, -1, v4
	v_not_b32_e32 v24, v5
	v_bitop3_b32 v27, v27, v5, s29 bitop3:0x78
	v_cndmask_b32_e64 v5, v86, -1, vcc
	v_not_b32_e32 v36, v4
	v_bitop3_b32 v22, v5, v4, s29 bitop3:0x78
	v_min_u32_e32 v4, v10, v20
	v_min_u32_e32 v5, v23, v21
	v_min_u32_e32 v3, v8, v3
	v_min_u32_e32 v2, v6, v2
	v_max_u32_e32 v10, v4, v5
	v_max_u32_e32 v6, v3, v2
	v_max_u32_e32 v8, v10, v6
	v_cmp_lt_i32_e32 vcc, -1, v8
	v_not_b32_e32 v20, v8
	v_min_u32_e32 v4, v4, v5
	v_cndmask_b32_e64 v21, v86, -1, vcc
	v_bitop3_b32 v8, v21, v8, s29 bitop3:0x78
	v_min_u32_e32 v21, v10, v6
	v_min_u32_e32 v2, v3, v2
	v_cmp_lt_i32_e32 vcc, -1, v21
	v_max_u32_e32 v37, v4, v2
	v_min_u32_e32 v39, v4, v2
	v_cndmask_b32_e64 v6, v86, -1, vcc
	v_cmp_lt_i32_e32 vcc, -1, v37
	v_and_b32_e32 v4, 0xffffff00, v13
	v_and_b32_e32 v5, 0xffffff00, v39
	v_cndmask_b32_e64 v3, v86, -1, vcc
	v_cmp_lt_i32_e32 vcc, -1, v13
	v_bitop3_b32 v38, v3, v37, s29 bitop3:0x78
	v_bitop3_b32 v23, v6, v21, s29 bitop3:0x78
	v_cndmask_b32_e64 v2, v86, -1, vcc
	v_cmp_lt_i32_e32 vcc, -1, v39
	v_xor_b32_e32 v40, v2, v4
	v_sub_f32_e32 v2, v40, v40
	v_cndmask_b32_e64 v3, v86, -1, vcc
	v_xor_b32_e32 v41, v3, v5
	v_mul_f32_e32 v2, 0x3fb8aa3b, v2
	v_sub_f32_e32 v3, v12, v40
	v_sub_f32_e32 v4, v18, v40
	v_exp_f32_e32 v2, v2
	v_mul_f32_e32 v3, 0x3fb8aa3b, v3
	v_mul_f32_e32 v4, 0x3fb8aa3b, v4
	v_exp_f32_e32 v3, v3
	v_exp_f32_e32 v10, v4
	v_sub_f32_e32 v4, v11, v40
	v_mul_f32_e32 v4, 0x3fb8aa3b, v4
	v_exp_f32_e32 v11, v4
	v_add_f32_e32 v4, 0, v2
	v_add_f32_e32 v4, v3, v4
	v_add_f32_e32 v4, v10, v4
	v_add_f32_e32 v6, v11, v4
	v_sub_f32_e32 v4, v17, v40
	v_mul_f32_e32 v4, 0x3fb8aa3b, v4
	v_sub_f32_e32 v5, v15, v40
	v_exp_f32_e32 v4, v4
	v_mul_f32_e32 v5, 0x3fb8aa3b, v5
	v_sub_f32_e32 v12, v16, v40
	v_not_b32_e32 v28, v13
	v_exp_f32_e32 v5, v5
	v_mul_f32_e32 v12, 0x3fb8aa3b, v12
	v_sub_f32_e32 v13, v14, v40
	v_exp_f32_e32 v12, v12
	v_mul_f32_e32 v13, 0x3fb8aa3b, v13
	v_exp_f32_e32 v13, v13
	v_add_f32_e32 v6, v4, v6
	v_add_f32_e32 v6, v5, v6
	v_add_f32_e32 v6, v12, v6
	v_add_f32_e32 v16, v13, v6
	v_sub_f32_e32 v6, v9, v40
	v_mul_f32_e32 v6, 0x3fb8aa3b, v6
	v_sub_f32_e32 v7, v7, v40
	v_sub_f32_e32 v9, v27, v40
	v_exp_f32_e32 v6, v6
	v_mul_f32_e32 v7, 0x3fb8aa3b, v7
	v_mul_f32_e32 v9, 0x3fb8aa3b, v9
	v_exp_f32_e32 v7, v7
	v_exp_f32_e32 v14, v9
	v_sub_f32_e32 v9, v22, v40
	v_mul_f32_e32 v9, 0x3fb8aa3b, v9
	v_exp_f32_e32 v15, v9
	v_add_f32_e32 v9, v6, v16
	v_add_f32_e32 v9, v7, v9
	v_add_f32_e32 v9, v14, v9
	v_sub_f32_e32 v8, v8, v40
	v_add_f32_e32 v18, v15, v9
	v_mul_f32_e32 v8, 0x3fb8aa3b, v8
	v_sub_f32_e32 v9, v23, v40
	v_exp_f32_e32 v8, v8
	v_mul_f32_e32 v9, 0x3fb8aa3b, v9
	v_sub_f32_e32 v16, v38, v40
	v_exp_f32_e32 v9, v9
	v_mul_f32_e32 v16, 0x3fb8aa3b, v16
	v_sub_f32_e32 v17, v41, v40
	v_exp_f32_e32 v16, v16
	v_mul_f32_e32 v17, 0x3fb8aa3b, v17
	v_exp_f32_e32 v17, v17
	v_add_f32_e32 v18, v8, v18
	v_add_f32_e32 v18, v9, v18
	v_add_f32_e32 v18, v16, v18
	v_add_f32_e32 v18, v17, v18
	v_div_scale_f32 v22, s[34:35], v18, v18, 1.0
	v_rcp_f32_e32 v23, v22
	v_not_b32_e32 v27, v37
	v_not_b32_e32 v37, v39
	v_not_b32_e32 v21, v21
	v_fma_f32 v38, -v22, v23, 1.0
	v_fmac_f32_e32 v23, v38, v23
	v_div_scale_f32 v38, vcc, 1.0, v18, 1.0
	v_mul_f32_e32 v39, v38, v23
	v_fma_f32 v40, -v22, v39, v38
	v_fmac_f32_e32 v39, v40, v23
	v_fma_f32 v22, -v22, v39, v38
	v_div_fmas_f32 v22, v22, v23, v39
	v_div_fixup_f32 v18, v22, v18, 1.0
	v_lshlrev_b32_e32 v22, 4, v37
	v_lshlrev_b32_e32 v23, 8, v37
	v_lshlrev_b32_e32 v38, 4, v27
	v_lshlrev_b32_e32 v27, 8, v27
	v_lshlrev_b32_e32 v39, 4, v21
	v_lshlrev_b32_e32 v21, 8, v21
	v_lshlrev_b32_e32 v40, 4, v20
	v_lshlrev_b32_e32 v20, 8, v20
	v_and_b32_e32 v22, 0xf00, v22
	v_and_b32_e32 v23, 0xf00, v23
	v_lshlrev_b32_e32 v37, 2, v87
	v_and_b32_e32 v38, 0xf00, v38
	v_and_b32_e32 v27, 0xf00, v27
	v_and_b32_e32 v39, 0xf00, v39
	v_and_b32_e32 v21, 0xf00, v21
	v_and_b32_e32 v40, 0xf00, v40
	v_and_b32_e32 v20, 0xf00, v20
	v_add_u32_e32 v22, v19, v22
	v_add3_u32 v23, s26, v23, v37
	v_add_u32_e32 v38, v19, v38
	v_add3_u32 v27, s26, v27, v37
	v_add_u32_e32 v39, v19, v39
	v_add3_u32 v21, s26, v21, v37
	v_add_u32_e32 v40, v19, v40
	v_add3_u32 v20, s26, v20, v37
	ds_read_b32 v22, v22
	ds_read_b32 v23, v23 offset:4096
	ds_read_b32 v38, v38
	ds_read_b32 v27, v27 offset:4096
	ds_read_b32 v39, v39
	ds_read_b32 v21, v21 offset:4096
	ds_read_b32 v40, v40
	ds_read_b32 v20, v20 offset:4096
	s_waitcnt lgkmcnt(6)
	v_lshl_add_u32 v23, v22, 7, v23
	s_waitcnt lgkmcnt(4)
	v_lshl_add_u32 v22, v38, 7, v27
	s_waitcnt lgkmcnt(2)
	v_lshl_add_u32 v21, v39, 7, v21
	v_lshlrev_b32_e32 v27, 4, v36
	v_lshlrev_b32_e32 v36, 8, v36
	v_lshlrev_b32_e32 v38, 4, v24
	v_lshlrev_b32_e32 v24, 8, v24
	v_lshlrev_b32_e32 v39, 4, v25
	v_lshlrev_b32_e32 v25, 8, v25
	v_lshlrev_b32_e32 v41, 4, v26
	v_and_b32_e32 v27, 0xf00, v27
	v_and_b32_e32 v36, 0xf00, v36
	v_and_b32_e32 v38, 0xf00, v38
	v_and_b32_e32 v24, 0xf00, v24
	v_and_b32_e32 v39, 0xf00, v39
	v_and_b32_e32 v25, 0xf00, v25
	v_and_b32_e32 v41, 0xf00, v41
	v_lshlrev_b32_e32 v26, 8, v26
	v_add_u32_e32 v27, v19, v27
	v_add3_u32 v36, s26, v36, v37
	v_add_u32_e32 v38, v19, v38
	v_add3_u32 v24, s26, v24, v37
	v_add_u32_e32 v39, v19, v39
	v_add3_u32 v25, s26, v25, v37
	v_add_u32_e32 v41, v19, v41
	v_and_b32_e32 v26, 0xf00, v26
	v_add3_u32 v26, s26, v26, v37
	ds_read_b32 v27, v27
	ds_read_b32 v36, v36 offset:4096
	ds_read_b32 v38, v38
	ds_read_b32 v24, v24 offset:4096
	ds_read_b32 v39, v39
	ds_read_b32 v25, v25 offset:4096
	ds_read_b32 v41, v41
	ds_read_b32 v42, v26 offset:4096
	s_waitcnt lgkmcnt(8)
	v_lshl_add_u32 v20, v40, 7, v20
	s_waitcnt lgkmcnt(6)
	v_lshl_add_u32 v27, v27, 7, v36
	s_waitcnt lgkmcnt(4)
	v_lshl_add_u32 v26, v38, 7, v24
	s_waitcnt lgkmcnt(2)
	v_lshl_add_u32 v25, v39, 7, v25
	v_lshlrev_b32_e32 v36, 4, v35
	v_lshlrev_b32_e32 v35, 8, v35
	v_lshlrev_b32_e32 v38, 4, v31
	v_lshlrev_b32_e32 v39, 4, v30
	v_lshlrev_b32_e32 v40, 4, v29
	v_and_b32_e32 v36, 0xf00, v36
	v_and_b32_e32 v35, 0xf00, v35
	v_and_b32_e32 v38, 0xf00, v38
	v_lshlrev_b32_e32 v31, 8, v31
	v_and_b32_e32 v39, 0xf00, v39
	v_lshlrev_b32_e32 v30, 8, v30
	v_and_b32_e32 v40, 0xf00, v40
	v_lshlrev_b32_e32 v29, 8, v29
	v_add_u32_e32 v36, v19, v36
	v_add3_u32 v35, s26, v35, v37
	v_add_u32_e32 v38, v19, v38
	v_and_b32_e32 v31, 0xf00, v31
	v_add_u32_e32 v39, v19, v39
	v_and_b32_e32 v30, 0xf00, v30
	v_add_u32_e32 v40, v19, v40
	v_and_b32_e32 v29, 0xf00, v29
	s_waitcnt lgkmcnt(0)
	v_lshl_add_u32 v24, v41, 7, v42
	v_add3_u32 v31, s26, v31, v37
	v_add3_u32 v30, s26, v30, v37
	v_add3_u32 v29, s26, v29, v37
	ds_read_b32 v36, v36
	ds_read_b32 v35, v35 offset:4096
	ds_read_b32 v38, v38
	ds_read_b32 v41, v31 offset:4096
	ds_read_b32 v39, v39
	ds_read_b32 v42, v30 offset:4096
	ds_read_b32 v40, v40
	ds_read_b32 v43, v29 offset:4096
	s_waitcnt lgkmcnt(6)
	v_lshl_add_u32 v31, v36, 7, v35
	s_waitcnt lgkmcnt(4)
	v_lshl_add_u32 v30, v38, 7, v41
	s_waitcnt lgkmcnt(2)
	v_lshl_add_u32 v29, v39, 7, v42
	v_lshlrev_b32_e32 v35, 4, v34
	v_lshlrev_b32_e32 v34, 8, v34
	v_lshlrev_b32_e32 v36, 4, v33
	v_lshlrev_b32_e32 v33, 8, v33
	v_lshlrev_b32_e32 v38, 4, v32
	v_lshlrev_b32_e32 v32, 8, v32
	v_lshlrev_b32_e32 v39, 4, v28
	v_and_b32_e32 v35, 0xf00, v35
	v_and_b32_e32 v34, 0xf00, v34
	v_and_b32_e32 v36, 0xf00, v36
	v_and_b32_e32 v33, 0xf00, v33
	v_and_b32_e32 v38, 0xf00, v38
	v_and_b32_e32 v32, 0xf00, v32
	v_and_b32_e32 v39, 0xf00, v39
	v_lshlrev_b32_e32 v28, 8, v28
	v_add_u32_e32 v35, v19, v35
	v_add3_u32 v34, s26, v34, v37
	v_add_u32_e32 v36, v19, v36
	v_add3_u32 v33, s26, v33, v37
	v_add_u32_e32 v38, v19, v38
	v_add3_u32 v32, s26, v32, v37
	v_add_u32_e32 v19, v19, v39
	v_and_b32_e32 v28, 0xf00, v28
	v_add3_u32 v28, s26, v28, v37
	ds_read_b32 v35, v35
	ds_read_b32 v34, v34 offset:4096
	ds_read_b32 v36, v36
	ds_read_b32 v33, v33 offset:4096
	ds_read_b32 v37, v38
	ds_read_b32 v32, v32 offset:4096
	ds_read_b32 v19, v19
	ds_read_b32 v38, v28 offset:4096
	s_waitcnt lgkmcnt(6)
	v_lshl_add_u32 v35, v35, 7, v34
	s_waitcnt lgkmcnt(4)
	v_lshl_add_u32 v34, v36, 7, v33
	v_or_b32_e32 v36, s31, v87
	s_waitcnt lgkmcnt(2)
	v_lshl_add_u32 v33, v37, 7, v32
	v_ashrrev_i32_e32 v37, 31, v36
	v_lshlrev_b64 v[36:37], 9, v[36:37]
	s_waitcnt lgkmcnt(0)
	v_lshl_add_u32 v32, v19, 7, v38
	v_lshl_add_u64 v[38:39], s[8:9], 0, v[36:37]
	v_lshl_add_u64 v[38:39], v[38:39], 0, s[12:13]
	v_lshl_add_u64 v[36:37], s[10:11], 0, v[36:37]
	v_lshl_add_u64 v[36:37], v[36:37], 0, s[12:13]
	global_store_dwordx4 v[38:39], v[32:35], off
	v_pk_mul_f32 v[12:13], v[12:13], v[18:19] op_sel_hi:[1,0]
	v_lshl_add_u32 v28, v40, 7, v43
	v_pk_mul_f32 v[34:35], v[10:11], v[18:19] op_sel_hi:[1,0]
	v_pk_mul_f32 v[32:33], v[2:3], v[18:19] op_sel_hi:[1,0]
	v_pk_mul_f32 v[10:11], v[4:5], v[18:19] op_sel_hi:[1,0]
	v_pk_mul_f32 v[4:5], v[14:15], v[18:19] op_sel_hi:[1,0]
	v_pk_mul_f32 v[2:3], v[6:7], v[18:19] op_sel_hi:[1,0]
	global_store_dwordx4 v[36:37], v[32:35], off
	global_store_dwordx4 v[38:39], v[28:31], off offset:16
	global_store_dwordx4 v[36:37], v[10:13], off offset:16
	global_store_dwordx4 v[38:39], v[24:27], off offset:32
	global_store_dwordx4 v[36:37], v[2:5], off offset:32
	global_store_dwordx4 v[38:39], v[20:23], off offset:48
	s_nop 0
	v_pk_mul_f32 v[4:5], v[16:17], v[18:19] op_sel_hi:[1,0]
	v_pk_mul_f32 v[2:3], v[8:9], v[18:19] op_sel_hi:[1,0]
	global_store_dwordx4 v[36:37], v[2:5], off offset:48
	s_branch .LBB0_801
.LBB0_804:
	s_load_dwordx2 s[6:7], s[68:69], 0x58
	s_waitcnt lgkmcnt(0)
	s_cmpk_eq_i32 s18, 0x100
	s_cbranch_scc1 .LBB0_807
	v_lshlrev_b32_e32 v2, 2, v76
	s_and_saveexec_b64 s[2:3], s[4:5]
	s_cbranch_execz .LBB0_807
	v_mov_b32_e32 v3, 0
	v_lshl_add_u64 v[4:5], s[6:7], 0, v[2:3]
	s_mov_b64 s[6:7], 0
	s_mov_b32 s8, 0x42580000
	s_mov_b64 s[10:11], 0x1000
	s_movk_i32 s9, 0x1000
	s_mov_b64 s[12:13], 0xfffff
	v_mov_b64_e32 v[6:7], v[70:71]

.LBB0_807:
	s_or_b64 exec, exec, s[2:3]
	s_load_dwordx2 s[6:7], s[68:69], 0x60
	s_waitcnt lgkmcnt(0)
	s_cmpk_eq_i32 s18, 0x100
	s_cbranch_scc1 .LBB0_810
	s_and_saveexec_b64 s[2:3], s[4:5]
	s_cbranch_execz .LBB0_810
	v_mov_b32_e32 v3, 0
	v_lshl_add_u64 v[2:3], s[6:7], 0, v[2:3]
	s_mov_b64 s[4:5], 0
	s_mov_b32 s6, 0x40b66666
	s_mov_b64 s[8:9], 0x1000
	s_movk_i32 s7, 0x1000
	s_mov_b64 s[10:11], 0xfffff
